# LDS-DMA GEMM core rolled out to inproj, outproj, ffn_in, ffn_out, lin mainloops (14 sites)
# speedup vs baseline: 1.0745x; 1.0356x over previous
.LBB0_200:
	s_cmp_gt_i32 s60, 2
	s_waitcnt lgkmcnt(0)
	s_cselect_b64 s[2:3], -1, 0
	s_cmp_lt_i32 s61, 2
	s_cselect_b64 s[4:5], -1, 0
	s_or_b64 s[2:3], s[2:3], s[4:5]
	s_and_b64 vcc, exec, s[2:3]
	s_cbranch_vccnz .LBB0_472
	s_mov_b64 s[14:15], s[0:1]
	s_cmpk_gt_i32 s58, 0xc3f
	s_cbranch_scc1 .LBB0_418
	s_load_dwordx2 s[16:17], s[14:15], 0xe0
	s_load_dword s3, s[0:1], 0xf0
	v_lshrrev_b32_e32 v9, 3, v162
	v_lshlrev_b32_e32 v0, 3, v162
	v_and_b32_e32 v0, 56, v0
	s_waitcnt lgkmcnt(0)
	s_add_u32 s18, s16, 0x8b7a100
	s_addc_u32 s19, s17, 0
	v_mov_b32_e32 v99, 0
	v_lshlrev_b32_e32 v98, 11, v9
	v_lshl_add_u64 v[4:5], s[18:19], 0, v[98:99]
	v_lshlrev_b32_e32 v6, 1, v0
	v_mov_b32_e32 v7, v99
	v_xor_b32_e32 v10, v163, v162
	v_lshl_add_u64 v[100:101], v[4:5], 0, v[6:7]
	v_lshl_add_u64 v[4:5], s[16:17], 0, v[98:99]
	v_lshl_add_u64 v[102:103], v[4:5], 0, v[6:7]
	v_lshlrev_b32_e32 v5, 4, v10
	v_and_b32_e32 v96, 15, v162
	v_bfe_u32 v4, v162, 1, 3
	v_and_b32_e32 v5, 0x70, v5
	v_bfe_u32 v1, v162, 6, 1
	v_lshrrev_b32_e32 v3, 7, v162
	v_bitop3_b32 v4, v163, v4, 3 bitop3:0x6c
	v_lshl_or_b32 v160, v9, 7, v5
	v_lshlrev_b32_e32 v5, 7, v96
	v_lshl_or_b32 v6, v3, 13, v5
	v_lshl_or_b32 v5, v1, 13, v5
	v_lshlrev_b32_e32 v4, 4, v4
	v_or_b32_e32 v161, v6, v4
	v_or_b32_e32 v165, v5, v4
	v_xor_b32_e32 v4, 64, v4
	v_or_b32_e32 v166, v6, v4
	v_or_b32_e32 v167, v5, v4
	v_lshlrev_b32_e32 v4, 2, v96
	v_mov_b32_e32 v5, v99
	v_lshl_add_u64 v[4:5], s[16:17], 0, v[4:5]
	s_mov_b64 s[6:7], 0x1237a100
	v_lshl_add_u64 v[104:105], v[4:5], 0, s[6:7]
	s_mov_b64 s[6:7], 0x1237a140
	v_lshl_add_u64 v[106:107], v[4:5], 0, s[6:7]
	v_lshlrev_b32_e32 v4, 7, v1
	v_mov_b32_e32 v5, v99
	v_lshl_add_u64 v[4:5], s[16:17], 0, v[4:5]
	s_mov_b64 s[6:7], 0xdb7a100
	s_add_u32 s22, s16, 0xef7a100
	v_lshl_add_u64 v[108:109], v[4:5], 0, s[6:7]
	s_mov_b64 s[6:7], 0xe37a100
	v_lshlrev_b32_e32 v169, 6, v1
	v_cmp_eq_u32_e64 s[4:5], 0, v1
	s_addc_u32 s23, s17, 0
	v_lshl_add_u64 v[110:111], v[4:5], 0, s[6:7]
	v_lshlrev_b32_e32 v4, 1, v96
	v_mov_b32_e32 v5, v99
	v_and_b32_e32 v1, 7, v162
	s_add_u32 s24, s16, 0x6b00000
	v_lshl_add_u64 v[4:5], s[16:17], 0, v[4:5]
	s_mov_b64 s[6:7], 0x9b7a100
	v_lshl_or_b32 v98, v1, 4, v98
	s_addc_u32 s25, s17, 0
	v_lshl_add_u64 v[112:113], v[4:5], 0, s[6:7]
	v_lshl_add_u64 v[4:5], s[16:17], 0, v[98:99]
	s_mov_b64 s[6:7], 0x200
	v_bfe_u32 v8, v162, 4, 2
	v_lshlrev_b32_e32 v2, 10, v9
	v_lshlrev_b32_e32 v3, 6, v3
	s_add_u32 s26, s16, 0xcb7a100
	v_lshl_add_u64 v[114:115], v[4:5], 0, s[6:7]
	s_mov_b64 s[6:7], 0x8b7a300
	v_lshl_or_b32 v168, v8, 2, v3
	s_mov_b32 s21, 0
	v_or_b32_e32 v170, v169, v96
	s_addc_u32 s27, s17, 0
	s_lshl_b32 s66, s58, 1
	s_lshl_b32 s67, s3, 1
	v_lshl_add_u64 v[116:117], v[4:5], 0, s[6:7]
	s_lshl_b32 s68, s58, 7
	s_lshl_b32 s69, s3, 7
	s_mov_b64 s[8:9], 0
	s_movk_i32 s70, 0xff80
	s_mov_b32 s71, 0x10000
	s_mov_b64 s[28:29], 0x100
	s_mov_b64 s[30:31], 0x10000
	s_mov_b64 s[34:35], 0x10100
	s_mov_b64 s[36:37], 0x20000
	s_mov_b64 s[38:39], 0x20100
	s_mov_b64 s[40:41], 0x30000
	s_mov_b64 s[42:43], 0x30100
	v_lshlrev_b32_e32 v118, 1, v2
	v_mov_b32_e32 v119, v99
	v_lshlrev_b32_e32 v120, 1, v0
	v_mov_b32_e32 v121, v99
	s_mov_b64 s[44:45], 0x780
	s_mov_b32 s72, 0x3fff80
	s_mov_b32 s73, 0xf77a000
	s_mov_b32 s74, 0xf786000
	s_mov_b64 s[46:47], 0xf79e500
	s_movk_i32 s75, 0xf400
	s_movk_i32 s76, 0x7e00
	s_mov_b64 s[48:49], 0x2000000
	s_movk_i32 s77, 0xf0
	s_movk_i32 s78, 0xc0
	s_movk_i32 s79, 0x600
	s_movk_i32 s80, 0x200
	s_movk_i32 s81, 0x3d0
	s_movk_i32 s82, 0x3e0
	s_movk_i32 s83, 0x3f0
	s_movk_i32 s59, 0x3c0
	s_mov_b32 s86, 0xab89000
	s_mov_b32 s87, 0xab8a000
	s_mov_b32 s88, 0xab8b000
	s_mov_b32 s89, 0xab8c000
	s_mov_b32 s90, 0xab99000
	s_mov_b32 s91, 0xab9a000
	s_mov_b32 s92, 0xab9b000
	s_mov_b32 s93, 0xab9c000
	s_mov_b32 s94, 0xaba9000
	s_mov_b32 s95, 0xabaa000
	s_mov_b32 s96, 0xabab000
	s_mov_b32 s97, 0xabac000
	s_mov_b64 s[50:51], 0x60
	s_mov_b32 s2, s58
	v_and_b32_e32 v240, 63, v162
	v_lshrrev_b32_e32 v247, 6, v162
	v_lshrrev_b32_e32 v242, 3, v240
	v_lshl_add_u32 v242, v247, 5, v242
	v_and_b32_e32 v243, 7, v240
	v_lshrrev_b32_e32 v244, 4, v240
	v_xor_b32_e32 v243, v243, v244
	v_lshlrev_b32_e32 v243, 4, v243
	v_mov_b32_e32 v241, 0x800
	v_mad_u32_u24 v248, v242, v241, v243
	v_xor_b32_e32 v249, 64, v248
	v_add_u32_e32 v249, 0x4000, v249
	v_add_u32_e32 v250, 0x8000, v248
	v_xor_b32_e32 v251, 64, v248
	v_add_u32_e32 v251, 0xc000, v251
	v_and_b32_e32 v241, 15, v240
	v_lshrrev_b32_e32 v242, 1, v241
	v_xor_b32_e32 v242, v242, v244
	v_lshlrev_b32_e32 v242, 4, v242
	v_lshl_or_b32 v242, v241, 7, v242
	v_lshrrev_b32_e32 v243, 1, v247
	v_lshl_or_b32 v252, v243, 13, v242
	v_xor_b32_e32 v253, 64, v252
	v_and_b32_e32 v243, 1, v247
	v_lshl_or_b32 v254, v243, 13, v242
	v_xor_b32_e32 v255, 64, v254
	s_branch .LBB0_204

.LBB0_204:
	s_lshl_b32 s6, s2, 7
	s_lshl_b32 s13, s2, 1
	s_and_b32 s12, s6, 0x1f80
	s_and_b32 s6, s13, 0xffffff80
	s_ashr_i32 s7, s6, 31
	s_lshl_b64 s[10:11], s[6:7], 11
	s_lshl_b32 s20, s12, 11
	v_lshl_add_u64 v[122:123], v[100:101], 0, s[20:21]
	v_lshl_add_u64 v[124:125], v[102:103], 0, s[10:11]
	s_and_b64 vcc, exec, s[8:9]
	s_mov_b64 s[8:9], -1
	s_cbranch_vccnz .LBB0_206
	v_add_co_u32_e32 v32, vcc, 0x10000, v122
	s_nop 0
	v_addc_co_u32_e32 v33, vcc, 0, v123, vcc
	v_add_co_u32_e32 v34, vcc, 0x20000, v122
	s_nop 0
	v_addc_co_u32_e32 v35, vcc, 0, v123, vcc
	v_add_co_u32_e32 v36, vcc, 0x30000, v122
	s_nop 0
	v_addc_co_u32_e32 v37, vcc, 0, v123, vcc
	v_add_co_u32_e32 v38, vcc, s71, v124
	s_mov_b64 s[8:9], 0
	s_nop 0
	v_addc_co_u32_e32 v39, vcc, 0, v125, vcc
	v_add_co_u32_e32 v40, vcc, 0x20000, v124
	s_nop 0
	v_addc_co_u32_e32 v41, vcc, 0, v125, vcc
	v_add_co_u32_e32 v42, vcc, 0x30000, v124
	s_nop 1
	v_addc_co_u32_e32 v43, vcc, 0, v125, vcc
.LBB0_206:
	s_andn2_b64 vcc, exec, s[8:9]
	s_cbranch_vccnz .LBB0_208
	v_add_co_u32_e32 v0, vcc, 0x10000, v122
	s_nop 1
	v_addc_co_u32_e32 v1, vcc, 0, v123, vcc
	v_add_co_u32_e32 v2, vcc, 0x20000, v122
	s_nop 1
	v_addc_co_u32_e32 v3, vcc, 0, v123, vcc
	v_add_co_u32_e32 v0, vcc, 0x30000, v122
	v_addc_co_u32_e32 v1, vcc, 0, v123, vcc
	v_add_co_u32_e32 v2, vcc, 0x10000, v124
	s_nop 1
	v_addc_co_u32_e32 v3, vcc, 0, v125, vcc
	v_add_co_u32_e32 v0, vcc, 0x20000, v124
	s_nop 1
	v_addc_co_u32_e32 v1, vcc, 0, v125, vcc
	v_add_co_u32_e32 v2, vcc, 0x30000, v124
	s_nop 1
	v_addc_co_u32_e32 v3, vcc, 0, v125, vcc
.LBB0_208:
	s_and_b32 s8, s66, 0xffffff80
	s_ashr_i32 s9, s8, 31
	s_lshl_b32 s7, s68, 11
	s_lshl_b64 s[8:9], s[8:9], 11
	s_and_b32 s20, s7, 0xfc0000
	s_add_i32 s2, s2, s3
	s_cmpk_gt_i32 s2, 0xc3f
	s_cselect_b64 s[54:55], -1, 0
	s_lshl_b32 s7, s2, 18
	s_and_b32 s7, s7, 0xfc0000
	s_add_u32 s7, s18, s7
	v_lshl_add_u64 v[126:127], v[114:115], 0, s[8:9]
	s_addc_u32 s10, s19, 0
	s_ashr_i32 s8, s2, 6
	s_ashr_i32 s9, s8, 31
	s_lshl_b64 s[8:9], s[8:9], 18
	v_lshl_add_u64 v[128:129], v[116:117], 0, s[20:21]
	s_add_u32 s20, s16, s8
	s_addc_u32 s11, s17, s9
	s_cmpk_lt_i32 s2, 0xc40
	s_cselect_b64 vcc, -1, 0
	s_and_b64 s[8:9], vcc, exec
	s_cselect_b32 s9, s10, 0
	s_cselect_b32 s8, s7, 0
	v_lshl_add_u64 v[2:3], s[8:9], 0, v[118:119]
	v_lshl_add_u64 v[0:1], v[122:123], 0, s[44:45]
	s_cselect_b32 s11, s11, 0
	s_cselect_b32 s10, s20, 0
	v_lshl_add_u64 v[2:3], v[2:3], 0, v[120:121]
	v_cndmask_b32_e32 v97, v1, v3, vcc
	v_cndmask_b32_e32 v98, v0, v2, vcc
	v_lshl_add_u64 v[0:1], s[10:11], 0, v[118:119]
	v_lshl_add_u64 v[0:1], v[0:1], 0, v[120:121]
	v_lshl_add_u64 v[2:3], v[124:125], 0, s[44:45]
	v_cndmask_b32_e32 v142, v2, v0, vcc
	v_mov_b32_e32 v0, 0
	v_lshl_add_u64 v[144:145], v[122:123], 0, s[28:29]
	v_lshl_add_u64 v[130:131], v[122:123], 0, s[30:31]
	v_lshl_add_u64 v[148:149], v[122:123], 0, s[34:35]
	v_lshl_add_u64 v[132:133], v[122:123], 0, s[36:37]
	v_lshl_add_u64 v[150:151], v[122:123], 0, s[38:39]
	v_lshl_add_u64 v[134:135], v[122:123], 0, s[40:41]
	v_lshl_add_u64 v[152:153], v[122:123], 0, s[42:43]
	v_lshl_add_u64 v[146:147], v[124:125], 0, s[28:29]
	v_lshl_add_u64 v[136:137], v[124:125], 0, s[30:31]
	v_lshl_add_u64 v[154:155], v[124:125], 0, s[34:35]
	v_lshl_add_u64 v[138:139], v[124:125], 0, s[36:37]
	v_lshl_add_u64 v[156:157], v[124:125], 0, s[38:39]
	v_lshl_add_u64 v[140:141], v[124:125], 0, s[40:41]
	v_lshl_add_u64 v[158:159], v[124:125], 0, s[42:43]
	v_cndmask_b32_e32 v143, v3, v1, vcc
	s_mov_b32 s7, -2
	v_mov_b32_e32 v1, v0
	v_mov_b32_e32 v2, v0
	v_mov_b32_e32 v3, v0
	v_mov_b32_e32 v20, v0
	v_mov_b32_e32 v21, v0
	v_mov_b32_e32 v22, v0
	v_mov_b32_e32 v23, v0
	v_mov_b32_e32 v24, v0
	v_mov_b32_e32 v25, v0
	v_mov_b32_e32 v26, v0
	v_mov_b32_e32 v27, v0
	v_mov_b32_e32 v32, v0
	v_mov_b32_e32 v33, v0
	v_mov_b32_e32 v34, v0
	v_mov_b32_e32 v35, v0
	v_mov_b32_e32 v8, v0
	v_mov_b32_e32 v9, v0
	v_mov_b32_e32 v10, v0
	v_mov_b32_e32 v11, v0
	v_mov_b32_e32 v4, v0
	v_mov_b32_e32 v5, v0
	v_mov_b32_e32 v6, v0
	v_mov_b32_e32 v7, v0
	v_mov_b32_e32 v12, v0
	v_mov_b32_e32 v13, v0
	v_mov_b32_e32 v14, v0
	v_mov_b32_e32 v15, v0
	v_mov_b32_e32 v16, v0
	v_mov_b32_e32 v17, v0
	v_mov_b32_e32 v18, v0
	v_mov_b32_e32 v19, v0
	v_mov_b32_e32 v28, v0
	v_mov_b32_e32 v29, v0
	v_mov_b32_e32 v30, v0
	v_mov_b32_e32 v31, v0
	v_mov_b32_e32 v36, v0
	v_mov_b32_e32 v37, v0
	v_mov_b32_e32 v38, v0
	v_mov_b32_e32 v39, v0
	v_mov_b32_e32 v40, v0
	v_mov_b32_e32 v41, v0
	v_mov_b32_e32 v42, v0
	v_mov_b32_e32 v43, v0
	v_mov_b32_e32 v44, v0
	v_mov_b32_e32 v45, v0
	v_mov_b32_e32 v46, v0
	v_mov_b32_e32 v47, v0
	v_mov_b32_e32 v48, v0
	v_mov_b32_e32 v49, v0
	v_mov_b32_e32 v50, v0
	v_mov_b32_e32 v51, v0
	v_mov_b32_e32 v52, v0
	v_mov_b32_e32 v53, v0
	v_mov_b32_e32 v54, v0
	v_mov_b32_e32 v55, v0
	v_mov_b32_e32 v56, v0
	v_mov_b32_e32 v57, v0
	v_mov_b32_e32 v58, v0
	v_mov_b32_e32 v59, v0
	v_mov_b32_e32 v60, v0
	v_mov_b32_e32 v61, v0
	v_mov_b32_e32 v62, v0
	v_mov_b32_e32 v63, v0
	v_readfirstlane_b32 s8, v122
	v_readfirstlane_b32 s9, v123
	v_readfirstlane_b32 s62, v124
	v_readfirstlane_b32 s63, v125
	v_readfirstlane_b32 s7, v247
	s_nop 3
	s_mul_i32 s64, s7, 0x4000
	s_sub_u32 s8, s8, s64
	s_subb_u32 s9, s9, 0
	s_sub_u32 s62, s62, s64
	s_subb_u32 s63, s63, 0
	s_lshl_b32 s7, s7, 12
	s_add_u32 m0, s7, 0x0
	v_mov_b32_e32 v60, 0
	global_load_lds_dwordx4 v248, s[8:9]
	v_mov_b32_e32 v61, 0
	s_add_u32 m0, s7, 0x400
	v_mov_b32_e32 v62, 0
	global_load_lds_dwordx4 v249, s[8:9]
	v_mov_b32_e32 v63, 0
	s_add_u32 m0, s7, 0x800
	v_mov_b32_e32 v56, 0
	global_load_lds_dwordx4 v250, s[8:9]
	v_mov_b32_e32 v57, 0
	s_add_u32 m0, s7, 0xc00
	v_mov_b32_e32 v58, 0
	global_load_lds_dwordx4 v251, s[8:9]
	v_mov_b32_e32 v59, 0
	s_add_u32 m0, s7, 0x8000
	v_mov_b32_e32 v52, 0
	global_load_lds_dwordx4 v248, s[62:63]
	v_mov_b32_e32 v53, 0
	s_add_u32 m0, s7, 0x8400
	v_mov_b32_e32 v54, 0
	global_load_lds_dwordx4 v249, s[62:63]
	v_mov_b32_e32 v55, 0
	s_add_u32 m0, s7, 0x8800
	v_mov_b32_e32 v48, 0
	global_load_lds_dwordx4 v250, s[62:63]
	v_mov_b32_e32 v49, 0
	s_add_u32 m0, s7, 0x8c00
	v_mov_b32_e32 v50, 0
	global_load_lds_dwordx4 v251, s[62:63]
	v_mov_b32_e32 v51, 0
	s_add_u32 s8, s8, 0x80
	s_addc_u32 s9, s9, 0
	s_add_u32 s62, s62, 0x80
	s_addc_u32 s63, s63, 0
	s_add_u32 m0, s7, 0x4000
	v_mov_b32_e32 v44, 0
	global_load_lds_dwordx4 v248, s[8:9]
	v_mov_b32_e32 v45, 0
	s_add_u32 m0, s7, 0x4400
	v_mov_b32_e32 v46, 0
	global_load_lds_dwordx4 v249, s[8:9]
	v_mov_b32_e32 v47, 0
	s_add_u32 m0, s7, 0x4800
	v_mov_b32_e32 v40, 0
	global_load_lds_dwordx4 v250, s[8:9]
	v_mov_b32_e32 v41, 0
	s_add_u32 m0, s7, 0x4c00
	v_mov_b32_e32 v42, 0
	global_load_lds_dwordx4 v251, s[8:9]
	v_mov_b32_e32 v43, 0
	s_add_u32 m0, s7, 0xc000
	v_mov_b32_e32 v36, 0
	global_load_lds_dwordx4 v248, s[62:63]
	v_mov_b32_e32 v37, 0
	s_add_u32 m0, s7, 0xc400
	v_mov_b32_e32 v38, 0
	global_load_lds_dwordx4 v249, s[62:63]
	v_mov_b32_e32 v39, 0
	s_add_u32 m0, s7, 0xc800
	v_mov_b32_e32 v28, 0
	global_load_lds_dwordx4 v250, s[62:63]
	v_mov_b32_e32 v29, 0
	s_add_u32 m0, s7, 0xcc00
	v_mov_b32_e32 v30, 0
	global_load_lds_dwordx4 v251, s[62:63]
	v_mov_b32_e32 v31, 0
	s_add_u32 s8, s8, 0x80
	s_addc_u32 s9, s9, 0
	s_add_u32 s62, s62, 0x80
	s_addc_u32 s63, s63, 0
	v_mov_b32_e32 v16, 0
	v_mov_b32_e32 v17, 0
	v_mov_b32_e32 v18, 0
	v_mov_b32_e32 v19, 0
	v_mov_b32_e32 v12, 0
	v_mov_b32_e32 v13, 0
	v_mov_b32_e32 v14, 0
	v_mov_b32_e32 v15, 0
	v_mov_b32_e32 v4, 0
	v_mov_b32_e32 v5, 0
	v_mov_b32_e32 v6, 0
	v_mov_b32_e32 v7, 0
	v_mov_b32_e32 v8, 0
	v_mov_b32_e32 v9, 0
	v_mov_b32_e32 v10, 0
	v_mov_b32_e32 v11, 0
	v_mov_b32_e32 v32, 0
	v_mov_b32_e32 v33, 0
	v_mov_b32_e32 v34, 0
	v_mov_b32_e32 v35, 0
	v_mov_b32_e32 v24, 0
	v_mov_b32_e32 v25, 0
	v_mov_b32_e32 v26, 0
	v_mov_b32_e32 v27, 0
	v_mov_b32_e32 v20, 0
	v_mov_b32_e32 v21, 0
	v_mov_b32_e32 v22, 0
	v_mov_b32_e32 v23, 0
	v_mov_b32_e32 v0, 0
	v_mov_b32_e32 v1, 0
	v_mov_b32_e32 v2, 0
	v_mov_b32_e32 v3, 0
	s_mov_b32 s32, 7
.Lg2_loop:
	s_waitcnt vmcnt(8)
	s_barrier
	ds_read_b128 v[80:83], v252 offset:0
	ds_read_b128 v[144:147], v254 offset:32768
	ds_read_b128 v[148:151], v254 offset:34816
	ds_read_b128 v[152:155], v254 offset:36864
	ds_read_b128 v[156:159], v254 offset:38912
	ds_read_b128 v[84:87], v252 offset:2048
	ds_read_b128 v[88:91], v252 offset:4096
	ds_read_b128 v[92:95], v252 offset:6144
	ds_read_b128 v[124:127], v253 offset:0
	ds_read_b128 v[172:175], v255 offset:32768
	ds_read_b128 v[176:179], v255 offset:34816
	ds_read_b128 v[180:183], v255 offset:36864
	ds_read_b128 v[184:187], v255 offset:38912
	s_waitcnt lgkmcnt(11)
	v_mfma_f32_16x16x32_bf16 v[60:63], v[80:83], v[144:147], v[60:63]
	s_waitcnt lgkmcnt(10)
	v_mfma_f32_16x16x32_bf16 v[56:59], v[80:83], v[148:151], v[56:59]
	s_waitcnt lgkmcnt(9)
	v_mfma_f32_16x16x32_bf16 v[52:55], v[80:83], v[152:155], v[52:55]
	s_waitcnt lgkmcnt(8)
	v_mfma_f32_16x16x32_bf16 v[48:51], v[80:83], v[156:159], v[48:51]
	ds_read_b128 v[132:135], v253 offset:2048
	ds_read_b128 v[136:139], v253 offset:4096
	ds_read_b128 v[140:143], v253 offset:6144
	s_waitcnt lgkmcnt(10)
	v_mfma_f32_16x16x32_bf16 v[44:47], v[84:87], v[144:147], v[44:47]
	v_mfma_f32_16x16x32_bf16 v[40:43], v[84:87], v[148:151], v[40:43]
	v_mfma_f32_16x16x32_bf16 v[36:39], v[84:87], v[152:155], v[36:39]
	v_mfma_f32_16x16x32_bf16 v[28:31], v[84:87], v[156:159], v[28:31]
	s_waitcnt lgkmcnt(9)
	v_mfma_f32_16x16x32_bf16 v[16:19], v[88:91], v[144:147], v[16:19]
	v_mfma_f32_16x16x32_bf16 v[12:15], v[88:91], v[148:151], v[12:15]
	v_mfma_f32_16x16x32_bf16 v[4:7], v[88:91], v[152:155], v[4:7]
	v_mfma_f32_16x16x32_bf16 v[8:11], v[88:91], v[156:159], v[8:11]
	s_waitcnt lgkmcnt(8)
	v_mfma_f32_16x16x32_bf16 v[32:35], v[92:95], v[144:147], v[32:35]
	v_mfma_f32_16x16x32_bf16 v[24:27], v[92:95], v[148:151], v[24:27]
	v_mfma_f32_16x16x32_bf16 v[20:23], v[92:95], v[152:155], v[20:23]
	v_mfma_f32_16x16x32_bf16 v[0:3], v[92:95], v[156:159], v[0:3]
	s_waitcnt lgkmcnt(0)
	s_barrier
	s_add_u32 m0, s7, 0x0
	v_mfma_f32_16x16x32_bf16 v[60:63], v[124:127], v[172:175], v[60:63]
	global_load_lds_dwordx4 v248, s[8:9]
	v_mfma_f32_16x16x32_bf16 v[56:59], v[124:127], v[176:179], v[56:59]
	s_add_u32 m0, s7, 0x400
	v_mfma_f32_16x16x32_bf16 v[52:55], v[124:127], v[180:183], v[52:55]
	global_load_lds_dwordx4 v249, s[8:9]
	v_mfma_f32_16x16x32_bf16 v[48:51], v[124:127], v[184:187], v[48:51]
	s_add_u32 m0, s7, 0x800
	v_mfma_f32_16x16x32_bf16 v[44:47], v[132:135], v[172:175], v[44:47]
	global_load_lds_dwordx4 v250, s[8:9]
	v_mfma_f32_16x16x32_bf16 v[40:43], v[132:135], v[176:179], v[40:43]
	s_add_u32 m0, s7, 0xc00
	v_mfma_f32_16x16x32_bf16 v[36:39], v[132:135], v[180:183], v[36:39]
	global_load_lds_dwordx4 v251, s[8:9]
	v_mfma_f32_16x16x32_bf16 v[28:31], v[132:135], v[184:187], v[28:31]
	s_add_u32 m0, s7, 0x8000
	v_mfma_f32_16x16x32_bf16 v[16:19], v[136:139], v[172:175], v[16:19]
	global_load_lds_dwordx4 v248, s[62:63]
	v_mfma_f32_16x16x32_bf16 v[12:15], v[136:139], v[176:179], v[12:15]
	s_add_u32 m0, s7, 0x8400
	v_mfma_f32_16x16x32_bf16 v[4:7], v[136:139], v[180:183], v[4:7]
	global_load_lds_dwordx4 v249, s[62:63]
	v_mfma_f32_16x16x32_bf16 v[8:11], v[136:139], v[184:187], v[8:11]
	s_add_u32 m0, s7, 0x8800
	v_mfma_f32_16x16x32_bf16 v[32:35], v[140:143], v[172:175], v[32:35]
	global_load_lds_dwordx4 v250, s[62:63]
	v_mfma_f32_16x16x32_bf16 v[24:27], v[140:143], v[176:179], v[24:27]
	s_add_u32 m0, s7, 0x8c00
	v_mfma_f32_16x16x32_bf16 v[20:23], v[140:143], v[180:183], v[20:23]
	global_load_lds_dwordx4 v251, s[62:63]
	v_mfma_f32_16x16x32_bf16 v[0:3], v[140:143], v[184:187], v[0:3]
	s_add_u32 s8, s8, 0x80
	s_addc_u32 s9, s9, 0
	s_add_u32 s62, s62, 0x80
	s_addc_u32 s63, s63, 0
	s_waitcnt vmcnt(8)
	s_barrier
	ds_read_b128 v[80:83], v252 offset:16384
	ds_read_b128 v[144:147], v254 offset:49152
	ds_read_b128 v[148:151], v254 offset:51200
	ds_read_b128 v[152:155], v254 offset:53248
	ds_read_b128 v[156:159], v254 offset:55296
	ds_read_b128 v[84:87], v252 offset:18432
	ds_read_b128 v[88:91], v252 offset:20480
	ds_read_b128 v[92:95], v252 offset:22528
	ds_read_b128 v[124:127], v253 offset:16384
	ds_read_b128 v[172:175], v255 offset:49152
	ds_read_b128 v[176:179], v255 offset:51200
	ds_read_b128 v[180:183], v255 offset:53248
	ds_read_b128 v[184:187], v255 offset:55296
	s_waitcnt lgkmcnt(11)
	v_mfma_f32_16x16x32_bf16 v[60:63], v[80:83], v[144:147], v[60:63]
	s_waitcnt lgkmcnt(10)
	v_mfma_f32_16x16x32_bf16 v[56:59], v[80:83], v[148:151], v[56:59]
	s_waitcnt lgkmcnt(9)
	v_mfma_f32_16x16x32_bf16 v[52:55], v[80:83], v[152:155], v[52:55]
	s_waitcnt lgkmcnt(8)
	v_mfma_f32_16x16x32_bf16 v[48:51], v[80:83], v[156:159], v[48:51]
	ds_read_b128 v[132:135], v253 offset:18432
	ds_read_b128 v[136:139], v253 offset:20480
	ds_read_b128 v[140:143], v253 offset:22528
	s_waitcnt lgkmcnt(10)
	v_mfma_f32_16x16x32_bf16 v[44:47], v[84:87], v[144:147], v[44:47]
	v_mfma_f32_16x16x32_bf16 v[40:43], v[84:87], v[148:151], v[40:43]
	v_mfma_f32_16x16x32_bf16 v[36:39], v[84:87], v[152:155], v[36:39]
	v_mfma_f32_16x16x32_bf16 v[28:31], v[84:87], v[156:159], v[28:31]
	s_waitcnt lgkmcnt(9)
	v_mfma_f32_16x16x32_bf16 v[16:19], v[88:91], v[144:147], v[16:19]
	v_mfma_f32_16x16x32_bf16 v[12:15], v[88:91], v[148:151], v[12:15]
	v_mfma_f32_16x16x32_bf16 v[4:7], v[88:91], v[152:155], v[4:7]
	v_mfma_f32_16x16x32_bf16 v[8:11], v[88:91], v[156:159], v[8:11]
	s_waitcnt lgkmcnt(8)
	v_mfma_f32_16x16x32_bf16 v[32:35], v[92:95], v[144:147], v[32:35]
	v_mfma_f32_16x16x32_bf16 v[24:27], v[92:95], v[148:151], v[24:27]
	v_mfma_f32_16x16x32_bf16 v[20:23], v[92:95], v[152:155], v[20:23]
	v_mfma_f32_16x16x32_bf16 v[0:3], v[92:95], v[156:159], v[0:3]
	s_waitcnt lgkmcnt(0)
	s_barrier
	s_add_u32 m0, s7, 0x4000
	v_mfma_f32_16x16x32_bf16 v[60:63], v[124:127], v[172:175], v[60:63]
	global_load_lds_dwordx4 v248, s[8:9]
	v_mfma_f32_16x16x32_bf16 v[56:59], v[124:127], v[176:179], v[56:59]
	s_add_u32 m0, s7, 0x4400
	v_mfma_f32_16x16x32_bf16 v[52:55], v[124:127], v[180:183], v[52:55]
	global_load_lds_dwordx4 v249, s[8:9]
	v_mfma_f32_16x16x32_bf16 v[48:51], v[124:127], v[184:187], v[48:51]
	s_add_u32 m0, s7, 0x4800
	v_mfma_f32_16x16x32_bf16 v[44:47], v[132:135], v[172:175], v[44:47]
	global_load_lds_dwordx4 v250, s[8:9]
	v_mfma_f32_16x16x32_bf16 v[40:43], v[132:135], v[176:179], v[40:43]
	s_add_u32 m0, s7, 0x4c00
	v_mfma_f32_16x16x32_bf16 v[36:39], v[132:135], v[180:183], v[36:39]
	global_load_lds_dwordx4 v251, s[8:9]
	v_mfma_f32_16x16x32_bf16 v[28:31], v[132:135], v[184:187], v[28:31]
	s_add_u32 m0, s7, 0xc000
	v_mfma_f32_16x16x32_bf16 v[16:19], v[136:139], v[172:175], v[16:19]
	global_load_lds_dwordx4 v248, s[62:63]
	v_mfma_f32_16x16x32_bf16 v[12:15], v[136:139], v[176:179], v[12:15]
	s_add_u32 m0, s7, 0xc400
	v_mfma_f32_16x16x32_bf16 v[4:7], v[136:139], v[180:183], v[4:7]
	global_load_lds_dwordx4 v249, s[62:63]
	v_mfma_f32_16x16x32_bf16 v[8:11], v[136:139], v[184:187], v[8:11]
	s_add_u32 m0, s7, 0xc800
	v_mfma_f32_16x16x32_bf16 v[32:35], v[140:143], v[172:175], v[32:35]
	global_load_lds_dwordx4 v250, s[62:63]
	v_mfma_f32_16x16x32_bf16 v[24:27], v[140:143], v[176:179], v[24:27]
	s_add_u32 m0, s7, 0xcc00
	v_mfma_f32_16x16x32_bf16 v[20:23], v[140:143], v[180:183], v[20:23]
	global_load_lds_dwordx4 v251, s[62:63]
	v_mfma_f32_16x16x32_bf16 v[0:3], v[140:143], v[184:187], v[0:3]
	s_add_u32 s8, s8, 0x80
	s_addc_u32 s9, s9, 0
	s_add_u32 s62, s62, 0x80
	s_addc_u32 s63, s63, 0
	s_sub_u32 s32, s32, 1
	s_cmp_lg_u32 s32, 0
	s_cbranch_scc1 .Lg2_loop
	s_waitcnt vmcnt(8)
	s_barrier
	ds_read_b128 v[80:83], v252 offset:0
	ds_read_b128 v[144:147], v254 offset:32768
	ds_read_b128 v[148:151], v254 offset:34816
	ds_read_b128 v[152:155], v254 offset:36864
	ds_read_b128 v[156:159], v254 offset:38912
	ds_read_b128 v[84:87], v252 offset:2048
	ds_read_b128 v[88:91], v252 offset:4096
	ds_read_b128 v[92:95], v252 offset:6144
	ds_read_b128 v[124:127], v253 offset:0
	ds_read_b128 v[172:175], v255 offset:32768
	ds_read_b128 v[176:179], v255 offset:34816
	ds_read_b128 v[180:183], v255 offset:36864
	ds_read_b128 v[184:187], v255 offset:38912
	s_waitcnt lgkmcnt(11)
	v_mfma_f32_16x16x32_bf16 v[60:63], v[80:83], v[144:147], v[60:63]
	s_waitcnt lgkmcnt(10)
	v_mfma_f32_16x16x32_bf16 v[56:59], v[80:83], v[148:151], v[56:59]
	s_waitcnt lgkmcnt(9)
	v_mfma_f32_16x16x32_bf16 v[52:55], v[80:83], v[152:155], v[52:55]
	s_waitcnt lgkmcnt(8)
	v_mfma_f32_16x16x32_bf16 v[48:51], v[80:83], v[156:159], v[48:51]
	ds_read_b128 v[132:135], v253 offset:2048
	ds_read_b128 v[136:139], v253 offset:4096
	ds_read_b128 v[140:143], v253 offset:6144
	s_waitcnt lgkmcnt(10)
	v_mfma_f32_16x16x32_bf16 v[44:47], v[84:87], v[144:147], v[44:47]
	v_mfma_f32_16x16x32_bf16 v[40:43], v[84:87], v[148:151], v[40:43]
	v_mfma_f32_16x16x32_bf16 v[36:39], v[84:87], v[152:155], v[36:39]
	v_mfma_f32_16x16x32_bf16 v[28:31], v[84:87], v[156:159], v[28:31]
	s_waitcnt lgkmcnt(9)
	v_mfma_f32_16x16x32_bf16 v[16:19], v[88:91], v[144:147], v[16:19]
	v_mfma_f32_16x16x32_bf16 v[12:15], v[88:91], v[148:151], v[12:15]
	v_mfma_f32_16x16x32_bf16 v[4:7], v[88:91], v[152:155], v[4:7]
	v_mfma_f32_16x16x32_bf16 v[8:11], v[88:91], v[156:159], v[8:11]
	s_waitcnt lgkmcnt(8)
	v_mfma_f32_16x16x32_bf16 v[32:35], v[92:95], v[144:147], v[32:35]
	v_mfma_f32_16x16x32_bf16 v[24:27], v[92:95], v[148:151], v[24:27]
	v_mfma_f32_16x16x32_bf16 v[20:23], v[92:95], v[152:155], v[20:23]
	v_mfma_f32_16x16x32_bf16 v[0:3], v[92:95], v[156:159], v[0:3]
	s_waitcnt lgkmcnt(0)
	s_barrier
	v_mfma_f32_16x16x32_bf16 v[60:63], v[124:127], v[172:175], v[60:63]
	v_mfma_f32_16x16x32_bf16 v[56:59], v[124:127], v[176:179], v[56:59]
	v_mfma_f32_16x16x32_bf16 v[52:55], v[124:127], v[180:183], v[52:55]
	v_mfma_f32_16x16x32_bf16 v[48:51], v[124:127], v[184:187], v[48:51]
	v_mfma_f32_16x16x32_bf16 v[44:47], v[132:135], v[172:175], v[44:47]
	v_mfma_f32_16x16x32_bf16 v[40:43], v[132:135], v[176:179], v[40:43]
	v_mfma_f32_16x16x32_bf16 v[36:39], v[132:135], v[180:183], v[36:39]
	v_mfma_f32_16x16x32_bf16 v[28:31], v[132:135], v[184:187], v[28:31]
	v_mfma_f32_16x16x32_bf16 v[16:19], v[136:139], v[172:175], v[16:19]
	v_mfma_f32_16x16x32_bf16 v[12:15], v[136:139], v[176:179], v[12:15]
	v_mfma_f32_16x16x32_bf16 v[4:7], v[136:139], v[180:183], v[4:7]
	v_mfma_f32_16x16x32_bf16 v[8:11], v[136:139], v[184:187], v[8:11]
	v_mfma_f32_16x16x32_bf16 v[32:35], v[140:143], v[172:175], v[32:35]
	v_mfma_f32_16x16x32_bf16 v[24:27], v[140:143], v[176:179], v[24:27]
	v_mfma_f32_16x16x32_bf16 v[20:23], v[140:143], v[180:183], v[20:23]
	v_mfma_f32_16x16x32_bf16 v[0:3], v[140:143], v[184:187], v[0:3]
	s_waitcnt vmcnt(0)
	s_barrier
	ds_read_b128 v[80:83], v252 offset:16384
	ds_read_b128 v[144:147], v254 offset:49152
	ds_read_b128 v[148:151], v254 offset:51200
	ds_read_b128 v[152:155], v254 offset:53248
	ds_read_b128 v[156:159], v254 offset:55296
	ds_read_b128 v[84:87], v252 offset:18432
	ds_read_b128 v[88:91], v252 offset:20480
	ds_read_b128 v[92:95], v252 offset:22528
	ds_read_b128 v[124:127], v253 offset:16384
	ds_read_b128 v[172:175], v255 offset:49152
	ds_read_b128 v[176:179], v255 offset:51200
	ds_read_b128 v[180:183], v255 offset:53248
	ds_read_b128 v[184:187], v255 offset:55296
	s_waitcnt lgkmcnt(11)
	v_mfma_f32_16x16x32_bf16 v[60:63], v[80:83], v[144:147], v[60:63]
	s_waitcnt lgkmcnt(10)
	v_mfma_f32_16x16x32_bf16 v[56:59], v[80:83], v[148:151], v[56:59]
	s_waitcnt lgkmcnt(9)
	v_mfma_f32_16x16x32_bf16 v[52:55], v[80:83], v[152:155], v[52:55]
	s_waitcnt lgkmcnt(8)
	v_mfma_f32_16x16x32_bf16 v[48:51], v[80:83], v[156:159], v[48:51]
	ds_read_b128 v[132:135], v253 offset:18432
	ds_read_b128 v[136:139], v253 offset:20480
	ds_read_b128 v[140:143], v253 offset:22528
	s_waitcnt lgkmcnt(10)
	v_mfma_f32_16x16x32_bf16 v[44:47], v[84:87], v[144:147], v[44:47]
	v_mfma_f32_16x16x32_bf16 v[40:43], v[84:87], v[148:151], v[40:43]
	v_mfma_f32_16x16x32_bf16 v[36:39], v[84:87], v[152:155], v[36:39]
	v_mfma_f32_16x16x32_bf16 v[28:31], v[84:87], v[156:159], v[28:31]
	s_waitcnt lgkmcnt(9)
	v_mfma_f32_16x16x32_bf16 v[16:19], v[88:91], v[144:147], v[16:19]
	v_mfma_f32_16x16x32_bf16 v[12:15], v[88:91], v[148:151], v[12:15]
	v_mfma_f32_16x16x32_bf16 v[4:7], v[88:91], v[152:155], v[4:7]
	v_mfma_f32_16x16x32_bf16 v[8:11], v[88:91], v[156:159], v[8:11]
	s_waitcnt lgkmcnt(8)
	v_mfma_f32_16x16x32_bf16 v[32:35], v[92:95], v[144:147], v[32:35]
	v_mfma_f32_16x16x32_bf16 v[24:27], v[92:95], v[148:151], v[24:27]
	v_mfma_f32_16x16x32_bf16 v[20:23], v[92:95], v[152:155], v[20:23]
	v_mfma_f32_16x16x32_bf16 v[0:3], v[92:95], v[156:159], v[0:3]
	s_waitcnt lgkmcnt(0)
	s_barrier
	v_mfma_f32_16x16x32_bf16 v[60:63], v[124:127], v[172:175], v[60:63]
	v_mfma_f32_16x16x32_bf16 v[56:59], v[124:127], v[176:179], v[56:59]
	v_mfma_f32_16x16x32_bf16 v[52:55], v[124:127], v[180:183], v[52:55]
	v_mfma_f32_16x16x32_bf16 v[48:51], v[124:127], v[184:187], v[48:51]
	v_mfma_f32_16x16x32_bf16 v[44:47], v[132:135], v[172:175], v[44:47]
	v_mfma_f32_16x16x32_bf16 v[40:43], v[132:135], v[176:179], v[40:43]
	v_mfma_f32_16x16x32_bf16 v[36:39], v[132:135], v[180:183], v[36:39]
	v_mfma_f32_16x16x32_bf16 v[28:31], v[132:135], v[184:187], v[28:31]
	v_mfma_f32_16x16x32_bf16 v[16:19], v[136:139], v[172:175], v[16:19]
	v_mfma_f32_16x16x32_bf16 v[12:15], v[136:139], v[176:179], v[12:15]
	v_mfma_f32_16x16x32_bf16 v[4:7], v[136:139], v[180:183], v[4:7]
	v_mfma_f32_16x16x32_bf16 v[8:11], v[136:139], v[184:187], v[8:11]
	v_mfma_f32_16x16x32_bf16 v[32:35], v[140:143], v[172:175], v[32:35]
	v_mfma_f32_16x16x32_bf16 v[24:27], v[140:143], v[176:179], v[24:27]
	v_mfma_f32_16x16x32_bf16 v[20:23], v[140:143], v[180:183], v[20:23]
	v_mfma_f32_16x16x32_bf16 v[0:3], v[140:143], v[184:187], v[0:3]
	s_nop 7
	s_nop 1
	s_waitcnt vmcnt(3)
	v_add_u32_e32 v80, s12, v168
	v_or_b32_e32 v64, s6, v169
	s_cmpk_gt_i32 s6, 0x3ff
	s_mov_b64 s[6:7], -1
	s_cbranch_scc0 .LBB0_416
	s_cmpk_gt_u32 s13, 0xbff
	s_cbranch_scc0 .LBB0_413
	s_cmpk_gt_u32 s13, 0x13ff
	s_cbranch_scc0 .LBB0_236
	s_cmpk_gt_u32 s13, 0x17ff
	s_cbranch_scc0 .LBB0_217
	s_and_saveexec_b64 s[6:7], s[4:5]
	s_cbranch_execz .LBB0_216
	v_lshlrev_b32_e32 v98, 7, v80
	v_lshl_add_u64 v[66:67], v[104:105], 0, v[98:99]
	global_store_dword v[66:67], v60, off
	global_store_dword v[66:67], v61, off offset:128
	global_store_dword v[66:67], v62, off offset:256
	global_store_dword v[66:67], v63, off offset:384
	global_store_dword v[66:67], v56, off offset:64
	global_store_dword v[66:67], v57, off offset:192
	global_store_dword v[66:67], v58, off offset:320
	global_store_dword v[66:67], v59, off offset:448
	global_store_dword v[66:67], v44, off offset:2048
	global_store_dword v[66:67], v45, off offset:2176
	global_store_dword v[66:67], v46, off offset:2304
	global_store_dword v[66:67], v47, off offset:2432
	global_store_dword v[66:67], v40, off offset:2112
	global_store_dword v[66:67], v41, off offset:2240
	global_store_dword v[66:67], v42, off offset:2368
	global_store_dword v[66:67], v43, off offset:2496
	v_or_b32_e32 v66, 0x1000, v98
	v_mov_b32_e32 v67, v99
	v_lshl_add_u64 v[68:69], v[104:105], 0, v[66:67]
	global_store_dword v[68:69], v16, off
	v_or_b32_e32 v68, 0x1080, v98
	v_mov_b32_e32 v69, v99
	v_lshl_add_u64 v[70:71], v[104:105], 0, v[68:69]
	global_store_dword v[70:71], v17, off
	v_or_b32_e32 v70, 0x1100, v98
	v_mov_b32_e32 v71, v99
	v_lshl_add_u64 v[66:67], v[106:107], 0, v[66:67]
	v_lshl_add_u64 v[72:73], v[104:105], 0, v[70:71]
	global_store_dword v[66:67], v12, off
	v_lshl_add_u64 v[66:67], v[106:107], 0, v[68:69]
	global_store_dword v[72:73], v18, off
	v_or_b32_e32 v72, 0x1180, v98
	v_mov_b32_e32 v73, v99
	global_store_dword v[66:67], v13, off
	v_lshl_add_u64 v[66:67], v[106:107], 0, v[70:71]
	global_store_dword v[66:67], v14, off
	v_lshl_add_u64 v[66:67], v[106:107], 0, v[72:73]
	global_store_dword v[66:67], v15, off
	v_or_b32_e32 v66, 0x1800, v98
	v_mov_b32_e32 v67, v99
	v_lshl_add_u64 v[68:69], v[104:105], 0, v[66:67]
	global_store_dword v[68:69], v32, off
	v_or_b32_e32 v68, 0x1880, v98
	v_mov_b32_e32 v69, v99
	v_lshl_add_u64 v[70:71], v[104:105], 0, v[68:69]
	v_lshl_add_u64 v[66:67], v[106:107], 0, v[66:67]
	global_store_dword v[70:71], v33, off
	v_or_b32_e32 v70, 0x1900, v98
	v_mov_b32_e32 v71, v99
	global_store_dword v[66:67], v24, off
	v_lshl_add_u64 v[66:67], v[106:107], 0, v[68:69]
	v_lshl_add_u64 v[74:75], v[104:105], 0, v[72:73]
	v_lshl_add_u64 v[72:73], v[104:105], 0, v[70:71]
	v_or_b32_e32 v98, 0x1980, v98
	global_store_dword v[66:67], v25, off
	v_lshl_add_u64 v[66:67], v[106:107], 0, v[70:71]
	global_store_dword v[72:73], v34, off
	v_lshl_add_u64 v[72:73], v[104:105], 0, v[98:99]
	global_store_dword v[66:67], v26, off
	v_lshl_add_u64 v[66:67], v[106:107], 0, v[98:99]
	global_store_dword v[74:75], v19, off
	global_store_dword v[72:73], v35, off
	global_store_dword v[66:67], v27, off

.LBB0_833:
	s_cmp_gt_i32 s60, 6
	s_cselect_b64 s[2:3], -1, 0
	s_cmp_lt_i32 s61, 6
	s_cselect_b64 s[4:5], -1, 0
	s_or_b64 s[2:3], s[2:3], s[4:5]
	s_and_b64 vcc, exec, s[2:3]
	s_cbranch_vccnz .LBB0_893
	s_mov_b64 s[4:5], s[0:1]
	s_cmpk_gt_i32 s58, 0x1ff
	s_cbranch_scc1 .LBB0_839
	s_load_dwordx2 s[6:7], s[4:5], 0xe0
	v_lshrrev_b32_e32 v8, 3, v162
	v_lshlrev_b32_e32 v96, 12, v8
	v_mov_b32_e32 v97, 0
	v_lshlrev_b32_e32 v0, 4, v162
	s_waitcnt lgkmcnt(0)
	s_add_u32 s2, s6, 0x6b04000
	s_addc_u32 s3, s7, 0
	s_add_u32 s4, s6, 0x6b7a100
	v_and_b32_e32 v0, 0x70, v0
	v_mov_b32_e32 v1, v97
	v_lshl_add_u64 v[2:3], s[6:7], 0, v[96:97]
	s_addc_u32 s5, s7, 0
	v_lshl_add_u64 v[0:1], v[2:3], 0, v[0:1]
	s_mov_b64 s[6:7], 0x1257a100
	v_xor_b32_e32 v9, v163, v162
	v_lshl_add_u64 v[98:99], v[0:1], 0, s[6:7]
	s_mov_b64 s[6:7], 0x1880000
	v_lshl_add_u64 v[100:101], v[0:1], 0, s[6:7]
	v_lshlrev_b32_e32 v1, 4, v9
	v_and_b32_e32 v6, 15, v162
	v_bfe_u32 v0, v162, 1, 3
	v_and_b32_e32 v1, 0x70, v1
	v_bfe_u32 v4, v162, 6, 1
	v_lshrrev_b32_e32 v5, 7, v162
	v_bitop3_b32 v0, v163, v0, 3 bitop3:0x6c
	v_lshl_or_b32 v129, v8, 7, v1
	v_lshlrev_b32_e32 v1, 7, v6
	s_load_dword s34, s[0:1], 0xf0
	v_lshl_or_b32 v2, v5, 13, v1
	v_lshl_or_b32 v1, v4, 13, v1
	v_lshlrev_b32_e32 v0, 4, v0
	v_or_b32_e32 v144, v2, v0
	v_or_b32_e32 v145, v1, v0
	v_xor_b32_e32 v0, 64, v0
	v_bfe_u32 v7, v162, 4, 2
	v_or_b32_e32 v146, v2, v0
	v_or_b32_e32 v147, v1, v0
	v_lshlrev_b32_e32 v0, 6, v5
	v_lshl_or_b32 v148, v4, 6, v6
	v_lshl_or_b32 v149, v7, 2, v0
	s_mov_b32 s7, 0
	s_mov_b64 s[8:9], 0x20000
	s_mov_b32 s35, 0x20000
	s_mov_b64 s[10:11], 0x40000
	s_mov_b32 s36, 0x40000
	s_mov_b64 s[12:13], 0x60000
	s_mov_b32 s37, 0x60000
	s_mov_b64 s[14:15], 0x60100
	s_mov_b64 s[16:17], 0x40100
	s_mov_b64 s[18:19], 0x20100
	s_mov_b64 s[20:21], 0x100
	s_mov_b64 s[22:23], 0x200
	s_mov_b64 s[24:25], 0x20200
	s_mov_b64 s[26:27], 0x40200
	s_mov_b64 s[28:29], 0x60200
	v_mov_b32_e32 v150, 0x1000
	s_mov_b32 s38, s58
	v_and_b32_e32 v240, 63, v162
	v_lshrrev_b32_e32 v247, 6, v162
	v_lshrrev_b32_e32 v242, 3, v240
	v_lshl_add_u32 v242, v247, 5, v242
	v_and_b32_e32 v243, 7, v240
	v_lshrrev_b32_e32 v244, 4, v240
	v_xor_b32_e32 v243, v243, v244
	v_lshlrev_b32_e32 v243, 4, v243
	v_mov_b32_e32 v241, 0x1000
	v_mad_u32_u24 v248, v242, v241, v243
	v_xor_b32_e32 v249, 64, v248
	v_add_u32_e32 v249, 0x8000, v249
	v_add_u32_e32 v250, 0x10000, v248
	v_xor_b32_e32 v251, 64, v248
	v_add_u32_e32 v251, 0x18000, v251
	v_and_b32_e32 v241, 15, v240
	v_lshrrev_b32_e32 v242, 1, v241
	v_xor_b32_e32 v242, v242, v244
	v_lshlrev_b32_e32 v242, 4, v242
	v_lshl_or_b32 v242, v241, 7, v242
	v_lshrrev_b32_e32 v243, 1, v247
	v_lshl_or_b32 v252, v243, 13, v242
	v_xor_b32_e32 v253, 64, v252
	v_and_b32_e32 v243, 1, v247
	v_lshl_or_b32 v254, v243, 13, v242
	v_xor_b32_e32 v255, 64, v254
.LBB0_836:
	s_lshl_b32 s6, s38, 7
	s_and_b32 s39, s6, 0x1f80
	s_lshl_b32 s6, s38, 1
	s_and_b32 s30, s6, 0xffffff80
	s_lshl_b32 s6, s39, 12
	v_lshl_add_u64 v[102:103], v[98:99], 0, s[6:7]
	v_add_co_u32_e32 v38, vcc, 0x20000, v102
	s_ashr_i32 s31, s30, 31
	s_nop 0
	v_addc_co_u32_e32 v39, vcc, 0, v103, vcc
	v_add_co_u32_e32 v44, vcc, 0x40000, v102
	s_lshl_b64 s[40:41], s[30:31], 12
	s_nop 0
	v_addc_co_u32_e32 v45, vcc, 0, v103, vcc
	v_add_co_u32_e32 v46, vcc, 0x60000, v102
	v_lshl_add_u64 v[104:105], v[100:101], 0, s[40:41]
	s_nop 0
	v_addc_co_u32_e32 v47, vcc, 0, v103, vcc
	v_add_co_u32_e32 v48, vcc, s35, v104
	s_nop 0
	v_addc_co_u32_e32 v49, vcc, 0, v105, vcc
	v_add_co_u32_e32 v50, vcc, s36, v104
	v_addc_co_u32_e32 v51, vcc, 0, v105, vcc
	v_add_co_u32_e32 v52, vcc, s37, v104
	v_addc_co_u32_e32 v53, vcc, 0, v105, vcc
	s_mov_b32 s31, -2
	v_mov_b32_e32 v8, 0
	v_mov_b32_e32 v9, v97
	v_mov_b32_e32 v10, v97
	v_mov_b32_e32 v11, v97
	v_mov_b32_e32 v24, 0
	v_mov_b32_e32 v25, v97
	v_mov_b32_e32 v26, v97
	v_mov_b32_e32 v27, v97
	v_mov_b32_e32 v36, 0
	v_mov_b32_e32 v37, v97
	v_mov_b32_e32 v38, v97
	v_lshl_add_u64 v[106:107], v[102:103], 0, s[8:9]
	v_lshl_add_u64 v[108:109], v[102:103], 0, s[10:11]
	v_lshl_add_u64 v[110:111], v[102:103], 0, s[12:13]
	v_lshl_add_u64 v[118:119], v[102:103], 0, s[14:15]
	v_lshl_add_u64 v[120:121], v[102:103], 0, s[16:17]
	v_lshl_add_u64 v[122:123], v[102:103], 0, s[18:19]
	v_lshl_add_u64 v[124:125], v[102:103], 0, s[20:21]
	v_lshl_add_u64 v[112:113], v[104:105], 0, s[8:9]
	v_lshl_add_u64 v[114:115], v[104:105], 0, s[10:11]
	v_lshl_add_u64 v[116:117], v[104:105], 0, s[12:13]
	v_lshl_add_u64 v[130:131], v[104:105], 0, s[14:15]
	v_lshl_add_u64 v[132:133], v[104:105], 0, s[16:17]
	v_lshl_add_u64 v[134:135], v[104:105], 0, s[18:19]
	v_lshl_add_u64 v[126:127], v[104:105], 0, s[20:21]
	v_mov_b32_e32 v39, v97
	v_mov_b32_e32 v48, 0
	v_mov_b32_e32 v49, v97
	v_mov_b32_e32 v50, v97
	v_mov_b32_e32 v51, v97
	v_mov_b32_e32 v52, 0
	v_mov_b32_e32 v53, v97
	v_mov_b32_e32 v54, v97
	v_mov_b32_e32 v55, v97
	v_mov_b32_e32 v56, 0
	v_mov_b32_e32 v57, v97
	v_mov_b32_e32 v58, v97
	v_mov_b32_e32 v59, v97
	v_mov_b32_e32 v44, 0
	v_mov_b32_e32 v45, v97
	v_mov_b32_e32 v46, v97
	v_mov_b32_e32 v47, v97
	v_mov_b32_e32 v60, 0
	v_mov_b32_e32 v61, v97
	v_mov_b32_e32 v62, v97
	v_mov_b32_e32 v63, v97
	v_mov_b32_e32 v0, 0
	v_mov_b32_e32 v1, v97
	v_mov_b32_e32 v2, v97
	v_mov_b32_e32 v3, v97
	v_mov_b32_e32 v16, 0
	v_mov_b32_e32 v17, v97
	v_mov_b32_e32 v18, v97
	v_mov_b32_e32 v19, v97
	v_mov_b32_e32 v32, 0
	v_mov_b32_e32 v33, v97
	v_mov_b32_e32 v34, v97
	v_mov_b32_e32 v35, v97
	v_mov_b32_e32 v4, 0
	v_mov_b32_e32 v5, v97
	v_mov_b32_e32 v6, v97
	v_mov_b32_e32 v7, v97
	v_mov_b32_e32 v20, 0
	v_mov_b32_e32 v21, v97
	v_mov_b32_e32 v22, v97
	v_mov_b32_e32 v23, v97
	v_mov_b32_e32 v40, 0
	v_mov_b32_e32 v41, v97
	v_mov_b32_e32 v42, v97
	v_mov_b32_e32 v43, v97
	v_mov_b32_e32 v12, 0
	v_mov_b32_e32 v13, v97
	v_mov_b32_e32 v14, v97
	v_mov_b32_e32 v15, v97
	v_mov_b32_e32 v28, 0
	v_mov_b32_e32 v29, v97
	v_mov_b32_e32 v30, v97
	v_mov_b32_e32 v31, v97
	v_readfirstlane_b32 s40, v102
	v_readfirstlane_b32 s41, v103
	v_readfirstlane_b32 s48, v104
	v_readfirstlane_b32 s49, v105
	v_readfirstlane_b32 s6, v247
	s_nop 3
	s_mul_i32 s32, s6, 0x8000
	s_sub_u32 s40, s40, s32
	s_subb_u32 s41, s41, 0
	s_sub_u32 s48, s48, s32
	s_subb_u32 s49, s49, 0
	s_lshl_b32 s6, s6, 12
	s_add_u32 m0, s6, 0x0
	v_mov_b32_e32 v60, 0
	global_load_lds_dwordx4 v248, s[40:41]
	v_mov_b32_e32 v61, 0
	s_add_u32 m0, s6, 0x400
	v_mov_b32_e32 v62, 0
	global_load_lds_dwordx4 v249, s[40:41]
	v_mov_b32_e32 v63, 0
	s_add_u32 m0, s6, 0x800
	v_mov_b32_e32 v44, 0
	global_load_lds_dwordx4 v250, s[40:41]
	v_mov_b32_e32 v45, 0
	s_add_u32 m0, s6, 0xc00
	v_mov_b32_e32 v46, 0
	global_load_lds_dwordx4 v251, s[40:41]
	v_mov_b32_e32 v47, 0
	s_add_u32 m0, s6, 0x8000
	v_mov_b32_e32 v28, 0
	global_load_lds_dwordx4 v248, s[48:49]
	v_mov_b32_e32 v29, 0
	s_add_u32 m0, s6, 0x8400
	v_mov_b32_e32 v30, 0
	global_load_lds_dwordx4 v249, s[48:49]
	v_mov_b32_e32 v31, 0
	s_add_u32 m0, s6, 0x8800
	v_mov_b32_e32 v12, 0
	global_load_lds_dwordx4 v250, s[48:49]
	v_mov_b32_e32 v13, 0
	s_add_u32 m0, s6, 0x8c00
	v_mov_b32_e32 v14, 0
	global_load_lds_dwordx4 v251, s[48:49]
	v_mov_b32_e32 v15, 0
	s_add_u32 s40, s40, 0x80
	s_addc_u32 s41, s41, 0
	s_add_u32 s48, s48, 0x80
	s_addc_u32 s49, s49, 0
	s_add_u32 m0, s6, 0x4000
	v_mov_b32_e32 v56, 0
	global_load_lds_dwordx4 v248, s[40:41]
	v_mov_b32_e32 v57, 0
	s_add_u32 m0, s6, 0x4400
	v_mov_b32_e32 v58, 0
	global_load_lds_dwordx4 v249, s[40:41]
	v_mov_b32_e32 v59, 0
	s_add_u32 m0, s6, 0x4800
	v_mov_b32_e32 v40, 0
	global_load_lds_dwordx4 v250, s[40:41]
	v_mov_b32_e32 v41, 0
	s_add_u32 m0, s6, 0x4c00
	v_mov_b32_e32 v42, 0
	global_load_lds_dwordx4 v251, s[40:41]
	v_mov_b32_e32 v43, 0
	s_add_u32 m0, s6, 0xc000
	v_mov_b32_e32 v20, 0
	global_load_lds_dwordx4 v248, s[48:49]
	v_mov_b32_e32 v21, 0
	s_add_u32 m0, s6, 0xc400
	v_mov_b32_e32 v22, 0
	global_load_lds_dwordx4 v249, s[48:49]
	v_mov_b32_e32 v23, 0
	s_add_u32 m0, s6, 0xc800
	v_mov_b32_e32 v4, 0
	global_load_lds_dwordx4 v250, s[48:49]
	v_mov_b32_e32 v5, 0
	s_add_u32 m0, s6, 0xcc00
	v_mov_b32_e32 v6, 0
	global_load_lds_dwordx4 v251, s[48:49]
	v_mov_b32_e32 v7, 0
	s_add_u32 s40, s40, 0x80
	s_addc_u32 s41, s41, 0
	s_add_u32 s48, s48, 0x80
	s_addc_u32 s49, s49, 0
	v_mov_b32_e32 v52, 0
	v_mov_b32_e32 v53, 0
	v_mov_b32_e32 v54, 0
	v_mov_b32_e32 v55, 0
	v_mov_b32_e32 v32, 0
	v_mov_b32_e32 v33, 0
	v_mov_b32_e32 v34, 0
	v_mov_b32_e32 v35, 0
	v_mov_b32_e32 v16, 0
	v_mov_b32_e32 v17, 0
	v_mov_b32_e32 v18, 0
	v_mov_b32_e32 v19, 0
	v_mov_b32_e32 v0, 0
	v_mov_b32_e32 v1, 0
	v_mov_b32_e32 v2, 0
	v_mov_b32_e32 v3, 0
	v_mov_b32_e32 v48, 0
	v_mov_b32_e32 v49, 0
	v_mov_b32_e32 v50, 0
	v_mov_b32_e32 v51, 0
	v_mov_b32_e32 v36, 0
	v_mov_b32_e32 v37, 0
	v_mov_b32_e32 v38, 0
	v_mov_b32_e32 v39, 0
	v_mov_b32_e32 v24, 0
	v_mov_b32_e32 v25, 0
	v_mov_b32_e32 v26, 0
	v_mov_b32_e32 v27, 0
	v_mov_b32_e32 v8, 0
	v_mov_b32_e32 v9, 0
	v_mov_b32_e32 v10, 0
	v_mov_b32_e32 v11, 0
	s_mov_b32 s31, 15
.Lg6_loop:
	s_waitcnt vmcnt(8)
	s_barrier
	ds_read_b128 v[64:67], v252 offset:0
	ds_read_b128 v[104:107], v254 offset:32768
	ds_read_b128 v[108:111], v254 offset:34816
	ds_read_b128 v[112:115], v254 offset:36864
	ds_read_b128 v[116:119], v254 offset:38912
	ds_read_b128 v[68:71], v252 offset:2048
	ds_read_b128 v[72:75], v252 offset:4096
	ds_read_b128 v[76:79], v252 offset:6144
	ds_read_b128 v[80:83], v253 offset:0
	ds_read_b128 v[120:123], v255 offset:32768
	ds_read_b128 v[124:127], v255 offset:34816
	ds_read_b128 v[132:135], v255 offset:36864
	ds_read_b128 v[136:139], v255 offset:38912
	s_waitcnt lgkmcnt(11)
	v_mfma_f32_16x16x32_bf16 v[60:63], v[64:67], v[104:107], v[60:63]
	s_waitcnt lgkmcnt(10)
	v_mfma_f32_16x16x32_bf16 v[44:47], v[64:67], v[108:111], v[44:47]
	s_waitcnt lgkmcnt(9)
	v_mfma_f32_16x16x32_bf16 v[28:31], v[64:67], v[112:115], v[28:31]
	s_waitcnt lgkmcnt(8)
	v_mfma_f32_16x16x32_bf16 v[12:15], v[64:67], v[116:119], v[12:15]
	ds_read_b128 v[84:87], v253 offset:2048
	ds_read_b128 v[88:91], v253 offset:4096
	ds_read_b128 v[92:95], v253 offset:6144
	s_waitcnt lgkmcnt(10)
	v_mfma_f32_16x16x32_bf16 v[56:59], v[68:71], v[104:107], v[56:59]
	v_mfma_f32_16x16x32_bf16 v[40:43], v[68:71], v[108:111], v[40:43]
	v_mfma_f32_16x16x32_bf16 v[20:23], v[68:71], v[112:115], v[20:23]
	v_mfma_f32_16x16x32_bf16 v[4:7], v[68:71], v[116:119], v[4:7]
	s_waitcnt lgkmcnt(9)
	v_mfma_f32_16x16x32_bf16 v[52:55], v[72:75], v[104:107], v[52:55]
	v_mfma_f32_16x16x32_bf16 v[32:35], v[72:75], v[108:111], v[32:35]
	v_mfma_f32_16x16x32_bf16 v[16:19], v[72:75], v[112:115], v[16:19]
	v_mfma_f32_16x16x32_bf16 v[0:3], v[72:75], v[116:119], v[0:3]
	s_waitcnt lgkmcnt(8)
	v_mfma_f32_16x16x32_bf16 v[48:51], v[76:79], v[104:107], v[48:51]
	v_mfma_f32_16x16x32_bf16 v[36:39], v[76:79], v[108:111], v[36:39]
	v_mfma_f32_16x16x32_bf16 v[24:27], v[76:79], v[112:115], v[24:27]
	v_mfma_f32_16x16x32_bf16 v[8:11], v[76:79], v[116:119], v[8:11]
	s_waitcnt lgkmcnt(0)
	s_barrier
	s_add_u32 m0, s6, 0x0
	v_mfma_f32_16x16x32_bf16 v[60:63], v[80:83], v[120:123], v[60:63]
	global_load_lds_dwordx4 v248, s[40:41]
	v_mfma_f32_16x16x32_bf16 v[44:47], v[80:83], v[124:127], v[44:47]
	s_add_u32 m0, s6, 0x400
	v_mfma_f32_16x16x32_bf16 v[28:31], v[80:83], v[132:135], v[28:31]
	global_load_lds_dwordx4 v249, s[40:41]
	v_mfma_f32_16x16x32_bf16 v[12:15], v[80:83], v[136:139], v[12:15]
	s_add_u32 m0, s6, 0x800
	v_mfma_f32_16x16x32_bf16 v[56:59], v[84:87], v[120:123], v[56:59]
	global_load_lds_dwordx4 v250, s[40:41]
	v_mfma_f32_16x16x32_bf16 v[40:43], v[84:87], v[124:127], v[40:43]
	s_add_u32 m0, s6, 0xc00
	v_mfma_f32_16x16x32_bf16 v[20:23], v[84:87], v[132:135], v[20:23]
	global_load_lds_dwordx4 v251, s[40:41]
	v_mfma_f32_16x16x32_bf16 v[4:7], v[84:87], v[136:139], v[4:7]
	s_add_u32 m0, s6, 0x8000
	v_mfma_f32_16x16x32_bf16 v[52:55], v[88:91], v[120:123], v[52:55]
	global_load_lds_dwordx4 v248, s[48:49]
	v_mfma_f32_16x16x32_bf16 v[32:35], v[88:91], v[124:127], v[32:35]
	s_add_u32 m0, s6, 0x8400
	v_mfma_f32_16x16x32_bf16 v[16:19], v[88:91], v[132:135], v[16:19]
	global_load_lds_dwordx4 v249, s[48:49]
	v_mfma_f32_16x16x32_bf16 v[0:3], v[88:91], v[136:139], v[0:3]
	s_add_u32 m0, s6, 0x8800
	v_mfma_f32_16x16x32_bf16 v[48:51], v[92:95], v[120:123], v[48:51]
	global_load_lds_dwordx4 v250, s[48:49]
	v_mfma_f32_16x16x32_bf16 v[36:39], v[92:95], v[124:127], v[36:39]
	s_add_u32 m0, s6, 0x8c00
	v_mfma_f32_16x16x32_bf16 v[24:27], v[92:95], v[132:135], v[24:27]
	global_load_lds_dwordx4 v251, s[48:49]
	v_mfma_f32_16x16x32_bf16 v[8:11], v[92:95], v[136:139], v[8:11]
	s_add_u32 s40, s40, 0x80
	s_addc_u32 s41, s41, 0
	s_add_u32 s48, s48, 0x80
	s_addc_u32 s49, s49, 0
	s_waitcnt vmcnt(8)
	s_barrier
	ds_read_b128 v[64:67], v252 offset:16384
	ds_read_b128 v[104:107], v254 offset:49152
	ds_read_b128 v[108:111], v254 offset:51200
	ds_read_b128 v[112:115], v254 offset:53248
	ds_read_b128 v[116:119], v254 offset:55296
	ds_read_b128 v[68:71], v252 offset:18432
	ds_read_b128 v[72:75], v252 offset:20480
	ds_read_b128 v[76:79], v252 offset:22528
	ds_read_b128 v[80:83], v253 offset:16384
	ds_read_b128 v[120:123], v255 offset:49152
	ds_read_b128 v[124:127], v255 offset:51200
	ds_read_b128 v[132:135], v255 offset:53248
	ds_read_b128 v[136:139], v255 offset:55296
	s_waitcnt lgkmcnt(11)
	v_mfma_f32_16x16x32_bf16 v[60:63], v[64:67], v[104:107], v[60:63]
	s_waitcnt lgkmcnt(10)
	v_mfma_f32_16x16x32_bf16 v[44:47], v[64:67], v[108:111], v[44:47]
	s_waitcnt lgkmcnt(9)
	v_mfma_f32_16x16x32_bf16 v[28:31], v[64:67], v[112:115], v[28:31]
	s_waitcnt lgkmcnt(8)
	v_mfma_f32_16x16x32_bf16 v[12:15], v[64:67], v[116:119], v[12:15]
	ds_read_b128 v[84:87], v253 offset:18432
	ds_read_b128 v[88:91], v253 offset:20480
	ds_read_b128 v[92:95], v253 offset:22528
	s_waitcnt lgkmcnt(10)
	v_mfma_f32_16x16x32_bf16 v[56:59], v[68:71], v[104:107], v[56:59]
	v_mfma_f32_16x16x32_bf16 v[40:43], v[68:71], v[108:111], v[40:43]
	v_mfma_f32_16x16x32_bf16 v[20:23], v[68:71], v[112:115], v[20:23]
	v_mfma_f32_16x16x32_bf16 v[4:7], v[68:71], v[116:119], v[4:7]
	s_waitcnt lgkmcnt(9)
	v_mfma_f32_16x16x32_bf16 v[52:55], v[72:75], v[104:107], v[52:55]
	v_mfma_f32_16x16x32_bf16 v[32:35], v[72:75], v[108:111], v[32:35]
	v_mfma_f32_16x16x32_bf16 v[16:19], v[72:75], v[112:115], v[16:19]
	v_mfma_f32_16x16x32_bf16 v[0:3], v[72:75], v[116:119], v[0:3]
	s_waitcnt lgkmcnt(8)
	v_mfma_f32_16x16x32_bf16 v[48:51], v[76:79], v[104:107], v[48:51]
	v_mfma_f32_16x16x32_bf16 v[36:39], v[76:79], v[108:111], v[36:39]
	v_mfma_f32_16x16x32_bf16 v[24:27], v[76:79], v[112:115], v[24:27]
	v_mfma_f32_16x16x32_bf16 v[8:11], v[76:79], v[116:119], v[8:11]
	s_waitcnt lgkmcnt(0)
	s_barrier
	s_add_u32 m0, s6, 0x4000
	v_mfma_f32_16x16x32_bf16 v[60:63], v[80:83], v[120:123], v[60:63]
	global_load_lds_dwordx4 v248, s[40:41]
	v_mfma_f32_16x16x32_bf16 v[44:47], v[80:83], v[124:127], v[44:47]
	s_add_u32 m0, s6, 0x4400
	v_mfma_f32_16x16x32_bf16 v[28:31], v[80:83], v[132:135], v[28:31]
	global_load_lds_dwordx4 v249, s[40:41]
	v_mfma_f32_16x16x32_bf16 v[12:15], v[80:83], v[136:139], v[12:15]
	s_add_u32 m0, s6, 0x4800
	v_mfma_f32_16x16x32_bf16 v[56:59], v[84:87], v[120:123], v[56:59]
	global_load_lds_dwordx4 v250, s[40:41]
	v_mfma_f32_16x16x32_bf16 v[40:43], v[84:87], v[124:127], v[40:43]
	s_add_u32 m0, s6, 0x4c00
	v_mfma_f32_16x16x32_bf16 v[20:23], v[84:87], v[132:135], v[20:23]
	global_load_lds_dwordx4 v251, s[40:41]
	v_mfma_f32_16x16x32_bf16 v[4:7], v[84:87], v[136:139], v[4:7]
	s_add_u32 m0, s6, 0xc000
	v_mfma_f32_16x16x32_bf16 v[52:55], v[88:91], v[120:123], v[52:55]
	global_load_lds_dwordx4 v248, s[48:49]
	v_mfma_f32_16x16x32_bf16 v[32:35], v[88:91], v[124:127], v[32:35]
	s_add_u32 m0, s6, 0xc400
	v_mfma_f32_16x16x32_bf16 v[16:19], v[88:91], v[132:135], v[16:19]
	global_load_lds_dwordx4 v249, s[48:49]
	v_mfma_f32_16x16x32_bf16 v[0:3], v[88:91], v[136:139], v[0:3]
	s_add_u32 m0, s6, 0xc800
	v_mfma_f32_16x16x32_bf16 v[48:51], v[92:95], v[120:123], v[48:51]
	global_load_lds_dwordx4 v250, s[48:49]
	v_mfma_f32_16x16x32_bf16 v[36:39], v[92:95], v[124:127], v[36:39]
	s_add_u32 m0, s6, 0xcc00
	v_mfma_f32_16x16x32_bf16 v[24:27], v[92:95], v[132:135], v[24:27]
	global_load_lds_dwordx4 v251, s[48:49]
	v_mfma_f32_16x16x32_bf16 v[8:11], v[92:95], v[136:139], v[8:11]
	s_add_u32 s40, s40, 0x80
	s_addc_u32 s41, s41, 0
	s_add_u32 s48, s48, 0x80
	s_addc_u32 s49, s49, 0
	s_sub_u32 s31, s31, 1
	s_cmp_lg_u32 s31, 0
	s_cbranch_scc1 .Lg6_loop
	s_waitcnt vmcnt(8)
	s_barrier
	ds_read_b128 v[64:67], v252 offset:0
	ds_read_b128 v[104:107], v254 offset:32768
	ds_read_b128 v[108:111], v254 offset:34816
	ds_read_b128 v[112:115], v254 offset:36864
	ds_read_b128 v[116:119], v254 offset:38912
	ds_read_b128 v[68:71], v252 offset:2048
	ds_read_b128 v[72:75], v252 offset:4096
	ds_read_b128 v[76:79], v252 offset:6144
	ds_read_b128 v[80:83], v253 offset:0
	ds_read_b128 v[120:123], v255 offset:32768
	ds_read_b128 v[124:127], v255 offset:34816
	ds_read_b128 v[132:135], v255 offset:36864
	ds_read_b128 v[136:139], v255 offset:38912
	s_waitcnt lgkmcnt(11)
	v_mfma_f32_16x16x32_bf16 v[60:63], v[64:67], v[104:107], v[60:63]
	s_waitcnt lgkmcnt(10)
	v_mfma_f32_16x16x32_bf16 v[44:47], v[64:67], v[108:111], v[44:47]
	s_waitcnt lgkmcnt(9)
	v_mfma_f32_16x16x32_bf16 v[28:31], v[64:67], v[112:115], v[28:31]
	s_waitcnt lgkmcnt(8)
	v_mfma_f32_16x16x32_bf16 v[12:15], v[64:67], v[116:119], v[12:15]
	ds_read_b128 v[84:87], v253 offset:2048
	ds_read_b128 v[88:91], v253 offset:4096
	ds_read_b128 v[92:95], v253 offset:6144
	s_waitcnt lgkmcnt(10)
	v_mfma_f32_16x16x32_bf16 v[56:59], v[68:71], v[104:107], v[56:59]
	v_mfma_f32_16x16x32_bf16 v[40:43], v[68:71], v[108:111], v[40:43]
	v_mfma_f32_16x16x32_bf16 v[20:23], v[68:71], v[112:115], v[20:23]
	v_mfma_f32_16x16x32_bf16 v[4:7], v[68:71], v[116:119], v[4:7]
	s_waitcnt lgkmcnt(9)
	v_mfma_f32_16x16x32_bf16 v[52:55], v[72:75], v[104:107], v[52:55]
	v_mfma_f32_16x16x32_bf16 v[32:35], v[72:75], v[108:111], v[32:35]
	v_mfma_f32_16x16x32_bf16 v[16:19], v[72:75], v[112:115], v[16:19]
	v_mfma_f32_16x16x32_bf16 v[0:3], v[72:75], v[116:119], v[0:3]
	s_waitcnt lgkmcnt(8)
	v_mfma_f32_16x16x32_bf16 v[48:51], v[76:79], v[104:107], v[48:51]
	v_mfma_f32_16x16x32_bf16 v[36:39], v[76:79], v[108:111], v[36:39]
	v_mfma_f32_16x16x32_bf16 v[24:27], v[76:79], v[112:115], v[24:27]
	v_mfma_f32_16x16x32_bf16 v[8:11], v[76:79], v[116:119], v[8:11]
	s_waitcnt lgkmcnt(0)
	s_barrier
	v_mfma_f32_16x16x32_bf16 v[60:63], v[80:83], v[120:123], v[60:63]
	v_mfma_f32_16x16x32_bf16 v[44:47], v[80:83], v[124:127], v[44:47]
	v_mfma_f32_16x16x32_bf16 v[28:31], v[80:83], v[132:135], v[28:31]
	v_mfma_f32_16x16x32_bf16 v[12:15], v[80:83], v[136:139], v[12:15]
	v_mfma_f32_16x16x32_bf16 v[56:59], v[84:87], v[120:123], v[56:59]
	v_mfma_f32_16x16x32_bf16 v[40:43], v[84:87], v[124:127], v[40:43]
	v_mfma_f32_16x16x32_bf16 v[20:23], v[84:87], v[132:135], v[20:23]
	v_mfma_f32_16x16x32_bf16 v[4:7], v[84:87], v[136:139], v[4:7]
	v_mfma_f32_16x16x32_bf16 v[52:55], v[88:91], v[120:123], v[52:55]
	v_mfma_f32_16x16x32_bf16 v[32:35], v[88:91], v[124:127], v[32:35]
	v_mfma_f32_16x16x32_bf16 v[16:19], v[88:91], v[132:135], v[16:19]
	v_mfma_f32_16x16x32_bf16 v[0:3], v[88:91], v[136:139], v[0:3]
	v_mfma_f32_16x16x32_bf16 v[48:51], v[92:95], v[120:123], v[48:51]
	v_mfma_f32_16x16x32_bf16 v[36:39], v[92:95], v[124:127], v[36:39]
	v_mfma_f32_16x16x32_bf16 v[24:27], v[92:95], v[132:135], v[24:27]
	v_mfma_f32_16x16x32_bf16 v[8:11], v[92:95], v[136:139], v[8:11]
	s_waitcnt vmcnt(0)
	s_barrier
	ds_read_b128 v[64:67], v252 offset:16384
	ds_read_b128 v[104:107], v254 offset:49152
	ds_read_b128 v[108:111], v254 offset:51200
	ds_read_b128 v[112:115], v254 offset:53248
	ds_read_b128 v[116:119], v254 offset:55296
	ds_read_b128 v[68:71], v252 offset:18432
	ds_read_b128 v[72:75], v252 offset:20480
	ds_read_b128 v[76:79], v252 offset:22528
	ds_read_b128 v[80:83], v253 offset:16384
	ds_read_b128 v[120:123], v255 offset:49152
	ds_read_b128 v[124:127], v255 offset:51200
	ds_read_b128 v[132:135], v255 offset:53248
	ds_read_b128 v[136:139], v255 offset:55296
	s_waitcnt lgkmcnt(11)
	v_mfma_f32_16x16x32_bf16 v[60:63], v[64:67], v[104:107], v[60:63]
	s_waitcnt lgkmcnt(10)
	v_mfma_f32_16x16x32_bf16 v[44:47], v[64:67], v[108:111], v[44:47]
	s_waitcnt lgkmcnt(9)
	v_mfma_f32_16x16x32_bf16 v[28:31], v[64:67], v[112:115], v[28:31]
	s_waitcnt lgkmcnt(8)
	v_mfma_f32_16x16x32_bf16 v[12:15], v[64:67], v[116:119], v[12:15]
	ds_read_b128 v[84:87], v253 offset:18432
	ds_read_b128 v[88:91], v253 offset:20480
	ds_read_b128 v[92:95], v253 offset:22528
	s_waitcnt lgkmcnt(10)
	v_mfma_f32_16x16x32_bf16 v[56:59], v[68:71], v[104:107], v[56:59]
	v_mfma_f32_16x16x32_bf16 v[40:43], v[68:71], v[108:111], v[40:43]
	v_mfma_f32_16x16x32_bf16 v[20:23], v[68:71], v[112:115], v[20:23]
	v_mfma_f32_16x16x32_bf16 v[4:7], v[68:71], v[116:119], v[4:7]
	s_waitcnt lgkmcnt(9)
	v_mfma_f32_16x16x32_bf16 v[52:55], v[72:75], v[104:107], v[52:55]
	v_mfma_f32_16x16x32_bf16 v[32:35], v[72:75], v[108:111], v[32:35]
	v_mfma_f32_16x16x32_bf16 v[16:19], v[72:75], v[112:115], v[16:19]
	v_mfma_f32_16x16x32_bf16 v[0:3], v[72:75], v[116:119], v[0:3]
	s_waitcnt lgkmcnt(8)
	v_mfma_f32_16x16x32_bf16 v[48:51], v[76:79], v[104:107], v[48:51]
	v_mfma_f32_16x16x32_bf16 v[36:39], v[76:79], v[108:111], v[36:39]
	v_mfma_f32_16x16x32_bf16 v[24:27], v[76:79], v[112:115], v[24:27]
	v_mfma_f32_16x16x32_bf16 v[8:11], v[76:79], v[116:119], v[8:11]
	s_waitcnt lgkmcnt(0)
	s_barrier
	v_mfma_f32_16x16x32_bf16 v[60:63], v[80:83], v[120:123], v[60:63]
	v_mfma_f32_16x16x32_bf16 v[44:47], v[80:83], v[124:127], v[44:47]
	v_mfma_f32_16x16x32_bf16 v[28:31], v[80:83], v[132:135], v[28:31]
	v_mfma_f32_16x16x32_bf16 v[12:15], v[80:83], v[136:139], v[12:15]
	v_mfma_f32_16x16x32_bf16 v[56:59], v[84:87], v[120:123], v[56:59]
	v_mfma_f32_16x16x32_bf16 v[40:43], v[84:87], v[124:127], v[40:43]
	v_mfma_f32_16x16x32_bf16 v[20:23], v[84:87], v[132:135], v[20:23]
	v_mfma_f32_16x16x32_bf16 v[4:7], v[84:87], v[136:139], v[4:7]
	v_mfma_f32_16x16x32_bf16 v[52:55], v[88:91], v[120:123], v[52:55]
	v_mfma_f32_16x16x32_bf16 v[32:35], v[88:91], v[124:127], v[32:35]
	v_mfma_f32_16x16x32_bf16 v[16:19], v[88:91], v[132:135], v[16:19]
	v_mfma_f32_16x16x32_bf16 v[0:3], v[88:91], v[136:139], v[0:3]
	v_mfma_f32_16x16x32_bf16 v[48:51], v[92:95], v[120:123], v[48:51]
	v_mfma_f32_16x16x32_bf16 v[36:39], v[92:95], v[124:127], v[36:39]
	v_mfma_f32_16x16x32_bf16 v[24:27], v[92:95], v[132:135], v[24:27]
	v_mfma_f32_16x16x32_bf16 v[8:11], v[92:95], v[136:139], v[8:11]
	s_nop 7
	s_nop 1
	s_waitcnt vmcnt(7)
	v_sub_co_u32_e32 v64, vcc, s39, v150
	s_nop 0
	v_readfirstlane_b32 s6, v64
	s_lshr_b32 s6, s6, 10
	s_add_i32 s6, s6, 1
	s_and_b64 s[40:41], vcc, exec
	s_cselect_b32 s6, 0, s6
	s_mul_hi_u32 s31, s6, 0x6000
	s_mulk_i32 s6, 0x6000
	v_or_b32_e32 v64, s30, v148
	s_add_u32 s40, s2, s6
	v_ashrrev_i32_e32 v65, 31, v64
	s_addc_u32 s41, s3, s31
	s_waitcnt vmcnt(0)
	v_add_lshl_u32 v94, v149, s39, 12
	v_lshlrev_b64 v[66:67], 2, v[64:65]
	v_lshl_add_u64 v[102:103], s[40:41], 0, v[66:67]
	v_lshl_add_u64 v[136:137], s[4:5], 0, v[66:67]
	v_mov_b32_e32 v95, v97
	v_or_b32_e32 v66, 0x1000, v94
	v_mov_b32_e32 v67, v97
	v_lshl_add_u64 v[104:105], v[136:137], 0, v[94:95]
	global_load_dword v65, v[102:103], off
	global_load_dword v151, v[104:105], off
	v_lshl_add_u64 v[106:107], v[136:137], 0, v[66:67]
	v_or_b32_e32 v68, 0x2000, v94
	v_mov_b32_e32 v69, v97
	v_or_b32_e32 v70, 0x3000, v94
	v_mov_b32_e32 v71, v97
	v_or_b32_e32 v72, 0x10000, v94
	v_mov_b32_e32 v73, v97
	global_load_dword v152, v[106:107], off
	v_lshl_add_u64 v[108:109], v[136:137], 0, v[68:69]
	v_lshl_add_u64 v[110:111], v[136:137], 0, v[70:71]
	v_lshl_add_u64 v[112:113], v[136:137], 0, v[72:73]
	v_or_b32_e32 v74, 0x11000, v94
	v_mov_b32_e32 v75, v97
	global_load_dword v153, v[108:109], off
	global_load_dword v154, v[110:111], off
	global_load_dword v155, v[112:113], off
	v_lshl_add_u64 v[114:115], v[136:137], 0, v[74:75]
	v_or_b32_e32 v76, 0x12000, v94
	v_mov_b32_e32 v77, v97
	v_or_b32_e32 v78, 0x13000, v94
	v_mov_b32_e32 v79, v97
	v_or_b32_e32 v80, 0x20000, v94
	v_mov_b32_e32 v81, v97
	global_load_dword v156, v[114:115], off
	v_or_b32_e32 v96, 0x30000, v94
	v_lshl_add_u64 v[116:117], v[136:137], 0, v[76:77]
	v_lshl_add_u64 v[118:119], v[136:137], 0, v[78:79]
	v_lshl_add_u64 v[120:121], v[136:137], 0, v[80:81]
	v_or_b32_e32 v82, 0x21000, v94
	v_mov_b32_e32 v83, v97
	global_load_dword v157, v[116:117], off
	global_load_dword v158, v[118:119], off
	global_load_dword v159, v[120:121], off
	v_lshl_add_u64 v[122:123], v[136:137], 0, v[82:83]
	v_or_b32_e32 v84, 0x22000, v94
	v_mov_b32_e32 v85, v97
	v_or_b32_e32 v86, 0x23000, v94
	v_mov_b32_e32 v87, v97
	v_lshl_add_u64 v[130:131], v[136:137], 0, v[96:97]
	v_lshl_add_u64 v[124:125], v[136:137], 0, v[84:85]
	v_lshl_add_u64 v[126:127], v[136:137], 0, v[86:87]
	global_load_dword v160, v[122:123], off
	global_load_dword v161, v[124:125], off
	global_load_dword v170, v[126:127], off
	global_load_dword v171, v[130:131], off
	v_or_b32_e32 v88, 0x31000, v94
	v_mov_b32_e32 v89, v97
	v_lshl_add_u64 v[132:133], v[136:137], 0, v[88:89]
	v_or_b32_e32 v90, 0x32000, v94
	v_mov_b32_e32 v91, v97
	v_or_b32_e32 v92, 0x33000, v94
	v_mov_b32_e32 v93, v97
	v_lshl_add_u64 v[134:135], v[136:137], 0, v[90:91]
	v_lshl_add_u64 v[136:137], v[136:137], 0, v[92:93]
	global_load_dword v172, v[132:133], off
	global_load_dword v173, v[134:135], off
	global_load_dword v174, v[136:137], off
	v_or_b32_e32 v138, 16, v64
	v_ashrrev_i32_e32 v139, 31, v138
	v_lshlrev_b64 v[138:139], 2, v[138:139]
	v_lshl_add_u64 v[94:95], s[4:5], 0, v[94:95]
	global_load_dword v175, v[102:103], off offset:64
	v_lshl_add_u64 v[142:143], s[4:5], 0, v[138:139]
	v_lshl_add_u64 v[138:139], v[94:95], 0, v[138:139]
	v_add_f32_e32 v60, 0, v60
	v_lshl_add_u64 v[140:141], v[142:143], 0, v[66:67]
	global_load_dword v176, v[138:139], off
	global_load_dword v177, v[140:141], off
	global_load_dword v178, v[102:103], off offset:128
	global_load_dword v179, v[102:103], off offset:192
	v_lshl_add_u64 v[102:103], v[142:143], 0, v[68:69]
	global_load_dword v180, v[102:103], off
	v_add_f32_e32 v56, 0, v56
	v_add_f32_e32 v58, 0, v58
	v_add_f32_e32 v52, 0, v52
	v_add_f32_e32 v48, 0, v48
	v_add_f32_e32 v44, 0, v44
	v_add_f32_e32 v50, 0, v50
	v_add_f32_e32 v32, 0, v32
	v_add_f32_e32 v34, 0, v34
	v_add_f32_e32 v40, 0, v40
	v_add_f32_e32 v38, 0, v38
	v_add_f32_e32 v36, 0, v36
	v_add_f32_e32 v28, 0, v28
	v_add_f32_e32 v30, 0, v30
	v_add_f32_e32 v20, 0, v20
	s_waitcnt vmcnt(21)
	v_fmac_f32_e32 v151, v60, v65
	v_add_f32_e32 v60, 0, v61
	global_store_dword v[104:105], v151, off
	v_lshl_add_u64 v[104:105], v[142:143], 0, v[72:73]
	v_add_f32_e32 v16, 0, v16
	v_add_f32_e32 v0, 0, v0
	v_add_f32_e32 v12, 0, v12
	v_add_f32_e32 v4, 0, v4
	s_waitcnt vmcnt(21)
	v_fmac_f32_e32 v152, v60, v65
	v_add_f32_e32 v60, 0, v62
	v_add_f32_e32 v62, 0, v63
	global_store_dword v[106:107], v152, off
	v_lshl_add_u64 v[106:107], v[142:143], 0, v[76:77]
	global_load_dword v152, v[104:105], off
	s_waitcnt vmcnt(22)
	v_fmac_f32_e32 v153, v60, v65
	global_store_dword v[108:109], v153, off
	s_waitcnt vmcnt(21)
	v_fmac_f32_e32 v155, v56, v65
	v_add_f32_e32 v56, 0, v57
	v_lshl_add_u64 v[108:109], v[142:143], 0, v[80:81]
	v_lshl_add_u64 v[60:61], v[142:143], 0, v[70:71]
	global_store_dword v[112:113], v155, off
	v_add_f32_e32 v112, 0, v59
	v_fmac_f32_e32 v154, v62, v65
	global_store_dword v[110:111], v154, off
	s_waitcnt vmcnt(22)
	v_fmac_f32_e32 v156, v56, v65
	global_store_dword v[114:115], v156, off
	global_load_dword v156, v[108:109], off
	v_lshl_add_u64 v[62:63], v[142:143], 0, v[74:75]
	global_load_dword v151, v[60:61], off
	global_load_dword v154, v[106:107], off
	v_lshl_add_u64 v[110:111], v[142:143], 0, v[82:83]
	s_waitcnt vmcnt(25)
	v_fmac_f32_e32 v157, v58, v65
	v_lshl_add_u64 v[58:59], v[142:143], 0, v[84:85]
	s_waitcnt vmcnt(23)
	v_fmac_f32_e32 v159, v52, v65
	v_add_f32_e32 v52, 0, v53
	global_store_dword v[116:117], v157, off
	global_load_dword v157, v[58:59], off
	v_fmac_f32_e32 v158, v112, v65
	v_lshl_add_u64 v[112:113], v[142:143], 0, v[86:87]
	global_load_dword v182, v[112:113], off
	s_waitcnt vmcnt(25)
	v_fmac_f32_e32 v160, v52, v65
	v_add_f32_e32 v52, 0, v54
	s_waitcnt vmcnt(24)
	v_fmac_f32_e32 v161, v52, v65
	s_waitcnt vmcnt(22)
	v_fmac_f32_e32 v171, v48, v65
	v_add_f32_e32 v48, 0, v49
	v_lshl_add_u64 v[52:53], v[142:143], 0, v[90:91]
	v_lshl_add_u64 v[114:115], v[142:143], 0, v[96:97]
	global_store_dword v[120:121], v159, off
	global_load_dword v120, v[52:53], off
	v_lshl_add_u64 v[56:57], v[142:143], 0, v[78:79]
	global_load_dword v181, v[110:111], off
	global_load_dword v155, v[56:57], off
	s_waitcnt vmcnt(25)
	v_fmac_f32_e32 v172, v48, v65
	v_lshl_add_u64 v[48:49], v[142:143], 0, v[92:93]
	global_load_dword v121, v[48:49], off
	s_waitcnt vmcnt(25)
	v_fmac_f32_e32 v173, v50, v65
	global_store_dword v[118:119], v158, off
	global_load_dword v118, v[114:115], off
	v_add_f32_e32 v50, 0, v51
	global_load_dword v153, v[62:63], off
	s_waitcnt vmcnt(25)
	v_fmac_f32_e32 v176, v44, v175
	v_add_f32_e32 v44, 0, v45
	s_waitcnt vmcnt(24)
	v_fmac_f32_e32 v177, v44, v175
	v_add_f32_e32 v44, 0, v46
	v_add_f32_e32 v54, 0, v55
	s_waitcnt vmcnt(21)
	v_fmac_f32_e32 v180, v44, v175
	v_or_b32_e32 v44, 32, v64
	v_ashrrev_i32_e32 v45, 31, v44
	v_lshlrev_b64 v[44:45], 2, v[44:45]
	v_fmac_f32_e32 v174, v50, v65
	v_lshl_add_u64 v[50:51], v[94:95], 0, v[44:45]
	v_lshl_add_u64 v[44:45], s[4:5], 0, v[44:45]
	v_fmac_f32_e32 v170, v54, v65
	v_lshl_add_u64 v[54:55], v[44:45], 0, v[78:79]
	v_add_f32_e32 v46, 0, v47
	v_lshl_add_u64 v[116:117], v[142:143], 0, v[88:89]
	global_load_dword v119, v[116:117], off
	v_or_b32_e32 v64, 48, v64
	global_store_dword v[102:103], v180, off
	v_ashrrev_i32_e32 v65, 31, v64
	v_lshlrev_b64 v[64:65], 2, v[64:65]
	global_store_dword v[122:123], v160, off
	global_store_dword v[124:125], v161, off
	global_store_dword v[126:127], v170, off
	global_store_dword v[130:131], v171, off
	global_store_dword v[132:133], v172, off
	global_store_dword v[134:135], v173, off
	global_store_dword v[136:137], v174, off
	global_store_dword v[138:139], v176, off
	global_store_dword v[140:141], v177, off
	v_lshl_add_u64 v[94:95], v[94:95], 0, v[64:65]
	v_lshl_add_u64 v[64:65], s[4:5], 0, v[64:65]
	v_add_f32_e32 v21, 0, v21
	s_waitcnt vmcnt(29)
	v_fmac_f32_e32 v152, v40, v175
	v_add_f32_e32 v40, 0, v41
	global_store_dword v[104:105], v152, off
	s_add_i32 s38, s38, s34
	s_cmpk_gt_i32 s38, 0x1ff
	s_waitcnt vmcnt(25)
	v_fmac_f32_e32 v156, v32, v175
	global_store_dword v[108:109], v156, off
	global_load_dword v109, v[54:55], off
	s_waitcnt vmcnt(26)
	v_fmac_f32_e32 v151, v46, v175
	v_lshl_add_u64 v[46:47], v[44:45], 0, v[66:67]
	global_load_dword v102, v[50:51], off
	global_load_dword v103, v[46:47], off
	v_add_f32_e32 v32, 0, v33
	global_store_dword v[60:61], v151, off
	v_lshl_add_u64 v[60:61], v[44:45], 0, v[88:89]
	s_waitcnt vmcnt(26)
	v_fmac_f32_e32 v157, v34, v175
	global_store_dword v[58:59], v157, off
	v_add_f32_e32 v34, 0, v35
	v_add_f32_e32 v58, 0, v39
	s_waitcnt vmcnt(26)
	v_fmac_f32_e32 v182, v34, v175
	global_store_dword v[112:113], v182, off
	v_lshl_add_u64 v[34:35], v[44:45], 0, v[72:73]
	v_lshl_add_u64 v[66:67], v[64:65], 0, v[66:67]
	s_waitcnt vmcnt(25)
	v_fmac_f32_e32 v120, v38, v175
	global_store_dword v[52:53], v120, off
	s_waitcnt vmcnt(25)
	v_fmac_f32_e32 v181, v32, v175
	v_lshl_add_u64 v[52:53], v[44:45], 0, v[82:83]
	global_store_dword v[110:111], v181, off
	v_lshl_add_u64 v[32:33], v[44:45], 0, v[70:71]
	s_waitcnt vmcnt(24)
	v_fmac_f32_e32 v121, v58, v175
	v_lshl_add_u64 v[58:59], v[44:45], 0, v[86:87]
	global_load_dword v113, v[58:59], off
	global_load_dword v111, v[52:53], off
	s_waitcnt vmcnt(24)
	v_fmac_f32_e32 v118, v36, v175
	s_waitcnt vmcnt(23)
	v_fmac_f32_e32 v153, v40, v175
	v_add_f32_e32 v40, 0, v42
	v_add_f32_e32 v42, 0, v43
	v_fmac_f32_e32 v155, v42, v175
	global_store_dword v[56:57], v155, off
	v_lshl_add_u64 v[56:57], v[44:45], 0, v[80:81]
	global_store_dword v[114:115], v118, off
	global_load_dword v110, v[56:57], off
	global_load_dword v105, v[32:33], off
	v_add_f32_e32 v36, 0, v37
	global_load_dword v115, v[60:61], off
	v_fmac_f32_e32 v154, v40, v175
	v_lshl_add_u64 v[40:41], v[44:45], 0, v[68:69]
	global_load_dword v104, v[40:41], off
	v_lshl_add_u64 v[42:43], v[44:45], 0, v[76:77]
	global_store_dword v[106:107], v154, off
	global_load_dword v106, v[34:35], off
	s_waitcnt vmcnt(30)
	v_fmac_f32_e32 v119, v36, v175
	global_store_dword v[48:49], v121, off
	v_lshl_add_u64 v[48:49], v[44:45], 0, v[96:97]
	global_store_dword v[62:63], v153, off
	v_lshl_add_u64 v[36:37], v[44:45], 0, v[74:75]
	global_store_dword v[116:117], v119, off
	v_lshl_add_u64 v[38:39], v[44:45], 0, v[84:85]
	global_load_dword v114, v[48:49], off
	v_lshl_add_u64 v[62:63], v[44:45], 0, v[90:91]
	global_load_dword v107, v[36:37], off
	global_load_dword v108, v[42:43], off
	global_load_dword v112, v[38:39], off
	v_lshl_add_u64 v[44:45], v[44:45], 0, v[92:93]
	global_load_dword v116, v[62:63], off
	global_load_dword v117, v[44:45], off
	v_lshl_add_u64 v[68:69], v[64:65], 0, v[68:69]
	global_load_dword v120, v[68:69], off
	global_load_dword v118, v[94:95], off
	global_load_dword v119, v[66:67], off
	s_waitcnt vmcnt(28)
	v_fmac_f32_e32 v102, v28, v178
	global_store_dword v[50:51], v102, off
	v_lshl_add_u64 v[50:51], v[64:65], 0, v[70:71]
	v_add_f32_e32 v70, 0, v29
	v_lshl_add_u64 v[28:29], v[64:65], 0, v[72:73]
	s_waitcnt vmcnt(28)
	v_fmac_f32_e32 v103, v70, v178
	v_lshl_add_u64 v[70:71], v[64:65], 0, v[74:75]
	v_lshl_add_u64 v[72:73], v[64:65], 0, v[78:79]
	v_lshl_add_u64 v[74:75], v[64:65], 0, v[80:81]
	global_load_dword v122, v[70:71], off
	global_load_dword v123, v[72:73], off
	global_load_dword v124, v[74:75], off
	global_load_dword v102, v[50:51], off
	global_load_dword v121, v[28:29], off
	v_lshl_add_u64 v[78:79], v[64:65], 0, v[88:89]
	global_store_dword v[46:47], v103, off
	v_lshl_add_u64 v[46:47], v[64:65], 0, v[76:77]
	global_load_dword v103, v[46:47], off
	v_add_f32_e32 v76, 0, v31
	v_lshl_add_u64 v[80:81], v[64:65], 0, v[90:91]
	s_waitcnt vmcnt(25)
	v_fmac_f32_e32 v110, v16, v178
	s_waitcnt vmcnt(24)
	v_fmac_f32_e32 v105, v76, v178
	v_lshl_add_u64 v[76:77], v[64:65], 0, v[86:87]
	global_store_dword v[32:33], v105, off
	v_lshl_add_u64 v[32:33], v[64:65], 0, v[96:97]
	global_load_dword v86, v[78:79], off
	s_waitcnt vmcnt(24)
	v_fmac_f32_e32 v104, v30, v178
	global_store_dword v[40:41], v104, off
	v_lshl_add_u64 v[40:41], v[64:65], 0, v[82:83]
	global_load_dword v82, v[40:41], off
	v_lshl_add_u64 v[30:31], v[64:65], 0, v[84:85]
	global_load_dword v83, v[30:31], off
	global_load_dword v85, v[32:33], off
	global_load_dword v84, v[76:77], off
	s_waitcnt vmcnt(27)
	v_fmac_f32_e32 v106, v20, v178
	global_load_dword v20, v[80:81], off
	v_add_f32_e32 v16, 0, v17
	global_store_dword v[34:35], v106, off
	v_lshl_add_u64 v[34:35], v[64:65], 0, v[92:93]
	global_load_dword v64, v[34:35], off
	v_fmac_f32_e32 v111, v16, v178
	v_add_f32_e32 v16, 0, v18
	s_waitcnt vmcnt(23)
	v_fmac_f32_e32 v112, v16, v178
	v_add_f32_e32 v16, 0, v19
	v_fmac_f32_e32 v113, v16, v178
	v_add_f32_e32 v16, 0, v24
	v_fmac_f32_e32 v114, v16, v178
	v_add_f32_e32 v16, 0, v25
	s_waitcnt vmcnt(19)
	v_fmac_f32_e32 v118, v12, v179
	v_add_f32_e32 v12, 0, v13
	v_fmac_f32_e32 v107, v21, v178
	v_add_f32_e32 v21, 0, v22
	v_fmac_f32_e32 v115, v16, v178
	v_add_f32_e32 v16, 0, v26
	s_waitcnt vmcnt(18)
	v_fmac_f32_e32 v119, v12, v179
	v_add_f32_e32 v12, 0, v14
	v_fmac_f32_e32 v108, v21, v178
	v_add_f32_e32 v21, 0, v23
	v_fmac_f32_e32 v116, v16, v178
	v_add_f32_e32 v16, 0, v27
	v_fmac_f32_e32 v120, v12, v179
	v_add_f32_e32 v12, 0, v15
	v_fmac_f32_e32 v109, v21, v178
	v_fmac_f32_e32 v117, v16, v178
	global_store_dword v[36:37], v107, off
	global_store_dword v[42:43], v108, off
	global_store_dword v[54:55], v109, off
	global_store_dword v[56:57], v110, off
	global_store_dword v[52:53], v111, off
	global_store_dword v[38:39], v112, off
	global_store_dword v[58:59], v113, off
	global_store_dword v[48:49], v114, off
	global_store_dword v[60:61], v115, off
	global_store_dword v[62:63], v116, off
	global_store_dword v[44:45], v117, off
	global_store_dword v[94:95], v118, off
	s_waitcnt vmcnt(26)
	v_fmac_f32_e32 v124, v0, v179
	v_add_f32_e32 v0, 0, v1
	s_waitcnt vmcnt(24)
	v_fmac_f32_e32 v121, v4, v179
	v_add_f32_e32 v4, 0, v5
	v_fmac_f32_e32 v122, v4, v179
	v_add_f32_e32 v4, 0, v6
	s_waitcnt vmcnt(22)
	v_fmac_f32_e32 v103, v4, v179
	v_add_f32_e32 v4, 0, v7
	v_fmac_f32_e32 v102, v12, v179
	v_fmac_f32_e32 v123, v4, v179
	global_store_dword v[66:67], v119, off
	global_store_dword v[68:69], v120, off
	global_store_dword v[50:51], v102, off
	global_store_dword v[28:29], v121, off
	global_store_dword v[70:71], v122, off
	global_store_dword v[46:47], v103, off
	global_store_dword v[72:73], v123, off
	global_store_dword v[74:75], v124, off
	s_waitcnt vmcnt(26)
	v_fmac_f32_e32 v82, v0, v179
	v_add_f32_e32 v0, 0, v2
	s_waitcnt vmcnt(25)
	v_fmac_f32_e32 v83, v0, v179
	v_add_f32_e32 v0, 0, v3
	s_waitcnt vmcnt(23)
	v_fmac_f32_e32 v84, v0, v179
	v_add_f32_e32 v0, 0, v8
	v_fmac_f32_e32 v85, v0, v179
	v_add_f32_e32 v0, 0, v9
	v_fmac_f32_e32 v86, v0, v179
	v_add_f32_e32 v0, 0, v10
	s_waitcnt vmcnt(22)
	v_fmac_f32_e32 v20, v0, v179
	v_add_f32_e32 v0, 0, v11
	s_waitcnt vmcnt(20)
	v_fmac_f32_e32 v64, v0, v179
	global_store_dword v[40:41], v82, off
	global_store_dword v[30:31], v83, off
	global_store_dword v[76:77], v84, off
	global_store_dword v[32:33], v85, off
	global_store_dword v[78:79], v86, off
	global_store_dword v[80:81], v20, off
	global_store_dword v[34:35], v64, off
	s_cbranch_scc0 .LBB0_836

.LBB0_1015:
	s_cmp_gt_i32 s60, 9
	s_cselect_b64 s[2:3], -1, 0
	s_cmp_lt_i32 s61, 9
	s_cselect_b64 s[4:5], -1, 0
	s_or_b64 s[2:3], s[2:3], s[4:5]
	s_and_b64 vcc, exec, s[2:3]
	s_cbranch_vccnz .LBB0_1075
	s_mov_b64 s[4:5], s[0:1]
	s_cmpk_gt_i32 s58, 0x1ff
	s_cbranch_scc1 .LBB0_1021
	s_load_dwordx2 s[6:7], s[4:5], 0xe0
	v_lshrrev_b32_e32 v8, 3, v162
	v_mul_u32_u24_e32 v0, 0xb00, v8
	v_lshlrev_b32_e32 v96, 1, v0
	v_mov_b32_e32 v97, 0
	s_waitcnt lgkmcnt(0)
	s_add_u32 s2, s6, 0x6b07000
	s_addc_u32 s3, s7, 0
	v_lshlrev_b32_e32 v0, 4, v162
	s_add_u32 s4, s6, 0x6b7a100
	v_and_b32_e32 v0, 0x70, v0
	v_mov_b32_e32 v1, v97
	v_lshl_add_u64 v[2:3], s[6:7], 0, v[96:97]
	s_addc_u32 s5, s7, 0
	v_lshl_add_u64 v[0:1], v[2:3], 0, v[0:1]
	s_mov_b64 s[6:7], 0x9b7a100
	v_xor_b32_e32 v9, v163, v162
	v_lshl_add_u64 v[98:99], v[0:1], 0, s[6:7]
	s_mov_b64 s[6:7], 0x5080000
	v_lshl_add_u64 v[100:101], v[0:1], 0, s[6:7]
	v_lshlrev_b32_e32 v1, 4, v9
	v_and_b32_e32 v6, 15, v162
	v_bfe_u32 v0, v162, 1, 3
	v_and_b32_e32 v1, 0x70, v1
	v_bfe_u32 v4, v162, 6, 1
	v_lshrrev_b32_e32 v5, 7, v162
	v_bitop3_b32 v0, v163, v0, 3 bitop3:0x6c
	v_lshl_or_b32 v129, v8, 7, v1
	v_lshlrev_b32_e32 v1, 7, v6
	s_load_dword s30, s[0:1], 0xf0
	v_lshl_or_b32 v2, v5, 13, v1
	v_lshl_or_b32 v1, v4, 13, v1
	v_lshlrev_b32_e32 v0, 4, v0
	v_or_b32_e32 v144, v2, v0
	v_or_b32_e32 v145, v1, v0
	v_xor_b32_e32 v0, 64, v0
	v_bfe_u32 v7, v162, 4, 2
	v_or_b32_e32 v146, v2, v0
	v_or_b32_e32 v147, v1, v0
	v_lshlrev_b32_e32 v0, 6, v5
	v_lshl_or_b32 v148, v4, 6, v6
	v_lshl_or_b32 v149, v7, 2, v0
	s_mov_b32 s7, 0
	v_mov_b32_e32 v150, 0x1600
	s_mov_b64 s[8:9], 0x2c000
	s_mov_b32 s31, 0x2c000
	s_mov_b64 s[10:11], 0x58000
	s_mov_b32 s34, 0x58000
	s_mov_b64 s[12:13], 0x84000
	s_mov_b32 s35, 0x84000
	s_mov_b64 s[14:15], 0x84100
	s_mov_b64 s[16:17], 0x58100
	s_mov_b64 s[18:19], 0x2c100
	s_mov_b64 s[20:21], 0x100
	s_mov_b64 s[22:23], 0x200
	s_mov_b64 s[24:25], 0x2c200
	s_mov_b64 s[26:27], 0x58200
	s_mov_b64 s[28:29], 0x84200
	v_mov_b32_e32 v151, 0x1000
	s_mov_b32 s36, s58
	v_and_b32_e32 v240, 63, v162
	v_lshrrev_b32_e32 v247, 6, v162
	v_lshrrev_b32_e32 v242, 3, v240
	v_lshl_add_u32 v242, v247, 5, v242
	v_and_b32_e32 v243, 7, v240
	v_lshrrev_b32_e32 v244, 4, v240
	v_xor_b32_e32 v243, v243, v244
	v_lshlrev_b32_e32 v243, 4, v243
	v_mov_b32_e32 v241, 0x1600
	v_mad_u32_u24 v248, v242, v241, v243
	v_xor_b32_e32 v249, 64, v248
	v_add_u32_e32 v249, 0xb000, v249
	v_add_u32_e32 v250, 0x16000, v248
	v_xor_b32_e32 v251, 64, v248
	v_add_u32_e32 v251, 0x21000, v251
	v_and_b32_e32 v241, 15, v240
	v_lshrrev_b32_e32 v242, 1, v241
	v_xor_b32_e32 v242, v242, v244
	v_lshlrev_b32_e32 v242, 4, v242
	v_lshl_or_b32 v242, v241, 7, v242
	v_lshrrev_b32_e32 v243, 1, v247
	v_lshl_or_b32 v252, v243, 13, v242
	v_xor_b32_e32 v253, 64, v252
	v_and_b32_e32 v243, 1, v247
	v_lshl_or_b32 v254, v243, 13, v242
	v_xor_b32_e32 v255, 64, v254
.LBB0_1018:
	s_lshl_b32 s6, s36, 7
	s_and_b32 s37, s6, 0x1f80
	s_lshl_b32 s6, s36, 1
	s_and_b32 s38, s6, 0xffffff80
	s_mul_i32 s6, s37, 0x1600
	v_lshl_add_u64 v[102:103], v[98:99], 0, s[6:7]
	v_add_co_u32_e32 v38, vcc, 0x2c000, v102
	v_mad_i64_i32 v[104:105], s[40:41], s38, v150, v[100:101]
	s_nop 0
	v_addc_co_u32_e32 v39, vcc, 0, v103, vcc
	v_add_co_u32_e32 v44, vcc, 0x58000, v102
	s_nop 0
	v_addc_co_u32_e32 v45, vcc, 0, v103, vcc
	v_add_co_u32_e32 v46, vcc, 0x84000, v102
	v_addc_co_u32_e32 v47, vcc, 0, v103, vcc
	v_add_co_u32_e32 v48, vcc, s31, v104
	v_addc_co_u32_e32 v49, vcc, 0, v105, vcc
	v_add_co_u32_e32 v50, vcc, s34, v104
	s_nop 0
	v_addc_co_u32_e32 v51, vcc, 0, v105, vcc
	v_add_co_u32_e32 v52, vcc, s35, v104
	s_nop 0
	v_addc_co_u32_e32 v53, vcc, 0, v105, vcc
	s_mov_b32 s39, -2
	v_mov_b32_e32 v8, 0
	v_mov_b32_e32 v9, v97
	v_mov_b32_e32 v10, v97
	v_mov_b32_e32 v11, v97
	v_mov_b32_e32 v24, 0
	v_mov_b32_e32 v25, v97
	v_mov_b32_e32 v26, v97
	v_mov_b32_e32 v27, v97
	v_mov_b32_e32 v36, 0
	v_mov_b32_e32 v37, v97
	v_mov_b32_e32 v38, v97
	v_mov_b32_e32 v39, v97
	v_lshl_add_u64 v[106:107], v[104:105], 0, s[8:9]
	v_lshl_add_u64 v[108:109], v[104:105], 0, s[10:11]
	v_lshl_add_u64 v[110:111], v[104:105], 0, s[12:13]
	v_lshl_add_u64 v[120:121], v[104:105], 0, s[14:15]
	v_lshl_add_u64 v[122:123], v[104:105], 0, s[16:17]
	v_lshl_add_u64 v[124:125], v[104:105], 0, s[18:19]
	v_lshl_add_u64 v[118:119], v[104:105], 0, s[20:21]
	v_lshl_add_u64 v[112:113], v[102:103], 0, s[8:9]
	v_lshl_add_u64 v[114:115], v[102:103], 0, s[10:11]
	v_lshl_add_u64 v[116:117], v[102:103], 0, s[12:13]
	v_lshl_add_u64 v[126:127], v[102:103], 0, s[14:15]
	v_lshl_add_u64 v[130:131], v[102:103], 0, s[16:17]
	v_lshl_add_u64 v[132:133], v[102:103], 0, s[18:19]
	v_lshl_add_u64 v[134:135], v[102:103], 0, s[20:21]
	v_mov_b32_e32 v48, 0
	v_mov_b32_e32 v49, v97
	v_mov_b32_e32 v50, v97
	v_mov_b32_e32 v51, v97
	v_mov_b32_e32 v52, 0
	v_mov_b32_e32 v53, v97
	v_mov_b32_e32 v54, v97
	v_mov_b32_e32 v55, v97
	v_mov_b32_e32 v56, 0
	v_mov_b32_e32 v57, v97
	v_mov_b32_e32 v58, v97
	v_mov_b32_e32 v59, v97
	v_mov_b32_e32 v44, 0
	v_mov_b32_e32 v45, v97
	v_mov_b32_e32 v46, v97
	v_mov_b32_e32 v47, v97
	v_mov_b32_e32 v60, 0
	v_mov_b32_e32 v61, v97
	v_mov_b32_e32 v62, v97
	v_mov_b32_e32 v63, v97
	v_mov_b32_e32 v0, 0
	v_mov_b32_e32 v1, v97
	v_mov_b32_e32 v2, v97
	v_mov_b32_e32 v3, v97
	v_mov_b32_e32 v16, 0
	v_mov_b32_e32 v17, v97
	v_mov_b32_e32 v18, v97
	v_mov_b32_e32 v19, v97
	v_mov_b32_e32 v32, 0
	v_mov_b32_e32 v33, v97
	v_mov_b32_e32 v34, v97
	v_mov_b32_e32 v35, v97
	v_mov_b32_e32 v4, 0
	v_mov_b32_e32 v5, v97
	v_mov_b32_e32 v6, v97
	v_mov_b32_e32 v7, v97
	v_mov_b32_e32 v20, 0
	v_mov_b32_e32 v21, v97
	v_mov_b32_e32 v22, v97
	v_mov_b32_e32 v23, v97
	v_mov_b32_e32 v40, 0
	v_mov_b32_e32 v41, v97
	v_mov_b32_e32 v42, v97
	v_mov_b32_e32 v43, v97
	v_mov_b32_e32 v12, 0
	v_mov_b32_e32 v13, v97
	v_mov_b32_e32 v14, v97
	v_mov_b32_e32 v15, v97
	v_mov_b32_e32 v28, 0
	v_mov_b32_e32 v29, v97
	v_mov_b32_e32 v30, v97
	v_mov_b32_e32 v31, v97
	v_readfirstlane_b32 s40, v102
	v_readfirstlane_b32 s41, v103
	v_readfirstlane_b32 s48, v104
	v_readfirstlane_b32 s49, v105
	v_readfirstlane_b32 s6, v247
	s_nop 3
	s_mul_i32 s39, s6, 0xb000
	s_sub_u32 s40, s40, s39
	s_subb_u32 s41, s41, 0
	s_sub_u32 s48, s48, s39
	s_subb_u32 s49, s49, 0
	s_lshl_b32 s6, s6, 12
	s_add_u32 m0, s6, 0x0
	v_mov_b32_e32 v60, 0
	global_load_lds_dwordx4 v248, s[40:41]
	v_mov_b32_e32 v61, 0
	s_add_u32 m0, s6, 0x400
	v_mov_b32_e32 v62, 0
	global_load_lds_dwordx4 v249, s[40:41]
	v_mov_b32_e32 v63, 0
	s_add_u32 m0, s6, 0x800
	v_mov_b32_e32 v44, 0
	global_load_lds_dwordx4 v250, s[40:41]
	v_mov_b32_e32 v45, 0
	s_add_u32 m0, s6, 0xc00
	v_mov_b32_e32 v46, 0
	global_load_lds_dwordx4 v251, s[40:41]
	v_mov_b32_e32 v47, 0
	s_add_u32 m0, s6, 0x8000
	v_mov_b32_e32 v28, 0
	global_load_lds_dwordx4 v248, s[48:49]
	v_mov_b32_e32 v29, 0
	s_add_u32 m0, s6, 0x8400
	v_mov_b32_e32 v30, 0
	global_load_lds_dwordx4 v249, s[48:49]
	v_mov_b32_e32 v31, 0
	s_add_u32 m0, s6, 0x8800
	v_mov_b32_e32 v12, 0
	global_load_lds_dwordx4 v250, s[48:49]
	v_mov_b32_e32 v13, 0
	s_add_u32 m0, s6, 0x8c00
	v_mov_b32_e32 v14, 0
	global_load_lds_dwordx4 v251, s[48:49]
	v_mov_b32_e32 v15, 0
	s_add_u32 s40, s40, 0x80
	s_addc_u32 s41, s41, 0
	s_add_u32 s48, s48, 0x80
	s_addc_u32 s49, s49, 0
	s_add_u32 m0, s6, 0x4000
	v_mov_b32_e32 v56, 0
	global_load_lds_dwordx4 v248, s[40:41]
	v_mov_b32_e32 v57, 0
	s_add_u32 m0, s6, 0x4400
	v_mov_b32_e32 v58, 0
	global_load_lds_dwordx4 v249, s[40:41]
	v_mov_b32_e32 v59, 0
	s_add_u32 m0, s6, 0x4800
	v_mov_b32_e32 v40, 0
	global_load_lds_dwordx4 v250, s[40:41]
	v_mov_b32_e32 v41, 0
	s_add_u32 m0, s6, 0x4c00
	v_mov_b32_e32 v42, 0
	global_load_lds_dwordx4 v251, s[40:41]
	v_mov_b32_e32 v43, 0
	s_add_u32 m0, s6, 0xc000
	v_mov_b32_e32 v20, 0
	global_load_lds_dwordx4 v248, s[48:49]
	v_mov_b32_e32 v21, 0
	s_add_u32 m0, s6, 0xc400
	v_mov_b32_e32 v22, 0
	global_load_lds_dwordx4 v249, s[48:49]
	v_mov_b32_e32 v23, 0
	s_add_u32 m0, s6, 0xc800
	v_mov_b32_e32 v4, 0
	global_load_lds_dwordx4 v250, s[48:49]
	v_mov_b32_e32 v5, 0
	s_add_u32 m0, s6, 0xcc00
	v_mov_b32_e32 v6, 0
	global_load_lds_dwordx4 v251, s[48:49]
	v_mov_b32_e32 v7, 0
	s_add_u32 s40, s40, 0x80
	s_addc_u32 s41, s41, 0
	s_add_u32 s48, s48, 0x80
	s_addc_u32 s49, s49, 0
	v_mov_b32_e32 v52, 0
	v_mov_b32_e32 v53, 0
	v_mov_b32_e32 v54, 0
	v_mov_b32_e32 v55, 0
	v_mov_b32_e32 v32, 0
	v_mov_b32_e32 v33, 0
	v_mov_b32_e32 v34, 0
	v_mov_b32_e32 v35, 0
	v_mov_b32_e32 v16, 0
	v_mov_b32_e32 v17, 0
	v_mov_b32_e32 v18, 0
	v_mov_b32_e32 v19, 0
	v_mov_b32_e32 v0, 0
	v_mov_b32_e32 v1, 0
	v_mov_b32_e32 v2, 0
	v_mov_b32_e32 v3, 0
	v_mov_b32_e32 v48, 0
	v_mov_b32_e32 v49, 0
	v_mov_b32_e32 v50, 0
	v_mov_b32_e32 v51, 0
	v_mov_b32_e32 v36, 0
	v_mov_b32_e32 v37, 0
	v_mov_b32_e32 v38, 0
	v_mov_b32_e32 v39, 0
	v_mov_b32_e32 v24, 0
	v_mov_b32_e32 v25, 0
	v_mov_b32_e32 v26, 0
	v_mov_b32_e32 v27, 0
	v_mov_b32_e32 v8, 0
	v_mov_b32_e32 v9, 0
	v_mov_b32_e32 v10, 0
	v_mov_b32_e32 v11, 0
	s_mov_b32 s32, 21
.Lg9_loop:
	s_waitcnt vmcnt(8)
	s_barrier
	ds_read_b128 v[64:67], v252 offset:0
	ds_read_b128 v[104:107], v254 offset:32768
	ds_read_b128 v[108:111], v254 offset:34816
	ds_read_b128 v[112:115], v254 offset:36864
	ds_read_b128 v[116:119], v254 offset:38912
	ds_read_b128 v[68:71], v252 offset:2048
	ds_read_b128 v[72:75], v252 offset:4096
	ds_read_b128 v[76:79], v252 offset:6144
	ds_read_b128 v[80:83], v253 offset:0
	ds_read_b128 v[120:123], v255 offset:32768
	ds_read_b128 v[124:127], v255 offset:34816
	ds_read_b128 v[132:135], v255 offset:36864
	ds_read_b128 v[136:139], v255 offset:38912
	s_waitcnt lgkmcnt(11)
	v_mfma_f32_16x16x32_bf16 v[60:63], v[64:67], v[104:107], v[60:63]
	s_waitcnt lgkmcnt(10)
	v_mfma_f32_16x16x32_bf16 v[44:47], v[64:67], v[108:111], v[44:47]
	s_waitcnt lgkmcnt(9)
	v_mfma_f32_16x16x32_bf16 v[28:31], v[64:67], v[112:115], v[28:31]
	s_waitcnt lgkmcnt(8)
	v_mfma_f32_16x16x32_bf16 v[12:15], v[64:67], v[116:119], v[12:15]
	ds_read_b128 v[84:87], v253 offset:2048
	ds_read_b128 v[88:91], v253 offset:4096
	ds_read_b128 v[92:95], v253 offset:6144
	s_waitcnt lgkmcnt(10)
	v_mfma_f32_16x16x32_bf16 v[56:59], v[68:71], v[104:107], v[56:59]
	v_mfma_f32_16x16x32_bf16 v[40:43], v[68:71], v[108:111], v[40:43]
	v_mfma_f32_16x16x32_bf16 v[20:23], v[68:71], v[112:115], v[20:23]
	v_mfma_f32_16x16x32_bf16 v[4:7], v[68:71], v[116:119], v[4:7]
	s_waitcnt lgkmcnt(9)
	v_mfma_f32_16x16x32_bf16 v[52:55], v[72:75], v[104:107], v[52:55]
	v_mfma_f32_16x16x32_bf16 v[32:35], v[72:75], v[108:111], v[32:35]
	v_mfma_f32_16x16x32_bf16 v[16:19], v[72:75], v[112:115], v[16:19]
	v_mfma_f32_16x16x32_bf16 v[0:3], v[72:75], v[116:119], v[0:3]
	s_waitcnt lgkmcnt(8)
	v_mfma_f32_16x16x32_bf16 v[48:51], v[76:79], v[104:107], v[48:51]
	v_mfma_f32_16x16x32_bf16 v[36:39], v[76:79], v[108:111], v[36:39]
	v_mfma_f32_16x16x32_bf16 v[24:27], v[76:79], v[112:115], v[24:27]
	v_mfma_f32_16x16x32_bf16 v[8:11], v[76:79], v[116:119], v[8:11]
	s_waitcnt lgkmcnt(0)
	s_barrier
	s_add_u32 m0, s6, 0x0
	v_mfma_f32_16x16x32_bf16 v[60:63], v[80:83], v[120:123], v[60:63]
	global_load_lds_dwordx4 v248, s[40:41]
	v_mfma_f32_16x16x32_bf16 v[44:47], v[80:83], v[124:127], v[44:47]
	s_add_u32 m0, s6, 0x400
	v_mfma_f32_16x16x32_bf16 v[28:31], v[80:83], v[132:135], v[28:31]
	global_load_lds_dwordx4 v249, s[40:41]
	v_mfma_f32_16x16x32_bf16 v[12:15], v[80:83], v[136:139], v[12:15]
	s_add_u32 m0, s6, 0x800
	v_mfma_f32_16x16x32_bf16 v[56:59], v[84:87], v[120:123], v[56:59]
	global_load_lds_dwordx4 v250, s[40:41]
	v_mfma_f32_16x16x32_bf16 v[40:43], v[84:87], v[124:127], v[40:43]
	s_add_u32 m0, s6, 0xc00
	v_mfma_f32_16x16x32_bf16 v[20:23], v[84:87], v[132:135], v[20:23]
	global_load_lds_dwordx4 v251, s[40:41]
	v_mfma_f32_16x16x32_bf16 v[4:7], v[84:87], v[136:139], v[4:7]
	s_add_u32 m0, s6, 0x8000
	v_mfma_f32_16x16x32_bf16 v[52:55], v[88:91], v[120:123], v[52:55]
	global_load_lds_dwordx4 v248, s[48:49]
	v_mfma_f32_16x16x32_bf16 v[32:35], v[88:91], v[124:127], v[32:35]
	s_add_u32 m0, s6, 0x8400
	v_mfma_f32_16x16x32_bf16 v[16:19], v[88:91], v[132:135], v[16:19]
	global_load_lds_dwordx4 v249, s[48:49]
	v_mfma_f32_16x16x32_bf16 v[0:3], v[88:91], v[136:139], v[0:3]
	s_add_u32 m0, s6, 0x8800
	v_mfma_f32_16x16x32_bf16 v[48:51], v[92:95], v[120:123], v[48:51]
	global_load_lds_dwordx4 v250, s[48:49]
	v_mfma_f32_16x16x32_bf16 v[36:39], v[92:95], v[124:127], v[36:39]
	s_add_u32 m0, s6, 0x8c00
	v_mfma_f32_16x16x32_bf16 v[24:27], v[92:95], v[132:135], v[24:27]
	global_load_lds_dwordx4 v251, s[48:49]
	v_mfma_f32_16x16x32_bf16 v[8:11], v[92:95], v[136:139], v[8:11]
	s_add_u32 s40, s40, 0x80
	s_addc_u32 s41, s41, 0
	s_add_u32 s48, s48, 0x80
	s_addc_u32 s49, s49, 0
	s_waitcnt vmcnt(8)
	s_barrier
	ds_read_b128 v[64:67], v252 offset:16384
	ds_read_b128 v[104:107], v254 offset:49152
	ds_read_b128 v[108:111], v254 offset:51200
	ds_read_b128 v[112:115], v254 offset:53248
	ds_read_b128 v[116:119], v254 offset:55296
	ds_read_b128 v[68:71], v252 offset:18432
	ds_read_b128 v[72:75], v252 offset:20480
	ds_read_b128 v[76:79], v252 offset:22528
	ds_read_b128 v[80:83], v253 offset:16384
	ds_read_b128 v[120:123], v255 offset:49152
	ds_read_b128 v[124:127], v255 offset:51200
	ds_read_b128 v[132:135], v255 offset:53248
	ds_read_b128 v[136:139], v255 offset:55296
	s_waitcnt lgkmcnt(11)
	v_mfma_f32_16x16x32_bf16 v[60:63], v[64:67], v[104:107], v[60:63]
	s_waitcnt lgkmcnt(10)
	v_mfma_f32_16x16x32_bf16 v[44:47], v[64:67], v[108:111], v[44:47]
	s_waitcnt lgkmcnt(9)
	v_mfma_f32_16x16x32_bf16 v[28:31], v[64:67], v[112:115], v[28:31]
	s_waitcnt lgkmcnt(8)
	v_mfma_f32_16x16x32_bf16 v[12:15], v[64:67], v[116:119], v[12:15]
	ds_read_b128 v[84:87], v253 offset:18432
	ds_read_b128 v[88:91], v253 offset:20480
	ds_read_b128 v[92:95], v253 offset:22528
	s_waitcnt lgkmcnt(10)
	v_mfma_f32_16x16x32_bf16 v[56:59], v[68:71], v[104:107], v[56:59]
	v_mfma_f32_16x16x32_bf16 v[40:43], v[68:71], v[108:111], v[40:43]
	v_mfma_f32_16x16x32_bf16 v[20:23], v[68:71], v[112:115], v[20:23]
	v_mfma_f32_16x16x32_bf16 v[4:7], v[68:71], v[116:119], v[4:7]
	s_waitcnt lgkmcnt(9)
	v_mfma_f32_16x16x32_bf16 v[52:55], v[72:75], v[104:107], v[52:55]
	v_mfma_f32_16x16x32_bf16 v[32:35], v[72:75], v[108:111], v[32:35]
	v_mfma_f32_16x16x32_bf16 v[16:19], v[72:75], v[112:115], v[16:19]
	v_mfma_f32_16x16x32_bf16 v[0:3], v[72:75], v[116:119], v[0:3]
	s_waitcnt lgkmcnt(8)
	v_mfma_f32_16x16x32_bf16 v[48:51], v[76:79], v[104:107], v[48:51]
	v_mfma_f32_16x16x32_bf16 v[36:39], v[76:79], v[108:111], v[36:39]
	v_mfma_f32_16x16x32_bf16 v[24:27], v[76:79], v[112:115], v[24:27]
	v_mfma_f32_16x16x32_bf16 v[8:11], v[76:79], v[116:119], v[8:11]
	s_waitcnt lgkmcnt(0)
	s_barrier
	s_add_u32 m0, s6, 0x4000
	v_mfma_f32_16x16x32_bf16 v[60:63], v[80:83], v[120:123], v[60:63]
	global_load_lds_dwordx4 v248, s[40:41]
	v_mfma_f32_16x16x32_bf16 v[44:47], v[80:83], v[124:127], v[44:47]
	s_add_u32 m0, s6, 0x4400
	v_mfma_f32_16x16x32_bf16 v[28:31], v[80:83], v[132:135], v[28:31]
	global_load_lds_dwordx4 v249, s[40:41]
	v_mfma_f32_16x16x32_bf16 v[12:15], v[80:83], v[136:139], v[12:15]
	s_add_u32 m0, s6, 0x4800
	v_mfma_f32_16x16x32_bf16 v[56:59], v[84:87], v[120:123], v[56:59]
	global_load_lds_dwordx4 v250, s[40:41]
	v_mfma_f32_16x16x32_bf16 v[40:43], v[84:87], v[124:127], v[40:43]
	s_add_u32 m0, s6, 0x4c00
	v_mfma_f32_16x16x32_bf16 v[20:23], v[84:87], v[132:135], v[20:23]
	global_load_lds_dwordx4 v251, s[40:41]
	v_mfma_f32_16x16x32_bf16 v[4:7], v[84:87], v[136:139], v[4:7]
	s_add_u32 m0, s6, 0xc000
	v_mfma_f32_16x16x32_bf16 v[52:55], v[88:91], v[120:123], v[52:55]
	global_load_lds_dwordx4 v248, s[48:49]
	v_mfma_f32_16x16x32_bf16 v[32:35], v[88:91], v[124:127], v[32:35]
	s_add_u32 m0, s6, 0xc400
	v_mfma_f32_16x16x32_bf16 v[16:19], v[88:91], v[132:135], v[16:19]
	global_load_lds_dwordx4 v249, s[48:49]
	v_mfma_f32_16x16x32_bf16 v[0:3], v[88:91], v[136:139], v[0:3]
	s_add_u32 m0, s6, 0xc800
	v_mfma_f32_16x16x32_bf16 v[48:51], v[92:95], v[120:123], v[48:51]
	global_load_lds_dwordx4 v250, s[48:49]
	v_mfma_f32_16x16x32_bf16 v[36:39], v[92:95], v[124:127], v[36:39]
	s_add_u32 m0, s6, 0xcc00
	v_mfma_f32_16x16x32_bf16 v[24:27], v[92:95], v[132:135], v[24:27]
	global_load_lds_dwordx4 v251, s[48:49]
	v_mfma_f32_16x16x32_bf16 v[8:11], v[92:95], v[136:139], v[8:11]
	s_add_u32 s40, s40, 0x80
	s_addc_u32 s41, s41, 0
	s_add_u32 s48, s48, 0x80
	s_addc_u32 s49, s49, 0
	s_sub_u32 s32, s32, 1
	s_cmp_lg_u32 s32, 0
	s_cbranch_scc1 .Lg9_loop
	s_waitcnt vmcnt(8)
	s_barrier
	ds_read_b128 v[64:67], v252 offset:0
	ds_read_b128 v[104:107], v254 offset:32768
	ds_read_b128 v[108:111], v254 offset:34816
	ds_read_b128 v[112:115], v254 offset:36864
	ds_read_b128 v[116:119], v254 offset:38912
	ds_read_b128 v[68:71], v252 offset:2048
	ds_read_b128 v[72:75], v252 offset:4096
	ds_read_b128 v[76:79], v252 offset:6144
	ds_read_b128 v[80:83], v253 offset:0
	ds_read_b128 v[120:123], v255 offset:32768
	ds_read_b128 v[124:127], v255 offset:34816
	ds_read_b128 v[132:135], v255 offset:36864
	ds_read_b128 v[136:139], v255 offset:38912
	s_waitcnt lgkmcnt(11)
	v_mfma_f32_16x16x32_bf16 v[60:63], v[64:67], v[104:107], v[60:63]
	s_waitcnt lgkmcnt(10)
	v_mfma_f32_16x16x32_bf16 v[44:47], v[64:67], v[108:111], v[44:47]
	s_waitcnt lgkmcnt(9)
	v_mfma_f32_16x16x32_bf16 v[28:31], v[64:67], v[112:115], v[28:31]
	s_waitcnt lgkmcnt(8)
	v_mfma_f32_16x16x32_bf16 v[12:15], v[64:67], v[116:119], v[12:15]
	ds_read_b128 v[84:87], v253 offset:2048
	ds_read_b128 v[88:91], v253 offset:4096
	ds_read_b128 v[92:95], v253 offset:6144
	s_waitcnt lgkmcnt(10)
	v_mfma_f32_16x16x32_bf16 v[56:59], v[68:71], v[104:107], v[56:59]
	v_mfma_f32_16x16x32_bf16 v[40:43], v[68:71], v[108:111], v[40:43]
	v_mfma_f32_16x16x32_bf16 v[20:23], v[68:71], v[112:115], v[20:23]
	v_mfma_f32_16x16x32_bf16 v[4:7], v[68:71], v[116:119], v[4:7]
	s_waitcnt lgkmcnt(9)
	v_mfma_f32_16x16x32_bf16 v[52:55], v[72:75], v[104:107], v[52:55]
	v_mfma_f32_16x16x32_bf16 v[32:35], v[72:75], v[108:111], v[32:35]
	v_mfma_f32_16x16x32_bf16 v[16:19], v[72:75], v[112:115], v[16:19]
	v_mfma_f32_16x16x32_bf16 v[0:3], v[72:75], v[116:119], v[0:3]
	s_waitcnt lgkmcnt(8)
	v_mfma_f32_16x16x32_bf16 v[48:51], v[76:79], v[104:107], v[48:51]
	v_mfma_f32_16x16x32_bf16 v[36:39], v[76:79], v[108:111], v[36:39]
	v_mfma_f32_16x16x32_bf16 v[24:27], v[76:79], v[112:115], v[24:27]
	v_mfma_f32_16x16x32_bf16 v[8:11], v[76:79], v[116:119], v[8:11]
	s_waitcnt lgkmcnt(0)
	s_barrier
	v_mfma_f32_16x16x32_bf16 v[60:63], v[80:83], v[120:123], v[60:63]
	v_mfma_f32_16x16x32_bf16 v[44:47], v[80:83], v[124:127], v[44:47]
	v_mfma_f32_16x16x32_bf16 v[28:31], v[80:83], v[132:135], v[28:31]
	v_mfma_f32_16x16x32_bf16 v[12:15], v[80:83], v[136:139], v[12:15]
	v_mfma_f32_16x16x32_bf16 v[56:59], v[84:87], v[120:123], v[56:59]
	v_mfma_f32_16x16x32_bf16 v[40:43], v[84:87], v[124:127], v[40:43]
	v_mfma_f32_16x16x32_bf16 v[20:23], v[84:87], v[132:135], v[20:23]
	v_mfma_f32_16x16x32_bf16 v[4:7], v[84:87], v[136:139], v[4:7]
	v_mfma_f32_16x16x32_bf16 v[52:55], v[88:91], v[120:123], v[52:55]
	v_mfma_f32_16x16x32_bf16 v[32:35], v[88:91], v[124:127], v[32:35]
	v_mfma_f32_16x16x32_bf16 v[16:19], v[88:91], v[132:135], v[16:19]
	v_mfma_f32_16x16x32_bf16 v[0:3], v[88:91], v[136:139], v[0:3]
	v_mfma_f32_16x16x32_bf16 v[48:51], v[92:95], v[120:123], v[48:51]
	v_mfma_f32_16x16x32_bf16 v[36:39], v[92:95], v[124:127], v[36:39]
	v_mfma_f32_16x16x32_bf16 v[24:27], v[92:95], v[132:135], v[24:27]
	v_mfma_f32_16x16x32_bf16 v[8:11], v[92:95], v[136:139], v[8:11]
	s_waitcnt vmcnt(0)
	s_barrier
	ds_read_b128 v[64:67], v252 offset:16384
	ds_read_b128 v[104:107], v254 offset:49152
	ds_read_b128 v[108:111], v254 offset:51200
	ds_read_b128 v[112:115], v254 offset:53248
	ds_read_b128 v[116:119], v254 offset:55296
	ds_read_b128 v[68:71], v252 offset:18432
	ds_read_b128 v[72:75], v252 offset:20480
	ds_read_b128 v[76:79], v252 offset:22528
	ds_read_b128 v[80:83], v253 offset:16384
	ds_read_b128 v[120:123], v255 offset:49152
	ds_read_b128 v[124:127], v255 offset:51200
	ds_read_b128 v[132:135], v255 offset:53248
	ds_read_b128 v[136:139], v255 offset:55296
	s_waitcnt lgkmcnt(11)
	v_mfma_f32_16x16x32_bf16 v[60:63], v[64:67], v[104:107], v[60:63]
	s_waitcnt lgkmcnt(10)
	v_mfma_f32_16x16x32_bf16 v[44:47], v[64:67], v[108:111], v[44:47]
	s_waitcnt lgkmcnt(9)
	v_mfma_f32_16x16x32_bf16 v[28:31], v[64:67], v[112:115], v[28:31]
	s_waitcnt lgkmcnt(8)
	v_mfma_f32_16x16x32_bf16 v[12:15], v[64:67], v[116:119], v[12:15]
	ds_read_b128 v[84:87], v253 offset:18432
	ds_read_b128 v[88:91], v253 offset:20480
	ds_read_b128 v[92:95], v253 offset:22528
	s_waitcnt lgkmcnt(10)
	v_mfma_f32_16x16x32_bf16 v[56:59], v[68:71], v[104:107], v[56:59]
	v_mfma_f32_16x16x32_bf16 v[40:43], v[68:71], v[108:111], v[40:43]
	v_mfma_f32_16x16x32_bf16 v[20:23], v[68:71], v[112:115], v[20:23]
	v_mfma_f32_16x16x32_bf16 v[4:7], v[68:71], v[116:119], v[4:7]
	s_waitcnt lgkmcnt(9)
	v_mfma_f32_16x16x32_bf16 v[52:55], v[72:75], v[104:107], v[52:55]
	v_mfma_f32_16x16x32_bf16 v[32:35], v[72:75], v[108:111], v[32:35]
	v_mfma_f32_16x16x32_bf16 v[16:19], v[72:75], v[112:115], v[16:19]
	v_mfma_f32_16x16x32_bf16 v[0:3], v[72:75], v[116:119], v[0:3]
	s_waitcnt lgkmcnt(8)
	v_mfma_f32_16x16x32_bf16 v[48:51], v[76:79], v[104:107], v[48:51]
	v_mfma_f32_16x16x32_bf16 v[36:39], v[76:79], v[108:111], v[36:39]
	v_mfma_f32_16x16x32_bf16 v[24:27], v[76:79], v[112:115], v[24:27]
	v_mfma_f32_16x16x32_bf16 v[8:11], v[76:79], v[116:119], v[8:11]
	s_waitcnt lgkmcnt(0)
	s_barrier
	v_mfma_f32_16x16x32_bf16 v[60:63], v[80:83], v[120:123], v[60:63]
	v_mfma_f32_16x16x32_bf16 v[44:47], v[80:83], v[124:127], v[44:47]
	v_mfma_f32_16x16x32_bf16 v[28:31], v[80:83], v[132:135], v[28:31]
	v_mfma_f32_16x16x32_bf16 v[12:15], v[80:83], v[136:139], v[12:15]
	v_mfma_f32_16x16x32_bf16 v[56:59], v[84:87], v[120:123], v[56:59]
	v_mfma_f32_16x16x32_bf16 v[40:43], v[84:87], v[124:127], v[40:43]
	v_mfma_f32_16x16x32_bf16 v[20:23], v[84:87], v[132:135], v[20:23]
	v_mfma_f32_16x16x32_bf16 v[4:7], v[84:87], v[136:139], v[4:7]
	v_mfma_f32_16x16x32_bf16 v[52:55], v[88:91], v[120:123], v[52:55]
	v_mfma_f32_16x16x32_bf16 v[32:35], v[88:91], v[124:127], v[32:35]
	v_mfma_f32_16x16x32_bf16 v[16:19], v[88:91], v[132:135], v[16:19]
	v_mfma_f32_16x16x32_bf16 v[0:3], v[88:91], v[136:139], v[0:3]
	v_mfma_f32_16x16x32_bf16 v[48:51], v[92:95], v[120:123], v[48:51]
	v_mfma_f32_16x16x32_bf16 v[36:39], v[92:95], v[124:127], v[36:39]
	v_mfma_f32_16x16x32_bf16 v[24:27], v[92:95], v[132:135], v[24:27]
	v_mfma_f32_16x16x32_bf16 v[8:11], v[92:95], v[136:139], v[8:11]
	s_nop 7
	s_nop 1
	s_waitcnt vmcnt(7)
	v_sub_co_u32_e32 v64, vcc, s37, v151
	s_nop 0
	v_readfirstlane_b32 s6, v64
	s_lshr_b32 s6, s6, 10
	s_add_i32 s6, s6, 1
	s_and_b64 s[40:41], vcc, exec
	s_cselect_b32 s6, 0, s6
	s_mul_hi_u32 s39, s6, 0x6000
	s_mulk_i32 s6, 0x6000
	v_or_b32_e32 v64, s38, v148
	s_add_u32 s40, s2, s6
	v_ashrrev_i32_e32 v65, 31, v64
	s_addc_u32 s41, s3, s39
	s_waitcnt vmcnt(0)
	v_add_lshl_u32 v94, v149, s37, 12
	v_lshlrev_b64 v[66:67], 2, v[64:65]
	v_lshl_add_u64 v[102:103], s[40:41], 0, v[66:67]
	v_lshl_add_u64 v[136:137], s[4:5], 0, v[66:67]
	v_mov_b32_e32 v95, v97
	v_or_b32_e32 v66, 0x1000, v94
	v_mov_b32_e32 v67, v97
	v_lshl_add_u64 v[104:105], v[136:137], 0, v[94:95]
	global_load_dword v65, v[102:103], off
	global_load_dword v152, v[104:105], off
	v_lshl_add_u64 v[106:107], v[136:137], 0, v[66:67]
	v_or_b32_e32 v68, 0x2000, v94
	v_mov_b32_e32 v69, v97
	v_or_b32_e32 v70, 0x3000, v94
	v_mov_b32_e32 v71, v97
	v_or_b32_e32 v72, 0x10000, v94
	v_mov_b32_e32 v73, v97
	global_load_dword v153, v[106:107], off
	v_lshl_add_u64 v[108:109], v[136:137], 0, v[68:69]
	v_lshl_add_u64 v[110:111], v[136:137], 0, v[70:71]
	v_lshl_add_u64 v[112:113], v[136:137], 0, v[72:73]
	v_or_b32_e32 v74, 0x11000, v94
	v_mov_b32_e32 v75, v97
	global_load_dword v154, v[108:109], off
	global_load_dword v155, v[110:111], off
	global_load_dword v156, v[112:113], off
	v_lshl_add_u64 v[114:115], v[136:137], 0, v[74:75]
	v_or_b32_e32 v76, 0x12000, v94
	v_mov_b32_e32 v77, v97
	v_or_b32_e32 v78, 0x13000, v94
	v_mov_b32_e32 v79, v97
	v_or_b32_e32 v80, 0x20000, v94
	v_mov_b32_e32 v81, v97
	global_load_dword v157, v[114:115], off
	v_or_b32_e32 v96, 0x30000, v94
	v_lshl_add_u64 v[116:117], v[136:137], 0, v[76:77]
	v_lshl_add_u64 v[118:119], v[136:137], 0, v[78:79]
	v_lshl_add_u64 v[120:121], v[136:137], 0, v[80:81]
	v_or_b32_e32 v82, 0x21000, v94
	v_mov_b32_e32 v83, v97
	global_load_dword v158, v[116:117], off
	global_load_dword v159, v[118:119], off
	global_load_dword v160, v[120:121], off
	v_lshl_add_u64 v[122:123], v[136:137], 0, v[82:83]
	v_or_b32_e32 v84, 0x22000, v94
	v_mov_b32_e32 v85, v97
	v_or_b32_e32 v86, 0x23000, v94
	v_mov_b32_e32 v87, v97
	v_lshl_add_u64 v[130:131], v[136:137], 0, v[96:97]
	v_lshl_add_u64 v[124:125], v[136:137], 0, v[84:85]
	v_lshl_add_u64 v[126:127], v[136:137], 0, v[86:87]
	global_load_dword v161, v[122:123], off
	global_load_dword v170, v[124:125], off
	global_load_dword v171, v[126:127], off
	global_load_dword v172, v[130:131], off
	v_or_b32_e32 v88, 0x31000, v94
	v_mov_b32_e32 v89, v97
	v_lshl_add_u64 v[132:133], v[136:137], 0, v[88:89]
	v_or_b32_e32 v90, 0x32000, v94
	v_mov_b32_e32 v91, v97
	v_or_b32_e32 v92, 0x33000, v94
	v_mov_b32_e32 v93, v97
	v_lshl_add_u64 v[134:135], v[136:137], 0, v[90:91]
	v_lshl_add_u64 v[136:137], v[136:137], 0, v[92:93]
	global_load_dword v173, v[132:133], off
	global_load_dword v174, v[134:135], off
	global_load_dword v175, v[136:137], off
	v_or_b32_e32 v138, 16, v64
	v_ashrrev_i32_e32 v139, 31, v138
	v_lshlrev_b64 v[138:139], 2, v[138:139]
	v_lshl_add_u64 v[94:95], s[4:5], 0, v[94:95]
	global_load_dword v176, v[102:103], off offset:64
	v_lshl_add_u64 v[142:143], s[4:5], 0, v[138:139]
	v_lshl_add_u64 v[138:139], v[94:95], 0, v[138:139]
	v_add_f32_e32 v60, 0, v60
	v_lshl_add_u64 v[140:141], v[142:143], 0, v[66:67]
	global_load_dword v177, v[138:139], off
	global_load_dword v178, v[140:141], off
	global_load_dword v179, v[102:103], off offset:128
	global_load_dword v180, v[102:103], off offset:192
	v_lshl_add_u64 v[102:103], v[142:143], 0, v[68:69]
	global_load_dword v181, v[102:103], off
	v_add_f32_e32 v56, 0, v56
	v_add_f32_e32 v58, 0, v58
	v_add_f32_e32 v52, 0, v52
	v_add_f32_e32 v48, 0, v48
	v_add_f32_e32 v44, 0, v44
	v_add_f32_e32 v50, 0, v50
	v_add_f32_e32 v32, 0, v32
	v_add_f32_e32 v34, 0, v34
	v_add_f32_e32 v40, 0, v40
	v_add_f32_e32 v38, 0, v38
	v_add_f32_e32 v36, 0, v36
	v_add_f32_e32 v28, 0, v28
	v_add_f32_e32 v30, 0, v30
	v_add_f32_e32 v20, 0, v20
	s_waitcnt vmcnt(21)
	v_fmac_f32_e32 v152, v60, v65
	v_add_f32_e32 v60, 0, v61
	global_store_dword v[104:105], v152, off
	v_lshl_add_u64 v[104:105], v[142:143], 0, v[72:73]
	v_add_f32_e32 v16, 0, v16
	v_add_f32_e32 v0, 0, v0
	v_add_f32_e32 v12, 0, v12
	v_add_f32_e32 v4, 0, v4
	s_waitcnt vmcnt(21)
	v_fmac_f32_e32 v153, v60, v65
	v_add_f32_e32 v60, 0, v62
	v_add_f32_e32 v62, 0, v63
	global_store_dword v[106:107], v153, off
	v_lshl_add_u64 v[106:107], v[142:143], 0, v[76:77]
	global_load_dword v153, v[104:105], off
	s_waitcnt vmcnt(22)
	v_fmac_f32_e32 v154, v60, v65
	global_store_dword v[108:109], v154, off
	s_waitcnt vmcnt(21)
	v_fmac_f32_e32 v156, v56, v65
	v_add_f32_e32 v56, 0, v57
	v_lshl_add_u64 v[108:109], v[142:143], 0, v[80:81]
	v_lshl_add_u64 v[60:61], v[142:143], 0, v[70:71]
	global_store_dword v[112:113], v156, off
	v_add_f32_e32 v112, 0, v59
	v_fmac_f32_e32 v155, v62, v65
	global_store_dword v[110:111], v155, off
	s_waitcnt vmcnt(22)
	v_fmac_f32_e32 v157, v56, v65
	global_store_dword v[114:115], v157, off
	global_load_dword v157, v[108:109], off
	v_lshl_add_u64 v[62:63], v[142:143], 0, v[74:75]
	global_load_dword v152, v[60:61], off
	global_load_dword v155, v[106:107], off
	v_lshl_add_u64 v[110:111], v[142:143], 0, v[82:83]
	s_waitcnt vmcnt(25)
	v_fmac_f32_e32 v158, v58, v65
	v_lshl_add_u64 v[58:59], v[142:143], 0, v[84:85]
	s_waitcnt vmcnt(23)
	v_fmac_f32_e32 v160, v52, v65
	v_add_f32_e32 v52, 0, v53
	global_store_dword v[116:117], v158, off
	global_load_dword v158, v[58:59], off
	v_fmac_f32_e32 v159, v112, v65
	v_lshl_add_u64 v[112:113], v[142:143], 0, v[86:87]
	global_load_dword v183, v[112:113], off
	s_waitcnt vmcnt(25)
	v_fmac_f32_e32 v161, v52, v65
	v_add_f32_e32 v52, 0, v54
	s_waitcnt vmcnt(24)
	v_fmac_f32_e32 v170, v52, v65
	s_waitcnt vmcnt(22)
	v_fmac_f32_e32 v172, v48, v65
	v_add_f32_e32 v48, 0, v49
	v_lshl_add_u64 v[52:53], v[142:143], 0, v[90:91]
	v_lshl_add_u64 v[114:115], v[142:143], 0, v[96:97]
	global_store_dword v[120:121], v160, off
	global_load_dword v120, v[52:53], off
	v_lshl_add_u64 v[56:57], v[142:143], 0, v[78:79]
	global_load_dword v182, v[110:111], off
	global_load_dword v156, v[56:57], off
	s_waitcnt vmcnt(25)
	v_fmac_f32_e32 v173, v48, v65
	v_lshl_add_u64 v[48:49], v[142:143], 0, v[92:93]
	global_load_dword v121, v[48:49], off
	s_waitcnt vmcnt(25)
	v_fmac_f32_e32 v174, v50, v65
	global_store_dword v[118:119], v159, off
	global_load_dword v118, v[114:115], off
	v_add_f32_e32 v50, 0, v51
	global_load_dword v154, v[62:63], off
	s_waitcnt vmcnt(25)
	v_fmac_f32_e32 v177, v44, v176
	v_add_f32_e32 v44, 0, v45
	s_waitcnt vmcnt(24)
	v_fmac_f32_e32 v178, v44, v176
	v_add_f32_e32 v44, 0, v46
	v_add_f32_e32 v54, 0, v55
	s_waitcnt vmcnt(21)
	v_fmac_f32_e32 v181, v44, v176
	v_or_b32_e32 v44, 32, v64
	v_ashrrev_i32_e32 v45, 31, v44
	v_lshlrev_b64 v[44:45], 2, v[44:45]
	v_fmac_f32_e32 v175, v50, v65
	v_lshl_add_u64 v[50:51], v[94:95], 0, v[44:45]
	v_lshl_add_u64 v[44:45], s[4:5], 0, v[44:45]
	v_fmac_f32_e32 v171, v54, v65
	v_lshl_add_u64 v[54:55], v[44:45], 0, v[78:79]
	v_add_f32_e32 v46, 0, v47
	v_lshl_add_u64 v[116:117], v[142:143], 0, v[88:89]
	global_load_dword v119, v[116:117], off
	v_or_b32_e32 v64, 48, v64
	global_store_dword v[102:103], v181, off
	v_ashrrev_i32_e32 v65, 31, v64
	v_lshlrev_b64 v[64:65], 2, v[64:65]
	global_store_dword v[122:123], v161, off
	global_store_dword v[124:125], v170, off
	global_store_dword v[126:127], v171, off
	global_store_dword v[130:131], v172, off
	global_store_dword v[132:133], v173, off
	global_store_dword v[134:135], v174, off
	global_store_dword v[136:137], v175, off
	global_store_dword v[138:139], v177, off
	global_store_dword v[140:141], v178, off
	v_lshl_add_u64 v[94:95], v[94:95], 0, v[64:65]
	v_lshl_add_u64 v[64:65], s[4:5], 0, v[64:65]
	v_add_f32_e32 v21, 0, v21
	s_waitcnt vmcnt(29)
	v_fmac_f32_e32 v153, v40, v176
	v_add_f32_e32 v40, 0, v41
	global_store_dword v[104:105], v153, off
	s_add_i32 s36, s36, s30
	s_cmpk_gt_i32 s36, 0x1ff
	s_waitcnt vmcnt(25)
	v_fmac_f32_e32 v157, v32, v176
	global_store_dword v[108:109], v157, off
	global_load_dword v109, v[54:55], off
	s_waitcnt vmcnt(26)
	v_fmac_f32_e32 v152, v46, v176
	v_lshl_add_u64 v[46:47], v[44:45], 0, v[66:67]
	global_load_dword v102, v[50:51], off
	global_load_dword v103, v[46:47], off
	v_add_f32_e32 v32, 0, v33
	global_store_dword v[60:61], v152, off
	v_lshl_add_u64 v[60:61], v[44:45], 0, v[88:89]
	s_waitcnt vmcnt(26)
	v_fmac_f32_e32 v158, v34, v176
	global_store_dword v[58:59], v158, off
	v_add_f32_e32 v34, 0, v35
	v_add_f32_e32 v58, 0, v39
	s_waitcnt vmcnt(26)
	v_fmac_f32_e32 v183, v34, v176
	global_store_dword v[112:113], v183, off
	v_lshl_add_u64 v[34:35], v[44:45], 0, v[72:73]
	v_lshl_add_u64 v[66:67], v[64:65], 0, v[66:67]
	s_waitcnt vmcnt(25)
	v_fmac_f32_e32 v120, v38, v176
	global_store_dword v[52:53], v120, off
	s_waitcnt vmcnt(25)
	v_fmac_f32_e32 v182, v32, v176
	v_lshl_add_u64 v[52:53], v[44:45], 0, v[82:83]
	global_store_dword v[110:111], v182, off
	v_lshl_add_u64 v[32:33], v[44:45], 0, v[70:71]
	s_waitcnt vmcnt(24)
	v_fmac_f32_e32 v121, v58, v176
	v_lshl_add_u64 v[58:59], v[44:45], 0, v[86:87]
	global_load_dword v113, v[58:59], off
	global_load_dword v111, v[52:53], off
	s_waitcnt vmcnt(24)
	v_fmac_f32_e32 v118, v36, v176
	s_waitcnt vmcnt(23)
	v_fmac_f32_e32 v154, v40, v176
	v_add_f32_e32 v40, 0, v42
	v_add_f32_e32 v42, 0, v43
	v_fmac_f32_e32 v156, v42, v176
	global_store_dword v[56:57], v156, off
	v_lshl_add_u64 v[56:57], v[44:45], 0, v[80:81]
	global_store_dword v[114:115], v118, off
	global_load_dword v110, v[56:57], off
	global_load_dword v105, v[32:33], off
	v_add_f32_e32 v36, 0, v37
	global_load_dword v115, v[60:61], off
	v_fmac_f32_e32 v155, v40, v176
	v_lshl_add_u64 v[40:41], v[44:45], 0, v[68:69]
	global_load_dword v104, v[40:41], off
	v_lshl_add_u64 v[42:43], v[44:45], 0, v[76:77]
	global_store_dword v[106:107], v155, off
	global_load_dword v106, v[34:35], off
	s_waitcnt vmcnt(30)
	v_fmac_f32_e32 v119, v36, v176
	global_store_dword v[48:49], v121, off
	v_lshl_add_u64 v[48:49], v[44:45], 0, v[96:97]
	global_store_dword v[62:63], v154, off
	v_lshl_add_u64 v[36:37], v[44:45], 0, v[74:75]
	global_store_dword v[116:117], v119, off
	v_lshl_add_u64 v[38:39], v[44:45], 0, v[84:85]
	global_load_dword v114, v[48:49], off
	v_lshl_add_u64 v[62:63], v[44:45], 0, v[90:91]
	global_load_dword v107, v[36:37], off
	global_load_dword v108, v[42:43], off
	global_load_dword v112, v[38:39], off
	v_lshl_add_u64 v[44:45], v[44:45], 0, v[92:93]
	global_load_dword v116, v[62:63], off
	global_load_dword v117, v[44:45], off
	v_lshl_add_u64 v[68:69], v[64:65], 0, v[68:69]
	global_load_dword v120, v[68:69], off
	global_load_dword v118, v[94:95], off
	global_load_dword v119, v[66:67], off
	s_waitcnt vmcnt(28)
	v_fmac_f32_e32 v102, v28, v179
	global_store_dword v[50:51], v102, off
	v_lshl_add_u64 v[50:51], v[64:65], 0, v[70:71]
	v_add_f32_e32 v70, 0, v29
	v_lshl_add_u64 v[28:29], v[64:65], 0, v[72:73]
	s_waitcnt vmcnt(28)
	v_fmac_f32_e32 v103, v70, v179
	v_lshl_add_u64 v[70:71], v[64:65], 0, v[74:75]
	v_lshl_add_u64 v[72:73], v[64:65], 0, v[78:79]
	v_lshl_add_u64 v[74:75], v[64:65], 0, v[80:81]
	global_load_dword v122, v[70:71], off
	global_load_dword v123, v[72:73], off
	global_load_dword v124, v[74:75], off
	global_load_dword v102, v[50:51], off
	global_load_dword v121, v[28:29], off
	v_lshl_add_u64 v[78:79], v[64:65], 0, v[88:89]
	global_store_dword v[46:47], v103, off
	v_lshl_add_u64 v[46:47], v[64:65], 0, v[76:77]
	global_load_dword v103, v[46:47], off
	v_add_f32_e32 v76, 0, v31
	v_lshl_add_u64 v[80:81], v[64:65], 0, v[90:91]
	s_waitcnt vmcnt(25)
	v_fmac_f32_e32 v110, v16, v179
	s_waitcnt vmcnt(24)
	v_fmac_f32_e32 v105, v76, v179
	v_lshl_add_u64 v[76:77], v[64:65], 0, v[86:87]
	global_store_dword v[32:33], v105, off
	v_lshl_add_u64 v[32:33], v[64:65], 0, v[96:97]
	global_load_dword v86, v[78:79], off
	s_waitcnt vmcnt(24)
	v_fmac_f32_e32 v104, v30, v179
	global_store_dword v[40:41], v104, off
	v_lshl_add_u64 v[40:41], v[64:65], 0, v[82:83]
	global_load_dword v82, v[40:41], off
	v_lshl_add_u64 v[30:31], v[64:65], 0, v[84:85]
	global_load_dword v83, v[30:31], off
	global_load_dword v85, v[32:33], off
	global_load_dword v84, v[76:77], off
	s_waitcnt vmcnt(27)
	v_fmac_f32_e32 v106, v20, v179
	global_load_dword v20, v[80:81], off
	v_add_f32_e32 v16, 0, v17
	global_store_dword v[34:35], v106, off
	v_lshl_add_u64 v[34:35], v[64:65], 0, v[92:93]
	global_load_dword v64, v[34:35], off
	v_fmac_f32_e32 v111, v16, v179
	v_add_f32_e32 v16, 0, v18
	s_waitcnt vmcnt(23)
	v_fmac_f32_e32 v112, v16, v179
	v_add_f32_e32 v16, 0, v19
	v_fmac_f32_e32 v113, v16, v179
	v_add_f32_e32 v16, 0, v24
	v_fmac_f32_e32 v114, v16, v179
	v_add_f32_e32 v16, 0, v25
	s_waitcnt vmcnt(19)
	v_fmac_f32_e32 v118, v12, v180
	v_add_f32_e32 v12, 0, v13
	v_fmac_f32_e32 v107, v21, v179
	v_add_f32_e32 v21, 0, v22
	v_fmac_f32_e32 v115, v16, v179
	v_add_f32_e32 v16, 0, v26
	s_waitcnt vmcnt(18)
	v_fmac_f32_e32 v119, v12, v180
	v_add_f32_e32 v12, 0, v14
	v_fmac_f32_e32 v108, v21, v179
	v_add_f32_e32 v21, 0, v23
	v_fmac_f32_e32 v116, v16, v179
	v_add_f32_e32 v16, 0, v27
	v_fmac_f32_e32 v120, v12, v180
	v_add_f32_e32 v12, 0, v15
	v_fmac_f32_e32 v109, v21, v179
	v_fmac_f32_e32 v117, v16, v179
	global_store_dword v[36:37], v107, off
	global_store_dword v[42:43], v108, off
	global_store_dword v[54:55], v109, off
	global_store_dword v[56:57], v110, off
	global_store_dword v[52:53], v111, off
	global_store_dword v[38:39], v112, off
	global_store_dword v[58:59], v113, off
	global_store_dword v[48:49], v114, off
	global_store_dword v[60:61], v115, off
	global_store_dword v[62:63], v116, off
	global_store_dword v[44:45], v117, off
	global_store_dword v[94:95], v118, off
	s_waitcnt vmcnt(26)
	v_fmac_f32_e32 v124, v0, v180
	v_add_f32_e32 v0, 0, v1
	s_waitcnt vmcnt(24)
	v_fmac_f32_e32 v121, v4, v180
	v_add_f32_e32 v4, 0, v5
	v_fmac_f32_e32 v122, v4, v180
	v_add_f32_e32 v4, 0, v6
	s_waitcnt vmcnt(22)
	v_fmac_f32_e32 v103, v4, v180
	v_add_f32_e32 v4, 0, v7
	v_fmac_f32_e32 v102, v12, v180
	v_fmac_f32_e32 v123, v4, v180
	global_store_dword v[66:67], v119, off
	global_store_dword v[68:69], v120, off
	global_store_dword v[50:51], v102, off
	global_store_dword v[28:29], v121, off
	global_store_dword v[70:71], v122, off
	global_store_dword v[46:47], v103, off
	global_store_dword v[72:73], v123, off
	global_store_dword v[74:75], v124, off
	s_waitcnt vmcnt(26)
	v_fmac_f32_e32 v82, v0, v180
	v_add_f32_e32 v0, 0, v2
	s_waitcnt vmcnt(25)
	v_fmac_f32_e32 v83, v0, v180
	v_add_f32_e32 v0, 0, v3
	s_waitcnt vmcnt(23)
	v_fmac_f32_e32 v84, v0, v180
	v_add_f32_e32 v0, 0, v8
	v_fmac_f32_e32 v85, v0, v180
	v_add_f32_e32 v0, 0, v9
	v_fmac_f32_e32 v86, v0, v180
	v_add_f32_e32 v0, 0, v10
	s_waitcnt vmcnt(22)
	v_fmac_f32_e32 v20, v0, v180
	v_add_f32_e32 v0, 0, v11
	s_waitcnt vmcnt(20)
	v_fmac_f32_e32 v64, v0, v180
	global_store_dword v[40:41], v82, off
	global_store_dword v[30:31], v83, off
	global_store_dword v[76:77], v84, off
	global_store_dword v[32:33], v85, off
	global_store_dword v[78:79], v86, off
	global_store_dword v[80:81], v20, off
	global_store_dword v[34:35], v64, off
	s_cbranch_scc0 .LBB0_1018

.LBB0_1260:
	s_cmp_gt_i32 s60, 13
	s_cselect_b64 s[2:3], -1, 0
	s_cmp_lt_i32 s61, 13
	s_cselect_b64 s[4:5], -1, 0
	s_or_b64 s[2:3], s[2:3], s[4:5]
	s_and_b64 vcc, exec, s[2:3]
	s_cbranch_vccnz .LBB0_1328
	s_mov_b64 s[4:5], s[0:1]
	s_cmpk_gt_i32 s58, 0x1ff
	s_cbranch_scc1 .LBB0_1274
	s_load_dwordx2 s[10:11], s[4:5], 0xe0
	s_load_dwordx2 s[6:7], s[4:5], 0xb8
	v_lshrrev_b32_e32 v8, 3, v162
	v_lshlrev_b32_e32 v96, 11, v8
	v_mov_b32_e32 v97, 0
	v_lshlrev_b32_e32 v0, 4, v162
	v_and_b32_e32 v0, 0x70, v0
	v_mov_b32_e32 v1, v97
	s_waitcnt lgkmcnt(0)
	v_lshl_add_u64 v[2:3], s[10:11], 0, v[96:97]
	v_lshl_add_u64 v[0:1], v[2:3], 0, v[0:1]
	s_mov_b64 s[4:5], 0x9b7a100
	v_xor_b32_e32 v9, v163, v162
	v_lshl_add_u64 v[98:99], v[0:1], 0, s[4:5]
	s_mov_b64 s[4:5], 0x2080000
	v_lshl_add_u64 v[100:101], v[0:1], 0, s[4:5]
	v_lshlrev_b32_e32 v1, 4, v9
	v_and_b32_e32 v6, 15, v162
	s_add_u32 s2, s10, 0x6b22000
	v_bfe_u32 v0, v162, 1, 3
	v_and_b32_e32 v1, 0x70, v1
	v_bfe_u32 v4, v162, 6, 1
	v_lshrrev_b32_e32 v5, 7, v162
	s_addc_u32 s3, s11, 0
	v_bitop3_b32 v0, v163, v0, 3 bitop3:0x6c
	v_lshl_or_b32 v129, v8, 7, v1
	v_lshlrev_b32_e32 v1, 7, v6
	s_load_dword s38, s[0:1], 0xf0
	s_add_u32 s8, s10, 0x6b7a100
	v_lshl_or_b32 v2, v5, 13, v1
	v_lshl_or_b32 v1, v4, 13, v1
	v_lshlrev_b32_e32 v0, 4, v0
	s_addc_u32 s9, s11, 0
	v_or_b32_e32 v136, v2, v0
	v_or_b32_e32 v137, v1, v0
	v_xor_b32_e32 v0, 64, v0
	v_bfe_u32 v7, v162, 4, 2
	v_or_b32_e32 v138, v2, v0
	v_or_b32_e32 v139, v1, v0
	v_lshlrev_b32_e32 v0, 6, v5
	s_cmp_lg_u64 s[6:7], 0
	v_lshl_or_b32 v140, v4, 6, v6
	s_cselect_b64 s[10:11], -1, 0
	v_lshl_or_b32 v141, v7, 2, v0
	s_mov_b32 s13, 0
	s_mov_b64 s[14:15], 0x10000
	s_mov_b32 s39, 0x10000
	s_mov_b64 s[16:17], 0x20000
	s_mov_b32 s40, 0x20000
	s_mov_b64 s[18:19], 0x30000
	s_mov_b32 s41, 0x30000
	s_mov_b64 s[20:21], 0x30100
	s_mov_b64 s[22:23], 0x20100
	s_mov_b64 s[24:25], 0x10100
	s_mov_b64 s[26:27], 0x100
	s_mov_b64 s[28:29], 0x200
	s_mov_b64 s[30:31], 0x10200
	s_mov_b64 s[34:35], 0x20200
	s_mov_b64 s[36:37], 0x30200
	v_mov_b32_e32 v142, 0x1000
	s_mov_b32 s42, s58
	v_and_b32_e32 v240, 63, v162
	v_lshrrev_b32_e32 v247, 6, v162
	v_lshrrev_b32_e32 v242, 3, v240
	v_lshl_add_u32 v242, v247, 5, v242
	v_and_b32_e32 v243, 7, v240
	v_lshrrev_b32_e32 v244, 4, v240
	v_xor_b32_e32 v243, v243, v244
	v_lshlrev_b32_e32 v243, 4, v243
	v_mov_b32_e32 v241, 0x800
	v_mad_u32_u24 v248, v242, v241, v243
	v_xor_b32_e32 v249, 64, v248
	v_add_u32_e32 v249, 0x4000, v249
	v_add_u32_e32 v250, 0x8000, v248
	v_xor_b32_e32 v251, 64, v248
	v_add_u32_e32 v251, 0xc000, v251
	v_and_b32_e32 v241, 15, v240
	v_lshrrev_b32_e32 v242, 1, v241
	v_xor_b32_e32 v242, v242, v244
	v_lshlrev_b32_e32 v242, 4, v242
	v_lshl_or_b32 v242, v241, 7, v242
	v_lshrrev_b32_e32 v243, 1, v247
	v_lshl_or_b32 v252, v243, 13, v242
	v_xor_b32_e32 v253, 64, v252
	v_and_b32_e32 v243, 1, v247
	v_lshl_or_b32 v254, v243, 13, v242
	v_xor_b32_e32 v255, 64, v254
	s_branch .LBB0_1264

.LBB0_1264:
	s_lshl_b32 s4, s42, 7
	s_and_b32 s43, s4, 0x1f80
	s_lshl_b32 s12, s43, 11
	v_lshl_add_u64 v[102:103], v[98:99], 0, s[12:13]
	v_add_co_u32_e32 v40, vcc, 0x10000, v102
	s_lshl_b32 s4, s42, 1
	s_nop 0
	v_addc_co_u32_e32 v41, vcc, 0, v103, vcc
	s_and_b32 s4, s4, 0xffffff80
	v_add_co_u32_e32 v42, vcc, 0x20000, v102
	s_ashr_i32 s5, s4, 31
	s_nop 0
	v_addc_co_u32_e32 v43, vcc, 0, v103, vcc
	s_lshl_b64 s[44:45], s[4:5], 11
	v_add_co_u32_e32 v46, vcc, 0x30000, v102
	v_lshl_add_u64 v[104:105], v[100:101], 0, s[44:45]
	s_nop 0
	v_addc_co_u32_e32 v47, vcc, 0, v103, vcc
	v_add_co_u32_e32 v48, vcc, s39, v104
	s_nop 0
	v_addc_co_u32_e32 v49, vcc, 0, v105, vcc
	v_add_co_u32_e32 v50, vcc, s40, v104
	v_addc_co_u32_e32 v51, vcc, 0, v105, vcc
	v_add_co_u32_e32 v52, vcc, s41, v104
	v_addc_co_u32_e32 v53, vcc, 0, v105, vcc
	s_mov_b32 s5, -2
	v_mov_b32_e32 v12, v97
	v_mov_b32_e32 v13, v97
	v_mov_b32_e32 v14, v97
	v_mov_b32_e32 v15, v97
	v_mov_b32_e32 v28, v97
	v_mov_b32_e32 v29, v97
	v_mov_b32_e32 v30, v97
	v_mov_b32_e32 v31, v97
	v_mov_b32_e32 v44, v97
	v_mov_b32_e32 v45, v97
	v_mov_b32_e32 v46, v97
	v_lshl_add_u64 v[106:107], v[102:103], 0, s[14:15]
	v_lshl_add_u64 v[108:109], v[102:103], 0, s[16:17]
	v_lshl_add_u64 v[110:111], v[102:103], 0, s[18:19]
	v_lshl_add_u64 v[118:119], v[102:103], 0, s[20:21]
	v_lshl_add_u64 v[120:121], v[102:103], 0, s[22:23]
	v_lshl_add_u64 v[122:123], v[102:103], 0, s[24:25]
	v_lshl_add_u64 v[124:125], v[102:103], 0, s[26:27]
	v_lshl_add_u64 v[112:113], v[104:105], 0, s[14:15]
	v_lshl_add_u64 v[114:115], v[104:105], 0, s[16:17]
	v_lshl_add_u64 v[116:117], v[104:105], 0, s[18:19]
	v_lshl_add_u64 v[130:131], v[104:105], 0, s[20:21]
	v_lshl_add_u64 v[132:133], v[104:105], 0, s[22:23]
	v_lshl_add_u64 v[134:135], v[104:105], 0, s[24:25]
	v_lshl_add_u64 v[126:127], v[104:105], 0, s[26:27]
	v_mov_b32_e32 v47, v97
	v_mov_b32_e32 v52, v97
	v_mov_b32_e32 v53, v97
	v_mov_b32_e32 v54, v97
	v_mov_b32_e32 v55, v97
	v_mov_b32_e32 v48, v97
	v_mov_b32_e32 v49, v97
	v_mov_b32_e32 v50, v97
	v_mov_b32_e32 v51, v97
	v_mov_b32_e32 v56, v97
	v_mov_b32_e32 v57, v97
	v_mov_b32_e32 v58, v97
	v_mov_b32_e32 v59, v97
	v_mov_b32_e32 v40, v97
	v_mov_b32_e32 v41, v97
	v_mov_b32_e32 v42, v97
	v_mov_b32_e32 v43, v97
	v_mov_b32_e32 v60, v97
	v_mov_b32_e32 v61, v97
	v_mov_b32_e32 v62, v97
	v_mov_b32_e32 v63, v97
	v_mov_b32_e32 v4, v97
	v_mov_b32_e32 v5, v97
	v_mov_b32_e32 v6, v97
	v_mov_b32_e32 v7, v97
	v_mov_b32_e32 v16, v97
	v_mov_b32_e32 v17, v97
	v_mov_b32_e32 v18, v97
	v_mov_b32_e32 v19, v97
	v_mov_b32_e32 v32, v97
	v_mov_b32_e32 v33, v97
	v_mov_b32_e32 v34, v97
	v_mov_b32_e32 v35, v97
	v_mov_b32_e32 v0, v97
	v_mov_b32_e32 v1, v97
	v_mov_b32_e32 v2, v97
	v_mov_b32_e32 v3, v97
	v_mov_b32_e32 v20, v97
	v_mov_b32_e32 v21, v97
	v_mov_b32_e32 v22, v97
	v_mov_b32_e32 v23, v97
	v_mov_b32_e32 v36, v97
	v_mov_b32_e32 v37, v97
	v_mov_b32_e32 v38, v97
	v_mov_b32_e32 v39, v97
	v_mov_b32_e32 v8, v97
	v_mov_b32_e32 v9, v97
	v_mov_b32_e32 v10, v97
	v_mov_b32_e32 v11, v97
	v_mov_b32_e32 v24, v97
	v_mov_b32_e32 v25, v97
	v_mov_b32_e32 v26, v97
	v_mov_b32_e32 v27, v97
	v_readfirstlane_b32 s44, v102
	v_readfirstlane_b32 s45, v103
	v_readfirstlane_b32 s48, v104
	v_readfirstlane_b32 s49, v105
	v_readfirstlane_b32 s5, v247
	s_nop 3
	s_mul_i32 s32, s5, 0x4000
	s_sub_u32 s44, s44, s32
	s_subb_u32 s45, s45, 0
	s_sub_u32 s48, s48, s32
	s_subb_u32 s49, s49, 0
	s_lshl_b32 s5, s5, 12
	s_add_u32 m0, s5, 0x0
	v_mov_b32_e32 v60, 0
	global_load_lds_dwordx4 v248, s[44:45]
	v_mov_b32_e32 v61, 0
	s_add_u32 m0, s5, 0x400
	v_mov_b32_e32 v62, 0
	global_load_lds_dwordx4 v249, s[44:45]
	v_mov_b32_e32 v63, 0
	s_add_u32 m0, s5, 0x800
	v_mov_b32_e32 v40, 0
	global_load_lds_dwordx4 v250, s[44:45]
	v_mov_b32_e32 v41, 0
	s_add_u32 m0, s5, 0xc00
	v_mov_b32_e32 v42, 0
	global_load_lds_dwordx4 v251, s[44:45]
	v_mov_b32_e32 v43, 0
	s_add_u32 m0, s5, 0x8000
	v_mov_b32_e32 v24, 0
	global_load_lds_dwordx4 v248, s[48:49]
	v_mov_b32_e32 v25, 0
	s_add_u32 m0, s5, 0x8400
	v_mov_b32_e32 v26, 0
	global_load_lds_dwordx4 v249, s[48:49]
	v_mov_b32_e32 v27, 0
	s_add_u32 m0, s5, 0x8800
	v_mov_b32_e32 v8, 0
	global_load_lds_dwordx4 v250, s[48:49]
	v_mov_b32_e32 v9, 0
	s_add_u32 m0, s5, 0x8c00
	v_mov_b32_e32 v10, 0
	global_load_lds_dwordx4 v251, s[48:49]
	v_mov_b32_e32 v11, 0
	s_add_u32 s44, s44, 0x80
	s_addc_u32 s45, s45, 0
	s_add_u32 s48, s48, 0x80
	s_addc_u32 s49, s49, 0
	s_add_u32 m0, s5, 0x4000
	v_mov_b32_e32 v56, 0
	global_load_lds_dwordx4 v248, s[44:45]
	v_mov_b32_e32 v57, 0
	s_add_u32 m0, s5, 0x4400
	v_mov_b32_e32 v58, 0
	global_load_lds_dwordx4 v249, s[44:45]
	v_mov_b32_e32 v59, 0
	s_add_u32 m0, s5, 0x4800
	v_mov_b32_e32 v36, 0
	global_load_lds_dwordx4 v250, s[44:45]
	v_mov_b32_e32 v37, 0
	s_add_u32 m0, s5, 0x4c00
	v_mov_b32_e32 v38, 0
	global_load_lds_dwordx4 v251, s[44:45]
	v_mov_b32_e32 v39, 0
	s_add_u32 m0, s5, 0xc000
	v_mov_b32_e32 v20, 0
	global_load_lds_dwordx4 v248, s[48:49]
	v_mov_b32_e32 v21, 0
	s_add_u32 m0, s5, 0xc400
	v_mov_b32_e32 v22, 0
	global_load_lds_dwordx4 v249, s[48:49]
	v_mov_b32_e32 v23, 0
	s_add_u32 m0, s5, 0xc800
	v_mov_b32_e32 v0, 0
	global_load_lds_dwordx4 v250, s[48:49]
	v_mov_b32_e32 v1, 0
	s_add_u32 m0, s5, 0xcc00
	v_mov_b32_e32 v2, 0
	global_load_lds_dwordx4 v251, s[48:49]
	v_mov_b32_e32 v3, 0
	s_add_u32 s44, s44, 0x80
	s_addc_u32 s45, s45, 0
	s_add_u32 s48, s48, 0x80
	s_addc_u32 s49, s49, 0
	v_mov_b32_e32 v48, 0
	v_mov_b32_e32 v49, 0
	v_mov_b32_e32 v50, 0
	v_mov_b32_e32 v51, 0
	v_mov_b32_e32 v32, 0
	v_mov_b32_e32 v33, 0
	v_mov_b32_e32 v34, 0
	v_mov_b32_e32 v35, 0
	v_mov_b32_e32 v16, 0
	v_mov_b32_e32 v17, 0
	v_mov_b32_e32 v18, 0
	v_mov_b32_e32 v19, 0
	v_mov_b32_e32 v4, 0
	v_mov_b32_e32 v5, 0
	v_mov_b32_e32 v6, 0
	v_mov_b32_e32 v7, 0
	v_mov_b32_e32 v52, 0
	v_mov_b32_e32 v53, 0
	v_mov_b32_e32 v54, 0
	v_mov_b32_e32 v55, 0
	v_mov_b32_e32 v44, 0
	v_mov_b32_e32 v45, 0
	v_mov_b32_e32 v46, 0
	v_mov_b32_e32 v47, 0
	v_mov_b32_e32 v28, 0
	v_mov_b32_e32 v29, 0
	v_mov_b32_e32 v30, 0
	v_mov_b32_e32 v31, 0
	v_mov_b32_e32 v12, 0
	v_mov_b32_e32 v13, 0
	v_mov_b32_e32 v14, 0
	v_mov_b32_e32 v15, 0
	s_mov_b32 s12, 7
.Lg13_loop:
	s_waitcnt vmcnt(8)
	s_barrier
	ds_read_b128 v[64:67], v252 offset:0
	ds_read_b128 v[104:107], v254 offset:32768
	ds_read_b128 v[108:111], v254 offset:34816
	ds_read_b128 v[112:115], v254 offset:36864
	ds_read_b128 v[116:119], v254 offset:38912
	ds_read_b128 v[68:71], v252 offset:2048
	ds_read_b128 v[72:75], v252 offset:4096
	ds_read_b128 v[76:79], v252 offset:6144
	ds_read_b128 v[80:83], v253 offset:0
	ds_read_b128 v[120:123], v255 offset:32768
	ds_read_b128 v[124:127], v255 offset:34816
	ds_read_b128 v[132:135], v255 offset:36864
	ds_read_b128 v[136:139], v255 offset:38912
	s_waitcnt lgkmcnt(11)
	v_mfma_f32_16x16x32_bf16 v[60:63], v[64:67], v[104:107], v[60:63]
	s_waitcnt lgkmcnt(10)
	v_mfma_f32_16x16x32_bf16 v[40:43], v[64:67], v[108:111], v[40:43]
	s_waitcnt lgkmcnt(9)
	v_mfma_f32_16x16x32_bf16 v[24:27], v[64:67], v[112:115], v[24:27]
	s_waitcnt lgkmcnt(8)
	v_mfma_f32_16x16x32_bf16 v[8:11], v[64:67], v[116:119], v[8:11]
	ds_read_b128 v[84:87], v253 offset:2048
	ds_read_b128 v[88:91], v253 offset:4096
	ds_read_b128 v[92:95], v253 offset:6144
	s_waitcnt lgkmcnt(10)
	v_mfma_f32_16x16x32_bf16 v[56:59], v[68:71], v[104:107], v[56:59]
	v_mfma_f32_16x16x32_bf16 v[36:39], v[68:71], v[108:111], v[36:39]
	v_mfma_f32_16x16x32_bf16 v[20:23], v[68:71], v[112:115], v[20:23]
	v_mfma_f32_16x16x32_bf16 v[0:3], v[68:71], v[116:119], v[0:3]
	s_waitcnt lgkmcnt(9)
	v_mfma_f32_16x16x32_bf16 v[48:51], v[72:75], v[104:107], v[48:51]
	v_mfma_f32_16x16x32_bf16 v[32:35], v[72:75], v[108:111], v[32:35]
	v_mfma_f32_16x16x32_bf16 v[16:19], v[72:75], v[112:115], v[16:19]
	v_mfma_f32_16x16x32_bf16 v[4:7], v[72:75], v[116:119], v[4:7]
	s_waitcnt lgkmcnt(8)
	v_mfma_f32_16x16x32_bf16 v[52:55], v[76:79], v[104:107], v[52:55]
	v_mfma_f32_16x16x32_bf16 v[44:47], v[76:79], v[108:111], v[44:47]
	v_mfma_f32_16x16x32_bf16 v[28:31], v[76:79], v[112:115], v[28:31]
	v_mfma_f32_16x16x32_bf16 v[12:15], v[76:79], v[116:119], v[12:15]
	s_waitcnt lgkmcnt(0)
	s_barrier
	s_add_u32 m0, s5, 0x0
	v_mfma_f32_16x16x32_bf16 v[60:63], v[80:83], v[120:123], v[60:63]
	global_load_lds_dwordx4 v248, s[44:45]
	v_mfma_f32_16x16x32_bf16 v[40:43], v[80:83], v[124:127], v[40:43]
	s_add_u32 m0, s5, 0x400
	v_mfma_f32_16x16x32_bf16 v[24:27], v[80:83], v[132:135], v[24:27]
	global_load_lds_dwordx4 v249, s[44:45]
	v_mfma_f32_16x16x32_bf16 v[8:11], v[80:83], v[136:139], v[8:11]
	s_add_u32 m0, s5, 0x800
	v_mfma_f32_16x16x32_bf16 v[56:59], v[84:87], v[120:123], v[56:59]
	global_load_lds_dwordx4 v250, s[44:45]
	v_mfma_f32_16x16x32_bf16 v[36:39], v[84:87], v[124:127], v[36:39]
	s_add_u32 m0, s5, 0xc00
	v_mfma_f32_16x16x32_bf16 v[20:23], v[84:87], v[132:135], v[20:23]
	global_load_lds_dwordx4 v251, s[44:45]
	v_mfma_f32_16x16x32_bf16 v[0:3], v[84:87], v[136:139], v[0:3]
	s_add_u32 m0, s5, 0x8000
	v_mfma_f32_16x16x32_bf16 v[48:51], v[88:91], v[120:123], v[48:51]
	global_load_lds_dwordx4 v248, s[48:49]
	v_mfma_f32_16x16x32_bf16 v[32:35], v[88:91], v[124:127], v[32:35]
	s_add_u32 m0, s5, 0x8400
	v_mfma_f32_16x16x32_bf16 v[16:19], v[88:91], v[132:135], v[16:19]
	global_load_lds_dwordx4 v249, s[48:49]
	v_mfma_f32_16x16x32_bf16 v[4:7], v[88:91], v[136:139], v[4:7]
	s_add_u32 m0, s5, 0x8800
	v_mfma_f32_16x16x32_bf16 v[52:55], v[92:95], v[120:123], v[52:55]
	global_load_lds_dwordx4 v250, s[48:49]
	v_mfma_f32_16x16x32_bf16 v[44:47], v[92:95], v[124:127], v[44:47]
	s_add_u32 m0, s5, 0x8c00
	v_mfma_f32_16x16x32_bf16 v[28:31], v[92:95], v[132:135], v[28:31]
	global_load_lds_dwordx4 v251, s[48:49]
	v_mfma_f32_16x16x32_bf16 v[12:15], v[92:95], v[136:139], v[12:15]
	s_add_u32 s44, s44, 0x80
	s_addc_u32 s45, s45, 0
	s_add_u32 s48, s48, 0x80
	s_addc_u32 s49, s49, 0
	s_waitcnt vmcnt(8)
	s_barrier
	ds_read_b128 v[64:67], v252 offset:16384
	ds_read_b128 v[104:107], v254 offset:49152
	ds_read_b128 v[108:111], v254 offset:51200
	ds_read_b128 v[112:115], v254 offset:53248
	ds_read_b128 v[116:119], v254 offset:55296
	ds_read_b128 v[68:71], v252 offset:18432
	ds_read_b128 v[72:75], v252 offset:20480
	ds_read_b128 v[76:79], v252 offset:22528
	ds_read_b128 v[80:83], v253 offset:16384
	ds_read_b128 v[120:123], v255 offset:49152
	ds_read_b128 v[124:127], v255 offset:51200
	ds_read_b128 v[132:135], v255 offset:53248
	ds_read_b128 v[136:139], v255 offset:55296
	s_waitcnt lgkmcnt(11)
	v_mfma_f32_16x16x32_bf16 v[60:63], v[64:67], v[104:107], v[60:63]
	s_waitcnt lgkmcnt(10)
	v_mfma_f32_16x16x32_bf16 v[40:43], v[64:67], v[108:111], v[40:43]
	s_waitcnt lgkmcnt(9)
	v_mfma_f32_16x16x32_bf16 v[24:27], v[64:67], v[112:115], v[24:27]
	s_waitcnt lgkmcnt(8)
	v_mfma_f32_16x16x32_bf16 v[8:11], v[64:67], v[116:119], v[8:11]
	ds_read_b128 v[84:87], v253 offset:18432
	ds_read_b128 v[88:91], v253 offset:20480
	ds_read_b128 v[92:95], v253 offset:22528
	s_waitcnt lgkmcnt(10)
	v_mfma_f32_16x16x32_bf16 v[56:59], v[68:71], v[104:107], v[56:59]
	v_mfma_f32_16x16x32_bf16 v[36:39], v[68:71], v[108:111], v[36:39]
	v_mfma_f32_16x16x32_bf16 v[20:23], v[68:71], v[112:115], v[20:23]
	v_mfma_f32_16x16x32_bf16 v[0:3], v[68:71], v[116:119], v[0:3]
	s_waitcnt lgkmcnt(9)
	v_mfma_f32_16x16x32_bf16 v[48:51], v[72:75], v[104:107], v[48:51]
	v_mfma_f32_16x16x32_bf16 v[32:35], v[72:75], v[108:111], v[32:35]
	v_mfma_f32_16x16x32_bf16 v[16:19], v[72:75], v[112:115], v[16:19]
	v_mfma_f32_16x16x32_bf16 v[4:7], v[72:75], v[116:119], v[4:7]
	s_waitcnt lgkmcnt(8)
	v_mfma_f32_16x16x32_bf16 v[52:55], v[76:79], v[104:107], v[52:55]
	v_mfma_f32_16x16x32_bf16 v[44:47], v[76:79], v[108:111], v[44:47]
	v_mfma_f32_16x16x32_bf16 v[28:31], v[76:79], v[112:115], v[28:31]
	v_mfma_f32_16x16x32_bf16 v[12:15], v[76:79], v[116:119], v[12:15]
	s_waitcnt lgkmcnt(0)
	s_barrier
	s_add_u32 m0, s5, 0x4000
	v_mfma_f32_16x16x32_bf16 v[60:63], v[80:83], v[120:123], v[60:63]
	global_load_lds_dwordx4 v248, s[44:45]
	v_mfma_f32_16x16x32_bf16 v[40:43], v[80:83], v[124:127], v[40:43]
	s_add_u32 m0, s5, 0x4400
	v_mfma_f32_16x16x32_bf16 v[24:27], v[80:83], v[132:135], v[24:27]
	global_load_lds_dwordx4 v249, s[44:45]
	v_mfma_f32_16x16x32_bf16 v[8:11], v[80:83], v[136:139], v[8:11]
	s_add_u32 m0, s5, 0x4800
	v_mfma_f32_16x16x32_bf16 v[56:59], v[84:87], v[120:123], v[56:59]
	global_load_lds_dwordx4 v250, s[44:45]
	v_mfma_f32_16x16x32_bf16 v[36:39], v[84:87], v[124:127], v[36:39]
	s_add_u32 m0, s5, 0x4c00
	v_mfma_f32_16x16x32_bf16 v[20:23], v[84:87], v[132:135], v[20:23]
	global_load_lds_dwordx4 v251, s[44:45]
	v_mfma_f32_16x16x32_bf16 v[0:3], v[84:87], v[136:139], v[0:3]
	s_add_u32 m0, s5, 0xc000
	v_mfma_f32_16x16x32_bf16 v[48:51], v[88:91], v[120:123], v[48:51]
	global_load_lds_dwordx4 v248, s[48:49]
	v_mfma_f32_16x16x32_bf16 v[32:35], v[88:91], v[124:127], v[32:35]
	s_add_u32 m0, s5, 0xc400
	v_mfma_f32_16x16x32_bf16 v[16:19], v[88:91], v[132:135], v[16:19]
	global_load_lds_dwordx4 v249, s[48:49]
	v_mfma_f32_16x16x32_bf16 v[4:7], v[88:91], v[136:139], v[4:7]
	s_add_u32 m0, s5, 0xc800
	v_mfma_f32_16x16x32_bf16 v[52:55], v[92:95], v[120:123], v[52:55]
	global_load_lds_dwordx4 v250, s[48:49]
	v_mfma_f32_16x16x32_bf16 v[44:47], v[92:95], v[124:127], v[44:47]
	s_add_u32 m0, s5, 0xcc00
	v_mfma_f32_16x16x32_bf16 v[28:31], v[92:95], v[132:135], v[28:31]
	global_load_lds_dwordx4 v251, s[48:49]
	v_mfma_f32_16x16x32_bf16 v[12:15], v[92:95], v[136:139], v[12:15]
	s_add_u32 s44, s44, 0x80
	s_addc_u32 s45, s45, 0
	s_add_u32 s48, s48, 0x80
	s_addc_u32 s49, s49, 0
	s_sub_u32 s12, s12, 1
	s_cmp_lg_u32 s12, 0
	s_cbranch_scc1 .Lg13_loop
	s_waitcnt vmcnt(8)
	s_barrier
	ds_read_b128 v[64:67], v252 offset:0
	ds_read_b128 v[104:107], v254 offset:32768
	ds_read_b128 v[108:111], v254 offset:34816
	ds_read_b128 v[112:115], v254 offset:36864
	ds_read_b128 v[116:119], v254 offset:38912
	ds_read_b128 v[68:71], v252 offset:2048
	ds_read_b128 v[72:75], v252 offset:4096
	ds_read_b128 v[76:79], v252 offset:6144
	ds_read_b128 v[80:83], v253 offset:0
	ds_read_b128 v[120:123], v255 offset:32768
	ds_read_b128 v[124:127], v255 offset:34816
	ds_read_b128 v[132:135], v255 offset:36864
	ds_read_b128 v[136:139], v255 offset:38912
	s_waitcnt lgkmcnt(11)
	v_mfma_f32_16x16x32_bf16 v[60:63], v[64:67], v[104:107], v[60:63]
	s_waitcnt lgkmcnt(10)
	v_mfma_f32_16x16x32_bf16 v[40:43], v[64:67], v[108:111], v[40:43]
	s_waitcnt lgkmcnt(9)
	v_mfma_f32_16x16x32_bf16 v[24:27], v[64:67], v[112:115], v[24:27]
	s_waitcnt lgkmcnt(8)
	v_mfma_f32_16x16x32_bf16 v[8:11], v[64:67], v[116:119], v[8:11]
	ds_read_b128 v[84:87], v253 offset:2048
	ds_read_b128 v[88:91], v253 offset:4096
	ds_read_b128 v[92:95], v253 offset:6144
	s_waitcnt lgkmcnt(10)
	v_mfma_f32_16x16x32_bf16 v[56:59], v[68:71], v[104:107], v[56:59]
	v_mfma_f32_16x16x32_bf16 v[36:39], v[68:71], v[108:111], v[36:39]
	v_mfma_f32_16x16x32_bf16 v[20:23], v[68:71], v[112:115], v[20:23]
	v_mfma_f32_16x16x32_bf16 v[0:3], v[68:71], v[116:119], v[0:3]
	s_waitcnt lgkmcnt(9)
	v_mfma_f32_16x16x32_bf16 v[48:51], v[72:75], v[104:107], v[48:51]
	v_mfma_f32_16x16x32_bf16 v[32:35], v[72:75], v[108:111], v[32:35]
	v_mfma_f32_16x16x32_bf16 v[16:19], v[72:75], v[112:115], v[16:19]
	v_mfma_f32_16x16x32_bf16 v[4:7], v[72:75], v[116:119], v[4:7]
	s_waitcnt lgkmcnt(8)
	v_mfma_f32_16x16x32_bf16 v[52:55], v[76:79], v[104:107], v[52:55]
	v_mfma_f32_16x16x32_bf16 v[44:47], v[76:79], v[108:111], v[44:47]
	v_mfma_f32_16x16x32_bf16 v[28:31], v[76:79], v[112:115], v[28:31]
	v_mfma_f32_16x16x32_bf16 v[12:15], v[76:79], v[116:119], v[12:15]
	s_waitcnt lgkmcnt(0)
	s_barrier
	v_mfma_f32_16x16x32_bf16 v[60:63], v[80:83], v[120:123], v[60:63]
	v_mfma_f32_16x16x32_bf16 v[40:43], v[80:83], v[124:127], v[40:43]
	v_mfma_f32_16x16x32_bf16 v[24:27], v[80:83], v[132:135], v[24:27]
	v_mfma_f32_16x16x32_bf16 v[8:11], v[80:83], v[136:139], v[8:11]
	v_mfma_f32_16x16x32_bf16 v[56:59], v[84:87], v[120:123], v[56:59]
	v_mfma_f32_16x16x32_bf16 v[36:39], v[84:87], v[124:127], v[36:39]
	v_mfma_f32_16x16x32_bf16 v[20:23], v[84:87], v[132:135], v[20:23]
	v_mfma_f32_16x16x32_bf16 v[0:3], v[84:87], v[136:139], v[0:3]
	v_mfma_f32_16x16x32_bf16 v[48:51], v[88:91], v[120:123], v[48:51]
	v_mfma_f32_16x16x32_bf16 v[32:35], v[88:91], v[124:127], v[32:35]
	v_mfma_f32_16x16x32_bf16 v[16:19], v[88:91], v[132:135], v[16:19]
	v_mfma_f32_16x16x32_bf16 v[4:7], v[88:91], v[136:139], v[4:7]
	v_mfma_f32_16x16x32_bf16 v[52:55], v[92:95], v[120:123], v[52:55]
	v_mfma_f32_16x16x32_bf16 v[44:47], v[92:95], v[124:127], v[44:47]
	v_mfma_f32_16x16x32_bf16 v[28:31], v[92:95], v[132:135], v[28:31]
	v_mfma_f32_16x16x32_bf16 v[12:15], v[92:95], v[136:139], v[12:15]
	s_waitcnt vmcnt(0)
	s_barrier
	ds_read_b128 v[64:67], v252 offset:16384
	ds_read_b128 v[104:107], v254 offset:49152
	ds_read_b128 v[108:111], v254 offset:51200
	ds_read_b128 v[112:115], v254 offset:53248
	ds_read_b128 v[116:119], v254 offset:55296
	ds_read_b128 v[68:71], v252 offset:18432
	ds_read_b128 v[72:75], v252 offset:20480
	ds_read_b128 v[76:79], v252 offset:22528
	ds_read_b128 v[80:83], v253 offset:16384
	ds_read_b128 v[120:123], v255 offset:49152
	ds_read_b128 v[124:127], v255 offset:51200
	ds_read_b128 v[132:135], v255 offset:53248
	ds_read_b128 v[136:139], v255 offset:55296
	s_waitcnt lgkmcnt(11)
	v_mfma_f32_16x16x32_bf16 v[60:63], v[64:67], v[104:107], v[60:63]
	s_waitcnt lgkmcnt(10)
	v_mfma_f32_16x16x32_bf16 v[40:43], v[64:67], v[108:111], v[40:43]
	s_waitcnt lgkmcnt(9)
	v_mfma_f32_16x16x32_bf16 v[24:27], v[64:67], v[112:115], v[24:27]
	s_waitcnt lgkmcnt(8)
	v_mfma_f32_16x16x32_bf16 v[8:11], v[64:67], v[116:119], v[8:11]
	ds_read_b128 v[84:87], v253 offset:18432
	ds_read_b128 v[88:91], v253 offset:20480
	ds_read_b128 v[92:95], v253 offset:22528
	s_waitcnt lgkmcnt(10)
	v_mfma_f32_16x16x32_bf16 v[56:59], v[68:71], v[104:107], v[56:59]
	v_mfma_f32_16x16x32_bf16 v[36:39], v[68:71], v[108:111], v[36:39]
	v_mfma_f32_16x16x32_bf16 v[20:23], v[68:71], v[112:115], v[20:23]
	v_mfma_f32_16x16x32_bf16 v[0:3], v[68:71], v[116:119], v[0:3]
	s_waitcnt lgkmcnt(9)
	v_mfma_f32_16x16x32_bf16 v[48:51], v[72:75], v[104:107], v[48:51]
	v_mfma_f32_16x16x32_bf16 v[32:35], v[72:75], v[108:111], v[32:35]
	v_mfma_f32_16x16x32_bf16 v[16:19], v[72:75], v[112:115], v[16:19]
	v_mfma_f32_16x16x32_bf16 v[4:7], v[72:75], v[116:119], v[4:7]
	s_waitcnt lgkmcnt(8)
	v_mfma_f32_16x16x32_bf16 v[52:55], v[76:79], v[104:107], v[52:55]
	v_mfma_f32_16x16x32_bf16 v[44:47], v[76:79], v[108:111], v[44:47]
	v_mfma_f32_16x16x32_bf16 v[28:31], v[76:79], v[112:115], v[28:31]
	v_mfma_f32_16x16x32_bf16 v[12:15], v[76:79], v[116:119], v[12:15]
	s_waitcnt lgkmcnt(0)
	s_barrier
	v_mfma_f32_16x16x32_bf16 v[60:63], v[80:83], v[120:123], v[60:63]
	v_mfma_f32_16x16x32_bf16 v[40:43], v[80:83], v[124:127], v[40:43]
	v_mfma_f32_16x16x32_bf16 v[24:27], v[80:83], v[132:135], v[24:27]
	v_mfma_f32_16x16x32_bf16 v[8:11], v[80:83], v[136:139], v[8:11]
	v_mfma_f32_16x16x32_bf16 v[56:59], v[84:87], v[120:123], v[56:59]
	v_mfma_f32_16x16x32_bf16 v[36:39], v[84:87], v[124:127], v[36:39]
	v_mfma_f32_16x16x32_bf16 v[20:23], v[84:87], v[132:135], v[20:23]
	v_mfma_f32_16x16x32_bf16 v[0:3], v[84:87], v[136:139], v[0:3]
	v_mfma_f32_16x16x32_bf16 v[48:51], v[88:91], v[120:123], v[48:51]
	v_mfma_f32_16x16x32_bf16 v[32:35], v[88:91], v[124:127], v[32:35]
	v_mfma_f32_16x16x32_bf16 v[16:19], v[88:91], v[132:135], v[16:19]
	v_mfma_f32_16x16x32_bf16 v[4:7], v[88:91], v[136:139], v[4:7]
	v_mfma_f32_16x16x32_bf16 v[52:55], v[92:95], v[120:123], v[52:55]
	v_mfma_f32_16x16x32_bf16 v[44:47], v[92:95], v[124:127], v[44:47]
	v_mfma_f32_16x16x32_bf16 v[28:31], v[92:95], v[132:135], v[28:31]
	v_mfma_f32_16x16x32_bf16 v[12:15], v[92:95], v[136:139], v[12:15]
	s_nop 7
	s_nop 1
	s_waitcnt vmcnt(7)
	v_sub_co_u32_e32 v64, vcc, s43, v142
	s_nop 0
	v_readfirstlane_b32 s5, v64
	s_lshr_b32 s5, s5, 10
	s_add_i32 s5, s5, 1
	s_and_b64 s[44:45], vcc, exec
	s_cselect_b32 s5, 0, s5
	s_mul_hi_u32 s12, s5, 0x6000
	s_mulk_i32 s5, 0x6000
	s_add_u32 s44, s2, s5
	v_or_b32_e32 v64, s4, v140
	s_addc_u32 s45, s3, s12
	v_ashrrev_i32_e32 v65, 31, v64
	v_lshl_add_u64 v[66:67], v[64:65], 2, s[44:45]
	global_load_dword v107, v[66:67], off
	s_waitcnt vmcnt(7)
	v_cndmask_b32_e64 v68, 0, 1, s[10:11]
	v_mov_b32_e32 v106, 0
	v_cmp_ne_u32_e64 s[4:5], 1, v68
	s_andn2_b64 vcc, exec, s[10:11]
	v_lshl_add_u64 v[68:69], v[64:65], 2, s[6:7]
	v_mov_b32_e32 v108, 0
	s_cbranch_vccnz .LBB0_1268
	global_load_dword v108, v[68:69], off

.LBB0_1450:
	s_cmp_gt_i32 s60, 16
	s_cselect_b64 s[2:3], -1, 0
	s_cmp_lt_i32 s61, 16
	s_cselect_b64 s[4:5], -1, 0
	s_or_b64 s[2:3], s[2:3], s[4:5]
	s_and_b64 vcc, exec, s[2:3]
	s_cbranch_vccnz .LBB0_1510
	s_mov_b64 s[4:5], s[0:1]
	s_cmpk_gt_i32 s58, 0x1ff
	s_cbranch_scc1 .LBB0_1456
	s_load_dwordx2 s[6:7], s[4:5], 0xe0
	v_lshrrev_b32_e32 v8, 3, v162
	v_mul_u32_u24_e32 v0, 0xb00, v8
	v_lshlrev_b32_e32 v96, 1, v0
	v_mov_b32_e32 v97, 0
	s_waitcnt lgkmcnt(0)
	s_add_u32 s2, s6, 0x6b25000
	s_addc_u32 s3, s7, 0
	v_lshlrev_b32_e32 v0, 4, v162
	s_add_u32 s4, s6, 0x6b7a100
	v_and_b32_e32 v0, 0x70, v0
	v_mov_b32_e32 v1, v97
	v_lshl_add_u64 v[2:3], s[6:7], 0, v[96:97]
	s_addc_u32 s5, s7, 0
	v_lshl_add_u64 v[0:1], v[2:3], 0, v[0:1]
	s_mov_b64 s[6:7], 0x9b7a100
	v_xor_b32_e32 v9, v163, v162
	v_lshl_add_u64 v[98:99], v[0:1], 0, s[6:7]
	s_mov_b64 s[6:7], 0x5600000
	v_lshl_add_u64 v[100:101], v[0:1], 0, s[6:7]
	v_lshlrev_b32_e32 v1, 4, v9
	v_and_b32_e32 v6, 15, v162
	v_bfe_u32 v0, v162, 1, 3
	v_and_b32_e32 v1, 0x70, v1
	v_bfe_u32 v4, v162, 6, 1
	v_lshrrev_b32_e32 v5, 7, v162
	v_bitop3_b32 v0, v163, v0, 3 bitop3:0x6c
	v_lshl_or_b32 v129, v8, 7, v1
	v_lshlrev_b32_e32 v1, 7, v6
	s_load_dword s30, s[0:1], 0xf0
	v_lshl_or_b32 v2, v5, 13, v1
	v_lshl_or_b32 v1, v4, 13, v1
	v_lshlrev_b32_e32 v0, 4, v0
	v_or_b32_e32 v144, v2, v0
	v_or_b32_e32 v145, v1, v0
	v_xor_b32_e32 v0, 64, v0
	v_bfe_u32 v7, v162, 4, 2
	v_or_b32_e32 v146, v2, v0
	v_or_b32_e32 v147, v1, v0
	v_lshlrev_b32_e32 v0, 6, v5
	v_lshl_or_b32 v148, v4, 6, v6
	v_lshl_or_b32 v149, v7, 2, v0
	s_mov_b32 s7, 0
	v_mov_b32_e32 v150, 0x1600
	s_mov_b64 s[8:9], 0x2c000
	s_mov_b32 s31, 0x2c000
	s_mov_b64 s[10:11], 0x58000
	s_mov_b32 s34, 0x58000
	s_mov_b64 s[12:13], 0x84000
	s_mov_b32 s35, 0x84000
	s_mov_b64 s[14:15], 0x84100
	s_mov_b64 s[16:17], 0x58100
	s_mov_b64 s[18:19], 0x2c100
	s_mov_b64 s[20:21], 0x100
	s_mov_b64 s[22:23], 0x200
	s_mov_b64 s[24:25], 0x2c200
	s_mov_b64 s[26:27], 0x58200
	s_mov_b64 s[28:29], 0x84200
	v_mov_b32_e32 v151, 0x1000
	s_mov_b32 s36, s58
	v_and_b32_e32 v240, 63, v162
	v_lshrrev_b32_e32 v247, 6, v162
	v_lshrrev_b32_e32 v242, 3, v240
	v_lshl_add_u32 v242, v247, 5, v242
	v_and_b32_e32 v243, 7, v240
	v_lshrrev_b32_e32 v244, 4, v240
	v_xor_b32_e32 v243, v243, v244
	v_lshlrev_b32_e32 v243, 4, v243
	v_mov_b32_e32 v241, 0x1600
	v_mad_u32_u24 v248, v242, v241, v243
	v_xor_b32_e32 v249, 64, v248
	v_add_u32_e32 v249, 0xb000, v249
	v_add_u32_e32 v250, 0x16000, v248
	v_xor_b32_e32 v251, 64, v248
	v_add_u32_e32 v251, 0x21000, v251
	v_and_b32_e32 v241, 15, v240
	v_lshrrev_b32_e32 v242, 1, v241
	v_xor_b32_e32 v242, v242, v244
	v_lshlrev_b32_e32 v242, 4, v242
	v_lshl_or_b32 v242, v241, 7, v242
	v_lshrrev_b32_e32 v243, 1, v247
	v_lshl_or_b32 v252, v243, 13, v242
	v_xor_b32_e32 v253, 64, v252
	v_and_b32_e32 v243, 1, v247
	v_lshl_or_b32 v254, v243, 13, v242
	v_xor_b32_e32 v255, 64, v254

.LBB0_1573:
	s_cmp_gt_i32 s60, 18
	s_waitcnt lgkmcnt(0)
	s_cselect_b64 s[2:3], -1, 0
	s_cmp_lt_i32 s61, 18
	s_cselect_b64 s[4:5], -1, 0
	s_or_b64 s[2:3], s[2:3], s[4:5]
	s_and_b64 vcc, exec, s[2:3]
	s_cbranch_vccnz .LBB0_1845
	s_mov_b64 s[76:77], s[84:85]
	s_mov_b64 s[14:15], s[0:1]
	s_cmpk_gt_i32 s58, 0xc3f
	s_cbranch_scc1 .LBB0_1791
	s_load_dwordx2 s[16:17], s[14:15], 0xe0
	s_load_dword s3, s[0:1], 0xf0
	v_lshrrev_b32_e32 v9, 3, v162
	v_lshlrev_b32_e32 v0, 3, v162
	v_and_b32_e32 v0, 56, v0
	s_waitcnt lgkmcnt(0)
	s_add_u32 s18, s16, 0x8b7a100
	s_addc_u32 s19, s17, 0
	s_add_u32 s20, s16, 0xc40000
	v_mov_b32_e32 v99, 0
	v_lshlrev_b32_e32 v98, 11, v9
	s_addc_u32 s21, s17, 0
	v_lshl_add_u64 v[4:5], s[18:19], 0, v[98:99]
	v_lshlrev_b32_e32 v6, 1, v0
	v_mov_b32_e32 v7, v99
	v_xor_b32_e32 v10, v163, v162
	v_lshl_add_u64 v[100:101], v[4:5], 0, v[6:7]
	v_lshl_add_u64 v[4:5], s[20:21], 0, v[98:99]
	v_lshl_add_u64 v[102:103], v[4:5], 0, v[6:7]
	v_lshlrev_b32_e32 v5, 4, v10
	v_and_b32_e32 v96, 15, v162
	v_bfe_u32 v4, v162, 1, 3
	v_and_b32_e32 v5, 0x70, v5
	v_bfe_u32 v1, v162, 6, 1
	v_lshrrev_b32_e32 v3, 7, v162
	v_bitop3_b32 v4, v163, v4, 3 bitop3:0x6c
	v_lshl_or_b32 v145, v9, 7, v5
	v_lshlrev_b32_e32 v5, 7, v96
	v_lshl_or_b32 v6, v3, 13, v5
	v_lshl_or_b32 v5, v1, 13, v5
	v_lshlrev_b32_e32 v4, 4, v4
	v_or_b32_e32 v170, v6, v4
	v_or_b32_e32 v171, v5, v4
	v_xor_b32_e32 v4, 64, v4
	v_or_b32_e32 v172, v6, v4
	v_or_b32_e32 v173, v5, v4
	v_lshlrev_b32_e32 v4, 2, v96
	v_mov_b32_e32 v5, v99
	v_lshl_add_u64 v[4:5], s[16:17], 0, v[4:5]
	s_mov_b64 s[6:7], 0x1237a100
	v_lshl_add_u64 v[104:105], v[4:5], 0, s[6:7]
	s_mov_b64 s[6:7], 0x1237a140
	v_lshl_add_u64 v[106:107], v[4:5], 0, s[6:7]
	v_lshlrev_b32_e32 v4, 7, v1
	v_mov_b32_e32 v5, v99
	v_lshl_add_u64 v[4:5], s[16:17], 0, v[4:5]
	s_mov_b64 s[6:7], 0xdb7a100
	s_add_u32 s24, s16, 0xef7a100
	v_lshl_add_u64 v[108:109], v[4:5], 0, s[6:7]
	s_mov_b64 s[6:7], 0xe37a100
	v_lshlrev_b32_e32 v175, 6, v1
	v_cmp_eq_u32_e64 s[4:5], 0, v1
	s_addc_u32 s25, s17, 0
	v_lshl_add_u64 v[110:111], v[4:5], 0, s[6:7]
	v_lshlrev_b32_e32 v4, 1, v96
	v_mov_b32_e32 v5, v99
	v_and_b32_e32 v1, 7, v162
	s_add_u32 s26, s16, 0x6b00000
	v_lshl_add_u64 v[4:5], s[16:17], 0, v[4:5]
	s_mov_b64 s[6:7], 0x9b7a100
	v_lshl_or_b32 v98, v1, 4, v98
	s_addc_u32 s27, s17, 0
	v_lshl_add_u64 v[112:113], v[4:5], 0, s[6:7]
	v_lshl_add_u64 v[4:5], s[16:17], 0, v[98:99]
	s_mov_b64 s[6:7], 0xc40200
	v_bfe_u32 v8, v162, 4, 2
	v_lshlrev_b32_e32 v2, 10, v9
	v_lshlrev_b32_e32 v3, 6, v3
	s_add_u32 s28, s16, 0xcb7a100
	v_lshl_add_u64 v[114:115], v[4:5], 0, s[6:7]
	s_mov_b64 s[6:7], 0x8b7a300
	v_lshl_or_b32 v174, v8, 2, v3
	s_mov_b32 s23, 0
	v_or_b32_e32 v176, v175, v96
	s_addc_u32 s29, s17, 0
	s_lshl_b32 s68, s58, 1
	s_lshl_b32 s69, s3, 1
	v_lshl_add_u64 v[116:117], v[4:5], 0, s[6:7]
	s_lshl_b32 s70, s58, 7
	s_lshl_b32 s71, s3, 7
	s_mov_b64 s[8:9], 0
	s_mov_b32 s73, 0x10000
	s_mov_b64 s[30:31], 0x100
	s_mov_b64 s[34:35], 0x10000
	s_mov_b64 s[36:37], 0x10100
	s_mov_b64 s[38:39], 0x20000
	s_mov_b64 s[40:41], 0x20100
	s_mov_b64 s[42:43], 0x30000
	s_mov_b64 s[44:45], 0x30100
	v_lshlrev_b32_e32 v118, 1, v2
	v_mov_b32_e32 v119, v99
	v_lshlrev_b32_e32 v120, 1, v0
	v_mov_b32_e32 v121, v99
	s_mov_b64 s[46:47], 0x780
	s_brev_b32 s75, 32
	s_mov_b32 s59, 0x3fff80
	s_mov_b32 s78, 0xf786000
	s_mov_b64 s[48:49], 0xf79e500
	s_movk_i32 s79, 0xf400
	s_movk_i32 s80, 0x7e00
	s_mov_b64 s[50:51], 0x2000000
	s_movk_i32 s81, 0xf0
	s_movk_i32 s83, 0x600
	s_movk_i32 s84, 0x200
	s_movk_i32 s85, 0x3d0
	s_movk_i32 s86, 0x3e0
	s_movk_i32 s87, 0x3f0
	s_movk_i32 s88, 0x3c0
	s_mov_b32 s90, 0xab89000
	s_mov_b32 s91, 0xab8a000
	s_mov_b32 s92, 0xab8b000
	s_mov_b32 s93, 0xab8c000
	s_mov_b32 s94, 0xab99000
	s_mov_b32 s95, 0xab9a000
	s_mov_b32 s96, 0xab9b000
	s_mov_b32 s97, 0xab9c000
	s_mov_b32 s89, 0xaba9000
	s_mov_b32 s72, 0xabaa000
	s_mov_b32 s74, 0xabab000
	s_mov_b32 s82, 0xabac000
	s_mov_b64 s[54:55], 0x60
	v_mov_b32_e32 v177, 0x100000
	s_mov_b32 s2, s58
	v_and_b32_e32 v240, 63, v162
	v_lshrrev_b32_e32 v247, 6, v162
	v_lshrrev_b32_e32 v242, 3, v240
	v_lshl_add_u32 v242, v247, 5, v242
	v_and_b32_e32 v243, 7, v240
	v_lshrrev_b32_e32 v244, 4, v240
	v_xor_b32_e32 v243, v243, v244
	v_lshlrev_b32_e32 v243, 4, v243
	v_mov_b32_e32 v241, 0x800
	v_mad_u32_u24 v248, v242, v241, v243
	v_xor_b32_e32 v249, 64, v248
	v_add_u32_e32 v249, 0x4000, v249
	v_add_u32_e32 v250, 0x8000, v248
	v_xor_b32_e32 v251, 64, v248
	v_add_u32_e32 v251, 0xc000, v251
	v_and_b32_e32 v241, 15, v240
	v_lshrrev_b32_e32 v242, 1, v241
	v_xor_b32_e32 v242, v242, v244
	v_lshlrev_b32_e32 v242, 4, v242
	v_lshl_or_b32 v242, v241, 7, v242
	v_lshrrev_b32_e32 v243, 1, v247
	v_lshl_or_b32 v252, v243, 13, v242
	v_xor_b32_e32 v253, 64, v252
	v_and_b32_e32 v243, 1, v247
	v_lshl_or_b32 v254, v243, 13, v242
	v_xor_b32_e32 v255, 64, v254
	s_branch .LBB0_1577

.LBB0_1577:
	s_lshl_b32 s6, s2, 7
	s_lshl_b32 s13, s2, 1
	s_and_b32 s12, s6, 0x1f80
	s_and_b32 s6, s13, 0xffffff80
	s_ashr_i32 s7, s6, 31
	s_lshl_b64 s[10:11], s[6:7], 11
	s_lshl_b32 s22, s12, 11
	v_lshl_add_u64 v[122:123], v[100:101], 0, s[22:23]
	v_lshl_add_u64 v[124:125], v[102:103], 0, s[10:11]
	s_and_b64 vcc, exec, s[8:9]
	s_mov_b64 s[8:9], -1
	s_cbranch_vccnz .LBB0_1579
	v_add_co_u32_e32 v32, vcc, 0x10000, v122
	s_nop 0
	v_addc_co_u32_e32 v33, vcc, 0, v123, vcc
	v_add_co_u32_e32 v34, vcc, 0x20000, v122
	s_nop 0
	v_addc_co_u32_e32 v35, vcc, 0, v123, vcc
	v_add_co_u32_e32 v36, vcc, 0x30000, v122
	s_nop 0
	v_addc_co_u32_e32 v37, vcc, 0, v123, vcc
	v_add_co_u32_e32 v38, vcc, s73, v124
	s_mov_b64 s[8:9], 0
	s_nop 0
	v_addc_co_u32_e32 v39, vcc, 0, v125, vcc
	v_add_co_u32_e32 v40, vcc, 0x20000, v124
	s_nop 0
	v_addc_co_u32_e32 v41, vcc, 0, v125, vcc
	v_add_co_u32_e32 v42, vcc, 0x30000, v124
	s_nop 1
	v_addc_co_u32_e32 v43, vcc, 0, v125, vcc

.LBB0_1581:
	s_and_b32 s8, s68, 0xffffff80
	s_ashr_i32 s9, s8, 31
	s_lshl_b32 s7, s70, 11
	s_lshl_b64 s[8:9], s[8:9], 11
	s_and_b32 s22, s7, 0xfc0000
	s_add_i32 s2, s2, s3
	s_cmpk_gt_i32 s2, 0xc3f
	s_cselect_b64 s[62:63], -1, 0
	s_lshl_b32 s7, s2, 18
	s_and_b32 s7, s7, 0xfc0000
	s_add_u32 s7, s18, s7
	v_lshl_add_u64 v[126:127], v[114:115], 0, s[8:9]
	s_addc_u32 s10, s19, 0
	s_ashr_i32 s8, s2, 6
	s_ashr_i32 s9, s8, 31
	s_lshl_b64 s[8:9], s[8:9], 18
	v_lshl_add_u64 v[130:131], v[116:117], 0, s[22:23]
	s_add_u32 s22, s20, s8
	s_addc_u32 s11, s21, s9
	s_cmpk_lt_i32 s2, 0xc40
	s_cselect_b64 vcc, -1, 0
	s_and_b64 s[8:9], vcc, exec
	s_cselect_b32 s9, s10, 0
	s_cselect_b32 s8, s7, 0
	v_lshl_add_u64 v[2:3], s[8:9], 0, v[118:119]
	v_lshl_add_u64 v[0:1], v[122:123], 0, s[46:47]
	s_cselect_b32 s11, s11, 0
	s_cselect_b32 s10, s22, 0
	v_lshl_add_u64 v[2:3], v[2:3], 0, v[120:121]
	v_cndmask_b32_e32 v97, v1, v3, vcc
	v_cndmask_b32_e32 v98, v0, v2, vcc
	v_lshl_add_u64 v[0:1], s[10:11], 0, v[118:119]
	v_lshl_add_u64 v[0:1], v[0:1], 0, v[120:121]
	v_lshl_add_u64 v[2:3], v[124:125], 0, s[46:47]
	v_cndmask_b32_e32 v144, v2, v0, vcc
	v_mov_b32_e32 v0, 0
	v_lshl_add_u64 v[146:147], v[122:123], 0, s[30:31]
	v_lshl_add_u64 v[132:133], v[122:123], 0, s[34:35]
	v_lshl_add_u64 v[150:151], v[122:123], 0, s[36:37]
	v_lshl_add_u64 v[134:135], v[122:123], 0, s[38:39]
	v_lshl_add_u64 v[152:153], v[122:123], 0, s[40:41]
	v_lshl_add_u64 v[136:137], v[122:123], 0, s[42:43]
	v_lshl_add_u64 v[154:155], v[122:123], 0, s[44:45]
	v_lshl_add_u64 v[148:149], v[124:125], 0, s[30:31]
	v_lshl_add_u64 v[138:139], v[124:125], 0, s[34:35]
	v_lshl_add_u64 v[156:157], v[124:125], 0, s[36:37]
	v_lshl_add_u64 v[140:141], v[124:125], 0, s[38:39]
	v_lshl_add_u64 v[158:159], v[124:125], 0, s[40:41]
	v_lshl_add_u64 v[142:143], v[124:125], 0, s[42:43]
	v_lshl_add_u64 v[160:161], v[124:125], 0, s[44:45]
	v_cndmask_b32_e32 v129, v3, v1, vcc
	s_mov_b32 s7, -2
	v_mov_b32_e32 v1, v0
	v_mov_b32_e32 v2, v0
	v_mov_b32_e32 v3, v0
	v_mov_b32_e32 v20, v0
	v_mov_b32_e32 v21, v0
	v_mov_b32_e32 v22, v0
	v_mov_b32_e32 v23, v0
	v_mov_b32_e32 v24, v0
	v_mov_b32_e32 v25, v0
	v_mov_b32_e32 v26, v0
	v_mov_b32_e32 v27, v0
	v_mov_b32_e32 v32, v0
	v_mov_b32_e32 v33, v0
	v_mov_b32_e32 v34, v0
	v_mov_b32_e32 v35, v0
	v_mov_b32_e32 v8, v0
	v_mov_b32_e32 v9, v0
	v_mov_b32_e32 v10, v0
	v_mov_b32_e32 v11, v0
	v_mov_b32_e32 v4, v0
	v_mov_b32_e32 v5, v0
	v_mov_b32_e32 v6, v0
	v_mov_b32_e32 v7, v0
	v_mov_b32_e32 v12, v0
	v_mov_b32_e32 v13, v0
	v_mov_b32_e32 v14, v0
	v_mov_b32_e32 v15, v0
	v_mov_b32_e32 v16, v0
	v_mov_b32_e32 v17, v0
	v_mov_b32_e32 v18, v0
	v_mov_b32_e32 v19, v0
	v_mov_b32_e32 v28, v0
	v_mov_b32_e32 v29, v0
	v_mov_b32_e32 v30, v0
	v_mov_b32_e32 v31, v0
	v_mov_b32_e32 v36, v0
	v_mov_b32_e32 v37, v0
	v_mov_b32_e32 v38, v0
	v_mov_b32_e32 v39, v0
	v_mov_b32_e32 v40, v0
	v_mov_b32_e32 v41, v0
	v_mov_b32_e32 v42, v0
	v_mov_b32_e32 v43, v0
	v_mov_b32_e32 v44, v0
	v_mov_b32_e32 v45, v0
	v_mov_b32_e32 v46, v0
	v_mov_b32_e32 v47, v0
	v_mov_b32_e32 v48, v0
	v_mov_b32_e32 v49, v0
	v_mov_b32_e32 v50, v0
	v_mov_b32_e32 v51, v0
	v_mov_b32_e32 v52, v0
	v_mov_b32_e32 v53, v0
	v_mov_b32_e32 v54, v0
	v_mov_b32_e32 v55, v0
	v_mov_b32_e32 v56, v0
	v_mov_b32_e32 v57, v0
	v_mov_b32_e32 v58, v0
	v_mov_b32_e32 v59, v0
	v_mov_b32_e32 v60, v0
	v_mov_b32_e32 v61, v0
	v_mov_b32_e32 v62, v0
	v_mov_b32_e32 v63, v0
	v_readfirstlane_b32 s8, v122
	v_readfirstlane_b32 s9, v123
	v_readfirstlane_b32 s64, v124
	v_readfirstlane_b32 s65, v125
	v_readfirstlane_b32 s7, v247
	s_nop 3
	s_mul_i32 s66, s7, 0x4000
	s_sub_u32 s8, s8, s66
	s_subb_u32 s9, s9, 0
	s_sub_u32 s64, s64, s66
	s_subb_u32 s65, s65, 0
	s_lshl_b32 s7, s7, 12
	s_add_u32 m0, s7, 0x0
	v_mov_b32_e32 v60, 0
	global_load_lds_dwordx4 v248, s[8:9]
	v_mov_b32_e32 v61, 0
	s_add_u32 m0, s7, 0x400
	v_mov_b32_e32 v62, 0
	global_load_lds_dwordx4 v249, s[8:9]
	v_mov_b32_e32 v63, 0
	s_add_u32 m0, s7, 0x800
	v_mov_b32_e32 v56, 0
	global_load_lds_dwordx4 v250, s[8:9]
	v_mov_b32_e32 v57, 0
	s_add_u32 m0, s7, 0xc00
	v_mov_b32_e32 v58, 0
	global_load_lds_dwordx4 v251, s[8:9]
	v_mov_b32_e32 v59, 0
	s_add_u32 m0, s7, 0x8000
	v_mov_b32_e32 v52, 0
	global_load_lds_dwordx4 v248, s[64:65]
	v_mov_b32_e32 v53, 0
	s_add_u32 m0, s7, 0x8400
	v_mov_b32_e32 v54, 0
	global_load_lds_dwordx4 v249, s[64:65]
	v_mov_b32_e32 v55, 0
	s_add_u32 m0, s7, 0x8800
	v_mov_b32_e32 v48, 0
	global_load_lds_dwordx4 v250, s[64:65]
	v_mov_b32_e32 v49, 0
	s_add_u32 m0, s7, 0x8c00
	v_mov_b32_e32 v50, 0
	global_load_lds_dwordx4 v251, s[64:65]
	v_mov_b32_e32 v51, 0
	s_add_u32 s8, s8, 0x80
	s_addc_u32 s9, s9, 0
	s_add_u32 s64, s64, 0x80
	s_addc_u32 s65, s65, 0
	s_add_u32 m0, s7, 0x4000
	v_mov_b32_e32 v44, 0
	global_load_lds_dwordx4 v248, s[8:9]
	v_mov_b32_e32 v45, 0
	s_add_u32 m0, s7, 0x4400
	v_mov_b32_e32 v46, 0
	global_load_lds_dwordx4 v249, s[8:9]
	v_mov_b32_e32 v47, 0
	s_add_u32 m0, s7, 0x4800
	v_mov_b32_e32 v40, 0
	global_load_lds_dwordx4 v250, s[8:9]
	v_mov_b32_e32 v41, 0
	s_add_u32 m0, s7, 0x4c00
	v_mov_b32_e32 v42, 0
	global_load_lds_dwordx4 v251, s[8:9]
	v_mov_b32_e32 v43, 0
	s_add_u32 m0, s7, 0xc000
	v_mov_b32_e32 v36, 0
	global_load_lds_dwordx4 v248, s[64:65]
	v_mov_b32_e32 v37, 0
	s_add_u32 m0, s7, 0xc400
	v_mov_b32_e32 v38, 0
	global_load_lds_dwordx4 v249, s[64:65]
	v_mov_b32_e32 v39, 0
	s_add_u32 m0, s7, 0xc800
	v_mov_b32_e32 v28, 0
	global_load_lds_dwordx4 v250, s[64:65]
	v_mov_b32_e32 v29, 0
	s_add_u32 m0, s7, 0xcc00
	v_mov_b32_e32 v30, 0
	global_load_lds_dwordx4 v251, s[64:65]
	v_mov_b32_e32 v31, 0
	s_add_u32 s8, s8, 0x80
	s_addc_u32 s9, s9, 0
	s_add_u32 s64, s64, 0x80
	s_addc_u32 s65, s65, 0
	v_mov_b32_e32 v16, 0
	v_mov_b32_e32 v17, 0
	v_mov_b32_e32 v18, 0
	v_mov_b32_e32 v19, 0
	v_mov_b32_e32 v12, 0
	v_mov_b32_e32 v13, 0
	v_mov_b32_e32 v14, 0
	v_mov_b32_e32 v15, 0
	v_mov_b32_e32 v4, 0
	v_mov_b32_e32 v5, 0
	v_mov_b32_e32 v6, 0
	v_mov_b32_e32 v7, 0
	v_mov_b32_e32 v8, 0
	v_mov_b32_e32 v9, 0
	v_mov_b32_e32 v10, 0
	v_mov_b32_e32 v11, 0
	v_mov_b32_e32 v32, 0
	v_mov_b32_e32 v33, 0
	v_mov_b32_e32 v34, 0
	v_mov_b32_e32 v35, 0
	v_mov_b32_e32 v24, 0
	v_mov_b32_e32 v25, 0
	v_mov_b32_e32 v26, 0
	v_mov_b32_e32 v27, 0
	v_mov_b32_e32 v20, 0
	v_mov_b32_e32 v21, 0
	v_mov_b32_e32 v22, 0
	v_mov_b32_e32 v23, 0
	v_mov_b32_e32 v0, 0
	v_mov_b32_e32 v1, 0
	v_mov_b32_e32 v2, 0
	v_mov_b32_e32 v3, 0
	s_mov_b32 s32, 7
.Lg18_loop:
	s_waitcnt vmcnt(8)
	s_barrier
	ds_read_b128 v[80:83], v252 offset:0
	ds_read_b128 v[144:147], v254 offset:32768
	ds_read_b128 v[148:151], v254 offset:34816
	ds_read_b128 v[152:155], v254 offset:36864
	ds_read_b128 v[156:159], v254 offset:38912
	ds_read_b128 v[84:87], v252 offset:2048
	ds_read_b128 v[88:91], v252 offset:4096
	ds_read_b128 v[92:95], v252 offset:6144
	ds_read_b128 v[124:127], v253 offset:0
	ds_read_b128 v[180:183], v255 offset:32768
	ds_read_b128 v[184:187], v255 offset:34816
	ds_read_b128 v[188:191], v255 offset:36864
	ds_read_b128 v[192:195], v255 offset:38912
	s_waitcnt lgkmcnt(11)
	v_mfma_f32_16x16x32_bf16 v[60:63], v[80:83], v[144:147], v[60:63]
	s_waitcnt lgkmcnt(10)
	v_mfma_f32_16x16x32_bf16 v[56:59], v[80:83], v[148:151], v[56:59]
	s_waitcnt lgkmcnt(9)
	v_mfma_f32_16x16x32_bf16 v[52:55], v[80:83], v[152:155], v[52:55]
	s_waitcnt lgkmcnt(8)
	v_mfma_f32_16x16x32_bf16 v[48:51], v[80:83], v[156:159], v[48:51]
	ds_read_b128 v[132:135], v253 offset:2048
	ds_read_b128 v[136:139], v253 offset:4096
	ds_read_b128 v[140:143], v253 offset:6144
	s_waitcnt lgkmcnt(10)
	v_mfma_f32_16x16x32_bf16 v[44:47], v[84:87], v[144:147], v[44:47]
	v_mfma_f32_16x16x32_bf16 v[40:43], v[84:87], v[148:151], v[40:43]
	v_mfma_f32_16x16x32_bf16 v[36:39], v[84:87], v[152:155], v[36:39]
	v_mfma_f32_16x16x32_bf16 v[28:31], v[84:87], v[156:159], v[28:31]
	s_waitcnt lgkmcnt(9)
	v_mfma_f32_16x16x32_bf16 v[16:19], v[88:91], v[144:147], v[16:19]
	v_mfma_f32_16x16x32_bf16 v[12:15], v[88:91], v[148:151], v[12:15]
	v_mfma_f32_16x16x32_bf16 v[4:7], v[88:91], v[152:155], v[4:7]
	v_mfma_f32_16x16x32_bf16 v[8:11], v[88:91], v[156:159], v[8:11]
	s_waitcnt lgkmcnt(8)
	v_mfma_f32_16x16x32_bf16 v[32:35], v[92:95], v[144:147], v[32:35]
	v_mfma_f32_16x16x32_bf16 v[24:27], v[92:95], v[148:151], v[24:27]
	v_mfma_f32_16x16x32_bf16 v[20:23], v[92:95], v[152:155], v[20:23]
	v_mfma_f32_16x16x32_bf16 v[0:3], v[92:95], v[156:159], v[0:3]
	s_waitcnt lgkmcnt(0)
	s_barrier
	s_add_u32 m0, s7, 0x0
	v_mfma_f32_16x16x32_bf16 v[60:63], v[124:127], v[180:183], v[60:63]
	global_load_lds_dwordx4 v248, s[8:9]
	v_mfma_f32_16x16x32_bf16 v[56:59], v[124:127], v[184:187], v[56:59]
	s_add_u32 m0, s7, 0x400
	v_mfma_f32_16x16x32_bf16 v[52:55], v[124:127], v[188:191], v[52:55]
	global_load_lds_dwordx4 v249, s[8:9]
	v_mfma_f32_16x16x32_bf16 v[48:51], v[124:127], v[192:195], v[48:51]
	s_add_u32 m0, s7, 0x800
	v_mfma_f32_16x16x32_bf16 v[44:47], v[132:135], v[180:183], v[44:47]
	global_load_lds_dwordx4 v250, s[8:9]
	v_mfma_f32_16x16x32_bf16 v[40:43], v[132:135], v[184:187], v[40:43]
	s_add_u32 m0, s7, 0xc00
	v_mfma_f32_16x16x32_bf16 v[36:39], v[132:135], v[188:191], v[36:39]
	global_load_lds_dwordx4 v251, s[8:9]
	v_mfma_f32_16x16x32_bf16 v[28:31], v[132:135], v[192:195], v[28:31]
	s_add_u32 m0, s7, 0x8000
	v_mfma_f32_16x16x32_bf16 v[16:19], v[136:139], v[180:183], v[16:19]
	global_load_lds_dwordx4 v248, s[64:65]
	v_mfma_f32_16x16x32_bf16 v[12:15], v[136:139], v[184:187], v[12:15]
	s_add_u32 m0, s7, 0x8400
	v_mfma_f32_16x16x32_bf16 v[4:7], v[136:139], v[188:191], v[4:7]
	global_load_lds_dwordx4 v249, s[64:65]
	v_mfma_f32_16x16x32_bf16 v[8:11], v[136:139], v[192:195], v[8:11]
	s_add_u32 m0, s7, 0x8800
	v_mfma_f32_16x16x32_bf16 v[32:35], v[140:143], v[180:183], v[32:35]
	global_load_lds_dwordx4 v250, s[64:65]
	v_mfma_f32_16x16x32_bf16 v[24:27], v[140:143], v[184:187], v[24:27]
	s_add_u32 m0, s7, 0x8c00
	v_mfma_f32_16x16x32_bf16 v[20:23], v[140:143], v[188:191], v[20:23]
	global_load_lds_dwordx4 v251, s[64:65]
	v_mfma_f32_16x16x32_bf16 v[0:3], v[140:143], v[192:195], v[0:3]
	s_add_u32 s8, s8, 0x80
	s_addc_u32 s9, s9, 0
	s_add_u32 s64, s64, 0x80
	s_addc_u32 s65, s65, 0
	s_waitcnt vmcnt(8)
	s_barrier
	ds_read_b128 v[80:83], v252 offset:16384
	ds_read_b128 v[144:147], v254 offset:49152
	ds_read_b128 v[148:151], v254 offset:51200
	ds_read_b128 v[152:155], v254 offset:53248
	ds_read_b128 v[156:159], v254 offset:55296
	ds_read_b128 v[84:87], v252 offset:18432
	ds_read_b128 v[88:91], v252 offset:20480
	ds_read_b128 v[92:95], v252 offset:22528
	ds_read_b128 v[124:127], v253 offset:16384
	ds_read_b128 v[180:183], v255 offset:49152
	ds_read_b128 v[184:187], v255 offset:51200
	ds_read_b128 v[188:191], v255 offset:53248
	ds_read_b128 v[192:195], v255 offset:55296
	s_waitcnt lgkmcnt(11)
	v_mfma_f32_16x16x32_bf16 v[60:63], v[80:83], v[144:147], v[60:63]
	s_waitcnt lgkmcnt(10)
	v_mfma_f32_16x16x32_bf16 v[56:59], v[80:83], v[148:151], v[56:59]
	s_waitcnt lgkmcnt(9)
	v_mfma_f32_16x16x32_bf16 v[52:55], v[80:83], v[152:155], v[52:55]
	s_waitcnt lgkmcnt(8)
	v_mfma_f32_16x16x32_bf16 v[48:51], v[80:83], v[156:159], v[48:51]
	ds_read_b128 v[132:135], v253 offset:18432
	ds_read_b128 v[136:139], v253 offset:20480
	ds_read_b128 v[140:143], v253 offset:22528
	s_waitcnt lgkmcnt(10)
	v_mfma_f32_16x16x32_bf16 v[44:47], v[84:87], v[144:147], v[44:47]
	v_mfma_f32_16x16x32_bf16 v[40:43], v[84:87], v[148:151], v[40:43]
	v_mfma_f32_16x16x32_bf16 v[36:39], v[84:87], v[152:155], v[36:39]
	v_mfma_f32_16x16x32_bf16 v[28:31], v[84:87], v[156:159], v[28:31]
	s_waitcnt lgkmcnt(9)
	v_mfma_f32_16x16x32_bf16 v[16:19], v[88:91], v[144:147], v[16:19]
	v_mfma_f32_16x16x32_bf16 v[12:15], v[88:91], v[148:151], v[12:15]
	v_mfma_f32_16x16x32_bf16 v[4:7], v[88:91], v[152:155], v[4:7]
	v_mfma_f32_16x16x32_bf16 v[8:11], v[88:91], v[156:159], v[8:11]
	s_waitcnt lgkmcnt(8)
	v_mfma_f32_16x16x32_bf16 v[32:35], v[92:95], v[144:147], v[32:35]
	v_mfma_f32_16x16x32_bf16 v[24:27], v[92:95], v[148:151], v[24:27]
	v_mfma_f32_16x16x32_bf16 v[20:23], v[92:95], v[152:155], v[20:23]
	v_mfma_f32_16x16x32_bf16 v[0:3], v[92:95], v[156:159], v[0:3]
	s_waitcnt lgkmcnt(0)
	s_barrier
	s_add_u32 m0, s7, 0x4000
	v_mfma_f32_16x16x32_bf16 v[60:63], v[124:127], v[180:183], v[60:63]
	global_load_lds_dwordx4 v248, s[8:9]
	v_mfma_f32_16x16x32_bf16 v[56:59], v[124:127], v[184:187], v[56:59]
	s_add_u32 m0, s7, 0x4400
	v_mfma_f32_16x16x32_bf16 v[52:55], v[124:127], v[188:191], v[52:55]
	global_load_lds_dwordx4 v249, s[8:9]
	v_mfma_f32_16x16x32_bf16 v[48:51], v[124:127], v[192:195], v[48:51]
	s_add_u32 m0, s7, 0x4800
	v_mfma_f32_16x16x32_bf16 v[44:47], v[132:135], v[180:183], v[44:47]
	global_load_lds_dwordx4 v250, s[8:9]
	v_mfma_f32_16x16x32_bf16 v[40:43], v[132:135], v[184:187], v[40:43]
	s_add_u32 m0, s7, 0x4c00
	v_mfma_f32_16x16x32_bf16 v[36:39], v[132:135], v[188:191], v[36:39]
	global_load_lds_dwordx4 v251, s[8:9]
	v_mfma_f32_16x16x32_bf16 v[28:31], v[132:135], v[192:195], v[28:31]
	s_add_u32 m0, s7, 0xc000
	v_mfma_f32_16x16x32_bf16 v[16:19], v[136:139], v[180:183], v[16:19]
	global_load_lds_dwordx4 v248, s[64:65]
	v_mfma_f32_16x16x32_bf16 v[12:15], v[136:139], v[184:187], v[12:15]
	s_add_u32 m0, s7, 0xc400
	v_mfma_f32_16x16x32_bf16 v[4:7], v[136:139], v[188:191], v[4:7]
	global_load_lds_dwordx4 v249, s[64:65]
	v_mfma_f32_16x16x32_bf16 v[8:11], v[136:139], v[192:195], v[8:11]
	s_add_u32 m0, s7, 0xc800
	v_mfma_f32_16x16x32_bf16 v[32:35], v[140:143], v[180:183], v[32:35]
	global_load_lds_dwordx4 v250, s[64:65]
	v_mfma_f32_16x16x32_bf16 v[24:27], v[140:143], v[184:187], v[24:27]
	s_add_u32 m0, s7, 0xcc00
	v_mfma_f32_16x16x32_bf16 v[20:23], v[140:143], v[188:191], v[20:23]
	global_load_lds_dwordx4 v251, s[64:65]
	v_mfma_f32_16x16x32_bf16 v[0:3], v[140:143], v[192:195], v[0:3]
	s_add_u32 s8, s8, 0x80
	s_addc_u32 s9, s9, 0
	s_add_u32 s64, s64, 0x80
	s_addc_u32 s65, s65, 0
	s_sub_u32 s32, s32, 1
	s_cmp_lg_u32 s32, 0
	s_cbranch_scc1 .Lg18_loop
	s_waitcnt vmcnt(8)
	s_barrier
	ds_read_b128 v[80:83], v252 offset:0
	ds_read_b128 v[144:147], v254 offset:32768
	ds_read_b128 v[148:151], v254 offset:34816
	ds_read_b128 v[152:155], v254 offset:36864
	ds_read_b128 v[156:159], v254 offset:38912
	ds_read_b128 v[84:87], v252 offset:2048
	ds_read_b128 v[88:91], v252 offset:4096
	ds_read_b128 v[92:95], v252 offset:6144
	ds_read_b128 v[124:127], v253 offset:0
	ds_read_b128 v[180:183], v255 offset:32768
	ds_read_b128 v[184:187], v255 offset:34816
	ds_read_b128 v[188:191], v255 offset:36864
	ds_read_b128 v[192:195], v255 offset:38912
	s_waitcnt lgkmcnt(11)
	v_mfma_f32_16x16x32_bf16 v[60:63], v[80:83], v[144:147], v[60:63]
	s_waitcnt lgkmcnt(10)
	v_mfma_f32_16x16x32_bf16 v[56:59], v[80:83], v[148:151], v[56:59]
	s_waitcnt lgkmcnt(9)
	v_mfma_f32_16x16x32_bf16 v[52:55], v[80:83], v[152:155], v[52:55]
	s_waitcnt lgkmcnt(8)
	v_mfma_f32_16x16x32_bf16 v[48:51], v[80:83], v[156:159], v[48:51]
	ds_read_b128 v[132:135], v253 offset:2048
	ds_read_b128 v[136:139], v253 offset:4096
	ds_read_b128 v[140:143], v253 offset:6144
	s_waitcnt lgkmcnt(10)
	v_mfma_f32_16x16x32_bf16 v[44:47], v[84:87], v[144:147], v[44:47]
	v_mfma_f32_16x16x32_bf16 v[40:43], v[84:87], v[148:151], v[40:43]
	v_mfma_f32_16x16x32_bf16 v[36:39], v[84:87], v[152:155], v[36:39]
	v_mfma_f32_16x16x32_bf16 v[28:31], v[84:87], v[156:159], v[28:31]
	s_waitcnt lgkmcnt(9)
	v_mfma_f32_16x16x32_bf16 v[16:19], v[88:91], v[144:147], v[16:19]
	v_mfma_f32_16x16x32_bf16 v[12:15], v[88:91], v[148:151], v[12:15]
	v_mfma_f32_16x16x32_bf16 v[4:7], v[88:91], v[152:155], v[4:7]
	v_mfma_f32_16x16x32_bf16 v[8:11], v[88:91], v[156:159], v[8:11]
	s_waitcnt lgkmcnt(8)
	v_mfma_f32_16x16x32_bf16 v[32:35], v[92:95], v[144:147], v[32:35]
	v_mfma_f32_16x16x32_bf16 v[24:27], v[92:95], v[148:151], v[24:27]
	v_mfma_f32_16x16x32_bf16 v[20:23], v[92:95], v[152:155], v[20:23]
	v_mfma_f32_16x16x32_bf16 v[0:3], v[92:95], v[156:159], v[0:3]
	s_waitcnt lgkmcnt(0)
	s_barrier
	v_mfma_f32_16x16x32_bf16 v[60:63], v[124:127], v[180:183], v[60:63]
	v_mfma_f32_16x16x32_bf16 v[56:59], v[124:127], v[184:187], v[56:59]
	v_mfma_f32_16x16x32_bf16 v[52:55], v[124:127], v[188:191], v[52:55]
	v_mfma_f32_16x16x32_bf16 v[48:51], v[124:127], v[192:195], v[48:51]
	v_mfma_f32_16x16x32_bf16 v[44:47], v[132:135], v[180:183], v[44:47]
	v_mfma_f32_16x16x32_bf16 v[40:43], v[132:135], v[184:187], v[40:43]
	v_mfma_f32_16x16x32_bf16 v[36:39], v[132:135], v[188:191], v[36:39]
	v_mfma_f32_16x16x32_bf16 v[28:31], v[132:135], v[192:195], v[28:31]
	v_mfma_f32_16x16x32_bf16 v[16:19], v[136:139], v[180:183], v[16:19]
	v_mfma_f32_16x16x32_bf16 v[12:15], v[136:139], v[184:187], v[12:15]
	v_mfma_f32_16x16x32_bf16 v[4:7], v[136:139], v[188:191], v[4:7]
	v_mfma_f32_16x16x32_bf16 v[8:11], v[136:139], v[192:195], v[8:11]
	v_mfma_f32_16x16x32_bf16 v[32:35], v[140:143], v[180:183], v[32:35]
	v_mfma_f32_16x16x32_bf16 v[24:27], v[140:143], v[184:187], v[24:27]
	v_mfma_f32_16x16x32_bf16 v[20:23], v[140:143], v[188:191], v[20:23]
	v_mfma_f32_16x16x32_bf16 v[0:3], v[140:143], v[192:195], v[0:3]
	s_waitcnt vmcnt(0)
	s_barrier
	ds_read_b128 v[80:83], v252 offset:16384
	ds_read_b128 v[144:147], v254 offset:49152
	ds_read_b128 v[148:151], v254 offset:51200
	ds_read_b128 v[152:155], v254 offset:53248
	ds_read_b128 v[156:159], v254 offset:55296
	ds_read_b128 v[84:87], v252 offset:18432
	ds_read_b128 v[88:91], v252 offset:20480
	ds_read_b128 v[92:95], v252 offset:22528
	ds_read_b128 v[124:127], v253 offset:16384
	ds_read_b128 v[180:183], v255 offset:49152
	ds_read_b128 v[184:187], v255 offset:51200
	ds_read_b128 v[188:191], v255 offset:53248
	ds_read_b128 v[192:195], v255 offset:55296
	s_waitcnt lgkmcnt(11)
	v_mfma_f32_16x16x32_bf16 v[60:63], v[80:83], v[144:147], v[60:63]
	s_waitcnt lgkmcnt(10)
	v_mfma_f32_16x16x32_bf16 v[56:59], v[80:83], v[148:151], v[56:59]
	s_waitcnt lgkmcnt(9)
	v_mfma_f32_16x16x32_bf16 v[52:55], v[80:83], v[152:155], v[52:55]
	s_waitcnt lgkmcnt(8)
	v_mfma_f32_16x16x32_bf16 v[48:51], v[80:83], v[156:159], v[48:51]
	ds_read_b128 v[132:135], v253 offset:18432
	ds_read_b128 v[136:139], v253 offset:20480
	ds_read_b128 v[140:143], v253 offset:22528
	s_waitcnt lgkmcnt(10)
	v_mfma_f32_16x16x32_bf16 v[44:47], v[84:87], v[144:147], v[44:47]
	v_mfma_f32_16x16x32_bf16 v[40:43], v[84:87], v[148:151], v[40:43]
	v_mfma_f32_16x16x32_bf16 v[36:39], v[84:87], v[152:155], v[36:39]
	v_mfma_f32_16x16x32_bf16 v[28:31], v[84:87], v[156:159], v[28:31]
	s_waitcnt lgkmcnt(9)
	v_mfma_f32_16x16x32_bf16 v[16:19], v[88:91], v[144:147], v[16:19]
	v_mfma_f32_16x16x32_bf16 v[12:15], v[88:91], v[148:151], v[12:15]
	v_mfma_f32_16x16x32_bf16 v[4:7], v[88:91], v[152:155], v[4:7]
	v_mfma_f32_16x16x32_bf16 v[8:11], v[88:91], v[156:159], v[8:11]
	s_waitcnt lgkmcnt(8)
	v_mfma_f32_16x16x32_bf16 v[32:35], v[92:95], v[144:147], v[32:35]
	v_mfma_f32_16x16x32_bf16 v[24:27], v[92:95], v[148:151], v[24:27]
	v_mfma_f32_16x16x32_bf16 v[20:23], v[92:95], v[152:155], v[20:23]
	v_mfma_f32_16x16x32_bf16 v[0:3], v[92:95], v[156:159], v[0:3]
	s_waitcnt lgkmcnt(0)
	s_barrier
	v_mfma_f32_16x16x32_bf16 v[60:63], v[124:127], v[180:183], v[60:63]
	v_mfma_f32_16x16x32_bf16 v[56:59], v[124:127], v[184:187], v[56:59]
	v_mfma_f32_16x16x32_bf16 v[52:55], v[124:127], v[188:191], v[52:55]
	v_mfma_f32_16x16x32_bf16 v[48:51], v[124:127], v[192:195], v[48:51]
	v_mfma_f32_16x16x32_bf16 v[44:47], v[132:135], v[180:183], v[44:47]
	v_mfma_f32_16x16x32_bf16 v[40:43], v[132:135], v[184:187], v[40:43]
	v_mfma_f32_16x16x32_bf16 v[36:39], v[132:135], v[188:191], v[36:39]
	v_mfma_f32_16x16x32_bf16 v[28:31], v[132:135], v[192:195], v[28:31]
	v_mfma_f32_16x16x32_bf16 v[16:19], v[136:139], v[180:183], v[16:19]
	v_mfma_f32_16x16x32_bf16 v[12:15], v[136:139], v[184:187], v[12:15]
	v_mfma_f32_16x16x32_bf16 v[4:7], v[136:139], v[188:191], v[4:7]
	v_mfma_f32_16x16x32_bf16 v[8:11], v[136:139], v[192:195], v[8:11]
	v_mfma_f32_16x16x32_bf16 v[32:35], v[140:143], v[180:183], v[32:35]
	v_mfma_f32_16x16x32_bf16 v[24:27], v[140:143], v[184:187], v[24:27]
	v_mfma_f32_16x16x32_bf16 v[20:23], v[140:143], v[188:191], v[20:23]
	v_mfma_f32_16x16x32_bf16 v[0:3], v[140:143], v[192:195], v[0:3]
	s_nop 7
	s_nop 1
	s_waitcnt vmcnt(3)
	v_add_u32_e32 v80, s12, v174
	v_or_b32_e32 v64, s6, v175
	s_cmpk_gt_i32 s6, 0x3ff
	s_mov_b64 s[6:7], -1
	s_cbranch_scc0 .LBB0_1789
	s_cmpk_gt_u32 s13, 0xbff
	s_cbranch_scc0 .LBB0_1786
	s_cmpk_gt_u32 s13, 0x13ff
	s_cbranch_scc0 .LBB0_1609
	s_cmpk_gt_u32 s13, 0x17ff
	s_cbranch_scc0 .LBB0_1590
	s_and_saveexec_b64 s[6:7], s[4:5]
	s_cbranch_execz .LBB0_1589
	v_lshlrev_b32_e32 v98, 7, v80
	v_lshl_add_u64 v[66:67], v[104:105], 0, v[98:99]
	global_store_dword v[66:67], v60, off
	global_store_dword v[66:67], v61, off offset:128
	global_store_dword v[66:67], v62, off offset:256
	global_store_dword v[66:67], v63, off offset:384
	global_store_dword v[66:67], v56, off offset:64
	global_store_dword v[66:67], v57, off offset:192
	global_store_dword v[66:67], v58, off offset:320
	global_store_dword v[66:67], v59, off offset:448
	global_store_dword v[66:67], v44, off offset:2048
	global_store_dword v[66:67], v45, off offset:2176
	global_store_dword v[66:67], v46, off offset:2304
	global_store_dword v[66:67], v47, off offset:2432
	global_store_dword v[66:67], v40, off offset:2112
	global_store_dword v[66:67], v41, off offset:2240
	global_store_dword v[66:67], v42, off offset:2368
	global_store_dword v[66:67], v43, off offset:2496
	v_or_b32_e32 v66, 0x1000, v98
	v_mov_b32_e32 v67, v99
	v_lshl_add_u64 v[68:69], v[104:105], 0, v[66:67]
	global_store_dword v[68:69], v16, off
	v_or_b32_e32 v68, 0x1080, v98
	v_mov_b32_e32 v69, v99
	v_lshl_add_u64 v[70:71], v[104:105], 0, v[68:69]
	global_store_dword v[70:71], v17, off
	v_or_b32_e32 v70, 0x1100, v98
	v_mov_b32_e32 v71, v99
	v_lshl_add_u64 v[66:67], v[106:107], 0, v[66:67]
	v_lshl_add_u64 v[72:73], v[104:105], 0, v[70:71]
	global_store_dword v[66:67], v12, off
	v_lshl_add_u64 v[66:67], v[106:107], 0, v[68:69]
	global_store_dword v[72:73], v18, off
	v_or_b32_e32 v72, 0x1180, v98
	v_mov_b32_e32 v73, v99
	global_store_dword v[66:67], v13, off
	v_lshl_add_u64 v[66:67], v[106:107], 0, v[70:71]
	global_store_dword v[66:67], v14, off
	v_lshl_add_u64 v[66:67], v[106:107], 0, v[72:73]
	global_store_dword v[66:67], v15, off
	v_or_b32_e32 v66, 0x1800, v98
	v_mov_b32_e32 v67, v99
	v_lshl_add_u64 v[68:69], v[104:105], 0, v[66:67]
	global_store_dword v[68:69], v32, off
	v_or_b32_e32 v68, 0x1880, v98
	v_mov_b32_e32 v69, v99
	v_lshl_add_u64 v[70:71], v[104:105], 0, v[68:69]
	v_lshl_add_u64 v[66:67], v[106:107], 0, v[66:67]
	global_store_dword v[70:71], v33, off
	v_or_b32_e32 v70, 0x1900, v98
	v_mov_b32_e32 v71, v99
	global_store_dword v[66:67], v24, off
	v_lshl_add_u64 v[66:67], v[106:107], 0, v[68:69]
	v_lshl_add_u64 v[74:75], v[104:105], 0, v[72:73]
	v_lshl_add_u64 v[72:73], v[104:105], 0, v[70:71]
	v_or_b32_e32 v98, 0x1980, v98
	global_store_dword v[66:67], v25, off
	v_lshl_add_u64 v[66:67], v[106:107], 0, v[70:71]
	global_store_dword v[72:73], v34, off
	v_lshl_add_u64 v[72:73], v[104:105], 0, v[98:99]
	global_store_dword v[66:67], v26, off
	v_lshl_add_u64 v[66:67], v[106:107], 0, v[98:99]
	global_store_dword v[74:75], v19, off
	global_store_dword v[72:73], v35, off
	global_store_dword v[66:67], v27, off

.LBB0_2292:
	s_cmp_gt_i32 s60, 22
	s_cselect_b64 s[2:3], -1, 0
	s_cmp_lt_i32 s61, 22
	s_cselect_b64 s[4:5], -1, 0
	s_or_b64 s[2:3], s[2:3], s[4:5]
	s_and_b64 vcc, exec, s[2:3]
	s_cbranch_vccnz .LBB0_2352
	s_mov_b64 s[4:5], s[0:1]
	s_cmpk_gt_i32 s58, 0x1ff
	s_cbranch_scc1 .LBB0_2298
	s_load_dwordx2 s[6:7], s[4:5], 0xe0
	v_lshrrev_b32_e32 v8, 3, v162
	v_lshlrev_b32_e32 v96, 12, v8
	v_mov_b32_e32 v97, 0
	v_lshlrev_b32_e32 v0, 4, v162
	s_waitcnt lgkmcnt(0)
	s_add_u32 s2, s6, 0x6b40000
	s_addc_u32 s3, s7, 0
	s_add_u32 s4, s6, 0x6b7a100
	v_and_b32_e32 v0, 0x70, v0
	v_mov_b32_e32 v1, v97
	v_lshl_add_u64 v[2:3], s[6:7], 0, v[96:97]
	s_addc_u32 s5, s7, 0
	v_lshl_add_u64 v[0:1], v[2:3], 0, v[0:1]
	s_mov_b64 s[6:7], 0x1257a100
	v_xor_b32_e32 v9, v163, v162
	v_lshl_add_u64 v[98:99], v[0:1], 0, s[6:7]
	s_mov_b64 s[6:7], 0x1c80000
	v_lshl_add_u64 v[100:101], v[0:1], 0, s[6:7]
	v_lshlrev_b32_e32 v1, 4, v9
	v_and_b32_e32 v6, 15, v162
	v_bfe_u32 v0, v162, 1, 3
	v_and_b32_e32 v1, 0x70, v1
	v_bfe_u32 v4, v162, 6, 1
	v_lshrrev_b32_e32 v5, 7, v162
	v_bitop3_b32 v0, v163, v0, 3 bitop3:0x6c
	v_lshl_or_b32 v142, v8, 7, v1
	v_lshlrev_b32_e32 v1, 7, v6
	s_load_dword s34, s[0:1], 0xf0
	v_lshl_or_b32 v2, v5, 13, v1
	v_lshl_or_b32 v1, v4, 13, v1
	v_lshlrev_b32_e32 v0, 4, v0
	v_or_b32_e32 v143, v2, v0
	v_or_b32_e32 v144, v1, v0
	v_xor_b32_e32 v0, 64, v0
	v_bfe_u32 v7, v162, 4, 2
	v_or_b32_e32 v145, v2, v0
	v_or_b32_e32 v146, v1, v0
	v_lshlrev_b32_e32 v0, 6, v5
	v_lshl_or_b32 v147, v4, 6, v6
	v_lshl_or_b32 v148, v7, 2, v0
	s_mov_b32 s7, 0
	s_mov_b64 s[8:9], 0x20000
	s_mov_b32 s35, 0x20000
	s_mov_b64 s[10:11], 0x40000
	s_mov_b32 s36, 0x40000
	s_mov_b64 s[12:13], 0x60000
	s_mov_b32 s37, 0x60000
	s_mov_b64 s[14:15], 0x60100
	s_mov_b64 s[16:17], 0x40100
	s_mov_b64 s[18:19], 0x20100
	s_mov_b64 s[20:21], 0x100
	s_mov_b64 s[22:23], 0x200
	s_mov_b64 s[24:25], 0x20200
	s_mov_b64 s[26:27], 0x40200
	s_mov_b64 s[28:29], 0x60200
	v_mov_b32_e32 v149, 0x1000
	s_mov_b32 s38, s58
	v_and_b32_e32 v240, 63, v162
	v_lshrrev_b32_e32 v247, 6, v162
	v_lshrrev_b32_e32 v242, 3, v240
	v_lshl_add_u32 v242, v247, 5, v242
	v_and_b32_e32 v243, 7, v240
	v_lshrrev_b32_e32 v244, 4, v240
	v_xor_b32_e32 v243, v243, v244
	v_lshlrev_b32_e32 v243, 4, v243
	v_mov_b32_e32 v241, 0x1000
	v_mad_u32_u24 v248, v242, v241, v243
	v_xor_b32_e32 v249, 64, v248
	v_add_u32_e32 v249, 0x8000, v249
	v_add_u32_e32 v250, 0x10000, v248
	v_xor_b32_e32 v251, 64, v248
	v_add_u32_e32 v251, 0x18000, v251
	v_and_b32_e32 v241, 15, v240
	v_lshrrev_b32_e32 v242, 1, v241
	v_xor_b32_e32 v242, v242, v244
	v_lshlrev_b32_e32 v242, 4, v242
	v_lshl_or_b32 v242, v241, 7, v242
	v_lshrrev_b32_e32 v243, 1, v247
	v_lshl_or_b32 v252, v243, 13, v242
	v_xor_b32_e32 v253, 64, v252
	v_and_b32_e32 v243, 1, v247
	v_lshl_or_b32 v254, v243, 13, v242
	v_xor_b32_e32 v255, 64, v254
.LBB0_2295:
	s_lshl_b32 s6, s38, 7
	s_and_b32 s39, s6, 0x1f80
	s_lshl_b32 s6, s38, 1
	s_and_b32 s30, s6, 0xffffff80
	s_lshl_b32 s6, s39, 12
	v_lshl_add_u64 v[102:103], v[98:99], 0, s[6:7]
	v_add_co_u32_e32 v38, vcc, 0x20000, v102
	s_ashr_i32 s31, s30, 31
	s_nop 0
	v_addc_co_u32_e32 v39, vcc, 0, v103, vcc
	v_add_co_u32_e32 v44, vcc, 0x40000, v102
	s_lshl_b64 s[40:41], s[30:31], 12
	s_nop 0
	v_addc_co_u32_e32 v45, vcc, 0, v103, vcc
	v_add_co_u32_e32 v46, vcc, 0x60000, v102
	v_lshl_add_u64 v[104:105], v[100:101], 0, s[40:41]
	s_nop 0
	v_addc_co_u32_e32 v47, vcc, 0, v103, vcc
	v_add_co_u32_e32 v48, vcc, s35, v104
	s_nop 0
	v_addc_co_u32_e32 v49, vcc, 0, v105, vcc
	v_add_co_u32_e32 v50, vcc, s36, v104
	v_addc_co_u32_e32 v51, vcc, 0, v105, vcc
	v_add_co_u32_e32 v52, vcc, s37, v104
	v_addc_co_u32_e32 v53, vcc, 0, v105, vcc
	s_mov_b32 s31, -2
	v_mov_b32_e32 v8, 0
	v_mov_b32_e32 v9, v97
	v_mov_b32_e32 v10, v97
	v_mov_b32_e32 v11, v97
	v_mov_b32_e32 v24, 0
	v_mov_b32_e32 v25, v97
	v_mov_b32_e32 v26, v97
	v_mov_b32_e32 v27, v97
	v_mov_b32_e32 v36, 0
	v_mov_b32_e32 v37, v97
	v_mov_b32_e32 v38, v97
	v_lshl_add_u64 v[106:107], v[102:103], 0, s[8:9]
	v_lshl_add_u64 v[108:109], v[102:103], 0, s[10:11]
	v_lshl_add_u64 v[110:111], v[102:103], 0, s[12:13]
	v_lshl_add_u64 v[118:119], v[102:103], 0, s[14:15]
	v_lshl_add_u64 v[120:121], v[102:103], 0, s[16:17]
	v_lshl_add_u64 v[122:123], v[102:103], 0, s[18:19]
	v_lshl_add_u64 v[124:125], v[102:103], 0, s[20:21]
	v_lshl_add_u64 v[112:113], v[104:105], 0, s[8:9]
	v_lshl_add_u64 v[114:115], v[104:105], 0, s[10:11]
	v_lshl_add_u64 v[116:117], v[104:105], 0, s[12:13]
	v_lshl_add_u64 v[128:129], v[104:105], 0, s[14:15]
	v_lshl_add_u64 v[130:131], v[104:105], 0, s[16:17]
	v_lshl_add_u64 v[132:133], v[104:105], 0, s[18:19]
	v_lshl_add_u64 v[126:127], v[104:105], 0, s[20:21]
	v_mov_b32_e32 v39, v97
	v_mov_b32_e32 v48, 0
	v_mov_b32_e32 v49, v97
	v_mov_b32_e32 v50, v97
	v_mov_b32_e32 v51, v97
	v_mov_b32_e32 v52, 0
	v_mov_b32_e32 v53, v97
	v_mov_b32_e32 v54, v97
	v_mov_b32_e32 v55, v97
	v_mov_b32_e32 v56, 0
	v_mov_b32_e32 v57, v97
	v_mov_b32_e32 v58, v97
	v_mov_b32_e32 v59, v97
	v_mov_b32_e32 v44, 0
	v_mov_b32_e32 v45, v97
	v_mov_b32_e32 v46, v97
	v_mov_b32_e32 v47, v97
	v_mov_b32_e32 v60, 0
	v_mov_b32_e32 v61, v97
	v_mov_b32_e32 v62, v97
	v_mov_b32_e32 v63, v97
	v_mov_b32_e32 v0, 0
	v_mov_b32_e32 v1, v97
	v_mov_b32_e32 v2, v97
	v_mov_b32_e32 v3, v97
	v_mov_b32_e32 v16, 0
	v_mov_b32_e32 v17, v97
	v_mov_b32_e32 v18, v97
	v_mov_b32_e32 v19, v97
	v_mov_b32_e32 v32, 0
	v_mov_b32_e32 v33, v97
	v_mov_b32_e32 v34, v97
	v_mov_b32_e32 v35, v97
	v_mov_b32_e32 v4, 0
	v_mov_b32_e32 v5, v97
	v_mov_b32_e32 v6, v97
	v_mov_b32_e32 v7, v97
	v_mov_b32_e32 v20, 0
	v_mov_b32_e32 v21, v97
	v_mov_b32_e32 v22, v97
	v_mov_b32_e32 v23, v97
	v_mov_b32_e32 v40, 0
	v_mov_b32_e32 v41, v97
	v_mov_b32_e32 v42, v97
	v_mov_b32_e32 v43, v97
	v_mov_b32_e32 v12, 0
	v_mov_b32_e32 v13, v97
	v_mov_b32_e32 v14, v97
	v_mov_b32_e32 v15, v97
	v_mov_b32_e32 v28, 0
	v_mov_b32_e32 v29, v97
	v_mov_b32_e32 v30, v97
	v_mov_b32_e32 v31, v97
	v_readfirstlane_b32 s40, v102
	v_readfirstlane_b32 s41, v103
	v_readfirstlane_b32 s48, v104
	v_readfirstlane_b32 s49, v105
	v_readfirstlane_b32 s6, v247
	s_nop 3
	s_mul_i32 s32, s6, 0x8000
	s_sub_u32 s40, s40, s32
	s_subb_u32 s41, s41, 0
	s_sub_u32 s48, s48, s32
	s_subb_u32 s49, s49, 0
	s_lshl_b32 s6, s6, 12
	s_add_u32 m0, s6, 0x0
	v_mov_b32_e32 v60, 0
	global_load_lds_dwordx4 v248, s[40:41]
	v_mov_b32_e32 v61, 0
	s_add_u32 m0, s6, 0x400
	v_mov_b32_e32 v62, 0
	global_load_lds_dwordx4 v249, s[40:41]
	v_mov_b32_e32 v63, 0
	s_add_u32 m0, s6, 0x800
	v_mov_b32_e32 v44, 0
	global_load_lds_dwordx4 v250, s[40:41]
	v_mov_b32_e32 v45, 0
	s_add_u32 m0, s6, 0xc00
	v_mov_b32_e32 v46, 0
	global_load_lds_dwordx4 v251, s[40:41]
	v_mov_b32_e32 v47, 0
	s_add_u32 m0, s6, 0x8000
	v_mov_b32_e32 v28, 0
	global_load_lds_dwordx4 v248, s[48:49]
	v_mov_b32_e32 v29, 0
	s_add_u32 m0, s6, 0x8400
	v_mov_b32_e32 v30, 0
	global_load_lds_dwordx4 v249, s[48:49]
	v_mov_b32_e32 v31, 0
	s_add_u32 m0, s6, 0x8800
	v_mov_b32_e32 v12, 0
	global_load_lds_dwordx4 v250, s[48:49]
	v_mov_b32_e32 v13, 0
	s_add_u32 m0, s6, 0x8c00
	v_mov_b32_e32 v14, 0
	global_load_lds_dwordx4 v251, s[48:49]
	v_mov_b32_e32 v15, 0
	s_add_u32 s40, s40, 0x80
	s_addc_u32 s41, s41, 0
	s_add_u32 s48, s48, 0x80
	s_addc_u32 s49, s49, 0
	s_add_u32 m0, s6, 0x4000
	v_mov_b32_e32 v56, 0
	global_load_lds_dwordx4 v248, s[40:41]
	v_mov_b32_e32 v57, 0
	s_add_u32 m0, s6, 0x4400
	v_mov_b32_e32 v58, 0
	global_load_lds_dwordx4 v249, s[40:41]
	v_mov_b32_e32 v59, 0
	s_add_u32 m0, s6, 0x4800
	v_mov_b32_e32 v40, 0
	global_load_lds_dwordx4 v250, s[40:41]
	v_mov_b32_e32 v41, 0
	s_add_u32 m0, s6, 0x4c00
	v_mov_b32_e32 v42, 0
	global_load_lds_dwordx4 v251, s[40:41]
	v_mov_b32_e32 v43, 0
	s_add_u32 m0, s6, 0xc000
	v_mov_b32_e32 v20, 0
	global_load_lds_dwordx4 v248, s[48:49]
	v_mov_b32_e32 v21, 0
	s_add_u32 m0, s6, 0xc400
	v_mov_b32_e32 v22, 0
	global_load_lds_dwordx4 v249, s[48:49]
	v_mov_b32_e32 v23, 0
	s_add_u32 m0, s6, 0xc800
	v_mov_b32_e32 v4, 0
	global_load_lds_dwordx4 v250, s[48:49]
	v_mov_b32_e32 v5, 0
	s_add_u32 m0, s6, 0xcc00
	v_mov_b32_e32 v6, 0
	global_load_lds_dwordx4 v251, s[48:49]
	v_mov_b32_e32 v7, 0
	s_add_u32 s40, s40, 0x80
	s_addc_u32 s41, s41, 0
	s_add_u32 s48, s48, 0x80
	s_addc_u32 s49, s49, 0
	v_mov_b32_e32 v52, 0
	v_mov_b32_e32 v53, 0
	v_mov_b32_e32 v54, 0
	v_mov_b32_e32 v55, 0
	v_mov_b32_e32 v32, 0
	v_mov_b32_e32 v33, 0
	v_mov_b32_e32 v34, 0
	v_mov_b32_e32 v35, 0
	v_mov_b32_e32 v16, 0
	v_mov_b32_e32 v17, 0
	v_mov_b32_e32 v18, 0
	v_mov_b32_e32 v19, 0
	v_mov_b32_e32 v0, 0
	v_mov_b32_e32 v1, 0
	v_mov_b32_e32 v2, 0
	v_mov_b32_e32 v3, 0
	v_mov_b32_e32 v48, 0
	v_mov_b32_e32 v49, 0
	v_mov_b32_e32 v50, 0
	v_mov_b32_e32 v51, 0
	v_mov_b32_e32 v36, 0
	v_mov_b32_e32 v37, 0
	v_mov_b32_e32 v38, 0
	v_mov_b32_e32 v39, 0
	v_mov_b32_e32 v24, 0
	v_mov_b32_e32 v25, 0
	v_mov_b32_e32 v26, 0
	v_mov_b32_e32 v27, 0
	v_mov_b32_e32 v8, 0
	v_mov_b32_e32 v9, 0
	v_mov_b32_e32 v10, 0
	v_mov_b32_e32 v11, 0
	s_mov_b32 s31, 15
.Lg22_loop:
	s_waitcnt vmcnt(8)
	s_barrier
	ds_read_b128 v[64:67], v252 offset:0
	ds_read_b128 v[104:107], v254 offset:32768
	ds_read_b128 v[108:111], v254 offset:34816
	ds_read_b128 v[112:115], v254 offset:36864
	ds_read_b128 v[116:119], v254 offset:38912
	ds_read_b128 v[68:71], v252 offset:2048
	ds_read_b128 v[72:75], v252 offset:4096
	ds_read_b128 v[76:79], v252 offset:6144
	ds_read_b128 v[80:83], v253 offset:0
	ds_read_b128 v[120:123], v255 offset:32768
	ds_read_b128 v[124:127], v255 offset:34816
	ds_read_b128 v[132:135], v255 offset:36864
	ds_read_b128 v[136:139], v255 offset:38912
	s_waitcnt lgkmcnt(11)
	v_mfma_f32_16x16x32_bf16 v[60:63], v[64:67], v[104:107], v[60:63]
	s_waitcnt lgkmcnt(10)
	v_mfma_f32_16x16x32_bf16 v[44:47], v[64:67], v[108:111], v[44:47]
	s_waitcnt lgkmcnt(9)
	v_mfma_f32_16x16x32_bf16 v[28:31], v[64:67], v[112:115], v[28:31]
	s_waitcnt lgkmcnt(8)
	v_mfma_f32_16x16x32_bf16 v[12:15], v[64:67], v[116:119], v[12:15]
	ds_read_b128 v[84:87], v253 offset:2048
	ds_read_b128 v[88:91], v253 offset:4096
	ds_read_b128 v[92:95], v253 offset:6144
	s_waitcnt lgkmcnt(10)
	v_mfma_f32_16x16x32_bf16 v[56:59], v[68:71], v[104:107], v[56:59]
	v_mfma_f32_16x16x32_bf16 v[40:43], v[68:71], v[108:111], v[40:43]
	v_mfma_f32_16x16x32_bf16 v[20:23], v[68:71], v[112:115], v[20:23]
	v_mfma_f32_16x16x32_bf16 v[4:7], v[68:71], v[116:119], v[4:7]
	s_waitcnt lgkmcnt(9)
	v_mfma_f32_16x16x32_bf16 v[52:55], v[72:75], v[104:107], v[52:55]
	v_mfma_f32_16x16x32_bf16 v[32:35], v[72:75], v[108:111], v[32:35]
	v_mfma_f32_16x16x32_bf16 v[16:19], v[72:75], v[112:115], v[16:19]
	v_mfma_f32_16x16x32_bf16 v[0:3], v[72:75], v[116:119], v[0:3]
	s_waitcnt lgkmcnt(8)
	v_mfma_f32_16x16x32_bf16 v[48:51], v[76:79], v[104:107], v[48:51]
	v_mfma_f32_16x16x32_bf16 v[36:39], v[76:79], v[108:111], v[36:39]
	v_mfma_f32_16x16x32_bf16 v[24:27], v[76:79], v[112:115], v[24:27]
	v_mfma_f32_16x16x32_bf16 v[8:11], v[76:79], v[116:119], v[8:11]
	s_waitcnt lgkmcnt(0)
	s_barrier
	s_add_u32 m0, s6, 0x0
	v_mfma_f32_16x16x32_bf16 v[60:63], v[80:83], v[120:123], v[60:63]
	global_load_lds_dwordx4 v248, s[40:41]
	v_mfma_f32_16x16x32_bf16 v[44:47], v[80:83], v[124:127], v[44:47]
	s_add_u32 m0, s6, 0x400
	v_mfma_f32_16x16x32_bf16 v[28:31], v[80:83], v[132:135], v[28:31]
	global_load_lds_dwordx4 v249, s[40:41]
	v_mfma_f32_16x16x32_bf16 v[12:15], v[80:83], v[136:139], v[12:15]
	s_add_u32 m0, s6, 0x800
	v_mfma_f32_16x16x32_bf16 v[56:59], v[84:87], v[120:123], v[56:59]
	global_load_lds_dwordx4 v250, s[40:41]
	v_mfma_f32_16x16x32_bf16 v[40:43], v[84:87], v[124:127], v[40:43]
	s_add_u32 m0, s6, 0xc00
	v_mfma_f32_16x16x32_bf16 v[20:23], v[84:87], v[132:135], v[20:23]
	global_load_lds_dwordx4 v251, s[40:41]
	v_mfma_f32_16x16x32_bf16 v[4:7], v[84:87], v[136:139], v[4:7]
	s_add_u32 m0, s6, 0x8000
	v_mfma_f32_16x16x32_bf16 v[52:55], v[88:91], v[120:123], v[52:55]
	global_load_lds_dwordx4 v248, s[48:49]
	v_mfma_f32_16x16x32_bf16 v[32:35], v[88:91], v[124:127], v[32:35]
	s_add_u32 m0, s6, 0x8400
	v_mfma_f32_16x16x32_bf16 v[16:19], v[88:91], v[132:135], v[16:19]
	global_load_lds_dwordx4 v249, s[48:49]
	v_mfma_f32_16x16x32_bf16 v[0:3], v[88:91], v[136:139], v[0:3]
	s_add_u32 m0, s6, 0x8800
	v_mfma_f32_16x16x32_bf16 v[48:51], v[92:95], v[120:123], v[48:51]
	global_load_lds_dwordx4 v250, s[48:49]
	v_mfma_f32_16x16x32_bf16 v[36:39], v[92:95], v[124:127], v[36:39]
	s_add_u32 m0, s6, 0x8c00
	v_mfma_f32_16x16x32_bf16 v[24:27], v[92:95], v[132:135], v[24:27]
	global_load_lds_dwordx4 v251, s[48:49]
	v_mfma_f32_16x16x32_bf16 v[8:11], v[92:95], v[136:139], v[8:11]
	s_add_u32 s40, s40, 0x80
	s_addc_u32 s41, s41, 0
	s_add_u32 s48, s48, 0x80
	s_addc_u32 s49, s49, 0
	s_waitcnt vmcnt(8)
	s_barrier
	ds_read_b128 v[64:67], v252 offset:16384
	ds_read_b128 v[104:107], v254 offset:49152
	ds_read_b128 v[108:111], v254 offset:51200
	ds_read_b128 v[112:115], v254 offset:53248
	ds_read_b128 v[116:119], v254 offset:55296
	ds_read_b128 v[68:71], v252 offset:18432
	ds_read_b128 v[72:75], v252 offset:20480
	ds_read_b128 v[76:79], v252 offset:22528
	ds_read_b128 v[80:83], v253 offset:16384
	ds_read_b128 v[120:123], v255 offset:49152
	ds_read_b128 v[124:127], v255 offset:51200
	ds_read_b128 v[132:135], v255 offset:53248
	ds_read_b128 v[136:139], v255 offset:55296
	s_waitcnt lgkmcnt(11)
	v_mfma_f32_16x16x32_bf16 v[60:63], v[64:67], v[104:107], v[60:63]
	s_waitcnt lgkmcnt(10)
	v_mfma_f32_16x16x32_bf16 v[44:47], v[64:67], v[108:111], v[44:47]
	s_waitcnt lgkmcnt(9)
	v_mfma_f32_16x16x32_bf16 v[28:31], v[64:67], v[112:115], v[28:31]
	s_waitcnt lgkmcnt(8)
	v_mfma_f32_16x16x32_bf16 v[12:15], v[64:67], v[116:119], v[12:15]
	ds_read_b128 v[84:87], v253 offset:18432
	ds_read_b128 v[88:91], v253 offset:20480
	ds_read_b128 v[92:95], v253 offset:22528
	s_waitcnt lgkmcnt(10)
	v_mfma_f32_16x16x32_bf16 v[56:59], v[68:71], v[104:107], v[56:59]
	v_mfma_f32_16x16x32_bf16 v[40:43], v[68:71], v[108:111], v[40:43]
	v_mfma_f32_16x16x32_bf16 v[20:23], v[68:71], v[112:115], v[20:23]
	v_mfma_f32_16x16x32_bf16 v[4:7], v[68:71], v[116:119], v[4:7]
	s_waitcnt lgkmcnt(9)
	v_mfma_f32_16x16x32_bf16 v[52:55], v[72:75], v[104:107], v[52:55]
	v_mfma_f32_16x16x32_bf16 v[32:35], v[72:75], v[108:111], v[32:35]
	v_mfma_f32_16x16x32_bf16 v[16:19], v[72:75], v[112:115], v[16:19]
	v_mfma_f32_16x16x32_bf16 v[0:3], v[72:75], v[116:119], v[0:3]
	s_waitcnt lgkmcnt(8)
	v_mfma_f32_16x16x32_bf16 v[48:51], v[76:79], v[104:107], v[48:51]
	v_mfma_f32_16x16x32_bf16 v[36:39], v[76:79], v[108:111], v[36:39]
	v_mfma_f32_16x16x32_bf16 v[24:27], v[76:79], v[112:115], v[24:27]
	v_mfma_f32_16x16x32_bf16 v[8:11], v[76:79], v[116:119], v[8:11]
	s_waitcnt lgkmcnt(0)
	s_barrier
	s_add_u32 m0, s6, 0x4000
	v_mfma_f32_16x16x32_bf16 v[60:63], v[80:83], v[120:123], v[60:63]
	global_load_lds_dwordx4 v248, s[40:41]
	v_mfma_f32_16x16x32_bf16 v[44:47], v[80:83], v[124:127], v[44:47]
	s_add_u32 m0, s6, 0x4400
	v_mfma_f32_16x16x32_bf16 v[28:31], v[80:83], v[132:135], v[28:31]
	global_load_lds_dwordx4 v249, s[40:41]
	v_mfma_f32_16x16x32_bf16 v[12:15], v[80:83], v[136:139], v[12:15]
	s_add_u32 m0, s6, 0x4800
	v_mfma_f32_16x16x32_bf16 v[56:59], v[84:87], v[120:123], v[56:59]
	global_load_lds_dwordx4 v250, s[40:41]
	v_mfma_f32_16x16x32_bf16 v[40:43], v[84:87], v[124:127], v[40:43]
	s_add_u32 m0, s6, 0x4c00
	v_mfma_f32_16x16x32_bf16 v[20:23], v[84:87], v[132:135], v[20:23]
	global_load_lds_dwordx4 v251, s[40:41]
	v_mfma_f32_16x16x32_bf16 v[4:7], v[84:87], v[136:139], v[4:7]
	s_add_u32 m0, s6, 0xc000
	v_mfma_f32_16x16x32_bf16 v[52:55], v[88:91], v[120:123], v[52:55]
	global_load_lds_dwordx4 v248, s[48:49]
	v_mfma_f32_16x16x32_bf16 v[32:35], v[88:91], v[124:127], v[32:35]
	s_add_u32 m0, s6, 0xc400
	v_mfma_f32_16x16x32_bf16 v[16:19], v[88:91], v[132:135], v[16:19]
	global_load_lds_dwordx4 v249, s[48:49]
	v_mfma_f32_16x16x32_bf16 v[0:3], v[88:91], v[136:139], v[0:3]
	s_add_u32 m0, s6, 0xc800
	v_mfma_f32_16x16x32_bf16 v[48:51], v[92:95], v[120:123], v[48:51]
	global_load_lds_dwordx4 v250, s[48:49]
	v_mfma_f32_16x16x32_bf16 v[36:39], v[92:95], v[124:127], v[36:39]
	s_add_u32 m0, s6, 0xcc00
	v_mfma_f32_16x16x32_bf16 v[24:27], v[92:95], v[132:135], v[24:27]
	global_load_lds_dwordx4 v251, s[48:49]
	v_mfma_f32_16x16x32_bf16 v[8:11], v[92:95], v[136:139], v[8:11]
	s_add_u32 s40, s40, 0x80
	s_addc_u32 s41, s41, 0
	s_add_u32 s48, s48, 0x80
	s_addc_u32 s49, s49, 0
	s_sub_u32 s31, s31, 1
	s_cmp_lg_u32 s31, 0
	s_cbranch_scc1 .Lg22_loop
	s_waitcnt vmcnt(8)
	s_barrier
	ds_read_b128 v[64:67], v252 offset:0
	ds_read_b128 v[104:107], v254 offset:32768
	ds_read_b128 v[108:111], v254 offset:34816
	ds_read_b128 v[112:115], v254 offset:36864
	ds_read_b128 v[116:119], v254 offset:38912
	ds_read_b128 v[68:71], v252 offset:2048
	ds_read_b128 v[72:75], v252 offset:4096
	ds_read_b128 v[76:79], v252 offset:6144
	ds_read_b128 v[80:83], v253 offset:0
	ds_read_b128 v[120:123], v255 offset:32768
	ds_read_b128 v[124:127], v255 offset:34816
	ds_read_b128 v[132:135], v255 offset:36864
	ds_read_b128 v[136:139], v255 offset:38912
	s_waitcnt lgkmcnt(11)
	v_mfma_f32_16x16x32_bf16 v[60:63], v[64:67], v[104:107], v[60:63]
	s_waitcnt lgkmcnt(10)
	v_mfma_f32_16x16x32_bf16 v[44:47], v[64:67], v[108:111], v[44:47]
	s_waitcnt lgkmcnt(9)
	v_mfma_f32_16x16x32_bf16 v[28:31], v[64:67], v[112:115], v[28:31]
	s_waitcnt lgkmcnt(8)
	v_mfma_f32_16x16x32_bf16 v[12:15], v[64:67], v[116:119], v[12:15]
	ds_read_b128 v[84:87], v253 offset:2048
	ds_read_b128 v[88:91], v253 offset:4096
	ds_read_b128 v[92:95], v253 offset:6144
	s_waitcnt lgkmcnt(10)
	v_mfma_f32_16x16x32_bf16 v[56:59], v[68:71], v[104:107], v[56:59]
	v_mfma_f32_16x16x32_bf16 v[40:43], v[68:71], v[108:111], v[40:43]
	v_mfma_f32_16x16x32_bf16 v[20:23], v[68:71], v[112:115], v[20:23]
	v_mfma_f32_16x16x32_bf16 v[4:7], v[68:71], v[116:119], v[4:7]
	s_waitcnt lgkmcnt(9)
	v_mfma_f32_16x16x32_bf16 v[52:55], v[72:75], v[104:107], v[52:55]
	v_mfma_f32_16x16x32_bf16 v[32:35], v[72:75], v[108:111], v[32:35]
	v_mfma_f32_16x16x32_bf16 v[16:19], v[72:75], v[112:115], v[16:19]
	v_mfma_f32_16x16x32_bf16 v[0:3], v[72:75], v[116:119], v[0:3]
	s_waitcnt lgkmcnt(8)
	v_mfma_f32_16x16x32_bf16 v[48:51], v[76:79], v[104:107], v[48:51]
	v_mfma_f32_16x16x32_bf16 v[36:39], v[76:79], v[108:111], v[36:39]
	v_mfma_f32_16x16x32_bf16 v[24:27], v[76:79], v[112:115], v[24:27]
	v_mfma_f32_16x16x32_bf16 v[8:11], v[76:79], v[116:119], v[8:11]
	s_waitcnt lgkmcnt(0)
	s_barrier
	v_mfma_f32_16x16x32_bf16 v[60:63], v[80:83], v[120:123], v[60:63]
	v_mfma_f32_16x16x32_bf16 v[44:47], v[80:83], v[124:127], v[44:47]
	v_mfma_f32_16x16x32_bf16 v[28:31], v[80:83], v[132:135], v[28:31]
	v_mfma_f32_16x16x32_bf16 v[12:15], v[80:83], v[136:139], v[12:15]
	v_mfma_f32_16x16x32_bf16 v[56:59], v[84:87], v[120:123], v[56:59]
	v_mfma_f32_16x16x32_bf16 v[40:43], v[84:87], v[124:127], v[40:43]
	v_mfma_f32_16x16x32_bf16 v[20:23], v[84:87], v[132:135], v[20:23]
	v_mfma_f32_16x16x32_bf16 v[4:7], v[84:87], v[136:139], v[4:7]
	v_mfma_f32_16x16x32_bf16 v[52:55], v[88:91], v[120:123], v[52:55]
	v_mfma_f32_16x16x32_bf16 v[32:35], v[88:91], v[124:127], v[32:35]
	v_mfma_f32_16x16x32_bf16 v[16:19], v[88:91], v[132:135], v[16:19]
	v_mfma_f32_16x16x32_bf16 v[0:3], v[88:91], v[136:139], v[0:3]
	v_mfma_f32_16x16x32_bf16 v[48:51], v[92:95], v[120:123], v[48:51]
	v_mfma_f32_16x16x32_bf16 v[36:39], v[92:95], v[124:127], v[36:39]
	v_mfma_f32_16x16x32_bf16 v[24:27], v[92:95], v[132:135], v[24:27]
	v_mfma_f32_16x16x32_bf16 v[8:11], v[92:95], v[136:139], v[8:11]
	s_waitcnt vmcnt(0)
	s_barrier
	ds_read_b128 v[64:67], v252 offset:16384
	ds_read_b128 v[104:107], v254 offset:49152
	ds_read_b128 v[108:111], v254 offset:51200
	ds_read_b128 v[112:115], v254 offset:53248
	ds_read_b128 v[116:119], v254 offset:55296
	ds_read_b128 v[68:71], v252 offset:18432
	ds_read_b128 v[72:75], v252 offset:20480
	ds_read_b128 v[76:79], v252 offset:22528
	ds_read_b128 v[80:83], v253 offset:16384
	ds_read_b128 v[120:123], v255 offset:49152
	ds_read_b128 v[124:127], v255 offset:51200
	ds_read_b128 v[132:135], v255 offset:53248
	ds_read_b128 v[136:139], v255 offset:55296
	s_waitcnt lgkmcnt(11)
	v_mfma_f32_16x16x32_bf16 v[60:63], v[64:67], v[104:107], v[60:63]
	s_waitcnt lgkmcnt(10)
	v_mfma_f32_16x16x32_bf16 v[44:47], v[64:67], v[108:111], v[44:47]
	s_waitcnt lgkmcnt(9)
	v_mfma_f32_16x16x32_bf16 v[28:31], v[64:67], v[112:115], v[28:31]
	s_waitcnt lgkmcnt(8)
	v_mfma_f32_16x16x32_bf16 v[12:15], v[64:67], v[116:119], v[12:15]
	ds_read_b128 v[84:87], v253 offset:18432
	ds_read_b128 v[88:91], v253 offset:20480
	ds_read_b128 v[92:95], v253 offset:22528
	s_waitcnt lgkmcnt(10)
	v_mfma_f32_16x16x32_bf16 v[56:59], v[68:71], v[104:107], v[56:59]
	v_mfma_f32_16x16x32_bf16 v[40:43], v[68:71], v[108:111], v[40:43]
	v_mfma_f32_16x16x32_bf16 v[20:23], v[68:71], v[112:115], v[20:23]
	v_mfma_f32_16x16x32_bf16 v[4:7], v[68:71], v[116:119], v[4:7]
	s_waitcnt lgkmcnt(9)
	v_mfma_f32_16x16x32_bf16 v[52:55], v[72:75], v[104:107], v[52:55]
	v_mfma_f32_16x16x32_bf16 v[32:35], v[72:75], v[108:111], v[32:35]
	v_mfma_f32_16x16x32_bf16 v[16:19], v[72:75], v[112:115], v[16:19]
	v_mfma_f32_16x16x32_bf16 v[0:3], v[72:75], v[116:119], v[0:3]
	s_waitcnt lgkmcnt(8)
	v_mfma_f32_16x16x32_bf16 v[48:51], v[76:79], v[104:107], v[48:51]
	v_mfma_f32_16x16x32_bf16 v[36:39], v[76:79], v[108:111], v[36:39]
	v_mfma_f32_16x16x32_bf16 v[24:27], v[76:79], v[112:115], v[24:27]
	v_mfma_f32_16x16x32_bf16 v[8:11], v[76:79], v[116:119], v[8:11]
	s_waitcnt lgkmcnt(0)
	s_barrier
	v_mfma_f32_16x16x32_bf16 v[60:63], v[80:83], v[120:123], v[60:63]
	v_mfma_f32_16x16x32_bf16 v[44:47], v[80:83], v[124:127], v[44:47]
	v_mfma_f32_16x16x32_bf16 v[28:31], v[80:83], v[132:135], v[28:31]
	v_mfma_f32_16x16x32_bf16 v[12:15], v[80:83], v[136:139], v[12:15]
	v_mfma_f32_16x16x32_bf16 v[56:59], v[84:87], v[120:123], v[56:59]
	v_mfma_f32_16x16x32_bf16 v[40:43], v[84:87], v[124:127], v[40:43]
	v_mfma_f32_16x16x32_bf16 v[20:23], v[84:87], v[132:135], v[20:23]
	v_mfma_f32_16x16x32_bf16 v[4:7], v[84:87], v[136:139], v[4:7]
	v_mfma_f32_16x16x32_bf16 v[52:55], v[88:91], v[120:123], v[52:55]
	v_mfma_f32_16x16x32_bf16 v[32:35], v[88:91], v[124:127], v[32:35]
	v_mfma_f32_16x16x32_bf16 v[16:19], v[88:91], v[132:135], v[16:19]
	v_mfma_f32_16x16x32_bf16 v[0:3], v[88:91], v[136:139], v[0:3]
	v_mfma_f32_16x16x32_bf16 v[48:51], v[92:95], v[120:123], v[48:51]
	v_mfma_f32_16x16x32_bf16 v[36:39], v[92:95], v[124:127], v[36:39]
	v_mfma_f32_16x16x32_bf16 v[24:27], v[92:95], v[132:135], v[24:27]
	v_mfma_f32_16x16x32_bf16 v[8:11], v[92:95], v[136:139], v[8:11]
	s_nop 7
	s_nop 1
	s_waitcnt vmcnt(7)
	v_sub_co_u32_e32 v64, vcc, s39, v149
	s_nop 0
	v_readfirstlane_b32 s6, v64
	s_lshr_b32 s6, s6, 10
	s_add_i32 s6, s6, 1
	s_and_b64 s[40:41], vcc, exec
	s_cselect_b32 s6, 0, s6
	s_mul_hi_u32 s31, s6, 0x6000
	s_mulk_i32 s6, 0x6000
	v_or_b32_e32 v64, s30, v147
	s_add_u32 s40, s2, s6
	v_ashrrev_i32_e32 v65, 31, v64
	s_addc_u32 s41, s3, s31
	s_waitcnt vmcnt(0)
	v_add_lshl_u32 v94, v148, s39, 12
	v_lshlrev_b64 v[66:67], 2, v[64:65]
	v_lshl_add_u64 v[102:103], s[40:41], 0, v[66:67]
	v_lshl_add_u64 v[134:135], s[4:5], 0, v[66:67]
	v_mov_b32_e32 v95, v97
	v_or_b32_e32 v66, 0x1000, v94
	v_mov_b32_e32 v67, v97
	v_lshl_add_u64 v[104:105], v[134:135], 0, v[94:95]
	global_load_dword v65, v[102:103], off
	global_load_dword v150, v[104:105], off
	v_lshl_add_u64 v[106:107], v[134:135], 0, v[66:67]
	v_or_b32_e32 v68, 0x2000, v94
	v_mov_b32_e32 v69, v97
	v_or_b32_e32 v70, 0x3000, v94
	v_mov_b32_e32 v71, v97
	v_or_b32_e32 v72, 0x10000, v94
	v_mov_b32_e32 v73, v97
	global_load_dword v151, v[106:107], off
	v_lshl_add_u64 v[108:109], v[134:135], 0, v[68:69]
	v_lshl_add_u64 v[110:111], v[134:135], 0, v[70:71]
	v_lshl_add_u64 v[112:113], v[134:135], 0, v[72:73]
	v_or_b32_e32 v74, 0x11000, v94
	v_mov_b32_e32 v75, v97
	global_load_dword v152, v[108:109], off
	global_load_dword v153, v[110:111], off
	global_load_dword v154, v[112:113], off
	v_lshl_add_u64 v[114:115], v[134:135], 0, v[74:75]
	v_or_b32_e32 v76, 0x12000, v94
	v_mov_b32_e32 v77, v97
	v_or_b32_e32 v78, 0x13000, v94
	v_mov_b32_e32 v79, v97
	v_or_b32_e32 v80, 0x20000, v94
	v_mov_b32_e32 v81, v97
	global_load_dword v155, v[114:115], off
	v_or_b32_e32 v96, 0x30000, v94
	v_lshl_add_u64 v[116:117], v[134:135], 0, v[76:77]
	v_lshl_add_u64 v[118:119], v[134:135], 0, v[78:79]
	v_lshl_add_u64 v[120:121], v[134:135], 0, v[80:81]
	v_or_b32_e32 v82, 0x21000, v94
	v_mov_b32_e32 v83, v97
	global_load_dword v156, v[116:117], off
	global_load_dword v157, v[118:119], off
	global_load_dword v158, v[120:121], off
	v_lshl_add_u64 v[122:123], v[134:135], 0, v[82:83]
	v_or_b32_e32 v84, 0x22000, v94
	v_mov_b32_e32 v85, v97
	v_or_b32_e32 v86, 0x23000, v94
	v_mov_b32_e32 v87, v97
	v_lshl_add_u64 v[128:129], v[134:135], 0, v[96:97]
	v_lshl_add_u64 v[124:125], v[134:135], 0, v[84:85]
	v_lshl_add_u64 v[126:127], v[134:135], 0, v[86:87]
	global_load_dword v159, v[122:123], off
	global_load_dword v160, v[124:125], off
	global_load_dword v161, v[126:127], off
	global_load_dword v164, v[128:129], off
	v_or_b32_e32 v88, 0x31000, v94
	v_mov_b32_e32 v89, v97
	v_lshl_add_u64 v[130:131], v[134:135], 0, v[88:89]
	v_or_b32_e32 v90, 0x32000, v94
	v_mov_b32_e32 v91, v97
	v_or_b32_e32 v92, 0x33000, v94
	v_mov_b32_e32 v93, v97
	v_lshl_add_u64 v[132:133], v[134:135], 0, v[90:91]
	v_lshl_add_u64 v[134:135], v[134:135], 0, v[92:93]
	global_load_dword v165, v[130:131], off
	global_load_dword v166, v[132:133], off
	global_load_dword v167, v[134:135], off
	v_or_b32_e32 v136, 16, v64
	v_ashrrev_i32_e32 v137, 31, v136
	v_lshlrev_b64 v[136:137], 2, v[136:137]
	v_lshl_add_u64 v[94:95], s[4:5], 0, v[94:95]
	global_load_dword v168, v[102:103], off offset:64
	v_lshl_add_u64 v[140:141], s[4:5], 0, v[136:137]
	v_lshl_add_u64 v[136:137], v[94:95], 0, v[136:137]
	v_add_f32_e32 v60, 0, v60
	v_lshl_add_u64 v[138:139], v[140:141], 0, v[66:67]
	global_load_dword v169, v[136:137], off
	global_load_dword v170, v[138:139], off
	global_load_dword v171, v[102:103], off offset:128
	global_load_dword v172, v[102:103], off offset:192
	v_lshl_add_u64 v[102:103], v[140:141], 0, v[68:69]
	global_load_dword v173, v[102:103], off
	v_add_f32_e32 v56, 0, v56
	v_add_f32_e32 v58, 0, v58
	v_add_f32_e32 v52, 0, v52
	v_add_f32_e32 v48, 0, v48
	v_add_f32_e32 v44, 0, v44
	v_add_f32_e32 v50, 0, v50
	v_add_f32_e32 v32, 0, v32
	v_add_f32_e32 v34, 0, v34
	v_add_f32_e32 v40, 0, v40
	v_add_f32_e32 v38, 0, v38
	v_add_f32_e32 v36, 0, v36
	v_add_f32_e32 v28, 0, v28
	v_add_f32_e32 v30, 0, v30
	v_add_f32_e32 v20, 0, v20
	s_waitcnt vmcnt(21)
	v_fmac_f32_e32 v150, v60, v65
	v_add_f32_e32 v60, 0, v61
	global_store_dword v[104:105], v150, off
	v_lshl_add_u64 v[104:105], v[140:141], 0, v[72:73]
	v_add_f32_e32 v16, 0, v16
	v_add_f32_e32 v0, 0, v0
	v_add_f32_e32 v12, 0, v12
	v_add_f32_e32 v4, 0, v4
	s_waitcnt vmcnt(21)
	v_fmac_f32_e32 v151, v60, v65
	v_add_f32_e32 v60, 0, v62
	v_add_f32_e32 v62, 0, v63
	global_store_dword v[106:107], v151, off
	v_lshl_add_u64 v[106:107], v[140:141], 0, v[76:77]
	global_load_dword v151, v[104:105], off
	s_waitcnt vmcnt(22)
	v_fmac_f32_e32 v152, v60, v65
	global_store_dword v[108:109], v152, off
	s_waitcnt vmcnt(21)
	v_fmac_f32_e32 v154, v56, v65
	v_add_f32_e32 v56, 0, v57
	v_lshl_add_u64 v[108:109], v[140:141], 0, v[80:81]
	v_lshl_add_u64 v[60:61], v[140:141], 0, v[70:71]
	global_store_dword v[112:113], v154, off
	v_add_f32_e32 v112, 0, v59
	v_fmac_f32_e32 v153, v62, v65
	global_store_dword v[110:111], v153, off
	s_waitcnt vmcnt(22)
	v_fmac_f32_e32 v155, v56, v65
	global_store_dword v[114:115], v155, off
	global_load_dword v155, v[108:109], off
	v_lshl_add_u64 v[62:63], v[140:141], 0, v[74:75]
	global_load_dword v150, v[60:61], off
	global_load_dword v153, v[106:107], off
	v_lshl_add_u64 v[110:111], v[140:141], 0, v[82:83]
	s_waitcnt vmcnt(25)
	v_fmac_f32_e32 v156, v58, v65
	v_lshl_add_u64 v[58:59], v[140:141], 0, v[84:85]
	s_waitcnt vmcnt(23)
	v_fmac_f32_e32 v158, v52, v65
	v_add_f32_e32 v52, 0, v53
	global_store_dword v[116:117], v156, off
	global_load_dword v156, v[58:59], off
	v_fmac_f32_e32 v157, v112, v65
	v_lshl_add_u64 v[112:113], v[140:141], 0, v[86:87]
	global_load_dword v175, v[112:113], off
	s_waitcnt vmcnt(25)
	v_fmac_f32_e32 v159, v52, v65
	v_add_f32_e32 v52, 0, v54
	s_waitcnt vmcnt(24)
	v_fmac_f32_e32 v160, v52, v65
	s_waitcnt vmcnt(22)
	v_fmac_f32_e32 v164, v48, v65
	v_add_f32_e32 v48, 0, v49
	v_lshl_add_u64 v[52:53], v[140:141], 0, v[90:91]
	v_lshl_add_u64 v[114:115], v[140:141], 0, v[96:97]
	global_store_dword v[120:121], v158, off
	global_load_dword v120, v[52:53], off
	v_lshl_add_u64 v[56:57], v[140:141], 0, v[78:79]
	global_load_dword v174, v[110:111], off
	global_load_dword v154, v[56:57], off
	s_waitcnt vmcnt(25)
	v_fmac_f32_e32 v165, v48, v65
	v_lshl_add_u64 v[48:49], v[140:141], 0, v[92:93]
	global_load_dword v121, v[48:49], off
	s_waitcnt vmcnt(25)
	v_fmac_f32_e32 v166, v50, v65
	global_store_dword v[118:119], v157, off
	global_load_dword v118, v[114:115], off
	v_add_f32_e32 v50, 0, v51
	global_load_dword v152, v[62:63], off
	s_waitcnt vmcnt(25)
	v_fmac_f32_e32 v169, v44, v168
	v_add_f32_e32 v44, 0, v45
	s_waitcnt vmcnt(24)
	v_fmac_f32_e32 v170, v44, v168
	v_add_f32_e32 v44, 0, v46
	v_add_f32_e32 v54, 0, v55
	s_waitcnt vmcnt(21)
	v_fmac_f32_e32 v173, v44, v168
	v_or_b32_e32 v44, 32, v64
	v_ashrrev_i32_e32 v45, 31, v44
	v_lshlrev_b64 v[44:45], 2, v[44:45]
	v_fmac_f32_e32 v167, v50, v65
	v_lshl_add_u64 v[50:51], v[94:95], 0, v[44:45]
	v_lshl_add_u64 v[44:45], s[4:5], 0, v[44:45]
	v_fmac_f32_e32 v161, v54, v65
	v_lshl_add_u64 v[54:55], v[44:45], 0, v[78:79]
	v_add_f32_e32 v46, 0, v47
	v_lshl_add_u64 v[116:117], v[140:141], 0, v[88:89]
	global_load_dword v119, v[116:117], off
	v_or_b32_e32 v64, 48, v64
	global_store_dword v[102:103], v173, off
	v_ashrrev_i32_e32 v65, 31, v64
	v_lshlrev_b64 v[64:65], 2, v[64:65]
	global_store_dword v[122:123], v159, off
	global_store_dword v[124:125], v160, off
	global_store_dword v[126:127], v161, off
	global_store_dword v[128:129], v164, off
	global_store_dword v[130:131], v165, off
	global_store_dword v[132:133], v166, off
	global_store_dword v[134:135], v167, off
	global_store_dword v[136:137], v169, off
	global_store_dword v[138:139], v170, off
	v_lshl_add_u64 v[94:95], v[94:95], 0, v[64:65]
	v_lshl_add_u64 v[64:65], s[4:5], 0, v[64:65]
	v_add_f32_e32 v21, 0, v21
	s_waitcnt vmcnt(29)
	v_fmac_f32_e32 v151, v40, v168
	v_add_f32_e32 v40, 0, v41
	global_store_dword v[104:105], v151, off
	s_add_i32 s38, s38, s34
	s_cmpk_gt_i32 s38, 0x1ff
	s_waitcnt vmcnt(25)
	v_fmac_f32_e32 v155, v32, v168
	global_store_dword v[108:109], v155, off
	global_load_dword v109, v[54:55], off
	s_waitcnt vmcnt(26)
	v_fmac_f32_e32 v150, v46, v168
	v_lshl_add_u64 v[46:47], v[44:45], 0, v[66:67]
	global_load_dword v102, v[50:51], off
	global_load_dword v103, v[46:47], off
	v_add_f32_e32 v32, 0, v33
	global_store_dword v[60:61], v150, off
	v_lshl_add_u64 v[60:61], v[44:45], 0, v[88:89]
	s_waitcnt vmcnt(26)
	v_fmac_f32_e32 v156, v34, v168
	global_store_dword v[58:59], v156, off
	v_add_f32_e32 v34, 0, v35
	v_add_f32_e32 v58, 0, v39
	s_waitcnt vmcnt(26)
	v_fmac_f32_e32 v175, v34, v168
	global_store_dword v[112:113], v175, off
	v_lshl_add_u64 v[34:35], v[44:45], 0, v[72:73]
	v_lshl_add_u64 v[66:67], v[64:65], 0, v[66:67]
	s_waitcnt vmcnt(25)
	v_fmac_f32_e32 v120, v38, v168
	global_store_dword v[52:53], v120, off
	s_waitcnt vmcnt(25)
	v_fmac_f32_e32 v174, v32, v168
	v_lshl_add_u64 v[52:53], v[44:45], 0, v[82:83]
	global_store_dword v[110:111], v174, off
	v_lshl_add_u64 v[32:33], v[44:45], 0, v[70:71]
	s_waitcnt vmcnt(24)
	v_fmac_f32_e32 v121, v58, v168
	v_lshl_add_u64 v[58:59], v[44:45], 0, v[86:87]
	global_load_dword v113, v[58:59], off
	global_load_dword v111, v[52:53], off
	s_waitcnt vmcnt(24)
	v_fmac_f32_e32 v118, v36, v168
	s_waitcnt vmcnt(23)
	v_fmac_f32_e32 v152, v40, v168
	v_add_f32_e32 v40, 0, v42
	v_add_f32_e32 v42, 0, v43
	v_fmac_f32_e32 v154, v42, v168
	global_store_dword v[56:57], v154, off
	v_lshl_add_u64 v[56:57], v[44:45], 0, v[80:81]
	global_store_dword v[114:115], v118, off
	global_load_dword v110, v[56:57], off
	global_load_dword v105, v[32:33], off
	v_add_f32_e32 v36, 0, v37
	global_load_dword v115, v[60:61], off
	v_fmac_f32_e32 v153, v40, v168
	v_lshl_add_u64 v[40:41], v[44:45], 0, v[68:69]
	global_load_dword v104, v[40:41], off
	v_lshl_add_u64 v[42:43], v[44:45], 0, v[76:77]
	global_store_dword v[106:107], v153, off
	global_load_dword v106, v[34:35], off
	s_waitcnt vmcnt(30)
	v_fmac_f32_e32 v119, v36, v168
	global_store_dword v[48:49], v121, off
	v_lshl_add_u64 v[48:49], v[44:45], 0, v[96:97]
	global_store_dword v[62:63], v152, off
	v_lshl_add_u64 v[36:37], v[44:45], 0, v[74:75]
	global_store_dword v[116:117], v119, off
	v_lshl_add_u64 v[38:39], v[44:45], 0, v[84:85]
	global_load_dword v114, v[48:49], off
	v_lshl_add_u64 v[62:63], v[44:45], 0, v[90:91]
	global_load_dword v107, v[36:37], off
	global_load_dword v108, v[42:43], off
	global_load_dword v112, v[38:39], off
	v_lshl_add_u64 v[44:45], v[44:45], 0, v[92:93]
	global_load_dword v116, v[62:63], off
	global_load_dword v117, v[44:45], off
	v_lshl_add_u64 v[68:69], v[64:65], 0, v[68:69]
	global_load_dword v120, v[68:69], off
	global_load_dword v118, v[94:95], off
	global_load_dword v119, v[66:67], off
	s_waitcnt vmcnt(28)
	v_fmac_f32_e32 v102, v28, v171
	global_store_dword v[50:51], v102, off
	v_lshl_add_u64 v[50:51], v[64:65], 0, v[70:71]
	v_add_f32_e32 v70, 0, v29
	v_lshl_add_u64 v[28:29], v[64:65], 0, v[72:73]
	s_waitcnt vmcnt(28)
	v_fmac_f32_e32 v103, v70, v171
	v_lshl_add_u64 v[70:71], v[64:65], 0, v[74:75]
	v_lshl_add_u64 v[72:73], v[64:65], 0, v[78:79]
	v_lshl_add_u64 v[74:75], v[64:65], 0, v[80:81]
	global_load_dword v122, v[70:71], off
	global_load_dword v123, v[72:73], off
	global_load_dword v124, v[74:75], off
	global_load_dword v102, v[50:51], off
	global_load_dword v121, v[28:29], off
	v_lshl_add_u64 v[78:79], v[64:65], 0, v[88:89]
	global_store_dword v[46:47], v103, off
	v_lshl_add_u64 v[46:47], v[64:65], 0, v[76:77]
	global_load_dword v103, v[46:47], off
	v_add_f32_e32 v76, 0, v31
	v_lshl_add_u64 v[80:81], v[64:65], 0, v[90:91]
	s_waitcnt vmcnt(25)
	v_fmac_f32_e32 v110, v16, v171
	s_waitcnt vmcnt(24)
	v_fmac_f32_e32 v105, v76, v171
	v_lshl_add_u64 v[76:77], v[64:65], 0, v[86:87]
	global_store_dword v[32:33], v105, off
	v_lshl_add_u64 v[32:33], v[64:65], 0, v[96:97]
	global_load_dword v86, v[78:79], off
	s_waitcnt vmcnt(24)
	v_fmac_f32_e32 v104, v30, v171
	global_store_dword v[40:41], v104, off
	v_lshl_add_u64 v[40:41], v[64:65], 0, v[82:83]
	global_load_dword v82, v[40:41], off
	v_lshl_add_u64 v[30:31], v[64:65], 0, v[84:85]
	global_load_dword v83, v[30:31], off
	global_load_dword v85, v[32:33], off
	global_load_dword v84, v[76:77], off
	s_waitcnt vmcnt(27)
	v_fmac_f32_e32 v106, v20, v171
	global_load_dword v20, v[80:81], off
	v_add_f32_e32 v16, 0, v17
	global_store_dword v[34:35], v106, off
	v_lshl_add_u64 v[34:35], v[64:65], 0, v[92:93]
	global_load_dword v64, v[34:35], off
	v_fmac_f32_e32 v111, v16, v171
	v_add_f32_e32 v16, 0, v18
	s_waitcnt vmcnt(23)
	v_fmac_f32_e32 v112, v16, v171
	v_add_f32_e32 v16, 0, v19
	v_fmac_f32_e32 v113, v16, v171
	v_add_f32_e32 v16, 0, v24
	v_fmac_f32_e32 v114, v16, v171
	v_add_f32_e32 v16, 0, v25
	s_waitcnt vmcnt(19)
	v_fmac_f32_e32 v118, v12, v172
	v_add_f32_e32 v12, 0, v13
	v_fmac_f32_e32 v107, v21, v171
	v_add_f32_e32 v21, 0, v22
	v_fmac_f32_e32 v115, v16, v171
	v_add_f32_e32 v16, 0, v26
	s_waitcnt vmcnt(18)
	v_fmac_f32_e32 v119, v12, v172
	v_add_f32_e32 v12, 0, v14
	v_fmac_f32_e32 v108, v21, v171
	v_add_f32_e32 v21, 0, v23
	v_fmac_f32_e32 v116, v16, v171
	v_add_f32_e32 v16, 0, v27
	v_fmac_f32_e32 v120, v12, v172
	v_add_f32_e32 v12, 0, v15
	v_fmac_f32_e32 v109, v21, v171
	v_fmac_f32_e32 v117, v16, v171
	global_store_dword v[36:37], v107, off
	global_store_dword v[42:43], v108, off
	global_store_dword v[54:55], v109, off
	global_store_dword v[56:57], v110, off
	global_store_dword v[52:53], v111, off
	global_store_dword v[38:39], v112, off
	global_store_dword v[58:59], v113, off
	global_store_dword v[48:49], v114, off
	global_store_dword v[60:61], v115, off
	global_store_dword v[62:63], v116, off
	global_store_dword v[44:45], v117, off
	global_store_dword v[94:95], v118, off
	s_waitcnt vmcnt(26)
	v_fmac_f32_e32 v124, v0, v172
	v_add_f32_e32 v0, 0, v1
	s_waitcnt vmcnt(24)
	v_fmac_f32_e32 v121, v4, v172
	v_add_f32_e32 v4, 0, v5
	v_fmac_f32_e32 v122, v4, v172
	v_add_f32_e32 v4, 0, v6
	s_waitcnt vmcnt(22)
	v_fmac_f32_e32 v103, v4, v172
	v_add_f32_e32 v4, 0, v7
	v_fmac_f32_e32 v102, v12, v172
	v_fmac_f32_e32 v123, v4, v172
	global_store_dword v[66:67], v119, off
	global_store_dword v[68:69], v120, off
	global_store_dword v[50:51], v102, off
	global_store_dword v[28:29], v121, off
	global_store_dword v[70:71], v122, off
	global_store_dword v[46:47], v103, off
	global_store_dword v[72:73], v123, off
	global_store_dword v[74:75], v124, off
	s_waitcnt vmcnt(26)
	v_fmac_f32_e32 v82, v0, v172
	v_add_f32_e32 v0, 0, v2
	s_waitcnt vmcnt(25)
	v_fmac_f32_e32 v83, v0, v172
	v_add_f32_e32 v0, 0, v3
	s_waitcnt vmcnt(23)
	v_fmac_f32_e32 v84, v0, v172
	v_add_f32_e32 v0, 0, v8
	v_fmac_f32_e32 v85, v0, v172
	v_add_f32_e32 v0, 0, v9
	v_fmac_f32_e32 v86, v0, v172
	v_add_f32_e32 v0, 0, v10
	s_waitcnt vmcnt(22)
	v_fmac_f32_e32 v20, v0, v172
	v_add_f32_e32 v0, 0, v11
	s_waitcnt vmcnt(20)
	v_fmac_f32_e32 v64, v0, v172
	global_store_dword v[40:41], v82, off
	global_store_dword v[30:31], v83, off
	global_store_dword v[76:77], v84, off
	global_store_dword v[32:33], v85, off
	global_store_dword v[78:79], v86, off
	global_store_dword v[80:81], v20, off
	global_store_dword v[34:35], v64, off
	s_cbranch_scc0 .LBB0_2295

.LBB0_2474:
	s_cmp_gt_i32 s60, 25
	s_cselect_b64 s[2:3], -1, 0
	s_cmp_lt_i32 s61, 25
	s_cselect_b64 s[4:5], -1, 0
	s_or_b64 s[2:3], s[2:3], s[4:5]
	s_and_b64 vcc, exec, s[2:3]
	s_cbranch_vccnz .LBB0_2534
	s_mov_b64 s[4:5], s[0:1]
	s_cmpk_gt_i32 s58, 0x1ff
	s_cbranch_scc1 .LBB0_2480
	s_load_dwordx2 s[6:7], s[4:5], 0xe0
	v_lshrrev_b32_e32 v8, 3, v162
	v_mul_u32_u24_e32 v0, 0xb00, v8
	v_lshlrev_b32_e32 v96, 1, v0
	v_mov_b32_e32 v97, 0
	s_waitcnt lgkmcnt(0)
	s_add_u32 s2, s6, 0x6b43000
	s_addc_u32 s3, s7, 0
	v_lshlrev_b32_e32 v0, 4, v162
	s_add_u32 s4, s6, 0x6b7a100
	v_and_b32_e32 v0, 0x70, v0
	v_mov_b32_e32 v1, v97
	v_lshl_add_u64 v[2:3], s[6:7], 0, v[96:97]
	s_addc_u32 s5, s7, 0
	v_lshl_add_u64 v[0:1], v[2:3], 0, v[0:1]
	s_mov_b64 s[6:7], 0x9b7a100
	v_xor_b32_e32 v9, v163, v162
	v_lshl_add_u64 v[98:99], v[0:1], 0, s[6:7]
	s_mov_b64 s[6:7], 0x5b80000
	v_lshl_add_u64 v[100:101], v[0:1], 0, s[6:7]
	v_lshlrev_b32_e32 v1, 4, v9
	v_and_b32_e32 v6, 15, v162
	v_bfe_u32 v0, v162, 1, 3
	v_and_b32_e32 v1, 0x70, v1
	v_bfe_u32 v4, v162, 6, 1
	v_lshrrev_b32_e32 v5, 7, v162
	v_bitop3_b32 v0, v163, v0, 3 bitop3:0x6c
	v_lshl_or_b32 v142, v8, 7, v1
	v_lshlrev_b32_e32 v1, 7, v6
	s_load_dword s30, s[0:1], 0xf0
	v_lshl_or_b32 v2, v5, 13, v1
	v_lshl_or_b32 v1, v4, 13, v1
	v_lshlrev_b32_e32 v0, 4, v0
	v_or_b32_e32 v143, v2, v0
	v_or_b32_e32 v144, v1, v0
	v_xor_b32_e32 v0, 64, v0
	v_bfe_u32 v7, v162, 4, 2
	v_or_b32_e32 v145, v2, v0
	v_or_b32_e32 v146, v1, v0
	v_lshlrev_b32_e32 v0, 6, v5
	v_lshl_or_b32 v147, v4, 6, v6
	v_lshl_or_b32 v148, v7, 2, v0
	s_mov_b32 s7, 0
	v_mov_b32_e32 v149, 0x1600
	s_mov_b64 s[8:9], 0x2c000
	s_mov_b32 s31, 0x2c000
	s_mov_b64 s[10:11], 0x58000
	s_mov_b32 s34, 0x58000
	s_mov_b64 s[12:13], 0x84000
	s_mov_b32 s35, 0x84000
	s_mov_b64 s[14:15], 0x84100
	s_mov_b64 s[16:17], 0x58100
	s_mov_b64 s[18:19], 0x2c100
	s_mov_b64 s[20:21], 0x100
	s_mov_b64 s[22:23], 0x200
	s_mov_b64 s[24:25], 0x2c200
	s_mov_b64 s[26:27], 0x58200
	s_mov_b64 s[28:29], 0x84200
	v_mov_b32_e32 v150, 0x1000
	s_mov_b32 s36, s58
	v_and_b32_e32 v240, 63, v162
	v_lshrrev_b32_e32 v247, 6, v162
	v_lshrrev_b32_e32 v242, 3, v240
	v_lshl_add_u32 v242, v247, 5, v242
	v_and_b32_e32 v243, 7, v240
	v_lshrrev_b32_e32 v244, 4, v240
	v_xor_b32_e32 v243, v243, v244
	v_lshlrev_b32_e32 v243, 4, v243
	v_mov_b32_e32 v241, 0x1600
	v_mad_u32_u24 v248, v242, v241, v243
	v_xor_b32_e32 v249, 64, v248
	v_add_u32_e32 v249, 0xb000, v249
	v_add_u32_e32 v250, 0x16000, v248
	v_xor_b32_e32 v251, 64, v248
	v_add_u32_e32 v251, 0x21000, v251
	v_and_b32_e32 v241, 15, v240
	v_lshrrev_b32_e32 v242, 1, v241
	v_xor_b32_e32 v242, v242, v244
	v_lshlrev_b32_e32 v242, 4, v242
	v_lshl_or_b32 v242, v241, 7, v242
	v_lshrrev_b32_e32 v243, 1, v247
	v_lshl_or_b32 v252, v243, 13, v242
	v_xor_b32_e32 v253, 64, v252
	v_and_b32_e32 v243, 1, v247
	v_lshl_or_b32 v254, v243, 13, v242
	v_xor_b32_e32 v255, 64, v254
.LBB0_2477:
	s_lshl_b32 s6, s36, 7
	s_and_b32 s37, s6, 0x1f80
	s_lshl_b32 s6, s36, 1
	s_and_b32 s38, s6, 0xffffff80
	s_mul_i32 s6, s37, 0x1600
	v_lshl_add_u64 v[102:103], v[98:99], 0, s[6:7]
	v_add_co_u32_e32 v38, vcc, 0x2c000, v102
	v_mad_i64_i32 v[104:105], s[40:41], s38, v149, v[100:101]
	s_nop 0
	v_addc_co_u32_e32 v39, vcc, 0, v103, vcc
	v_add_co_u32_e32 v44, vcc, 0x58000, v102
	s_nop 0
	v_addc_co_u32_e32 v45, vcc, 0, v103, vcc
	v_add_co_u32_e32 v46, vcc, 0x84000, v102
	v_addc_co_u32_e32 v47, vcc, 0, v103, vcc
	v_add_co_u32_e32 v48, vcc, s31, v104
	v_addc_co_u32_e32 v49, vcc, 0, v105, vcc
	v_add_co_u32_e32 v50, vcc, s34, v104
	s_nop 0
	v_addc_co_u32_e32 v51, vcc, 0, v105, vcc
	v_add_co_u32_e32 v52, vcc, s35, v104
	s_nop 0
	v_addc_co_u32_e32 v53, vcc, 0, v105, vcc
	s_mov_b32 s39, -2
	v_mov_b32_e32 v8, 0
	v_mov_b32_e32 v9, v97
	v_mov_b32_e32 v10, v97
	v_mov_b32_e32 v11, v97
	v_mov_b32_e32 v24, 0
	v_mov_b32_e32 v25, v97
	v_mov_b32_e32 v26, v97
	v_mov_b32_e32 v27, v97
	v_mov_b32_e32 v36, 0
	v_mov_b32_e32 v37, v97
	v_mov_b32_e32 v38, v97
	v_mov_b32_e32 v39, v97
	v_lshl_add_u64 v[106:107], v[104:105], 0, s[8:9]
	v_lshl_add_u64 v[108:109], v[104:105], 0, s[10:11]
	v_lshl_add_u64 v[110:111], v[104:105], 0, s[12:13]
	v_lshl_add_u64 v[120:121], v[104:105], 0, s[14:15]
	v_lshl_add_u64 v[122:123], v[104:105], 0, s[16:17]
	v_lshl_add_u64 v[124:125], v[104:105], 0, s[18:19]
	v_lshl_add_u64 v[118:119], v[104:105], 0, s[20:21]
	v_lshl_add_u64 v[112:113], v[102:103], 0, s[8:9]
	v_lshl_add_u64 v[114:115], v[102:103], 0, s[10:11]
	v_lshl_add_u64 v[116:117], v[102:103], 0, s[12:13]
	v_lshl_add_u64 v[126:127], v[102:103], 0, s[14:15]
	v_lshl_add_u64 v[128:129], v[102:103], 0, s[16:17]
	v_lshl_add_u64 v[130:131], v[102:103], 0, s[18:19]
	v_lshl_add_u64 v[132:133], v[102:103], 0, s[20:21]
	v_mov_b32_e32 v48, 0
	v_mov_b32_e32 v49, v97
	v_mov_b32_e32 v50, v97
	v_mov_b32_e32 v51, v97
	v_mov_b32_e32 v52, 0
	v_mov_b32_e32 v53, v97
	v_mov_b32_e32 v54, v97
	v_mov_b32_e32 v55, v97
	v_mov_b32_e32 v56, 0
	v_mov_b32_e32 v57, v97
	v_mov_b32_e32 v58, v97
	v_mov_b32_e32 v59, v97
	v_mov_b32_e32 v44, 0
	v_mov_b32_e32 v45, v97
	v_mov_b32_e32 v46, v97
	v_mov_b32_e32 v47, v97
	v_mov_b32_e32 v60, 0
	v_mov_b32_e32 v61, v97
	v_mov_b32_e32 v62, v97
	v_mov_b32_e32 v63, v97
	v_mov_b32_e32 v0, 0
	v_mov_b32_e32 v1, v97
	v_mov_b32_e32 v2, v97
	v_mov_b32_e32 v3, v97
	v_mov_b32_e32 v16, 0
	v_mov_b32_e32 v17, v97
	v_mov_b32_e32 v18, v97
	v_mov_b32_e32 v19, v97
	v_mov_b32_e32 v32, 0
	v_mov_b32_e32 v33, v97
	v_mov_b32_e32 v34, v97
	v_mov_b32_e32 v35, v97
	v_mov_b32_e32 v4, 0
	v_mov_b32_e32 v5, v97
	v_mov_b32_e32 v6, v97
	v_mov_b32_e32 v7, v97
	v_mov_b32_e32 v20, 0
	v_mov_b32_e32 v21, v97
	v_mov_b32_e32 v22, v97
	v_mov_b32_e32 v23, v97
	v_mov_b32_e32 v40, 0
	v_mov_b32_e32 v41, v97
	v_mov_b32_e32 v42, v97
	v_mov_b32_e32 v43, v97
	v_mov_b32_e32 v12, 0
	v_mov_b32_e32 v13, v97
	v_mov_b32_e32 v14, v97
	v_mov_b32_e32 v15, v97
	v_mov_b32_e32 v28, 0
	v_mov_b32_e32 v29, v97
	v_mov_b32_e32 v30, v97
	v_mov_b32_e32 v31, v97
	v_readfirstlane_b32 s40, v102
	v_readfirstlane_b32 s41, v103
	v_readfirstlane_b32 s48, v104
	v_readfirstlane_b32 s49, v105
	v_readfirstlane_b32 s6, v247
	s_nop 3
	s_mul_i32 s39, s6, 0xb000
	s_sub_u32 s40, s40, s39
	s_subb_u32 s41, s41, 0
	s_sub_u32 s48, s48, s39
	s_subb_u32 s49, s49, 0
	s_lshl_b32 s6, s6, 12
	s_add_u32 m0, s6, 0x0
	v_mov_b32_e32 v60, 0
	global_load_lds_dwordx4 v248, s[40:41]
	v_mov_b32_e32 v61, 0
	s_add_u32 m0, s6, 0x400
	v_mov_b32_e32 v62, 0
	global_load_lds_dwordx4 v249, s[40:41]
	v_mov_b32_e32 v63, 0
	s_add_u32 m0, s6, 0x800
	v_mov_b32_e32 v44, 0
	global_load_lds_dwordx4 v250, s[40:41]
	v_mov_b32_e32 v45, 0
	s_add_u32 m0, s6, 0xc00
	v_mov_b32_e32 v46, 0
	global_load_lds_dwordx4 v251, s[40:41]
	v_mov_b32_e32 v47, 0
	s_add_u32 m0, s6, 0x8000
	v_mov_b32_e32 v28, 0
	global_load_lds_dwordx4 v248, s[48:49]
	v_mov_b32_e32 v29, 0
	s_add_u32 m0, s6, 0x8400
	v_mov_b32_e32 v30, 0
	global_load_lds_dwordx4 v249, s[48:49]
	v_mov_b32_e32 v31, 0
	s_add_u32 m0, s6, 0x8800
	v_mov_b32_e32 v12, 0
	global_load_lds_dwordx4 v250, s[48:49]
	v_mov_b32_e32 v13, 0
	s_add_u32 m0, s6, 0x8c00
	v_mov_b32_e32 v14, 0
	global_load_lds_dwordx4 v251, s[48:49]
	v_mov_b32_e32 v15, 0
	s_add_u32 s40, s40, 0x80
	s_addc_u32 s41, s41, 0
	s_add_u32 s48, s48, 0x80
	s_addc_u32 s49, s49, 0
	s_add_u32 m0, s6, 0x4000
	v_mov_b32_e32 v56, 0
	global_load_lds_dwordx4 v248, s[40:41]
	v_mov_b32_e32 v57, 0
	s_add_u32 m0, s6, 0x4400
	v_mov_b32_e32 v58, 0
	global_load_lds_dwordx4 v249, s[40:41]
	v_mov_b32_e32 v59, 0
	s_add_u32 m0, s6, 0x4800
	v_mov_b32_e32 v40, 0
	global_load_lds_dwordx4 v250, s[40:41]
	v_mov_b32_e32 v41, 0
	s_add_u32 m0, s6, 0x4c00
	v_mov_b32_e32 v42, 0
	global_load_lds_dwordx4 v251, s[40:41]
	v_mov_b32_e32 v43, 0
	s_add_u32 m0, s6, 0xc000
	v_mov_b32_e32 v20, 0
	global_load_lds_dwordx4 v248, s[48:49]
	v_mov_b32_e32 v21, 0
	s_add_u32 m0, s6, 0xc400
	v_mov_b32_e32 v22, 0
	global_load_lds_dwordx4 v249, s[48:49]
	v_mov_b32_e32 v23, 0
	s_add_u32 m0, s6, 0xc800
	v_mov_b32_e32 v4, 0
	global_load_lds_dwordx4 v250, s[48:49]
	v_mov_b32_e32 v5, 0
	s_add_u32 m0, s6, 0xcc00
	v_mov_b32_e32 v6, 0
	global_load_lds_dwordx4 v251, s[48:49]
	v_mov_b32_e32 v7, 0
	s_add_u32 s40, s40, 0x80
	s_addc_u32 s41, s41, 0
	s_add_u32 s48, s48, 0x80
	s_addc_u32 s49, s49, 0
	v_mov_b32_e32 v52, 0
	v_mov_b32_e32 v53, 0
	v_mov_b32_e32 v54, 0
	v_mov_b32_e32 v55, 0
	v_mov_b32_e32 v32, 0
	v_mov_b32_e32 v33, 0
	v_mov_b32_e32 v34, 0
	v_mov_b32_e32 v35, 0
	v_mov_b32_e32 v16, 0
	v_mov_b32_e32 v17, 0
	v_mov_b32_e32 v18, 0
	v_mov_b32_e32 v19, 0
	v_mov_b32_e32 v0, 0
	v_mov_b32_e32 v1, 0
	v_mov_b32_e32 v2, 0
	v_mov_b32_e32 v3, 0
	v_mov_b32_e32 v48, 0
	v_mov_b32_e32 v49, 0
	v_mov_b32_e32 v50, 0
	v_mov_b32_e32 v51, 0
	v_mov_b32_e32 v36, 0
	v_mov_b32_e32 v37, 0
	v_mov_b32_e32 v38, 0
	v_mov_b32_e32 v39, 0
	v_mov_b32_e32 v24, 0
	v_mov_b32_e32 v25, 0
	v_mov_b32_e32 v26, 0
	v_mov_b32_e32 v27, 0
	v_mov_b32_e32 v8, 0
	v_mov_b32_e32 v9, 0
	v_mov_b32_e32 v10, 0
	v_mov_b32_e32 v11, 0
	s_mov_b32 s32, 21
.Lg25_loop:
	s_waitcnt vmcnt(8)
	s_barrier
	ds_read_b128 v[64:67], v252 offset:0
	ds_read_b128 v[104:107], v254 offset:32768
	ds_read_b128 v[108:111], v254 offset:34816
	ds_read_b128 v[112:115], v254 offset:36864
	ds_read_b128 v[116:119], v254 offset:38912
	ds_read_b128 v[68:71], v252 offset:2048
	ds_read_b128 v[72:75], v252 offset:4096
	ds_read_b128 v[76:79], v252 offset:6144
	ds_read_b128 v[80:83], v253 offset:0
	ds_read_b128 v[120:123], v255 offset:32768
	ds_read_b128 v[124:127], v255 offset:34816
	ds_read_b128 v[132:135], v255 offset:36864
	ds_read_b128 v[136:139], v255 offset:38912
	s_waitcnt lgkmcnt(11)
	v_mfma_f32_16x16x32_bf16 v[60:63], v[64:67], v[104:107], v[60:63]
	s_waitcnt lgkmcnt(10)
	v_mfma_f32_16x16x32_bf16 v[44:47], v[64:67], v[108:111], v[44:47]
	s_waitcnt lgkmcnt(9)
	v_mfma_f32_16x16x32_bf16 v[28:31], v[64:67], v[112:115], v[28:31]
	s_waitcnt lgkmcnt(8)
	v_mfma_f32_16x16x32_bf16 v[12:15], v[64:67], v[116:119], v[12:15]
	ds_read_b128 v[84:87], v253 offset:2048
	ds_read_b128 v[88:91], v253 offset:4096
	ds_read_b128 v[92:95], v253 offset:6144
	s_waitcnt lgkmcnt(10)
	v_mfma_f32_16x16x32_bf16 v[56:59], v[68:71], v[104:107], v[56:59]
	v_mfma_f32_16x16x32_bf16 v[40:43], v[68:71], v[108:111], v[40:43]
	v_mfma_f32_16x16x32_bf16 v[20:23], v[68:71], v[112:115], v[20:23]
	v_mfma_f32_16x16x32_bf16 v[4:7], v[68:71], v[116:119], v[4:7]
	s_waitcnt lgkmcnt(9)
	v_mfma_f32_16x16x32_bf16 v[52:55], v[72:75], v[104:107], v[52:55]
	v_mfma_f32_16x16x32_bf16 v[32:35], v[72:75], v[108:111], v[32:35]
	v_mfma_f32_16x16x32_bf16 v[16:19], v[72:75], v[112:115], v[16:19]
	v_mfma_f32_16x16x32_bf16 v[0:3], v[72:75], v[116:119], v[0:3]
	s_waitcnt lgkmcnt(8)
	v_mfma_f32_16x16x32_bf16 v[48:51], v[76:79], v[104:107], v[48:51]
	v_mfma_f32_16x16x32_bf16 v[36:39], v[76:79], v[108:111], v[36:39]
	v_mfma_f32_16x16x32_bf16 v[24:27], v[76:79], v[112:115], v[24:27]
	v_mfma_f32_16x16x32_bf16 v[8:11], v[76:79], v[116:119], v[8:11]
	s_waitcnt lgkmcnt(0)
	s_barrier
	s_add_u32 m0, s6, 0x0
	v_mfma_f32_16x16x32_bf16 v[60:63], v[80:83], v[120:123], v[60:63]
	global_load_lds_dwordx4 v248, s[40:41]
	v_mfma_f32_16x16x32_bf16 v[44:47], v[80:83], v[124:127], v[44:47]
	s_add_u32 m0, s6, 0x400
	v_mfma_f32_16x16x32_bf16 v[28:31], v[80:83], v[132:135], v[28:31]
	global_load_lds_dwordx4 v249, s[40:41]
	v_mfma_f32_16x16x32_bf16 v[12:15], v[80:83], v[136:139], v[12:15]
	s_add_u32 m0, s6, 0x800
	v_mfma_f32_16x16x32_bf16 v[56:59], v[84:87], v[120:123], v[56:59]
	global_load_lds_dwordx4 v250, s[40:41]
	v_mfma_f32_16x16x32_bf16 v[40:43], v[84:87], v[124:127], v[40:43]
	s_add_u32 m0, s6, 0xc00
	v_mfma_f32_16x16x32_bf16 v[20:23], v[84:87], v[132:135], v[20:23]
	global_load_lds_dwordx4 v251, s[40:41]
	v_mfma_f32_16x16x32_bf16 v[4:7], v[84:87], v[136:139], v[4:7]
	s_add_u32 m0, s6, 0x8000
	v_mfma_f32_16x16x32_bf16 v[52:55], v[88:91], v[120:123], v[52:55]
	global_load_lds_dwordx4 v248, s[48:49]
	v_mfma_f32_16x16x32_bf16 v[32:35], v[88:91], v[124:127], v[32:35]
	s_add_u32 m0, s6, 0x8400
	v_mfma_f32_16x16x32_bf16 v[16:19], v[88:91], v[132:135], v[16:19]
	global_load_lds_dwordx4 v249, s[48:49]
	v_mfma_f32_16x16x32_bf16 v[0:3], v[88:91], v[136:139], v[0:3]
	s_add_u32 m0, s6, 0x8800
	v_mfma_f32_16x16x32_bf16 v[48:51], v[92:95], v[120:123], v[48:51]
	global_load_lds_dwordx4 v250, s[48:49]
	v_mfma_f32_16x16x32_bf16 v[36:39], v[92:95], v[124:127], v[36:39]
	s_add_u32 m0, s6, 0x8c00
	v_mfma_f32_16x16x32_bf16 v[24:27], v[92:95], v[132:135], v[24:27]
	global_load_lds_dwordx4 v251, s[48:49]
	v_mfma_f32_16x16x32_bf16 v[8:11], v[92:95], v[136:139], v[8:11]
	s_add_u32 s40, s40, 0x80
	s_addc_u32 s41, s41, 0
	s_add_u32 s48, s48, 0x80
	s_addc_u32 s49, s49, 0
	s_waitcnt vmcnt(8)
	s_barrier
	ds_read_b128 v[64:67], v252 offset:16384
	ds_read_b128 v[104:107], v254 offset:49152
	ds_read_b128 v[108:111], v254 offset:51200
	ds_read_b128 v[112:115], v254 offset:53248
	ds_read_b128 v[116:119], v254 offset:55296
	ds_read_b128 v[68:71], v252 offset:18432
	ds_read_b128 v[72:75], v252 offset:20480
	ds_read_b128 v[76:79], v252 offset:22528
	ds_read_b128 v[80:83], v253 offset:16384
	ds_read_b128 v[120:123], v255 offset:49152
	ds_read_b128 v[124:127], v255 offset:51200
	ds_read_b128 v[132:135], v255 offset:53248
	ds_read_b128 v[136:139], v255 offset:55296
	s_waitcnt lgkmcnt(11)
	v_mfma_f32_16x16x32_bf16 v[60:63], v[64:67], v[104:107], v[60:63]
	s_waitcnt lgkmcnt(10)
	v_mfma_f32_16x16x32_bf16 v[44:47], v[64:67], v[108:111], v[44:47]
	s_waitcnt lgkmcnt(9)
	v_mfma_f32_16x16x32_bf16 v[28:31], v[64:67], v[112:115], v[28:31]
	s_waitcnt lgkmcnt(8)
	v_mfma_f32_16x16x32_bf16 v[12:15], v[64:67], v[116:119], v[12:15]
	ds_read_b128 v[84:87], v253 offset:18432
	ds_read_b128 v[88:91], v253 offset:20480
	ds_read_b128 v[92:95], v253 offset:22528
	s_waitcnt lgkmcnt(10)
	v_mfma_f32_16x16x32_bf16 v[56:59], v[68:71], v[104:107], v[56:59]
	v_mfma_f32_16x16x32_bf16 v[40:43], v[68:71], v[108:111], v[40:43]
	v_mfma_f32_16x16x32_bf16 v[20:23], v[68:71], v[112:115], v[20:23]
	v_mfma_f32_16x16x32_bf16 v[4:7], v[68:71], v[116:119], v[4:7]
	s_waitcnt lgkmcnt(9)
	v_mfma_f32_16x16x32_bf16 v[52:55], v[72:75], v[104:107], v[52:55]
	v_mfma_f32_16x16x32_bf16 v[32:35], v[72:75], v[108:111], v[32:35]
	v_mfma_f32_16x16x32_bf16 v[16:19], v[72:75], v[112:115], v[16:19]
	v_mfma_f32_16x16x32_bf16 v[0:3], v[72:75], v[116:119], v[0:3]
	s_waitcnt lgkmcnt(8)
	v_mfma_f32_16x16x32_bf16 v[48:51], v[76:79], v[104:107], v[48:51]
	v_mfma_f32_16x16x32_bf16 v[36:39], v[76:79], v[108:111], v[36:39]
	v_mfma_f32_16x16x32_bf16 v[24:27], v[76:79], v[112:115], v[24:27]
	v_mfma_f32_16x16x32_bf16 v[8:11], v[76:79], v[116:119], v[8:11]
	s_waitcnt lgkmcnt(0)
	s_barrier
	s_add_u32 m0, s6, 0x4000
	v_mfma_f32_16x16x32_bf16 v[60:63], v[80:83], v[120:123], v[60:63]
	global_load_lds_dwordx4 v248, s[40:41]
	v_mfma_f32_16x16x32_bf16 v[44:47], v[80:83], v[124:127], v[44:47]
	s_add_u32 m0, s6, 0x4400
	v_mfma_f32_16x16x32_bf16 v[28:31], v[80:83], v[132:135], v[28:31]
	global_load_lds_dwordx4 v249, s[40:41]
	v_mfma_f32_16x16x32_bf16 v[12:15], v[80:83], v[136:139], v[12:15]
	s_add_u32 m0, s6, 0x4800
	v_mfma_f32_16x16x32_bf16 v[56:59], v[84:87], v[120:123], v[56:59]
	global_load_lds_dwordx4 v250, s[40:41]
	v_mfma_f32_16x16x32_bf16 v[40:43], v[84:87], v[124:127], v[40:43]
	s_add_u32 m0, s6, 0x4c00
	v_mfma_f32_16x16x32_bf16 v[20:23], v[84:87], v[132:135], v[20:23]
	global_load_lds_dwordx4 v251, s[40:41]
	v_mfma_f32_16x16x32_bf16 v[4:7], v[84:87], v[136:139], v[4:7]
	s_add_u32 m0, s6, 0xc000
	v_mfma_f32_16x16x32_bf16 v[52:55], v[88:91], v[120:123], v[52:55]
	global_load_lds_dwordx4 v248, s[48:49]
	v_mfma_f32_16x16x32_bf16 v[32:35], v[88:91], v[124:127], v[32:35]
	s_add_u32 m0, s6, 0xc400
	v_mfma_f32_16x16x32_bf16 v[16:19], v[88:91], v[132:135], v[16:19]
	global_load_lds_dwordx4 v249, s[48:49]
	v_mfma_f32_16x16x32_bf16 v[0:3], v[88:91], v[136:139], v[0:3]
	s_add_u32 m0, s6, 0xc800
	v_mfma_f32_16x16x32_bf16 v[48:51], v[92:95], v[120:123], v[48:51]
	global_load_lds_dwordx4 v250, s[48:49]
	v_mfma_f32_16x16x32_bf16 v[36:39], v[92:95], v[124:127], v[36:39]
	s_add_u32 m0, s6, 0xcc00
	v_mfma_f32_16x16x32_bf16 v[24:27], v[92:95], v[132:135], v[24:27]
	global_load_lds_dwordx4 v251, s[48:49]
	v_mfma_f32_16x16x32_bf16 v[8:11], v[92:95], v[136:139], v[8:11]
	s_add_u32 s40, s40, 0x80
	s_addc_u32 s41, s41, 0
	s_add_u32 s48, s48, 0x80
	s_addc_u32 s49, s49, 0
	s_sub_u32 s32, s32, 1
	s_cmp_lg_u32 s32, 0
	s_cbranch_scc1 .Lg25_loop
	s_waitcnt vmcnt(8)
	s_barrier
	ds_read_b128 v[64:67], v252 offset:0
	ds_read_b128 v[104:107], v254 offset:32768
	ds_read_b128 v[108:111], v254 offset:34816
	ds_read_b128 v[112:115], v254 offset:36864
	ds_read_b128 v[116:119], v254 offset:38912
	ds_read_b128 v[68:71], v252 offset:2048
	ds_read_b128 v[72:75], v252 offset:4096
	ds_read_b128 v[76:79], v252 offset:6144
	ds_read_b128 v[80:83], v253 offset:0
	ds_read_b128 v[120:123], v255 offset:32768
	ds_read_b128 v[124:127], v255 offset:34816
	ds_read_b128 v[132:135], v255 offset:36864
	ds_read_b128 v[136:139], v255 offset:38912
	s_waitcnt lgkmcnt(11)
	v_mfma_f32_16x16x32_bf16 v[60:63], v[64:67], v[104:107], v[60:63]
	s_waitcnt lgkmcnt(10)
	v_mfma_f32_16x16x32_bf16 v[44:47], v[64:67], v[108:111], v[44:47]
	s_waitcnt lgkmcnt(9)
	v_mfma_f32_16x16x32_bf16 v[28:31], v[64:67], v[112:115], v[28:31]
	s_waitcnt lgkmcnt(8)
	v_mfma_f32_16x16x32_bf16 v[12:15], v[64:67], v[116:119], v[12:15]
	ds_read_b128 v[84:87], v253 offset:2048
	ds_read_b128 v[88:91], v253 offset:4096
	ds_read_b128 v[92:95], v253 offset:6144
	s_waitcnt lgkmcnt(10)
	v_mfma_f32_16x16x32_bf16 v[56:59], v[68:71], v[104:107], v[56:59]
	v_mfma_f32_16x16x32_bf16 v[40:43], v[68:71], v[108:111], v[40:43]
	v_mfma_f32_16x16x32_bf16 v[20:23], v[68:71], v[112:115], v[20:23]
	v_mfma_f32_16x16x32_bf16 v[4:7], v[68:71], v[116:119], v[4:7]
	s_waitcnt lgkmcnt(9)
	v_mfma_f32_16x16x32_bf16 v[52:55], v[72:75], v[104:107], v[52:55]
	v_mfma_f32_16x16x32_bf16 v[32:35], v[72:75], v[108:111], v[32:35]
	v_mfma_f32_16x16x32_bf16 v[16:19], v[72:75], v[112:115], v[16:19]
	v_mfma_f32_16x16x32_bf16 v[0:3], v[72:75], v[116:119], v[0:3]
	s_waitcnt lgkmcnt(8)
	v_mfma_f32_16x16x32_bf16 v[48:51], v[76:79], v[104:107], v[48:51]
	v_mfma_f32_16x16x32_bf16 v[36:39], v[76:79], v[108:111], v[36:39]
	v_mfma_f32_16x16x32_bf16 v[24:27], v[76:79], v[112:115], v[24:27]
	v_mfma_f32_16x16x32_bf16 v[8:11], v[76:79], v[116:119], v[8:11]
	s_waitcnt lgkmcnt(0)
	s_barrier
	v_mfma_f32_16x16x32_bf16 v[60:63], v[80:83], v[120:123], v[60:63]
	v_mfma_f32_16x16x32_bf16 v[44:47], v[80:83], v[124:127], v[44:47]
	v_mfma_f32_16x16x32_bf16 v[28:31], v[80:83], v[132:135], v[28:31]
	v_mfma_f32_16x16x32_bf16 v[12:15], v[80:83], v[136:139], v[12:15]
	v_mfma_f32_16x16x32_bf16 v[56:59], v[84:87], v[120:123], v[56:59]
	v_mfma_f32_16x16x32_bf16 v[40:43], v[84:87], v[124:127], v[40:43]
	v_mfma_f32_16x16x32_bf16 v[20:23], v[84:87], v[132:135], v[20:23]
	v_mfma_f32_16x16x32_bf16 v[4:7], v[84:87], v[136:139], v[4:7]
	v_mfma_f32_16x16x32_bf16 v[52:55], v[88:91], v[120:123], v[52:55]
	v_mfma_f32_16x16x32_bf16 v[32:35], v[88:91], v[124:127], v[32:35]
	v_mfma_f32_16x16x32_bf16 v[16:19], v[88:91], v[132:135], v[16:19]
	v_mfma_f32_16x16x32_bf16 v[0:3], v[88:91], v[136:139], v[0:3]
	v_mfma_f32_16x16x32_bf16 v[48:51], v[92:95], v[120:123], v[48:51]
	v_mfma_f32_16x16x32_bf16 v[36:39], v[92:95], v[124:127], v[36:39]
	v_mfma_f32_16x16x32_bf16 v[24:27], v[92:95], v[132:135], v[24:27]
	v_mfma_f32_16x16x32_bf16 v[8:11], v[92:95], v[136:139], v[8:11]
	s_waitcnt vmcnt(0)
	s_barrier
	ds_read_b128 v[64:67], v252 offset:16384
	ds_read_b128 v[104:107], v254 offset:49152
	ds_read_b128 v[108:111], v254 offset:51200
	ds_read_b128 v[112:115], v254 offset:53248
	ds_read_b128 v[116:119], v254 offset:55296
	ds_read_b128 v[68:71], v252 offset:18432
	ds_read_b128 v[72:75], v252 offset:20480
	ds_read_b128 v[76:79], v252 offset:22528
	ds_read_b128 v[80:83], v253 offset:16384
	ds_read_b128 v[120:123], v255 offset:49152
	ds_read_b128 v[124:127], v255 offset:51200
	ds_read_b128 v[132:135], v255 offset:53248
	ds_read_b128 v[136:139], v255 offset:55296
	s_waitcnt lgkmcnt(11)
	v_mfma_f32_16x16x32_bf16 v[60:63], v[64:67], v[104:107], v[60:63]
	s_waitcnt lgkmcnt(10)
	v_mfma_f32_16x16x32_bf16 v[44:47], v[64:67], v[108:111], v[44:47]
	s_waitcnt lgkmcnt(9)
	v_mfma_f32_16x16x32_bf16 v[28:31], v[64:67], v[112:115], v[28:31]
	s_waitcnt lgkmcnt(8)
	v_mfma_f32_16x16x32_bf16 v[12:15], v[64:67], v[116:119], v[12:15]
	ds_read_b128 v[84:87], v253 offset:18432
	ds_read_b128 v[88:91], v253 offset:20480
	ds_read_b128 v[92:95], v253 offset:22528
	s_waitcnt lgkmcnt(10)
	v_mfma_f32_16x16x32_bf16 v[56:59], v[68:71], v[104:107], v[56:59]
	v_mfma_f32_16x16x32_bf16 v[40:43], v[68:71], v[108:111], v[40:43]
	v_mfma_f32_16x16x32_bf16 v[20:23], v[68:71], v[112:115], v[20:23]
	v_mfma_f32_16x16x32_bf16 v[4:7], v[68:71], v[116:119], v[4:7]
	s_waitcnt lgkmcnt(9)
	v_mfma_f32_16x16x32_bf16 v[52:55], v[72:75], v[104:107], v[52:55]
	v_mfma_f32_16x16x32_bf16 v[32:35], v[72:75], v[108:111], v[32:35]
	v_mfma_f32_16x16x32_bf16 v[16:19], v[72:75], v[112:115], v[16:19]
	v_mfma_f32_16x16x32_bf16 v[0:3], v[72:75], v[116:119], v[0:3]
	s_waitcnt lgkmcnt(8)
	v_mfma_f32_16x16x32_bf16 v[48:51], v[76:79], v[104:107], v[48:51]
	v_mfma_f32_16x16x32_bf16 v[36:39], v[76:79], v[108:111], v[36:39]
	v_mfma_f32_16x16x32_bf16 v[24:27], v[76:79], v[112:115], v[24:27]
	v_mfma_f32_16x16x32_bf16 v[8:11], v[76:79], v[116:119], v[8:11]
	s_waitcnt lgkmcnt(0)
	s_barrier
	v_mfma_f32_16x16x32_bf16 v[60:63], v[80:83], v[120:123], v[60:63]
	v_mfma_f32_16x16x32_bf16 v[44:47], v[80:83], v[124:127], v[44:47]
	v_mfma_f32_16x16x32_bf16 v[28:31], v[80:83], v[132:135], v[28:31]
	v_mfma_f32_16x16x32_bf16 v[12:15], v[80:83], v[136:139], v[12:15]
	v_mfma_f32_16x16x32_bf16 v[56:59], v[84:87], v[120:123], v[56:59]
	v_mfma_f32_16x16x32_bf16 v[40:43], v[84:87], v[124:127], v[40:43]
	v_mfma_f32_16x16x32_bf16 v[20:23], v[84:87], v[132:135], v[20:23]
	v_mfma_f32_16x16x32_bf16 v[4:7], v[84:87], v[136:139], v[4:7]
	v_mfma_f32_16x16x32_bf16 v[52:55], v[88:91], v[120:123], v[52:55]
	v_mfma_f32_16x16x32_bf16 v[32:35], v[88:91], v[124:127], v[32:35]
	v_mfma_f32_16x16x32_bf16 v[16:19], v[88:91], v[132:135], v[16:19]
	v_mfma_f32_16x16x32_bf16 v[0:3], v[88:91], v[136:139], v[0:3]
	v_mfma_f32_16x16x32_bf16 v[48:51], v[92:95], v[120:123], v[48:51]
	v_mfma_f32_16x16x32_bf16 v[36:39], v[92:95], v[124:127], v[36:39]
	v_mfma_f32_16x16x32_bf16 v[24:27], v[92:95], v[132:135], v[24:27]
	v_mfma_f32_16x16x32_bf16 v[8:11], v[92:95], v[136:139], v[8:11]
	s_nop 7
	s_nop 1
	s_waitcnt vmcnt(7)
	v_sub_co_u32_e32 v64, vcc, s37, v150
	s_nop 0
	v_readfirstlane_b32 s6, v64
	s_lshr_b32 s6, s6, 10
	s_add_i32 s6, s6, 1
	s_and_b64 s[40:41], vcc, exec
	s_cselect_b32 s6, 0, s6
	s_mul_hi_u32 s39, s6, 0x6000
	s_mulk_i32 s6, 0x6000
	v_or_b32_e32 v64, s38, v147
	s_add_u32 s40, s2, s6
	v_ashrrev_i32_e32 v65, 31, v64
	s_addc_u32 s41, s3, s39
	s_waitcnt vmcnt(0)
	v_add_lshl_u32 v94, v148, s37, 12
	v_lshlrev_b64 v[66:67], 2, v[64:65]
	v_lshl_add_u64 v[102:103], s[40:41], 0, v[66:67]
	v_lshl_add_u64 v[134:135], s[4:5], 0, v[66:67]
	v_mov_b32_e32 v95, v97
	v_or_b32_e32 v66, 0x1000, v94
	v_mov_b32_e32 v67, v97
	v_lshl_add_u64 v[104:105], v[134:135], 0, v[94:95]
	global_load_dword v65, v[102:103], off
	global_load_dword v151, v[104:105], off
	v_lshl_add_u64 v[106:107], v[134:135], 0, v[66:67]
	v_or_b32_e32 v68, 0x2000, v94
	v_mov_b32_e32 v69, v97
	v_or_b32_e32 v70, 0x3000, v94
	v_mov_b32_e32 v71, v97
	v_or_b32_e32 v72, 0x10000, v94
	v_mov_b32_e32 v73, v97
	global_load_dword v152, v[106:107], off
	v_lshl_add_u64 v[108:109], v[134:135], 0, v[68:69]
	v_lshl_add_u64 v[110:111], v[134:135], 0, v[70:71]
	v_lshl_add_u64 v[112:113], v[134:135], 0, v[72:73]
	v_or_b32_e32 v74, 0x11000, v94
	v_mov_b32_e32 v75, v97
	global_load_dword v153, v[108:109], off
	global_load_dword v154, v[110:111], off
	global_load_dword v155, v[112:113], off
	v_lshl_add_u64 v[114:115], v[134:135], 0, v[74:75]
	v_or_b32_e32 v76, 0x12000, v94
	v_mov_b32_e32 v77, v97
	v_or_b32_e32 v78, 0x13000, v94
	v_mov_b32_e32 v79, v97
	v_or_b32_e32 v80, 0x20000, v94
	v_mov_b32_e32 v81, v97
	global_load_dword v156, v[114:115], off
	v_or_b32_e32 v96, 0x30000, v94
	v_lshl_add_u64 v[116:117], v[134:135], 0, v[76:77]
	v_lshl_add_u64 v[118:119], v[134:135], 0, v[78:79]
	v_lshl_add_u64 v[120:121], v[134:135], 0, v[80:81]
	v_or_b32_e32 v82, 0x21000, v94
	v_mov_b32_e32 v83, v97
	global_load_dword v157, v[116:117], off
	global_load_dword v158, v[118:119], off
	global_load_dword v159, v[120:121], off
	v_lshl_add_u64 v[122:123], v[134:135], 0, v[82:83]
	v_or_b32_e32 v84, 0x22000, v94
	v_mov_b32_e32 v85, v97
	v_or_b32_e32 v86, 0x23000, v94
	v_mov_b32_e32 v87, v97
	v_lshl_add_u64 v[128:129], v[134:135], 0, v[96:97]
	v_lshl_add_u64 v[124:125], v[134:135], 0, v[84:85]
	v_lshl_add_u64 v[126:127], v[134:135], 0, v[86:87]
	global_load_dword v160, v[122:123], off
	global_load_dword v161, v[124:125], off
	global_load_dword v164, v[126:127], off
	global_load_dword v165, v[128:129], off
	v_or_b32_e32 v88, 0x31000, v94
	v_mov_b32_e32 v89, v97
	v_lshl_add_u64 v[130:131], v[134:135], 0, v[88:89]
	v_or_b32_e32 v90, 0x32000, v94
	v_mov_b32_e32 v91, v97
	v_or_b32_e32 v92, 0x33000, v94
	v_mov_b32_e32 v93, v97
	v_lshl_add_u64 v[132:133], v[134:135], 0, v[90:91]
	v_lshl_add_u64 v[134:135], v[134:135], 0, v[92:93]
	global_load_dword v166, v[130:131], off
	global_load_dword v167, v[132:133], off
	global_load_dword v168, v[134:135], off
	v_or_b32_e32 v136, 16, v64
	v_ashrrev_i32_e32 v137, 31, v136
	v_lshlrev_b64 v[136:137], 2, v[136:137]
	v_lshl_add_u64 v[94:95], s[4:5], 0, v[94:95]
	global_load_dword v169, v[102:103], off offset:64
	v_lshl_add_u64 v[140:141], s[4:5], 0, v[136:137]
	v_lshl_add_u64 v[136:137], v[94:95], 0, v[136:137]
	v_add_f32_e32 v60, 0, v60
	v_lshl_add_u64 v[138:139], v[140:141], 0, v[66:67]
	global_load_dword v170, v[136:137], off
	global_load_dword v171, v[138:139], off
	global_load_dword v172, v[102:103], off offset:128
	global_load_dword v173, v[102:103], off offset:192
	v_lshl_add_u64 v[102:103], v[140:141], 0, v[68:69]
	global_load_dword v174, v[102:103], off
	v_add_f32_e32 v56, 0, v56
	v_add_f32_e32 v58, 0, v58
	v_add_f32_e32 v52, 0, v52
	v_add_f32_e32 v48, 0, v48
	v_add_f32_e32 v44, 0, v44
	v_add_f32_e32 v50, 0, v50
	v_add_f32_e32 v32, 0, v32
	v_add_f32_e32 v34, 0, v34
	v_add_f32_e32 v40, 0, v40
	v_add_f32_e32 v38, 0, v38
	v_add_f32_e32 v36, 0, v36
	v_add_f32_e32 v28, 0, v28
	v_add_f32_e32 v30, 0, v30
	v_add_f32_e32 v20, 0, v20
	s_waitcnt vmcnt(21)
	v_fmac_f32_e32 v151, v60, v65
	v_add_f32_e32 v60, 0, v61
	global_store_dword v[104:105], v151, off
	v_lshl_add_u64 v[104:105], v[140:141], 0, v[72:73]
	v_add_f32_e32 v16, 0, v16
	v_add_f32_e32 v0, 0, v0
	v_add_f32_e32 v12, 0, v12
	v_add_f32_e32 v4, 0, v4
	s_waitcnt vmcnt(21)
	v_fmac_f32_e32 v152, v60, v65
	v_add_f32_e32 v60, 0, v62
	v_add_f32_e32 v62, 0, v63
	global_store_dword v[106:107], v152, off
	v_lshl_add_u64 v[106:107], v[140:141], 0, v[76:77]
	global_load_dword v152, v[104:105], off
	s_waitcnt vmcnt(22)
	v_fmac_f32_e32 v153, v60, v65
	global_store_dword v[108:109], v153, off
	s_waitcnt vmcnt(21)
	v_fmac_f32_e32 v155, v56, v65
	v_add_f32_e32 v56, 0, v57
	v_lshl_add_u64 v[108:109], v[140:141], 0, v[80:81]
	v_lshl_add_u64 v[60:61], v[140:141], 0, v[70:71]
	global_store_dword v[112:113], v155, off
	v_add_f32_e32 v112, 0, v59
	v_fmac_f32_e32 v154, v62, v65
	global_store_dword v[110:111], v154, off
	s_waitcnt vmcnt(22)
	v_fmac_f32_e32 v156, v56, v65
	global_store_dword v[114:115], v156, off
	global_load_dword v156, v[108:109], off
	v_lshl_add_u64 v[62:63], v[140:141], 0, v[74:75]
	global_load_dword v151, v[60:61], off
	global_load_dword v154, v[106:107], off
	v_lshl_add_u64 v[110:111], v[140:141], 0, v[82:83]
	s_waitcnt vmcnt(25)
	v_fmac_f32_e32 v157, v58, v65
	v_lshl_add_u64 v[58:59], v[140:141], 0, v[84:85]
	s_waitcnt vmcnt(23)
	v_fmac_f32_e32 v159, v52, v65
	v_add_f32_e32 v52, 0, v53
	global_store_dword v[116:117], v157, off
	global_load_dword v157, v[58:59], off
	v_fmac_f32_e32 v158, v112, v65
	v_lshl_add_u64 v[112:113], v[140:141], 0, v[86:87]
	global_load_dword v176, v[112:113], off
	s_waitcnt vmcnt(25)
	v_fmac_f32_e32 v160, v52, v65
	v_add_f32_e32 v52, 0, v54
	s_waitcnt vmcnt(24)
	v_fmac_f32_e32 v161, v52, v65
	s_waitcnt vmcnt(22)
	v_fmac_f32_e32 v165, v48, v65
	v_add_f32_e32 v48, 0, v49
	v_lshl_add_u64 v[52:53], v[140:141], 0, v[90:91]
	v_lshl_add_u64 v[114:115], v[140:141], 0, v[96:97]
	global_store_dword v[120:121], v159, off
	global_load_dword v120, v[52:53], off
	v_lshl_add_u64 v[56:57], v[140:141], 0, v[78:79]
	global_load_dword v175, v[110:111], off
	global_load_dword v155, v[56:57], off
	s_waitcnt vmcnt(25)
	v_fmac_f32_e32 v166, v48, v65
	v_lshl_add_u64 v[48:49], v[140:141], 0, v[92:93]
	global_load_dword v121, v[48:49], off
	s_waitcnt vmcnt(25)
	v_fmac_f32_e32 v167, v50, v65
	global_store_dword v[118:119], v158, off
	global_load_dword v118, v[114:115], off
	v_add_f32_e32 v50, 0, v51
	global_load_dword v153, v[62:63], off
	s_waitcnt vmcnt(25)
	v_fmac_f32_e32 v170, v44, v169
	v_add_f32_e32 v44, 0, v45
	s_waitcnt vmcnt(24)
	v_fmac_f32_e32 v171, v44, v169
	v_add_f32_e32 v44, 0, v46
	v_add_f32_e32 v54, 0, v55
	s_waitcnt vmcnt(21)
	v_fmac_f32_e32 v174, v44, v169
	v_or_b32_e32 v44, 32, v64
	v_ashrrev_i32_e32 v45, 31, v44
	v_lshlrev_b64 v[44:45], 2, v[44:45]
	v_fmac_f32_e32 v168, v50, v65
	v_lshl_add_u64 v[50:51], v[94:95], 0, v[44:45]
	v_lshl_add_u64 v[44:45], s[4:5], 0, v[44:45]
	v_fmac_f32_e32 v164, v54, v65
	v_lshl_add_u64 v[54:55], v[44:45], 0, v[78:79]
	v_add_f32_e32 v46, 0, v47
	v_lshl_add_u64 v[116:117], v[140:141], 0, v[88:89]
	global_load_dword v119, v[116:117], off
	v_or_b32_e32 v64, 48, v64
	global_store_dword v[102:103], v174, off
	v_ashrrev_i32_e32 v65, 31, v64
	v_lshlrev_b64 v[64:65], 2, v[64:65]
	global_store_dword v[122:123], v160, off
	global_store_dword v[124:125], v161, off
	global_store_dword v[126:127], v164, off
	global_store_dword v[128:129], v165, off
	global_store_dword v[130:131], v166, off
	global_store_dword v[132:133], v167, off
	global_store_dword v[134:135], v168, off
	global_store_dword v[136:137], v170, off
	global_store_dword v[138:139], v171, off
	v_lshl_add_u64 v[94:95], v[94:95], 0, v[64:65]
	v_lshl_add_u64 v[64:65], s[4:5], 0, v[64:65]
	v_add_f32_e32 v21, 0, v21
	s_waitcnt vmcnt(29)
	v_fmac_f32_e32 v152, v40, v169
	v_add_f32_e32 v40, 0, v41
	global_store_dword v[104:105], v152, off
	s_add_i32 s36, s36, s30
	s_cmpk_gt_i32 s36, 0x1ff
	s_waitcnt vmcnt(25)
	v_fmac_f32_e32 v156, v32, v169
	global_store_dword v[108:109], v156, off
	global_load_dword v109, v[54:55], off
	s_waitcnt vmcnt(26)
	v_fmac_f32_e32 v151, v46, v169
	v_lshl_add_u64 v[46:47], v[44:45], 0, v[66:67]
	global_load_dword v102, v[50:51], off
	global_load_dword v103, v[46:47], off
	v_add_f32_e32 v32, 0, v33
	global_store_dword v[60:61], v151, off
	v_lshl_add_u64 v[60:61], v[44:45], 0, v[88:89]
	s_waitcnt vmcnt(26)
	v_fmac_f32_e32 v157, v34, v169
	global_store_dword v[58:59], v157, off
	v_add_f32_e32 v34, 0, v35
	v_add_f32_e32 v58, 0, v39
	s_waitcnt vmcnt(26)
	v_fmac_f32_e32 v176, v34, v169
	global_store_dword v[112:113], v176, off
	v_lshl_add_u64 v[34:35], v[44:45], 0, v[72:73]
	v_lshl_add_u64 v[66:67], v[64:65], 0, v[66:67]
	s_waitcnt vmcnt(25)
	v_fmac_f32_e32 v120, v38, v169
	global_store_dword v[52:53], v120, off
	s_waitcnt vmcnt(25)
	v_fmac_f32_e32 v175, v32, v169
	v_lshl_add_u64 v[52:53], v[44:45], 0, v[82:83]
	global_store_dword v[110:111], v175, off
	v_lshl_add_u64 v[32:33], v[44:45], 0, v[70:71]
	s_waitcnt vmcnt(24)
	v_fmac_f32_e32 v121, v58, v169
	v_lshl_add_u64 v[58:59], v[44:45], 0, v[86:87]
	global_load_dword v113, v[58:59], off
	global_load_dword v111, v[52:53], off
	s_waitcnt vmcnt(24)
	v_fmac_f32_e32 v118, v36, v169
	s_waitcnt vmcnt(23)
	v_fmac_f32_e32 v153, v40, v169
	v_add_f32_e32 v40, 0, v42
	v_add_f32_e32 v42, 0, v43
	v_fmac_f32_e32 v155, v42, v169
	global_store_dword v[56:57], v155, off
	v_lshl_add_u64 v[56:57], v[44:45], 0, v[80:81]
	global_store_dword v[114:115], v118, off
	global_load_dword v110, v[56:57], off
	global_load_dword v105, v[32:33], off
	v_add_f32_e32 v36, 0, v37
	global_load_dword v115, v[60:61], off
	v_fmac_f32_e32 v154, v40, v169
	v_lshl_add_u64 v[40:41], v[44:45], 0, v[68:69]
	global_load_dword v104, v[40:41], off
	v_lshl_add_u64 v[42:43], v[44:45], 0, v[76:77]
	global_store_dword v[106:107], v154, off
	global_load_dword v106, v[34:35], off
	s_waitcnt vmcnt(30)
	v_fmac_f32_e32 v119, v36, v169
	global_store_dword v[48:49], v121, off
	v_lshl_add_u64 v[48:49], v[44:45], 0, v[96:97]
	global_store_dword v[62:63], v153, off
	v_lshl_add_u64 v[36:37], v[44:45], 0, v[74:75]
	global_store_dword v[116:117], v119, off
	v_lshl_add_u64 v[38:39], v[44:45], 0, v[84:85]
	global_load_dword v114, v[48:49], off
	v_lshl_add_u64 v[62:63], v[44:45], 0, v[90:91]
	global_load_dword v107, v[36:37], off
	global_load_dword v108, v[42:43], off
	global_load_dword v112, v[38:39], off
	v_lshl_add_u64 v[44:45], v[44:45], 0, v[92:93]
	global_load_dword v116, v[62:63], off
	global_load_dword v117, v[44:45], off
	v_lshl_add_u64 v[68:69], v[64:65], 0, v[68:69]
	global_load_dword v120, v[68:69], off
	global_load_dword v118, v[94:95], off
	global_load_dword v119, v[66:67], off
	s_waitcnt vmcnt(28)
	v_fmac_f32_e32 v102, v28, v172
	global_store_dword v[50:51], v102, off
	v_lshl_add_u64 v[50:51], v[64:65], 0, v[70:71]
	v_add_f32_e32 v70, 0, v29
	v_lshl_add_u64 v[28:29], v[64:65], 0, v[72:73]
	s_waitcnt vmcnt(28)
	v_fmac_f32_e32 v103, v70, v172
	v_lshl_add_u64 v[70:71], v[64:65], 0, v[74:75]
	v_lshl_add_u64 v[72:73], v[64:65], 0, v[78:79]
	v_lshl_add_u64 v[74:75], v[64:65], 0, v[80:81]
	global_load_dword v122, v[70:71], off
	global_load_dword v123, v[72:73], off
	global_load_dword v124, v[74:75], off
	global_load_dword v102, v[50:51], off
	global_load_dword v121, v[28:29], off
	v_lshl_add_u64 v[78:79], v[64:65], 0, v[88:89]
	global_store_dword v[46:47], v103, off
	v_lshl_add_u64 v[46:47], v[64:65], 0, v[76:77]
	global_load_dword v103, v[46:47], off
	v_add_f32_e32 v76, 0, v31
	v_lshl_add_u64 v[80:81], v[64:65], 0, v[90:91]
	s_waitcnt vmcnt(25)
	v_fmac_f32_e32 v110, v16, v172
	s_waitcnt vmcnt(24)
	v_fmac_f32_e32 v105, v76, v172
	v_lshl_add_u64 v[76:77], v[64:65], 0, v[86:87]
	global_store_dword v[32:33], v105, off
	v_lshl_add_u64 v[32:33], v[64:65], 0, v[96:97]
	global_load_dword v86, v[78:79], off
	s_waitcnt vmcnt(24)
	v_fmac_f32_e32 v104, v30, v172
	global_store_dword v[40:41], v104, off
	v_lshl_add_u64 v[40:41], v[64:65], 0, v[82:83]
	global_load_dword v82, v[40:41], off
	v_lshl_add_u64 v[30:31], v[64:65], 0, v[84:85]
	global_load_dword v83, v[30:31], off
	global_load_dword v85, v[32:33], off
	global_load_dword v84, v[76:77], off
	s_waitcnt vmcnt(27)
	v_fmac_f32_e32 v106, v20, v172
	global_load_dword v20, v[80:81], off
	v_add_f32_e32 v16, 0, v17
	global_store_dword v[34:35], v106, off
	v_lshl_add_u64 v[34:35], v[64:65], 0, v[92:93]
	global_load_dword v64, v[34:35], off
	v_fmac_f32_e32 v111, v16, v172
	v_add_f32_e32 v16, 0, v18
	s_waitcnt vmcnt(23)
	v_fmac_f32_e32 v112, v16, v172
	v_add_f32_e32 v16, 0, v19
	v_fmac_f32_e32 v113, v16, v172
	v_add_f32_e32 v16, 0, v24
	v_fmac_f32_e32 v114, v16, v172
	v_add_f32_e32 v16, 0, v25
	s_waitcnt vmcnt(19)
	v_fmac_f32_e32 v118, v12, v173
	v_add_f32_e32 v12, 0, v13
	v_fmac_f32_e32 v107, v21, v172
	v_add_f32_e32 v21, 0, v22
	v_fmac_f32_e32 v115, v16, v172
	v_add_f32_e32 v16, 0, v26
	s_waitcnt vmcnt(18)
	v_fmac_f32_e32 v119, v12, v173
	v_add_f32_e32 v12, 0, v14
	v_fmac_f32_e32 v108, v21, v172
	v_add_f32_e32 v21, 0, v23
	v_fmac_f32_e32 v116, v16, v172
	v_add_f32_e32 v16, 0, v27
	v_fmac_f32_e32 v120, v12, v173
	v_add_f32_e32 v12, 0, v15
	v_fmac_f32_e32 v109, v21, v172
	v_fmac_f32_e32 v117, v16, v172
	global_store_dword v[36:37], v107, off
	global_store_dword v[42:43], v108, off
	global_store_dword v[54:55], v109, off
	global_store_dword v[56:57], v110, off
	global_store_dword v[52:53], v111, off
	global_store_dword v[38:39], v112, off
	global_store_dword v[58:59], v113, off
	global_store_dword v[48:49], v114, off
	global_store_dword v[60:61], v115, off
	global_store_dword v[62:63], v116, off
	global_store_dword v[44:45], v117, off
	global_store_dword v[94:95], v118, off
	s_waitcnt vmcnt(26)
	v_fmac_f32_e32 v124, v0, v173
	v_add_f32_e32 v0, 0, v1
	s_waitcnt vmcnt(24)
	v_fmac_f32_e32 v121, v4, v173
	v_add_f32_e32 v4, 0, v5
	v_fmac_f32_e32 v122, v4, v173
	v_add_f32_e32 v4, 0, v6
	s_waitcnt vmcnt(22)
	v_fmac_f32_e32 v103, v4, v173
	v_add_f32_e32 v4, 0, v7
	v_fmac_f32_e32 v102, v12, v173
	v_fmac_f32_e32 v123, v4, v173
	global_store_dword v[66:67], v119, off
	global_store_dword v[68:69], v120, off
	global_store_dword v[50:51], v102, off
	global_store_dword v[28:29], v121, off
	global_store_dword v[70:71], v122, off
	global_store_dword v[46:47], v103, off
	global_store_dword v[72:73], v123, off
	global_store_dword v[74:75], v124, off
	s_waitcnt vmcnt(26)
	v_fmac_f32_e32 v82, v0, v173
	v_add_f32_e32 v0, 0, v2
	s_waitcnt vmcnt(25)
	v_fmac_f32_e32 v83, v0, v173
	v_add_f32_e32 v0, 0, v3
	s_waitcnt vmcnt(23)
	v_fmac_f32_e32 v84, v0, v173
	v_add_f32_e32 v0, 0, v8
	v_fmac_f32_e32 v85, v0, v173
	v_add_f32_e32 v0, 0, v9
	v_fmac_f32_e32 v86, v0, v173
	v_add_f32_e32 v0, 0, v10
	s_waitcnt vmcnt(22)
	v_fmac_f32_e32 v20, v0, v173
	v_add_f32_e32 v0, 0, v11
	s_waitcnt vmcnt(20)
	v_fmac_f32_e32 v64, v0, v173
	global_store_dword v[40:41], v82, off
	global_store_dword v[30:31], v83, off
	global_store_dword v[76:77], v84, off
	global_store_dword v[32:33], v85, off
	global_store_dword v[78:79], v86, off
	global_store_dword v[80:81], v20, off
	global_store_dword v[34:35], v64, off
	s_cbranch_scc0 .LBB0_2477

.LBB0_2719:
	s_cmp_gt_i32 s60, 29
	s_cselect_b64 s[2:3], -1, 0
	s_cmp_lt_i32 s61, 29
	s_cselect_b64 s[4:5], -1, 0
	s_or_b64 s[2:3], s[2:3], s[4:5]
	s_and_b64 vcc, exec, s[2:3]
	s_cbranch_vccnz .LBB0_2787
	s_mov_b64 s[4:5], s[0:1]
	s_cmpk_gt_i32 s58, 0x1ff
	s_cbranch_scc1 .LBB0_2733
	s_load_dwordx2 s[10:11], s[4:5], 0xe0
	s_load_dwordx2 s[12:13], s[4:5], 0xb8
	v_lshrrev_b32_e32 v8, 3, v162
	v_lshlrev_b32_e32 v96, 11, v8
	v_mov_b32_e32 v97, 0
	v_lshlrev_b32_e32 v0, 4, v162
	v_and_b32_e32 v0, 0x70, v0
	v_mov_b32_e32 v1, v97
	s_waitcnt lgkmcnt(0)
	v_lshl_add_u64 v[2:3], s[10:11], 0, v[96:97]
	v_lshl_add_u64 v[0:1], v[2:3], 0, v[0:1]
	s_mov_b64 s[4:5], 0x9b7a100
	s_add_u32 s2, s10, 0x6b5e000
	v_xor_b32_e32 v9, v163, v162
	v_lshl_add_u64 v[98:99], v[0:1], 0, s[4:5]
	s_mov_b64 s[4:5], 0x2280000
	s_addc_u32 s3, s11, 0
	v_lshl_add_u64 v[100:101], v[0:1], 0, s[4:5]
	v_lshlrev_b32_e32 v1, 4, v9
	v_and_b32_e32 v6, 15, v162
	s_add_u32 s6, s12, 0x1000
	v_bfe_u32 v0, v162, 1, 3
	v_and_b32_e32 v1, 0x70, v1
	v_bfe_u32 v4, v162, 6, 1
	v_lshrrev_b32_e32 v5, 7, v162
	s_addc_u32 s7, s13, 0
	v_bitop3_b32 v0, v163, v0, 3 bitop3:0x6c
	v_lshl_or_b32 v134, v8, 7, v1
	v_lshlrev_b32_e32 v1, 7, v6
	s_load_dword s38, s[0:1], 0xf0
	s_add_u32 s8, s10, 0x6b7a100
	v_lshl_or_b32 v2, v5, 13, v1
	v_lshl_or_b32 v1, v4, 13, v1
	v_lshlrev_b32_e32 v0, 4, v0
	s_addc_u32 s9, s11, 0
	v_or_b32_e32 v135, v2, v0
	v_or_b32_e32 v136, v1, v0
	v_xor_b32_e32 v0, 64, v0
	v_bfe_u32 v7, v162, 4, 2
	v_or_b32_e32 v137, v2, v0
	v_or_b32_e32 v138, v1, v0
	v_lshlrev_b32_e32 v0, 6, v5
	s_cmp_lg_u64 s[12:13], 0
	v_lshl_or_b32 v139, v4, 6, v6
	s_cselect_b64 s[10:11], -1, 0
	v_lshl_or_b32 v140, v7, 2, v0
	s_mov_b32 s13, 0
	s_mov_b64 s[14:15], 0x10000
	s_mov_b32 s39, 0x10000
	s_mov_b64 s[16:17], 0x20000
	s_mov_b32 s40, 0x20000
	s_mov_b64 s[18:19], 0x30000
	s_mov_b32 s41, 0x30000
	s_mov_b64 s[20:21], 0x30100
	s_mov_b64 s[22:23], 0x20100
	s_mov_b64 s[24:25], 0x10100
	s_mov_b64 s[26:27], 0x100
	s_mov_b64 s[28:29], 0x200
	s_mov_b64 s[30:31], 0x10200
	s_mov_b64 s[34:35], 0x20200
	s_mov_b64 s[36:37], 0x30200
	v_mov_b32_e32 v141, 0x1000
	s_mov_b32 s42, s58
	v_and_b32_e32 v240, 63, v162
	v_lshrrev_b32_e32 v247, 6, v162
	v_lshrrev_b32_e32 v242, 3, v240
	v_lshl_add_u32 v242, v247, 5, v242
	v_and_b32_e32 v243, 7, v240
	v_lshrrev_b32_e32 v244, 4, v240
	v_xor_b32_e32 v243, v243, v244
	v_lshlrev_b32_e32 v243, 4, v243
	v_mov_b32_e32 v241, 0x800
	v_mad_u32_u24 v248, v242, v241, v243
	v_xor_b32_e32 v249, 64, v248
	v_add_u32_e32 v249, 0x4000, v249
	v_add_u32_e32 v250, 0x8000, v248
	v_xor_b32_e32 v251, 64, v248
	v_add_u32_e32 v251, 0xc000, v251
	v_and_b32_e32 v241, 15, v240
	v_lshrrev_b32_e32 v242, 1, v241
	v_xor_b32_e32 v242, v242, v244
	v_lshlrev_b32_e32 v242, 4, v242
	v_lshl_or_b32 v242, v241, 7, v242
	v_lshrrev_b32_e32 v243, 1, v247
	v_lshl_or_b32 v252, v243, 13, v242
	v_xor_b32_e32 v253, 64, v252
	v_and_b32_e32 v243, 1, v247
	v_lshl_or_b32 v254, v243, 13, v242
	v_xor_b32_e32 v255, 64, v254
	s_branch .LBB0_2723

.LBB0_2723:
	s_lshl_b32 s4, s42, 7
	s_and_b32 s43, s4, 0x1f80
	s_lshl_b32 s12, s43, 11
	v_lshl_add_u64 v[102:103], v[98:99], 0, s[12:13]
	v_add_co_u32_e32 v40, vcc, 0x10000, v102
	s_lshl_b32 s4, s42, 1
	s_nop 0
	v_addc_co_u32_e32 v41, vcc, 0, v103, vcc
	s_and_b32 s4, s4, 0xffffff80
	v_add_co_u32_e32 v42, vcc, 0x20000, v102
	s_ashr_i32 s5, s4, 31
	s_nop 0
	v_addc_co_u32_e32 v43, vcc, 0, v103, vcc
	s_lshl_b64 s[44:45], s[4:5], 11
	v_add_co_u32_e32 v46, vcc, 0x30000, v102
	v_lshl_add_u64 v[104:105], v[100:101], 0, s[44:45]
	s_nop 0
	v_addc_co_u32_e32 v47, vcc, 0, v103, vcc
	v_add_co_u32_e32 v48, vcc, s39, v104
	s_nop 0
	v_addc_co_u32_e32 v49, vcc, 0, v105, vcc
	v_add_co_u32_e32 v50, vcc, s40, v104
	v_addc_co_u32_e32 v51, vcc, 0, v105, vcc
	v_add_co_u32_e32 v52, vcc, s41, v104
	v_addc_co_u32_e32 v53, vcc, 0, v105, vcc
	s_mov_b32 s5, -2
	v_mov_b32_e32 v12, v97
	v_mov_b32_e32 v13, v97
	v_mov_b32_e32 v14, v97
	v_mov_b32_e32 v15, v97
	v_mov_b32_e32 v28, v97
	v_mov_b32_e32 v29, v97
	v_mov_b32_e32 v30, v97
	v_mov_b32_e32 v31, v97
	v_mov_b32_e32 v44, v97
	v_mov_b32_e32 v45, v97
	v_mov_b32_e32 v46, v97
	v_lshl_add_u64 v[106:107], v[102:103], 0, s[14:15]
	v_lshl_add_u64 v[108:109], v[102:103], 0, s[16:17]
	v_lshl_add_u64 v[110:111], v[102:103], 0, s[18:19]
	v_lshl_add_u64 v[118:119], v[102:103], 0, s[20:21]
	v_lshl_add_u64 v[120:121], v[102:103], 0, s[22:23]
	v_lshl_add_u64 v[122:123], v[102:103], 0, s[24:25]
	v_lshl_add_u64 v[124:125], v[102:103], 0, s[26:27]
	v_lshl_add_u64 v[112:113], v[104:105], 0, s[14:15]
	v_lshl_add_u64 v[114:115], v[104:105], 0, s[16:17]
	v_lshl_add_u64 v[116:117], v[104:105], 0, s[18:19]
	v_lshl_add_u64 v[128:129], v[104:105], 0, s[20:21]
	v_lshl_add_u64 v[130:131], v[104:105], 0, s[22:23]
	v_lshl_add_u64 v[132:133], v[104:105], 0, s[24:25]
	v_lshl_add_u64 v[126:127], v[104:105], 0, s[26:27]
	v_mov_b32_e32 v47, v97
	v_mov_b32_e32 v52, v97
	v_mov_b32_e32 v53, v97
	v_mov_b32_e32 v54, v97
	v_mov_b32_e32 v55, v97
	v_mov_b32_e32 v48, v97
	v_mov_b32_e32 v49, v97
	v_mov_b32_e32 v50, v97
	v_mov_b32_e32 v51, v97
	v_mov_b32_e32 v56, v97
	v_mov_b32_e32 v57, v97
	v_mov_b32_e32 v58, v97
	v_mov_b32_e32 v59, v97
	v_mov_b32_e32 v40, v97
	v_mov_b32_e32 v41, v97
	v_mov_b32_e32 v42, v97
	v_mov_b32_e32 v43, v97
	v_mov_b32_e32 v60, v97
	v_mov_b32_e32 v61, v97
	v_mov_b32_e32 v62, v97
	v_mov_b32_e32 v63, v97
	v_mov_b32_e32 v4, v97
	v_mov_b32_e32 v5, v97
	v_mov_b32_e32 v6, v97
	v_mov_b32_e32 v7, v97
	v_mov_b32_e32 v16, v97
	v_mov_b32_e32 v17, v97
	v_mov_b32_e32 v18, v97
	v_mov_b32_e32 v19, v97
	v_mov_b32_e32 v32, v97
	v_mov_b32_e32 v33, v97
	v_mov_b32_e32 v34, v97
	v_mov_b32_e32 v35, v97
	v_mov_b32_e32 v0, v97
	v_mov_b32_e32 v1, v97
	v_mov_b32_e32 v2, v97
	v_mov_b32_e32 v3, v97
	v_mov_b32_e32 v20, v97
	v_mov_b32_e32 v21, v97
	v_mov_b32_e32 v22, v97
	v_mov_b32_e32 v23, v97
	v_mov_b32_e32 v36, v97
	v_mov_b32_e32 v37, v97
	v_mov_b32_e32 v38, v97
	v_mov_b32_e32 v39, v97
	v_mov_b32_e32 v8, v97
	v_mov_b32_e32 v9, v97
	v_mov_b32_e32 v10, v97
	v_mov_b32_e32 v11, v97
	v_mov_b32_e32 v24, v97
	v_mov_b32_e32 v25, v97
	v_mov_b32_e32 v26, v97
	v_mov_b32_e32 v27, v97
	v_readfirstlane_b32 s44, v102
	v_readfirstlane_b32 s45, v103
	v_readfirstlane_b32 s48, v104
	v_readfirstlane_b32 s49, v105
	v_readfirstlane_b32 s5, v247
	s_nop 3
	s_mul_i32 s32, s5, 0x4000
	s_sub_u32 s44, s44, s32
	s_subb_u32 s45, s45, 0
	s_sub_u32 s48, s48, s32
	s_subb_u32 s49, s49, 0
	s_lshl_b32 s5, s5, 12
	s_add_u32 m0, s5, 0x0
	v_mov_b32_e32 v60, 0
	global_load_lds_dwordx4 v248, s[44:45]
	v_mov_b32_e32 v61, 0
	s_add_u32 m0, s5, 0x400
	v_mov_b32_e32 v62, 0
	global_load_lds_dwordx4 v249, s[44:45]
	v_mov_b32_e32 v63, 0
	s_add_u32 m0, s5, 0x800
	v_mov_b32_e32 v40, 0
	global_load_lds_dwordx4 v250, s[44:45]
	v_mov_b32_e32 v41, 0
	s_add_u32 m0, s5, 0xc00
	v_mov_b32_e32 v42, 0
	global_load_lds_dwordx4 v251, s[44:45]
	v_mov_b32_e32 v43, 0
	s_add_u32 m0, s5, 0x8000
	v_mov_b32_e32 v24, 0
	global_load_lds_dwordx4 v248, s[48:49]
	v_mov_b32_e32 v25, 0
	s_add_u32 m0, s5, 0x8400
	v_mov_b32_e32 v26, 0
	global_load_lds_dwordx4 v249, s[48:49]
	v_mov_b32_e32 v27, 0
	s_add_u32 m0, s5, 0x8800
	v_mov_b32_e32 v8, 0
	global_load_lds_dwordx4 v250, s[48:49]
	v_mov_b32_e32 v9, 0
	s_add_u32 m0, s5, 0x8c00
	v_mov_b32_e32 v10, 0
	global_load_lds_dwordx4 v251, s[48:49]
	v_mov_b32_e32 v11, 0
	s_add_u32 s44, s44, 0x80
	s_addc_u32 s45, s45, 0
	s_add_u32 s48, s48, 0x80
	s_addc_u32 s49, s49, 0
	s_add_u32 m0, s5, 0x4000
	v_mov_b32_e32 v56, 0
	global_load_lds_dwordx4 v248, s[44:45]
	v_mov_b32_e32 v57, 0
	s_add_u32 m0, s5, 0x4400
	v_mov_b32_e32 v58, 0
	global_load_lds_dwordx4 v249, s[44:45]
	v_mov_b32_e32 v59, 0
	s_add_u32 m0, s5, 0x4800
	v_mov_b32_e32 v36, 0
	global_load_lds_dwordx4 v250, s[44:45]
	v_mov_b32_e32 v37, 0
	s_add_u32 m0, s5, 0x4c00
	v_mov_b32_e32 v38, 0
	global_load_lds_dwordx4 v251, s[44:45]
	v_mov_b32_e32 v39, 0
	s_add_u32 m0, s5, 0xc000
	v_mov_b32_e32 v20, 0
	global_load_lds_dwordx4 v248, s[48:49]
	v_mov_b32_e32 v21, 0
	s_add_u32 m0, s5, 0xc400
	v_mov_b32_e32 v22, 0
	global_load_lds_dwordx4 v249, s[48:49]
	v_mov_b32_e32 v23, 0
	s_add_u32 m0, s5, 0xc800
	v_mov_b32_e32 v0, 0
	global_load_lds_dwordx4 v250, s[48:49]
	v_mov_b32_e32 v1, 0
	s_add_u32 m0, s5, 0xcc00
	v_mov_b32_e32 v2, 0
	global_load_lds_dwordx4 v251, s[48:49]
	v_mov_b32_e32 v3, 0
	s_add_u32 s44, s44, 0x80
	s_addc_u32 s45, s45, 0
	s_add_u32 s48, s48, 0x80
	s_addc_u32 s49, s49, 0
	v_mov_b32_e32 v48, 0
	v_mov_b32_e32 v49, 0
	v_mov_b32_e32 v50, 0
	v_mov_b32_e32 v51, 0
	v_mov_b32_e32 v32, 0
	v_mov_b32_e32 v33, 0
	v_mov_b32_e32 v34, 0
	v_mov_b32_e32 v35, 0
	v_mov_b32_e32 v16, 0
	v_mov_b32_e32 v17, 0
	v_mov_b32_e32 v18, 0
	v_mov_b32_e32 v19, 0
	v_mov_b32_e32 v4, 0
	v_mov_b32_e32 v5, 0
	v_mov_b32_e32 v6, 0
	v_mov_b32_e32 v7, 0
	v_mov_b32_e32 v52, 0
	v_mov_b32_e32 v53, 0
	v_mov_b32_e32 v54, 0
	v_mov_b32_e32 v55, 0
	v_mov_b32_e32 v44, 0
	v_mov_b32_e32 v45, 0
	v_mov_b32_e32 v46, 0
	v_mov_b32_e32 v47, 0
	v_mov_b32_e32 v28, 0
	v_mov_b32_e32 v29, 0
	v_mov_b32_e32 v30, 0
	v_mov_b32_e32 v31, 0
	v_mov_b32_e32 v12, 0
	v_mov_b32_e32 v13, 0
	v_mov_b32_e32 v14, 0
	v_mov_b32_e32 v15, 0
	s_mov_b32 s12, 7
.Lg29_loop:
	s_waitcnt vmcnt(8)
	s_barrier
	ds_read_b128 v[64:67], v252 offset:0
	ds_read_b128 v[104:107], v254 offset:32768
	ds_read_b128 v[108:111], v254 offset:34816
	ds_read_b128 v[112:115], v254 offset:36864
	ds_read_b128 v[116:119], v254 offset:38912
	ds_read_b128 v[68:71], v252 offset:2048
	ds_read_b128 v[72:75], v252 offset:4096
	ds_read_b128 v[76:79], v252 offset:6144
	ds_read_b128 v[80:83], v253 offset:0
	ds_read_b128 v[120:123], v255 offset:32768
	ds_read_b128 v[124:127], v255 offset:34816
	ds_read_b128 v[132:135], v255 offset:36864
	ds_read_b128 v[144:147], v255 offset:38912
	s_waitcnt lgkmcnt(11)
	v_mfma_f32_16x16x32_bf16 v[60:63], v[64:67], v[104:107], v[60:63]
	s_waitcnt lgkmcnt(10)
	v_mfma_f32_16x16x32_bf16 v[40:43], v[64:67], v[108:111], v[40:43]
	s_waitcnt lgkmcnt(9)
	v_mfma_f32_16x16x32_bf16 v[24:27], v[64:67], v[112:115], v[24:27]
	s_waitcnt lgkmcnt(8)
	v_mfma_f32_16x16x32_bf16 v[8:11], v[64:67], v[116:119], v[8:11]
	ds_read_b128 v[84:87], v253 offset:2048
	ds_read_b128 v[88:91], v253 offset:4096
	ds_read_b128 v[92:95], v253 offset:6144
	s_waitcnt lgkmcnt(10)
	v_mfma_f32_16x16x32_bf16 v[56:59], v[68:71], v[104:107], v[56:59]
	v_mfma_f32_16x16x32_bf16 v[36:39], v[68:71], v[108:111], v[36:39]
	v_mfma_f32_16x16x32_bf16 v[20:23], v[68:71], v[112:115], v[20:23]
	v_mfma_f32_16x16x32_bf16 v[0:3], v[68:71], v[116:119], v[0:3]
	s_waitcnt lgkmcnt(9)
	v_mfma_f32_16x16x32_bf16 v[48:51], v[72:75], v[104:107], v[48:51]
	v_mfma_f32_16x16x32_bf16 v[32:35], v[72:75], v[108:111], v[32:35]
	v_mfma_f32_16x16x32_bf16 v[16:19], v[72:75], v[112:115], v[16:19]
	v_mfma_f32_16x16x32_bf16 v[4:7], v[72:75], v[116:119], v[4:7]
	s_waitcnt lgkmcnt(8)
	v_mfma_f32_16x16x32_bf16 v[52:55], v[76:79], v[104:107], v[52:55]
	v_mfma_f32_16x16x32_bf16 v[44:47], v[76:79], v[108:111], v[44:47]
	v_mfma_f32_16x16x32_bf16 v[28:31], v[76:79], v[112:115], v[28:31]
	v_mfma_f32_16x16x32_bf16 v[12:15], v[76:79], v[116:119], v[12:15]
	s_waitcnt lgkmcnt(0)
	s_barrier
	s_add_u32 m0, s5, 0x0
	v_mfma_f32_16x16x32_bf16 v[60:63], v[80:83], v[120:123], v[60:63]
	global_load_lds_dwordx4 v248, s[44:45]
	v_mfma_f32_16x16x32_bf16 v[40:43], v[80:83], v[124:127], v[40:43]
	s_add_u32 m0, s5, 0x400
	v_mfma_f32_16x16x32_bf16 v[24:27], v[80:83], v[132:135], v[24:27]
	global_load_lds_dwordx4 v249, s[44:45]
	v_mfma_f32_16x16x32_bf16 v[8:11], v[80:83], v[144:147], v[8:11]
	s_add_u32 m0, s5, 0x800
	v_mfma_f32_16x16x32_bf16 v[56:59], v[84:87], v[120:123], v[56:59]
	global_load_lds_dwordx4 v250, s[44:45]
	v_mfma_f32_16x16x32_bf16 v[36:39], v[84:87], v[124:127], v[36:39]
	s_add_u32 m0, s5, 0xc00
	v_mfma_f32_16x16x32_bf16 v[20:23], v[84:87], v[132:135], v[20:23]
	global_load_lds_dwordx4 v251, s[44:45]
	v_mfma_f32_16x16x32_bf16 v[0:3], v[84:87], v[144:147], v[0:3]
	s_add_u32 m0, s5, 0x8000
	v_mfma_f32_16x16x32_bf16 v[48:51], v[88:91], v[120:123], v[48:51]
	global_load_lds_dwordx4 v248, s[48:49]
	v_mfma_f32_16x16x32_bf16 v[32:35], v[88:91], v[124:127], v[32:35]
	s_add_u32 m0, s5, 0x8400
	v_mfma_f32_16x16x32_bf16 v[16:19], v[88:91], v[132:135], v[16:19]
	global_load_lds_dwordx4 v249, s[48:49]
	v_mfma_f32_16x16x32_bf16 v[4:7], v[88:91], v[144:147], v[4:7]
	s_add_u32 m0, s5, 0x8800
	v_mfma_f32_16x16x32_bf16 v[52:55], v[92:95], v[120:123], v[52:55]
	global_load_lds_dwordx4 v250, s[48:49]
	v_mfma_f32_16x16x32_bf16 v[44:47], v[92:95], v[124:127], v[44:47]
	s_add_u32 m0, s5, 0x8c00
	v_mfma_f32_16x16x32_bf16 v[28:31], v[92:95], v[132:135], v[28:31]
	global_load_lds_dwordx4 v251, s[48:49]
	v_mfma_f32_16x16x32_bf16 v[12:15], v[92:95], v[144:147], v[12:15]
	s_add_u32 s44, s44, 0x80
	s_addc_u32 s45, s45, 0
	s_add_u32 s48, s48, 0x80
	s_addc_u32 s49, s49, 0
	s_waitcnt vmcnt(8)
	s_barrier
	ds_read_b128 v[64:67], v252 offset:16384
	ds_read_b128 v[104:107], v254 offset:49152
	ds_read_b128 v[108:111], v254 offset:51200
	ds_read_b128 v[112:115], v254 offset:53248
	ds_read_b128 v[116:119], v254 offset:55296
	ds_read_b128 v[68:71], v252 offset:18432
	ds_read_b128 v[72:75], v252 offset:20480
	ds_read_b128 v[76:79], v252 offset:22528
	ds_read_b128 v[80:83], v253 offset:16384
	ds_read_b128 v[120:123], v255 offset:49152
	ds_read_b128 v[124:127], v255 offset:51200
	ds_read_b128 v[132:135], v255 offset:53248
	ds_read_b128 v[144:147], v255 offset:55296
	s_waitcnt lgkmcnt(11)
	v_mfma_f32_16x16x32_bf16 v[60:63], v[64:67], v[104:107], v[60:63]
	s_waitcnt lgkmcnt(10)
	v_mfma_f32_16x16x32_bf16 v[40:43], v[64:67], v[108:111], v[40:43]
	s_waitcnt lgkmcnt(9)
	v_mfma_f32_16x16x32_bf16 v[24:27], v[64:67], v[112:115], v[24:27]
	s_waitcnt lgkmcnt(8)
	v_mfma_f32_16x16x32_bf16 v[8:11], v[64:67], v[116:119], v[8:11]
	ds_read_b128 v[84:87], v253 offset:18432
	ds_read_b128 v[88:91], v253 offset:20480
	ds_read_b128 v[92:95], v253 offset:22528
	s_waitcnt lgkmcnt(10)
	v_mfma_f32_16x16x32_bf16 v[56:59], v[68:71], v[104:107], v[56:59]
	v_mfma_f32_16x16x32_bf16 v[36:39], v[68:71], v[108:111], v[36:39]
	v_mfma_f32_16x16x32_bf16 v[20:23], v[68:71], v[112:115], v[20:23]
	v_mfma_f32_16x16x32_bf16 v[0:3], v[68:71], v[116:119], v[0:3]
	s_waitcnt lgkmcnt(9)
	v_mfma_f32_16x16x32_bf16 v[48:51], v[72:75], v[104:107], v[48:51]
	v_mfma_f32_16x16x32_bf16 v[32:35], v[72:75], v[108:111], v[32:35]
	v_mfma_f32_16x16x32_bf16 v[16:19], v[72:75], v[112:115], v[16:19]
	v_mfma_f32_16x16x32_bf16 v[4:7], v[72:75], v[116:119], v[4:7]
	s_waitcnt lgkmcnt(8)
	v_mfma_f32_16x16x32_bf16 v[52:55], v[76:79], v[104:107], v[52:55]
	v_mfma_f32_16x16x32_bf16 v[44:47], v[76:79], v[108:111], v[44:47]
	v_mfma_f32_16x16x32_bf16 v[28:31], v[76:79], v[112:115], v[28:31]
	v_mfma_f32_16x16x32_bf16 v[12:15], v[76:79], v[116:119], v[12:15]
	s_waitcnt lgkmcnt(0)
	s_barrier
	s_add_u32 m0, s5, 0x4000
	v_mfma_f32_16x16x32_bf16 v[60:63], v[80:83], v[120:123], v[60:63]
	global_load_lds_dwordx4 v248, s[44:45]
	v_mfma_f32_16x16x32_bf16 v[40:43], v[80:83], v[124:127], v[40:43]
	s_add_u32 m0, s5, 0x4400
	v_mfma_f32_16x16x32_bf16 v[24:27], v[80:83], v[132:135], v[24:27]
	global_load_lds_dwordx4 v249, s[44:45]
	v_mfma_f32_16x16x32_bf16 v[8:11], v[80:83], v[144:147], v[8:11]
	s_add_u32 m0, s5, 0x4800
	v_mfma_f32_16x16x32_bf16 v[56:59], v[84:87], v[120:123], v[56:59]
	global_load_lds_dwordx4 v250, s[44:45]
	v_mfma_f32_16x16x32_bf16 v[36:39], v[84:87], v[124:127], v[36:39]
	s_add_u32 m0, s5, 0x4c00
	v_mfma_f32_16x16x32_bf16 v[20:23], v[84:87], v[132:135], v[20:23]
	global_load_lds_dwordx4 v251, s[44:45]
	v_mfma_f32_16x16x32_bf16 v[0:3], v[84:87], v[144:147], v[0:3]
	s_add_u32 m0, s5, 0xc000
	v_mfma_f32_16x16x32_bf16 v[48:51], v[88:91], v[120:123], v[48:51]
	global_load_lds_dwordx4 v248, s[48:49]
	v_mfma_f32_16x16x32_bf16 v[32:35], v[88:91], v[124:127], v[32:35]
	s_add_u32 m0, s5, 0xc400
	v_mfma_f32_16x16x32_bf16 v[16:19], v[88:91], v[132:135], v[16:19]
	global_load_lds_dwordx4 v249, s[48:49]
	v_mfma_f32_16x16x32_bf16 v[4:7], v[88:91], v[144:147], v[4:7]
	s_add_u32 m0, s5, 0xc800
	v_mfma_f32_16x16x32_bf16 v[52:55], v[92:95], v[120:123], v[52:55]
	global_load_lds_dwordx4 v250, s[48:49]
	v_mfma_f32_16x16x32_bf16 v[44:47], v[92:95], v[124:127], v[44:47]
	s_add_u32 m0, s5, 0xcc00
	v_mfma_f32_16x16x32_bf16 v[28:31], v[92:95], v[132:135], v[28:31]
	global_load_lds_dwordx4 v251, s[48:49]
	v_mfma_f32_16x16x32_bf16 v[12:15], v[92:95], v[144:147], v[12:15]
	s_add_u32 s44, s44, 0x80
	s_addc_u32 s45, s45, 0
	s_add_u32 s48, s48, 0x80
	s_addc_u32 s49, s49, 0
	s_sub_u32 s12, s12, 1
	s_cmp_lg_u32 s12, 0
	s_cbranch_scc1 .Lg29_loop
	s_waitcnt vmcnt(8)
	s_barrier
	ds_read_b128 v[64:67], v252 offset:0
	ds_read_b128 v[104:107], v254 offset:32768
	ds_read_b128 v[108:111], v254 offset:34816
	ds_read_b128 v[112:115], v254 offset:36864
	ds_read_b128 v[116:119], v254 offset:38912
	ds_read_b128 v[68:71], v252 offset:2048
	ds_read_b128 v[72:75], v252 offset:4096
	ds_read_b128 v[76:79], v252 offset:6144
	ds_read_b128 v[80:83], v253 offset:0
	ds_read_b128 v[120:123], v255 offset:32768
	ds_read_b128 v[124:127], v255 offset:34816
	ds_read_b128 v[132:135], v255 offset:36864
	ds_read_b128 v[144:147], v255 offset:38912
	s_waitcnt lgkmcnt(11)
	v_mfma_f32_16x16x32_bf16 v[60:63], v[64:67], v[104:107], v[60:63]
	s_waitcnt lgkmcnt(10)
	v_mfma_f32_16x16x32_bf16 v[40:43], v[64:67], v[108:111], v[40:43]
	s_waitcnt lgkmcnt(9)
	v_mfma_f32_16x16x32_bf16 v[24:27], v[64:67], v[112:115], v[24:27]
	s_waitcnt lgkmcnt(8)
	v_mfma_f32_16x16x32_bf16 v[8:11], v[64:67], v[116:119], v[8:11]
	ds_read_b128 v[84:87], v253 offset:2048
	ds_read_b128 v[88:91], v253 offset:4096
	ds_read_b128 v[92:95], v253 offset:6144
	s_waitcnt lgkmcnt(10)
	v_mfma_f32_16x16x32_bf16 v[56:59], v[68:71], v[104:107], v[56:59]
	v_mfma_f32_16x16x32_bf16 v[36:39], v[68:71], v[108:111], v[36:39]
	v_mfma_f32_16x16x32_bf16 v[20:23], v[68:71], v[112:115], v[20:23]
	v_mfma_f32_16x16x32_bf16 v[0:3], v[68:71], v[116:119], v[0:3]
	s_waitcnt lgkmcnt(9)
	v_mfma_f32_16x16x32_bf16 v[48:51], v[72:75], v[104:107], v[48:51]
	v_mfma_f32_16x16x32_bf16 v[32:35], v[72:75], v[108:111], v[32:35]
	v_mfma_f32_16x16x32_bf16 v[16:19], v[72:75], v[112:115], v[16:19]
	v_mfma_f32_16x16x32_bf16 v[4:7], v[72:75], v[116:119], v[4:7]
	s_waitcnt lgkmcnt(8)
	v_mfma_f32_16x16x32_bf16 v[52:55], v[76:79], v[104:107], v[52:55]
	v_mfma_f32_16x16x32_bf16 v[44:47], v[76:79], v[108:111], v[44:47]
	v_mfma_f32_16x16x32_bf16 v[28:31], v[76:79], v[112:115], v[28:31]
	v_mfma_f32_16x16x32_bf16 v[12:15], v[76:79], v[116:119], v[12:15]
	s_waitcnt lgkmcnt(0)
	s_barrier
	v_mfma_f32_16x16x32_bf16 v[60:63], v[80:83], v[120:123], v[60:63]
	v_mfma_f32_16x16x32_bf16 v[40:43], v[80:83], v[124:127], v[40:43]
	v_mfma_f32_16x16x32_bf16 v[24:27], v[80:83], v[132:135], v[24:27]
	v_mfma_f32_16x16x32_bf16 v[8:11], v[80:83], v[144:147], v[8:11]
	v_mfma_f32_16x16x32_bf16 v[56:59], v[84:87], v[120:123], v[56:59]
	v_mfma_f32_16x16x32_bf16 v[36:39], v[84:87], v[124:127], v[36:39]
	v_mfma_f32_16x16x32_bf16 v[20:23], v[84:87], v[132:135], v[20:23]
	v_mfma_f32_16x16x32_bf16 v[0:3], v[84:87], v[144:147], v[0:3]
	v_mfma_f32_16x16x32_bf16 v[48:51], v[88:91], v[120:123], v[48:51]
	v_mfma_f32_16x16x32_bf16 v[32:35], v[88:91], v[124:127], v[32:35]
	v_mfma_f32_16x16x32_bf16 v[16:19], v[88:91], v[132:135], v[16:19]
	v_mfma_f32_16x16x32_bf16 v[4:7], v[88:91], v[144:147], v[4:7]
	v_mfma_f32_16x16x32_bf16 v[52:55], v[92:95], v[120:123], v[52:55]
	v_mfma_f32_16x16x32_bf16 v[44:47], v[92:95], v[124:127], v[44:47]
	v_mfma_f32_16x16x32_bf16 v[28:31], v[92:95], v[132:135], v[28:31]
	v_mfma_f32_16x16x32_bf16 v[12:15], v[92:95], v[144:147], v[12:15]
	s_waitcnt vmcnt(0)
	s_barrier
	ds_read_b128 v[64:67], v252 offset:16384
	ds_read_b128 v[104:107], v254 offset:49152
	ds_read_b128 v[108:111], v254 offset:51200
	ds_read_b128 v[112:115], v254 offset:53248
	ds_read_b128 v[116:119], v254 offset:55296
	ds_read_b128 v[68:71], v252 offset:18432
	ds_read_b128 v[72:75], v252 offset:20480
	ds_read_b128 v[76:79], v252 offset:22528
	ds_read_b128 v[80:83], v253 offset:16384
	ds_read_b128 v[120:123], v255 offset:49152
	ds_read_b128 v[124:127], v255 offset:51200
	ds_read_b128 v[132:135], v255 offset:53248
	ds_read_b128 v[144:147], v255 offset:55296
	s_waitcnt lgkmcnt(11)
	v_mfma_f32_16x16x32_bf16 v[60:63], v[64:67], v[104:107], v[60:63]
	s_waitcnt lgkmcnt(10)
	v_mfma_f32_16x16x32_bf16 v[40:43], v[64:67], v[108:111], v[40:43]
	s_waitcnt lgkmcnt(9)
	v_mfma_f32_16x16x32_bf16 v[24:27], v[64:67], v[112:115], v[24:27]
	s_waitcnt lgkmcnt(8)
	v_mfma_f32_16x16x32_bf16 v[8:11], v[64:67], v[116:119], v[8:11]
	ds_read_b128 v[84:87], v253 offset:18432
	ds_read_b128 v[88:91], v253 offset:20480
	ds_read_b128 v[92:95], v253 offset:22528
	s_waitcnt lgkmcnt(10)
	v_mfma_f32_16x16x32_bf16 v[56:59], v[68:71], v[104:107], v[56:59]
	v_mfma_f32_16x16x32_bf16 v[36:39], v[68:71], v[108:111], v[36:39]
	v_mfma_f32_16x16x32_bf16 v[20:23], v[68:71], v[112:115], v[20:23]
	v_mfma_f32_16x16x32_bf16 v[0:3], v[68:71], v[116:119], v[0:3]
	s_waitcnt lgkmcnt(9)
	v_mfma_f32_16x16x32_bf16 v[48:51], v[72:75], v[104:107], v[48:51]
	v_mfma_f32_16x16x32_bf16 v[32:35], v[72:75], v[108:111], v[32:35]
	v_mfma_f32_16x16x32_bf16 v[16:19], v[72:75], v[112:115], v[16:19]
	v_mfma_f32_16x16x32_bf16 v[4:7], v[72:75], v[116:119], v[4:7]
	s_waitcnt lgkmcnt(8)
	v_mfma_f32_16x16x32_bf16 v[52:55], v[76:79], v[104:107], v[52:55]
	v_mfma_f32_16x16x32_bf16 v[44:47], v[76:79], v[108:111], v[44:47]
	v_mfma_f32_16x16x32_bf16 v[28:31], v[76:79], v[112:115], v[28:31]
	v_mfma_f32_16x16x32_bf16 v[12:15], v[76:79], v[116:119], v[12:15]
	s_waitcnt lgkmcnt(0)
	s_barrier
	v_mfma_f32_16x16x32_bf16 v[60:63], v[80:83], v[120:123], v[60:63]
	v_mfma_f32_16x16x32_bf16 v[40:43], v[80:83], v[124:127], v[40:43]
	v_mfma_f32_16x16x32_bf16 v[24:27], v[80:83], v[132:135], v[24:27]
	v_mfma_f32_16x16x32_bf16 v[8:11], v[80:83], v[144:147], v[8:11]
	v_mfma_f32_16x16x32_bf16 v[56:59], v[84:87], v[120:123], v[56:59]
	v_mfma_f32_16x16x32_bf16 v[36:39], v[84:87], v[124:127], v[36:39]
	v_mfma_f32_16x16x32_bf16 v[20:23], v[84:87], v[132:135], v[20:23]
	v_mfma_f32_16x16x32_bf16 v[0:3], v[84:87], v[144:147], v[0:3]
	v_mfma_f32_16x16x32_bf16 v[48:51], v[88:91], v[120:123], v[48:51]
	v_mfma_f32_16x16x32_bf16 v[32:35], v[88:91], v[124:127], v[32:35]
	v_mfma_f32_16x16x32_bf16 v[16:19], v[88:91], v[132:135], v[16:19]
	v_mfma_f32_16x16x32_bf16 v[4:7], v[88:91], v[144:147], v[4:7]
	v_mfma_f32_16x16x32_bf16 v[52:55], v[92:95], v[120:123], v[52:55]
	v_mfma_f32_16x16x32_bf16 v[44:47], v[92:95], v[124:127], v[44:47]
	v_mfma_f32_16x16x32_bf16 v[28:31], v[92:95], v[132:135], v[28:31]
	v_mfma_f32_16x16x32_bf16 v[12:15], v[92:95], v[144:147], v[12:15]
	s_nop 7
	s_nop 1
	s_waitcnt vmcnt(7)
	v_sub_co_u32_e32 v64, vcc, s43, v141
	s_nop 0
	v_readfirstlane_b32 s5, v64
	s_lshr_b32 s5, s5, 10
	s_add_i32 s5, s5, 1
	s_and_b64 s[44:45], vcc, exec
	s_cselect_b32 s5, 0, s5
	s_mul_hi_u32 s12, s5, 0x6000
	s_mulk_i32 s5, 0x6000
	s_add_u32 s44, s2, s5
	v_or_b32_e32 v64, s4, v139
	s_addc_u32 s45, s3, s12
	v_ashrrev_i32_e32 v65, 31, v64
	v_lshl_add_u64 v[66:67], v[64:65], 2, s[44:45]
	global_load_dword v105, v[66:67], off
	s_waitcnt vmcnt(7)
	v_cndmask_b32_e64 v68, 0, 1, s[10:11]
	v_mov_b32_e32 v104, 0
	v_cmp_ne_u32_e64 s[4:5], 1, v68
	s_andn2_b64 vcc, exec, s[10:11]
	v_mov_b32_e32 v106, 0
	s_cbranch_vccnz .LBB0_2727
	v_lshl_add_u64 v[68:69], v[64:65], 2, s[6:7]
	global_load_dword v106, v[68:69], off

.LBB0_2909:
	s_cmp_gt_i32 s60, 32
	s_cselect_b64 s[2:3], -1, 0
	s_cmp_lt_i32 s61, 32
	s_cselect_b64 s[4:5], -1, 0
	s_or_b64 s[2:3], s[2:3], s[4:5]
	s_and_b64 vcc, exec, s[2:3]
	s_cbranch_vccnz .LBB0_2969
	s_mov_b64 s[4:5], s[0:1]
	s_cmpk_gt_i32 s58, 0x1ff
	s_cbranch_scc1 .LBB0_2915
	s_load_dwordx2 s[6:7], s[4:5], 0xe0
	v_lshrrev_b32_e32 v8, 3, v162
	v_mul_u32_u24_e32 v0, 0xb00, v8
	v_lshlrev_b32_e32 v96, 1, v0
	v_mov_b32_e32 v97, 0
	s_waitcnt lgkmcnt(0)
	s_add_u32 s2, s6, 0x6b61000
	s_addc_u32 s3, s7, 0
	v_lshlrev_b32_e32 v0, 4, v162
	s_add_u32 s4, s6, 0x6b7a100
	v_and_b32_e32 v0, 0x70, v0
	v_mov_b32_e32 v1, v97
	v_lshl_add_u64 v[2:3], s[6:7], 0, v[96:97]
	s_addc_u32 s5, s7, 0
	v_lshl_add_u64 v[0:1], v[2:3], 0, v[0:1]
	s_mov_b64 s[6:7], 0x9b7a100
	v_xor_b32_e32 v9, v163, v162
	v_lshl_add_u64 v[98:99], v[0:1], 0, s[6:7]
	s_mov_b64 s[6:7], 0x6100000
	v_lshl_add_u64 v[100:101], v[0:1], 0, s[6:7]
	v_lshlrev_b32_e32 v1, 4, v9
	v_and_b32_e32 v6, 15, v162
	v_bfe_u32 v0, v162, 1, 3
	v_and_b32_e32 v1, 0x70, v1
	v_bfe_u32 v4, v162, 6, 1
	v_lshrrev_b32_e32 v5, 7, v162
	v_bitop3_b32 v0, v163, v0, 3 bitop3:0x6c
	v_lshl_or_b32 v142, v8, 7, v1
	v_lshlrev_b32_e32 v1, 7, v6
	s_load_dword s30, s[0:1], 0xf0
	v_lshl_or_b32 v2, v5, 13, v1
	v_lshl_or_b32 v1, v4, 13, v1
	v_lshlrev_b32_e32 v0, 4, v0
	v_or_b32_e32 v143, v2, v0
	v_or_b32_e32 v144, v1, v0
	v_xor_b32_e32 v0, 64, v0
	v_bfe_u32 v7, v162, 4, 2
	v_or_b32_e32 v145, v2, v0
	v_or_b32_e32 v146, v1, v0
	v_lshlrev_b32_e32 v0, 6, v5
	v_lshl_or_b32 v147, v4, 6, v6
	v_lshl_or_b32 v148, v7, 2, v0
	s_mov_b32 s7, 0
	v_mov_b32_e32 v149, 0x1600
	s_mov_b64 s[8:9], 0x2c000
	s_mov_b32 s31, 0x2c000
	s_mov_b64 s[10:11], 0x58000
	s_mov_b32 s34, 0x58000
	s_mov_b64 s[12:13], 0x84000
	s_mov_b32 s35, 0x84000
	s_mov_b64 s[14:15], 0x84100
	s_mov_b64 s[16:17], 0x58100
	s_mov_b64 s[18:19], 0x2c100
	s_mov_b64 s[20:21], 0x100
	s_mov_b64 s[22:23], 0x200
	s_mov_b64 s[24:25], 0x2c200
	s_mov_b64 s[26:27], 0x58200
	s_mov_b64 s[28:29], 0x84200
	v_mov_b32_e32 v150, 0x1000
	s_mov_b32 s36, s58
	v_and_b32_e32 v240, 63, v162
	v_lshrrev_b32_e32 v247, 6, v162
	v_lshrrev_b32_e32 v242, 3, v240
	v_lshl_add_u32 v242, v247, 5, v242
	v_and_b32_e32 v243, 7, v240
	v_lshrrev_b32_e32 v244, 4, v240
	v_xor_b32_e32 v243, v243, v244
	v_lshlrev_b32_e32 v243, 4, v243
	v_mov_b32_e32 v241, 0x1600
	v_mad_u32_u24 v248, v242, v241, v243
	v_xor_b32_e32 v249, 64, v248
	v_add_u32_e32 v249, 0xb000, v249
	v_add_u32_e32 v250, 0x16000, v248
	v_xor_b32_e32 v251, 64, v248
	v_add_u32_e32 v251, 0x21000, v251
	v_and_b32_e32 v241, 15, v240
	v_lshrrev_b32_e32 v242, 1, v241
	v_xor_b32_e32 v242, v242, v244
	v_lshlrev_b32_e32 v242, 4, v242
	v_lshl_or_b32 v242, v241, 7, v242
	v_lshrrev_b32_e32 v243, 1, v247
	v_lshl_or_b32 v252, v243, 13, v242
	v_xor_b32_e32 v253, 64, v252
	v_and_b32_e32 v243, 1, v247
	v_lshl_or_b32 v254, v243, 13, v242
	v_xor_b32_e32 v255, 64, v254
